# all GEMM K-loops: removed the redundant s_waitcnt lgkmcnt(0) between the barrier and the first MFMA of each block (the wait before the barrier already covers every LDS read)
# speedup vs baseline: 1.0059x; 1.0059x over previous
.LBB0_175:
	s_ashr_i32 s57, s56, 31
	s_lshl_b64 s[52:53], s[56:57], 20
	v_readlane_b32 s66, v254, 17
	v_readlane_b32 s67, v254, 18
	s_add_u32 s66, s66, s52
	s_addc_u32 s67, s67, s53
	s_and_b64 s[52:53], s[6:7], exec
	s_cselect_b32 s11, s67, s9
	s_cselect_b32 s13, s66, s8
	s_ashr_i32 s61, s60, 31
	s_lshl_b64 s[52:53], s[60:61], 20
	v_readlane_b32 s68, v254, 21
	v_readlane_b32 s69, v254, 22
	s_add_u32 s88, s68, s52
	s_addc_u32 s89, s69, s53
	s_and_b64 s[52:53], s[6:7], exec
	s_cselect_b32 s57, s89, s15
	s_cselect_b32 s61, s88, s14
	s_add_u32 s8, s8, 0x80080
	s_addc_u32 s9, s9, 0
	s_add_u32 s68, s14, 0x100
	s_addc_u32 s69, s15, 0
	s_mov_b32 s90, -2
	s_add_u32 s14, s8, 0xfff80080
	s_addc_u32 s15, s9, -1
	s_add_i32 s91, 0, 0x10000
	s_cmp_eq_u32 s90, 28
	s_cselect_b32 s53, s11, s15
	s_cselect_b32 s52, s13, s14
	v_add_u32_e32 v14, s91, v188
	s_cselect_b32 s15, s57, s69
	s_cselect_b32 s14, s61, s68
	s_add_i32 s96, 0, 0x14000
	ds_read_b128 v[6:9], v14
	ds_read_b128 v[10:13], v14 offset:1024
	ds_read_b128 v[140:143], v14 offset:2048
	ds_read_b128 v[144:147], v14 offset:3072
	v_add_u32_e32 v14, s96, v188
	ds_read_b128 v[148:151], v14
	ds_read_b128 v[152:155], v14 offset:1024
	ds_read_b128 v[180:183], v14 offset:2048
	ds_read_b128 v[208:211], v14 offset:3072
	v_lshl_add_u64 v[14:15], s[8:9], 0, v[176:177]
	s_add_i32 m0, s40, 0xc000
	ds_read_b128 v[212:215], v206
	ds_read_b128 v[216:219], v206 offset:1024
	ds_read_b128 v[220:223], v206 offset:2048
	ds_read_b128 v[224:227], v206 offset:3072
	ds_read_b128 v[238:241], v206 offset:4096
	ds_read_b128 v[242:245], v206 offset:5120
	ds_read_b128 v[246:249], v206 offset:6144
	ds_read_b128 v[250:253], v206 offset:7168
	global_load_lds_dwordx4 v[14:15], off
	v_lshl_add_u64 v[14:15], s[8:9], 0, v[178:179]
	s_add_i32 m0, s40, 0xe000
	s_nop 0
	global_load_lds_dwordx4 v[14:15], off
	s_waitcnt vmcnt(8)
	s_waitcnt lgkmcnt(0)
	s_barrier
	s_setprio 1
	v_mfma_f32_16x16x32_bf16 v[136:139], v[6:9], v[212:215], 0
	v_mfma_f32_16x16x32_bf16 v[104:107], v[140:143], v[212:215], 0
	v_mfma_f32_16x16x32_bf16 v[132:135], v[6:9], v[220:223], 0
	v_mfma_f32_16x16x32_bf16 v[100:103], v[140:143], v[220:223], 0
	v_mfma_f32_16x16x32_bf16 v[128:131], v[6:9], v[238:241], 0
	v_mfma_f32_16x16x32_bf16 v[96:99], v[140:143], v[238:241], 0
	v_mfma_f32_16x16x32_bf16 v[124:127], v[6:9], v[246:249], 0
	v_mfma_f32_16x16x32_bf16 v[92:95], v[140:143], v[246:249], 0
	v_mfma_f32_16x16x32_bf16 v[136:139], v[10:13], v[216:219], v[136:139]
	v_mfma_f32_16x16x32_bf16 v[104:107], v[144:147], v[216:219], v[104:107]
	v_mfma_f32_16x16x32_bf16 v[132:135], v[10:13], v[224:227], v[132:135]
	v_mfma_f32_16x16x32_bf16 v[100:103], v[144:147], v[224:227], v[100:103]
	v_mfma_f32_16x16x32_bf16 v[128:131], v[10:13], v[242:245], v[128:131]
	v_mfma_f32_16x16x32_bf16 v[96:99], v[144:147], v[242:245], v[96:99]
	v_mfma_f32_16x16x32_bf16 v[124:127], v[10:13], v[250:253], v[124:127]
	v_mfma_f32_16x16x32_bf16 v[92:95], v[144:147], v[250:253], v[92:95]
	s_setprio 0
	s_setprio 1
	v_mfma_f32_16x16x32_bf16 v[72:75], v[148:151], v[212:215], 0
	v_mfma_f32_16x16x32_bf16 v[40:43], v[180:183], v[212:215], 0
	v_mfma_f32_16x16x32_bf16 v[68:71], v[148:151], v[220:223], 0
	v_mfma_f32_16x16x32_bf16 v[36:39], v[180:183], v[220:223], 0
	v_mfma_f32_16x16x32_bf16 v[64:67], v[148:151], v[238:241], 0
	v_mfma_f32_16x16x32_bf16 v[32:35], v[180:183], v[238:241], 0
	v_mfma_f32_16x16x32_bf16 v[60:63], v[148:151], v[246:249], 0
	v_mfma_f32_16x16x32_bf16 v[28:31], v[180:183], v[246:249], 0
	v_mfma_f32_16x16x32_bf16 v[72:75], v[152:155], v[216:219], v[72:75]
	v_mfma_f32_16x16x32_bf16 v[40:43], v[208:211], v[216:219], v[40:43]
	v_mfma_f32_16x16x32_bf16 v[68:71], v[152:155], v[224:227], v[68:71]
	v_mfma_f32_16x16x32_bf16 v[36:39], v[208:211], v[224:227], v[36:39]
	v_mfma_f32_16x16x32_bf16 v[64:67], v[152:155], v[242:245], v[64:67]
	v_mfma_f32_16x16x32_bf16 v[32:35], v[208:211], v[242:245], v[32:35]
	v_mfma_f32_16x16x32_bf16 v[60:63], v[152:155], v[250:253], v[60:63]
	v_mfma_f32_16x16x32_bf16 v[28:31], v[208:211], v[250:253], v[28:31]
	s_setprio 0
	s_barrier
	s_add_i32 s91, s91, s33
	v_lshl_add_u64 v[156:157], s[14:15], 0, v[160:161]
	s_mov_b32 m0, s91
	ds_read_b128 v[212:215], v206 offset:16384
	ds_read_b128 v[216:219], v206 offset:17408
	ds_read_b128 v[220:223], v206 offset:18432
	ds_read_b128 v[224:227], v206 offset:19456
	ds_read_b128 v[238:241], v206 offset:20480
	ds_read_b128 v[242:245], v206 offset:21504
	ds_read_b128 v[246:249], v206 offset:22528
	ds_read_b128 v[250:253], v206 offset:23552
	global_load_lds_dwordx4 v[156:157], off
	s_add_i32 m0, s91, 0x2000
	s_add_u32 vcc_lo, s14, 0x80000
	v_lshl_add_u64 v[184:185], s[14:15], 0, v[164:165]
	s_addc_u32 vcc_hi, s15, 0
	s_add_i32 s91, s96, s33
	global_load_lds_dwordx4 v[184:185], off
	v_lshl_add_u64 v[14:15], vcc, 0, v[160:161]
	s_mov_b32 m0, s91
	v_lshl_add_u64 v[196:197], s[52:53], 0, v[158:159]
	global_load_lds_dwordx4 v[14:15], off
	v_lshl_add_u64 v[14:15], vcc, 0, v[164:165]
	s_add_i32 m0, s91, 0x2000
	v_lshl_add_u64 v[198:199], s[52:53], 0, v[162:163]
	global_load_lds_dwordx4 v[14:15], off
	s_mov_b32 m0, s40
	s_nop 0
	global_load_lds_dwordx4 v[196:197], off
	s_mov_b32 m0, s41
	s_nop 0
	global_load_lds_dwordx4 v[198:199], off
	s_waitcnt vmcnt(8)
	s_waitcnt lgkmcnt(0)
	s_barrier
	s_setprio 1
	v_mfma_f32_16x16x32_bf16 v[120:123], v[6:9], v[212:215], 0
	v_mfma_f32_16x16x32_bf16 v[88:91], v[140:143], v[212:215], 0
	v_mfma_f32_16x16x32_bf16 v[116:119], v[6:9], v[220:223], 0
	v_mfma_f32_16x16x32_bf16 v[84:87], v[140:143], v[220:223], 0
	v_mfma_f32_16x16x32_bf16 v[112:115], v[6:9], v[238:241], 0
	v_mfma_f32_16x16x32_bf16 v[80:83], v[140:143], v[238:241], 0
	v_mfma_f32_16x16x32_bf16 v[6:9], v[6:9], v[246:249], 0
	v_mfma_f32_16x16x32_bf16 v[120:123], v[10:13], v[216:219], v[120:123]
	v_mfma_f32_16x16x32_bf16 v[88:91], v[144:147], v[216:219], v[88:91]
	v_mfma_f32_16x16x32_bf16 v[116:119], v[10:13], v[224:227], v[116:119]
	v_mfma_f32_16x16x32_bf16 v[84:87], v[144:147], v[224:227], v[84:87]
	v_mfma_f32_16x16x32_bf16 v[112:115], v[10:13], v[242:245], v[112:115]
	v_mfma_f32_16x16x32_bf16 v[80:83], v[144:147], v[242:245], v[80:83]
	v_mfma_f32_16x16x32_bf16 v[6:9], v[10:13], v[250:253], v[6:9]
	v_mfma_f32_16x16x32_bf16 v[10:13], v[140:143], v[246:249], 0
	v_mfma_f32_16x16x32_bf16 v[10:13], v[144:147], v[250:253], v[10:13]
	s_setprio 0
	s_setprio 1
	v_mfma_f32_16x16x32_bf16 v[56:59], v[148:151], v[212:215], 0
	v_mfma_f32_16x16x32_bf16 v[24:27], v[180:183], v[212:215], 0
	v_mfma_f32_16x16x32_bf16 v[52:55], v[148:151], v[220:223], 0
	v_mfma_f32_16x16x32_bf16 v[20:23], v[180:183], v[220:223], 0
	v_mfma_f32_16x16x32_bf16 v[48:51], v[148:151], v[238:241], 0
	v_mfma_f32_16x16x32_bf16 v[14:17], v[180:183], v[238:241], 0
	v_mfma_f32_16x16x32_bf16 v[44:47], v[148:151], v[246:249], 0
	v_mfma_f32_16x16x32_bf16 v[2:5], v[180:183], v[246:249], 0
	v_mfma_f32_16x16x32_bf16 v[56:59], v[152:155], v[216:219], v[56:59]
	v_mfma_f32_16x16x32_bf16 v[24:27], v[208:211], v[216:219], v[24:27]
	v_mfma_f32_16x16x32_bf16 v[52:55], v[152:155], v[224:227], v[52:55]
	v_mfma_f32_16x16x32_bf16 v[20:23], v[208:211], v[224:227], v[20:23]
	v_mfma_f32_16x16x32_bf16 v[48:51], v[152:155], v[242:245], v[48:51]
	v_mfma_f32_16x16x32_bf16 v[14:17], v[208:211], v[242:245], v[14:17]
	v_mfma_f32_16x16x32_bf16 v[44:47], v[152:155], v[250:253], v[44:47]
	v_mfma_f32_16x16x32_bf16 v[2:5], v[208:211], v[250:253], v[2:5]
	s_setprio 0
	s_barrier
	s_add_i32 s91, 0, 0x18000
	v_add_u32_e32 v18, s91, v188
	s_add_i32 s96, 0, 0x1c000
	ds_read_b128 v[76:79], v18
	ds_read_b128 v[108:111], v18 offset:1024
	ds_read_b128 v[140:143], v18 offset:2048
	ds_read_b128 v[144:147], v18 offset:3072
	v_add_u32_e32 v18, s96, v188
	ds_read_b128 v[148:151], v18
	ds_read_b128 v[152:155], v18 offset:1024
	ds_read_b128 v[180:183], v18 offset:2048
	ds_read_b128 v[208:211], v18 offset:3072
	s_add_u32 s52, s52, 0x80000
	s_addc_u32 s53, s53, 0
	s_mov_b32 m0, s42
	v_lshl_add_u64 v[18:19], s[52:53], 0, v[158:159]
	ds_read_b128 v[212:215], v206 offset:32768
	ds_read_b128 v[216:219], v206 offset:33792
	ds_read_b128 v[220:223], v206 offset:34816
	ds_read_b128 v[224:227], v206 offset:35840
	ds_read_b128 v[238:241], v206 offset:36864
	ds_read_b128 v[242:245], v206 offset:37888
	ds_read_b128 v[246:249], v206 offset:38912
	ds_read_b128 v[250:253], v206 offset:39936
	global_load_lds_dwordx4 v[18:19], off
	v_lshl_add_u64 v[18:19], s[52:53], 0, v[162:163]
	s_mov_b32 m0, s43
	s_nop 0
	global_load_lds_dwordx4 v[18:19], off
	s_waitcnt vmcnt(8)
	s_waitcnt lgkmcnt(0)
	s_barrier
	s_setprio 1
	v_mfma_f32_16x16x32_bf16 v[136:139], v[76:79], v[212:215], v[136:139]
	v_mfma_f32_16x16x32_bf16 v[104:107], v[140:143], v[212:215], v[104:107]
	v_mfma_f32_16x16x32_bf16 v[132:135], v[76:79], v[220:223], v[132:135]
	v_mfma_f32_16x16x32_bf16 v[100:103], v[140:143], v[220:223], v[100:103]
	v_mfma_f32_16x16x32_bf16 v[128:131], v[76:79], v[238:241], v[128:131]
	v_mfma_f32_16x16x32_bf16 v[96:99], v[140:143], v[238:241], v[96:99]
	v_mfma_f32_16x16x32_bf16 v[124:127], v[76:79], v[246:249], v[124:127]
	v_mfma_f32_16x16x32_bf16 v[92:95], v[140:143], v[246:249], v[92:95]
	v_mfma_f32_16x16x32_bf16 v[136:139], v[108:111], v[216:219], v[136:139]
	v_mfma_f32_16x16x32_bf16 v[104:107], v[144:147], v[216:219], v[104:107]
	v_mfma_f32_16x16x32_bf16 v[132:135], v[108:111], v[224:227], v[132:135]
	v_mfma_f32_16x16x32_bf16 v[100:103], v[144:147], v[224:227], v[100:103]
	v_mfma_f32_16x16x32_bf16 v[128:131], v[108:111], v[242:245], v[128:131]
	v_mfma_f32_16x16x32_bf16 v[96:99], v[144:147], v[242:245], v[96:99]
	v_mfma_f32_16x16x32_bf16 v[124:127], v[108:111], v[250:253], v[124:127]
	v_mfma_f32_16x16x32_bf16 v[92:95], v[144:147], v[250:253], v[92:95]
	s_setprio 0
	s_setprio 1
	v_mfma_f32_16x16x32_bf16 v[72:75], v[148:151], v[212:215], v[72:75]
	v_mfma_f32_16x16x32_bf16 v[40:43], v[180:183], v[212:215], v[40:43]
	v_mfma_f32_16x16x32_bf16 v[68:71], v[148:151], v[220:223], v[68:71]
	v_mfma_f32_16x16x32_bf16 v[36:39], v[180:183], v[220:223], v[36:39]
	v_mfma_f32_16x16x32_bf16 v[64:67], v[148:151], v[238:241], v[64:67]
	v_mfma_f32_16x16x32_bf16 v[32:35], v[180:183], v[238:241], v[32:35]
	v_mfma_f32_16x16x32_bf16 v[60:63], v[148:151], v[246:249], v[60:63]
	v_mfma_f32_16x16x32_bf16 v[28:31], v[180:183], v[246:249], v[28:31]
	v_mfma_f32_16x16x32_bf16 v[72:75], v[152:155], v[216:219], v[72:75]
	v_mfma_f32_16x16x32_bf16 v[40:43], v[208:211], v[216:219], v[40:43]
	v_mfma_f32_16x16x32_bf16 v[68:71], v[152:155], v[224:227], v[68:71]
	v_mfma_f32_16x16x32_bf16 v[36:39], v[208:211], v[224:227], v[36:39]
	v_mfma_f32_16x16x32_bf16 v[64:67], v[152:155], v[242:245], v[64:67]
	v_mfma_f32_16x16x32_bf16 v[32:35], v[208:211], v[242:245], v[32:35]
	v_mfma_f32_16x16x32_bf16 v[60:63], v[152:155], v[250:253], v[60:63]
	v_mfma_f32_16x16x32_bf16 v[28:31], v[208:211], v[250:253], v[28:31]
	s_setprio 0
	s_barrier
	s_add_i32 s52, s91, s33
	v_lshl_add_u64 v[18:19], v[156:157], 0, s[58:59]
	s_mov_b32 m0, s52
	ds_read_b128 v[212:215], v206 offset:49152
	ds_read_b128 v[216:219], v206 offset:50176
	ds_read_b128 v[220:223], v206 offset:51200
	ds_read_b128 v[224:227], v206 offset:52224
	ds_read_b128 v[238:241], v206 offset:53248
	ds_read_b128 v[242:245], v206 offset:54272
	ds_read_b128 v[246:249], v206 offset:55296
	ds_read_b128 v[250:253], v206 offset:56320
	global_load_lds_dwordx4 v[18:19], off
	s_add_i32 m0, s52, 0x2000
	s_add_u32 s14, s14, 0x80080
	v_lshl_add_u64 v[18:19], v[184:185], 0, s[58:59]
	s_addc_u32 s15, s15, 0
	s_add_i32 s52, s96, s33
	global_load_lds_dwordx4 v[18:19], off
	v_lshl_add_u64 v[18:19], s[14:15], 0, v[160:161]
	s_mov_b32 m0, s52
	s_nop 0
	global_load_lds_dwordx4 v[18:19], off
	v_lshl_add_u64 v[18:19], s[14:15], 0, v[164:165]
	s_add_i32 m0, s52, 0x2000
	s_nop 0
	global_load_lds_dwordx4 v[18:19], off
	v_lshl_add_u64 v[18:19], v[196:197], 0, s[58:59]
	s_mov_b32 m0, s55
	s_nop 0
	global_load_lds_dwordx4 v[18:19], off
	v_lshl_add_u64 v[18:19], v[198:199], 0, s[58:59]
	s_mov_b32 m0, s77
	s_nop 0
	global_load_lds_dwordx4 v[18:19], off
	s_waitcnt vmcnt(8)
	s_waitcnt lgkmcnt(0)
	s_barrier
	s_setprio 1
	v_mfma_f32_16x16x32_bf16 v[120:123], v[76:79], v[212:215], v[120:123]
	v_mfma_f32_16x16x32_bf16 v[116:119], v[76:79], v[220:223], v[116:119]
	v_mfma_f32_16x16x32_bf16 v[112:115], v[76:79], v[238:241], v[112:115]
	v_mfma_f32_16x16x32_bf16 v[6:9], v[76:79], v[246:249], v[6:9]
	v_mfma_f32_16x16x32_bf16 v[120:123], v[108:111], v[216:219], v[120:123]
	v_mfma_f32_16x16x32_bf16 v[88:91], v[140:143], v[212:215], v[88:91]
	v_mfma_f32_16x16x32_bf16 v[116:119], v[108:111], v[224:227], v[116:119]
	v_mfma_f32_16x16x32_bf16 v[84:87], v[140:143], v[220:223], v[84:87]
	v_mfma_f32_16x16x32_bf16 v[112:115], v[108:111], v[242:245], v[112:115]
	v_mfma_f32_16x16x32_bf16 v[80:83], v[140:143], v[238:241], v[80:83]
	v_mfma_f32_16x16x32_bf16 v[108:111], v[108:111], v[250:253], v[6:9]
	v_mfma_f32_16x16x32_bf16 v[6:9], v[140:143], v[246:249], v[10:13]
	v_mfma_f32_16x16x32_bf16 v[88:91], v[144:147], v[216:219], v[88:91]
	v_mfma_f32_16x16x32_bf16 v[84:87], v[144:147], v[224:227], v[84:87]
	v_mfma_f32_16x16x32_bf16 v[80:83], v[144:147], v[242:245], v[80:83]
	v_mfma_f32_16x16x32_bf16 v[76:79], v[144:147], v[250:253], v[6:9]
	s_setprio 0
	s_setprio 1
	v_mfma_f32_16x16x32_bf16 v[6:9], v[148:151], v[212:215], v[56:59]
	v_mfma_f32_16x16x32_bf16 v[56:59], v[152:155], v[216:219], v[6:9]
	v_mfma_f32_16x16x32_bf16 v[6:9], v[180:183], v[212:215], v[24:27]
	v_mfma_f32_16x16x32_bf16 v[24:27], v[208:211], v[216:219], v[6:9]
	v_mfma_f32_16x16x32_bf16 v[6:9], v[148:151], v[220:223], v[52:55]
	v_mfma_f32_16x16x32_bf16 v[52:55], v[152:155], v[224:227], v[6:9]
	v_mfma_f32_16x16x32_bf16 v[6:9], v[180:183], v[220:223], v[20:23]
	v_mfma_f32_16x16x32_bf16 v[20:23], v[208:211], v[224:227], v[6:9]
	v_mfma_f32_16x16x32_bf16 v[6:9], v[148:151], v[238:241], v[48:51]
	v_mfma_f32_16x16x32_bf16 v[48:51], v[152:155], v[242:245], v[6:9]
	v_mfma_f32_16x16x32_bf16 v[6:9], v[180:183], v[238:241], v[14:17]
	v_mfma_f32_16x16x32_bf16 v[16:19], v[208:211], v[242:245], v[6:9]
	v_mfma_f32_16x16x32_bf16 v[6:9], v[148:151], v[246:249], v[44:47]
	v_mfma_f32_16x16x32_bf16 v[2:5], v[180:183], v[246:249], v[2:5]
	v_mfma_f32_16x16x32_bf16 v[44:47], v[152:155], v[250:253], v[6:9]
	v_mfma_f32_16x16x32_bf16 v[2:5], v[208:211], v[250:253], v[2:5]
	s_setprio 0
	s_barrier
	s_add_i32 s90, s90, 2
	s_add_u32 s8, s8, 0x100
	s_addc_u32 s9, s9, 0
	s_add_u32 s68, s68, 0x100
	s_addc_u32 s69, s69, 0
	s_cmp_gt_u32 s90, 29
	s_cbranch_scc1 .Lpeel_done_0
.LBB0_176:
	s_add_u32 s14, s8, 0xfff80080
	s_addc_u32 s15, s9, -1
	s_add_i32 s91, 0, 0x10000
	s_cmp_eq_u32 s90, 28
	s_cselect_b32 s53, s11, s15
	s_cselect_b32 s52, s13, s14
	v_add_u32_e32 v14, s91, v188
	s_cselect_b32 s15, s57, s69
	s_cselect_b32 s14, s61, s68
	s_add_i32 s96, 0, 0x14000
	ds_read_b128 v[6:9], v14
	ds_read_b128 v[10:13], v14 offset:1024
	ds_read_b128 v[140:143], v14 offset:2048
	ds_read_b128 v[144:147], v14 offset:3072
	v_add_u32_e32 v14, s96, v188
	ds_read_b128 v[148:151], v14
	ds_read_b128 v[152:155], v14 offset:1024
	ds_read_b128 v[180:183], v14 offset:2048
	ds_read_b128 v[208:211], v14 offset:3072
	v_lshl_add_u64 v[14:15], s[8:9], 0, v[176:177]
	s_add_i32 m0, s40, 0xc000
	ds_read_b128 v[212:215], v206
	ds_read_b128 v[216:219], v206 offset:1024
	ds_read_b128 v[220:223], v206 offset:2048
	ds_read_b128 v[224:227], v206 offset:3072
	ds_read_b128 v[238:241], v206 offset:4096
	ds_read_b128 v[242:245], v206 offset:5120
	ds_read_b128 v[246:249], v206 offset:6144
	ds_read_b128 v[250:253], v206 offset:7168
	global_load_lds_dwordx4 v[14:15], off
	v_lshl_add_u64 v[14:15], s[8:9], 0, v[178:179]
	s_add_i32 m0, s40, 0xe000
	s_nop 0
	global_load_lds_dwordx4 v[14:15], off
	s_waitcnt vmcnt(8)
	s_waitcnt lgkmcnt(0)
	s_barrier
	s_setprio 1
	v_mfma_f32_16x16x32_bf16 v[136:139], v[6:9], v[212:215], v[136:139]
	v_mfma_f32_16x16x32_bf16 v[104:107], v[140:143], v[212:215], v[104:107]
	v_mfma_f32_16x16x32_bf16 v[132:135], v[6:9], v[220:223], v[132:135]
	v_mfma_f32_16x16x32_bf16 v[100:103], v[140:143], v[220:223], v[100:103]
	v_mfma_f32_16x16x32_bf16 v[128:131], v[6:9], v[238:241], v[128:131]
	v_mfma_f32_16x16x32_bf16 v[96:99], v[140:143], v[238:241], v[96:99]
	v_mfma_f32_16x16x32_bf16 v[124:127], v[6:9], v[246:249], v[124:127]
	v_mfma_f32_16x16x32_bf16 v[92:95], v[140:143], v[246:249], v[92:95]
	v_mfma_f32_16x16x32_bf16 v[136:139], v[10:13], v[216:219], v[136:139]
	v_mfma_f32_16x16x32_bf16 v[104:107], v[144:147], v[216:219], v[104:107]
	v_mfma_f32_16x16x32_bf16 v[132:135], v[10:13], v[224:227], v[132:135]
	v_mfma_f32_16x16x32_bf16 v[100:103], v[144:147], v[224:227], v[100:103]
	v_mfma_f32_16x16x32_bf16 v[128:131], v[10:13], v[242:245], v[128:131]
	v_mfma_f32_16x16x32_bf16 v[96:99], v[144:147], v[242:245], v[96:99]
	v_mfma_f32_16x16x32_bf16 v[124:127], v[10:13], v[250:253], v[124:127]
	v_mfma_f32_16x16x32_bf16 v[92:95], v[144:147], v[250:253], v[92:95]
	s_setprio 0
	s_setprio 1
	v_mfma_f32_16x16x32_bf16 v[72:75], v[148:151], v[212:215], v[72:75]
	v_mfma_f32_16x16x32_bf16 v[40:43], v[180:183], v[212:215], v[40:43]
	v_mfma_f32_16x16x32_bf16 v[68:71], v[148:151], v[220:223], v[68:71]
	v_mfma_f32_16x16x32_bf16 v[36:39], v[180:183], v[220:223], v[36:39]
	v_mfma_f32_16x16x32_bf16 v[64:67], v[148:151], v[238:241], v[64:67]
	v_mfma_f32_16x16x32_bf16 v[32:35], v[180:183], v[238:241], v[32:35]
	v_mfma_f32_16x16x32_bf16 v[60:63], v[148:151], v[246:249], v[60:63]
	v_mfma_f32_16x16x32_bf16 v[28:31], v[180:183], v[246:249], v[28:31]
	v_mfma_f32_16x16x32_bf16 v[72:75], v[152:155], v[216:219], v[72:75]
	v_mfma_f32_16x16x32_bf16 v[40:43], v[208:211], v[216:219], v[40:43]
	v_mfma_f32_16x16x32_bf16 v[68:71], v[152:155], v[224:227], v[68:71]
	v_mfma_f32_16x16x32_bf16 v[36:39], v[208:211], v[224:227], v[36:39]
	v_mfma_f32_16x16x32_bf16 v[64:67], v[152:155], v[242:245], v[64:67]
	v_mfma_f32_16x16x32_bf16 v[32:35], v[208:211], v[242:245], v[32:35]
	v_mfma_f32_16x16x32_bf16 v[60:63], v[152:155], v[250:253], v[60:63]
	v_mfma_f32_16x16x32_bf16 v[28:31], v[208:211], v[250:253], v[28:31]
	s_setprio 0
	s_barrier
	s_add_i32 s91, s91, s33
	v_lshl_add_u64 v[156:157], s[14:15], 0, v[160:161]
	s_mov_b32 m0, s91
	ds_read_b128 v[212:215], v206 offset:16384
	ds_read_b128 v[216:219], v206 offset:17408
	ds_read_b128 v[220:223], v206 offset:18432
	ds_read_b128 v[224:227], v206 offset:19456
	ds_read_b128 v[238:241], v206 offset:20480
	ds_read_b128 v[242:245], v206 offset:21504
	ds_read_b128 v[246:249], v206 offset:22528
	ds_read_b128 v[250:253], v206 offset:23552
	global_load_lds_dwordx4 v[156:157], off
	s_add_i32 m0, s91, 0x2000
	s_add_u32 vcc_lo, s14, 0x80000
	v_lshl_add_u64 v[184:185], s[14:15], 0, v[164:165]
	s_addc_u32 vcc_hi, s15, 0
	s_add_i32 s91, s96, s33
	global_load_lds_dwordx4 v[184:185], off
	v_lshl_add_u64 v[14:15], vcc, 0, v[160:161]
	s_mov_b32 m0, s91
	v_lshl_add_u64 v[196:197], s[52:53], 0, v[158:159]
	global_load_lds_dwordx4 v[14:15], off
	v_lshl_add_u64 v[14:15], vcc, 0, v[164:165]
	s_add_i32 m0, s91, 0x2000
	v_lshl_add_u64 v[198:199], s[52:53], 0, v[162:163]
	global_load_lds_dwordx4 v[14:15], off
	s_mov_b32 m0, s40
	s_nop 0
	global_load_lds_dwordx4 v[196:197], off
	s_mov_b32 m0, s41
	s_nop 0
	global_load_lds_dwordx4 v[198:199], off
	s_waitcnt vmcnt(8)
	s_waitcnt lgkmcnt(0)
	s_barrier
	s_setprio 1
	v_mfma_f32_16x16x32_bf16 v[120:123], v[6:9], v[212:215], v[120:123]
	v_mfma_f32_16x16x32_bf16 v[88:91], v[140:143], v[212:215], v[88:91]
	v_mfma_f32_16x16x32_bf16 v[116:119], v[6:9], v[220:223], v[116:119]
	v_mfma_f32_16x16x32_bf16 v[84:87], v[140:143], v[220:223], v[84:87]
	v_mfma_f32_16x16x32_bf16 v[112:115], v[6:9], v[238:241], v[112:115]
	v_mfma_f32_16x16x32_bf16 v[80:83], v[140:143], v[238:241], v[80:83]
	v_mfma_f32_16x16x32_bf16 v[6:9], v[6:9], v[246:249], v[108:111]
	v_mfma_f32_16x16x32_bf16 v[120:123], v[10:13], v[216:219], v[120:123]
	v_mfma_f32_16x16x32_bf16 v[88:91], v[144:147], v[216:219], v[88:91]
	v_mfma_f32_16x16x32_bf16 v[116:119], v[10:13], v[224:227], v[116:119]
	v_mfma_f32_16x16x32_bf16 v[84:87], v[144:147], v[224:227], v[84:87]
	v_mfma_f32_16x16x32_bf16 v[112:115], v[10:13], v[242:245], v[112:115]
	v_mfma_f32_16x16x32_bf16 v[80:83], v[144:147], v[242:245], v[80:83]
	v_mfma_f32_16x16x32_bf16 v[6:9], v[10:13], v[250:253], v[6:9]
	v_mfma_f32_16x16x32_bf16 v[10:13], v[140:143], v[246:249], v[76:79]
	v_mfma_f32_16x16x32_bf16 v[10:13], v[144:147], v[250:253], v[10:13]
	s_setprio 0
	s_setprio 1
	v_mfma_f32_16x16x32_bf16 v[56:59], v[148:151], v[212:215], v[56:59]
	v_mfma_f32_16x16x32_bf16 v[24:27], v[180:183], v[212:215], v[24:27]
	v_mfma_f32_16x16x32_bf16 v[52:55], v[148:151], v[220:223], v[52:55]
	v_mfma_f32_16x16x32_bf16 v[20:23], v[180:183], v[220:223], v[20:23]
	v_mfma_f32_16x16x32_bf16 v[48:51], v[148:151], v[238:241], v[48:51]
	v_mfma_f32_16x16x32_bf16 v[14:17], v[180:183], v[238:241], v[16:19]
	v_mfma_f32_16x16x32_bf16 v[44:47], v[148:151], v[246:249], v[44:47]
	v_mfma_f32_16x16x32_bf16 v[2:5], v[180:183], v[246:249], v[2:5]
	v_mfma_f32_16x16x32_bf16 v[56:59], v[152:155], v[216:219], v[56:59]
	v_mfma_f32_16x16x32_bf16 v[24:27], v[208:211], v[216:219], v[24:27]
	v_mfma_f32_16x16x32_bf16 v[52:55], v[152:155], v[224:227], v[52:55]
	v_mfma_f32_16x16x32_bf16 v[20:23], v[208:211], v[224:227], v[20:23]
	v_mfma_f32_16x16x32_bf16 v[48:51], v[152:155], v[242:245], v[48:51]
	v_mfma_f32_16x16x32_bf16 v[14:17], v[208:211], v[242:245], v[14:17]
	v_mfma_f32_16x16x32_bf16 v[44:47], v[152:155], v[250:253], v[44:47]
	v_mfma_f32_16x16x32_bf16 v[2:5], v[208:211], v[250:253], v[2:5]
	s_setprio 0
	s_barrier
	s_add_i32 s91, 0, 0x18000
	v_add_u32_e32 v18, s91, v188
	s_add_i32 s96, 0, 0x1c000
	ds_read_b128 v[76:79], v18
	ds_read_b128 v[108:111], v18 offset:1024
	ds_read_b128 v[140:143], v18 offset:2048
	ds_read_b128 v[144:147], v18 offset:3072
	v_add_u32_e32 v18, s96, v188
	ds_read_b128 v[148:151], v18
	ds_read_b128 v[152:155], v18 offset:1024
	ds_read_b128 v[180:183], v18 offset:2048
	ds_read_b128 v[208:211], v18 offset:3072
	s_add_u32 s52, s52, 0x80000
	s_addc_u32 s53, s53, 0
	s_mov_b32 m0, s42
	v_lshl_add_u64 v[18:19], s[52:53], 0, v[158:159]
	ds_read_b128 v[212:215], v206 offset:32768
	ds_read_b128 v[216:219], v206 offset:33792
	ds_read_b128 v[220:223], v206 offset:34816
	ds_read_b128 v[224:227], v206 offset:35840
	ds_read_b128 v[238:241], v206 offset:36864
	ds_read_b128 v[242:245], v206 offset:37888
	ds_read_b128 v[246:249], v206 offset:38912
	ds_read_b128 v[250:253], v206 offset:39936
	global_load_lds_dwordx4 v[18:19], off
	v_lshl_add_u64 v[18:19], s[52:53], 0, v[162:163]
	s_mov_b32 m0, s43
	s_nop 0
	global_load_lds_dwordx4 v[18:19], off
	s_waitcnt vmcnt(8)
	s_waitcnt lgkmcnt(0)
	s_barrier
	s_setprio 1
	v_mfma_f32_16x16x32_bf16 v[136:139], v[76:79], v[212:215], v[136:139]
	v_mfma_f32_16x16x32_bf16 v[104:107], v[140:143], v[212:215], v[104:107]
	v_mfma_f32_16x16x32_bf16 v[132:135], v[76:79], v[220:223], v[132:135]
	v_mfma_f32_16x16x32_bf16 v[100:103], v[140:143], v[220:223], v[100:103]
	v_mfma_f32_16x16x32_bf16 v[128:131], v[76:79], v[238:241], v[128:131]
	v_mfma_f32_16x16x32_bf16 v[96:99], v[140:143], v[238:241], v[96:99]
	v_mfma_f32_16x16x32_bf16 v[124:127], v[76:79], v[246:249], v[124:127]
	v_mfma_f32_16x16x32_bf16 v[92:95], v[140:143], v[246:249], v[92:95]
	v_mfma_f32_16x16x32_bf16 v[136:139], v[108:111], v[216:219], v[136:139]
	v_mfma_f32_16x16x32_bf16 v[104:107], v[144:147], v[216:219], v[104:107]
	v_mfma_f32_16x16x32_bf16 v[132:135], v[108:111], v[224:227], v[132:135]
	v_mfma_f32_16x16x32_bf16 v[100:103], v[144:147], v[224:227], v[100:103]
	v_mfma_f32_16x16x32_bf16 v[128:131], v[108:111], v[242:245], v[128:131]
	v_mfma_f32_16x16x32_bf16 v[96:99], v[144:147], v[242:245], v[96:99]
	v_mfma_f32_16x16x32_bf16 v[124:127], v[108:111], v[250:253], v[124:127]
	v_mfma_f32_16x16x32_bf16 v[92:95], v[144:147], v[250:253], v[92:95]
	s_setprio 0
	s_setprio 1
	v_mfma_f32_16x16x32_bf16 v[72:75], v[148:151], v[212:215], v[72:75]
	v_mfma_f32_16x16x32_bf16 v[40:43], v[180:183], v[212:215], v[40:43]
	v_mfma_f32_16x16x32_bf16 v[68:71], v[148:151], v[220:223], v[68:71]
	v_mfma_f32_16x16x32_bf16 v[36:39], v[180:183], v[220:223], v[36:39]
	v_mfma_f32_16x16x32_bf16 v[64:67], v[148:151], v[238:241], v[64:67]
	v_mfma_f32_16x16x32_bf16 v[32:35], v[180:183], v[238:241], v[32:35]
	v_mfma_f32_16x16x32_bf16 v[60:63], v[148:151], v[246:249], v[60:63]
	v_mfma_f32_16x16x32_bf16 v[28:31], v[180:183], v[246:249], v[28:31]
	v_mfma_f32_16x16x32_bf16 v[72:75], v[152:155], v[216:219], v[72:75]
	v_mfma_f32_16x16x32_bf16 v[40:43], v[208:211], v[216:219], v[40:43]
	v_mfma_f32_16x16x32_bf16 v[68:71], v[152:155], v[224:227], v[68:71]
	v_mfma_f32_16x16x32_bf16 v[36:39], v[208:211], v[224:227], v[36:39]
	v_mfma_f32_16x16x32_bf16 v[64:67], v[152:155], v[242:245], v[64:67]
	v_mfma_f32_16x16x32_bf16 v[32:35], v[208:211], v[242:245], v[32:35]
	v_mfma_f32_16x16x32_bf16 v[60:63], v[152:155], v[250:253], v[60:63]
	v_mfma_f32_16x16x32_bf16 v[28:31], v[208:211], v[250:253], v[28:31]
	s_setprio 0
	s_barrier
	s_add_i32 s52, s91, s33
	v_lshl_add_u64 v[18:19], v[156:157], 0, s[58:59]
	s_mov_b32 m0, s52
	ds_read_b128 v[212:215], v206 offset:49152
	ds_read_b128 v[216:219], v206 offset:50176
	ds_read_b128 v[220:223], v206 offset:51200
	ds_read_b128 v[224:227], v206 offset:52224
	ds_read_b128 v[238:241], v206 offset:53248
	ds_read_b128 v[242:245], v206 offset:54272
	ds_read_b128 v[246:249], v206 offset:55296
	ds_read_b128 v[250:253], v206 offset:56320
	global_load_lds_dwordx4 v[18:19], off
	s_add_i32 m0, s52, 0x2000
	s_add_u32 s14, s14, 0x80080
	v_lshl_add_u64 v[18:19], v[184:185], 0, s[58:59]
	s_addc_u32 s15, s15, 0
	s_add_i32 s52, s96, s33
	global_load_lds_dwordx4 v[18:19], off
	v_lshl_add_u64 v[18:19], s[14:15], 0, v[160:161]
	s_mov_b32 m0, s52
	s_nop 0
	global_load_lds_dwordx4 v[18:19], off
	v_lshl_add_u64 v[18:19], s[14:15], 0, v[164:165]
	s_add_i32 m0, s52, 0x2000
	s_nop 0
	global_load_lds_dwordx4 v[18:19], off
	v_lshl_add_u64 v[18:19], v[196:197], 0, s[58:59]
	s_mov_b32 m0, s55
	s_nop 0
	global_load_lds_dwordx4 v[18:19], off
	v_lshl_add_u64 v[18:19], v[198:199], 0, s[58:59]
	s_mov_b32 m0, s77
	s_nop 0
	global_load_lds_dwordx4 v[18:19], off
	s_waitcnt vmcnt(8)
	s_waitcnt lgkmcnt(0)
	s_barrier
	s_setprio 1
	v_mfma_f32_16x16x32_bf16 v[120:123], v[76:79], v[212:215], v[120:123]
	v_mfma_f32_16x16x32_bf16 v[116:119], v[76:79], v[220:223], v[116:119]
	v_mfma_f32_16x16x32_bf16 v[112:115], v[76:79], v[238:241], v[112:115]
	v_mfma_f32_16x16x32_bf16 v[6:9], v[76:79], v[246:249], v[6:9]
	v_mfma_f32_16x16x32_bf16 v[120:123], v[108:111], v[216:219], v[120:123]
	v_mfma_f32_16x16x32_bf16 v[88:91], v[140:143], v[212:215], v[88:91]
	v_mfma_f32_16x16x32_bf16 v[116:119], v[108:111], v[224:227], v[116:119]
	v_mfma_f32_16x16x32_bf16 v[84:87], v[140:143], v[220:223], v[84:87]
	v_mfma_f32_16x16x32_bf16 v[112:115], v[108:111], v[242:245], v[112:115]
	v_mfma_f32_16x16x32_bf16 v[80:83], v[140:143], v[238:241], v[80:83]
	v_mfma_f32_16x16x32_bf16 v[108:111], v[108:111], v[250:253], v[6:9]
	v_mfma_f32_16x16x32_bf16 v[6:9], v[140:143], v[246:249], v[10:13]
	v_mfma_f32_16x16x32_bf16 v[88:91], v[144:147], v[216:219], v[88:91]
	v_mfma_f32_16x16x32_bf16 v[84:87], v[144:147], v[224:227], v[84:87]
	v_mfma_f32_16x16x32_bf16 v[80:83], v[144:147], v[242:245], v[80:83]
	v_mfma_f32_16x16x32_bf16 v[76:79], v[144:147], v[250:253], v[6:9]
	s_setprio 0
	s_setprio 1
	v_mfma_f32_16x16x32_bf16 v[6:9], v[148:151], v[212:215], v[56:59]
	v_mfma_f32_16x16x32_bf16 v[56:59], v[152:155], v[216:219], v[6:9]
	v_mfma_f32_16x16x32_bf16 v[6:9], v[180:183], v[212:215], v[24:27]
	v_mfma_f32_16x16x32_bf16 v[24:27], v[208:211], v[216:219], v[6:9]
	v_mfma_f32_16x16x32_bf16 v[6:9], v[148:151], v[220:223], v[52:55]
	v_mfma_f32_16x16x32_bf16 v[52:55], v[152:155], v[224:227], v[6:9]
	v_mfma_f32_16x16x32_bf16 v[6:9], v[180:183], v[220:223], v[20:23]
	v_mfma_f32_16x16x32_bf16 v[20:23], v[208:211], v[224:227], v[6:9]
	v_mfma_f32_16x16x32_bf16 v[6:9], v[148:151], v[238:241], v[48:51]
	v_mfma_f32_16x16x32_bf16 v[48:51], v[152:155], v[242:245], v[6:9]
	v_mfma_f32_16x16x32_bf16 v[6:9], v[180:183], v[238:241], v[14:17]
	v_mfma_f32_16x16x32_bf16 v[16:19], v[208:211], v[242:245], v[6:9]
	v_mfma_f32_16x16x32_bf16 v[6:9], v[148:151], v[246:249], v[44:47]
	v_mfma_f32_16x16x32_bf16 v[2:5], v[180:183], v[246:249], v[2:5]
	v_mfma_f32_16x16x32_bf16 v[44:47], v[152:155], v[250:253], v[6:9]
	v_mfma_f32_16x16x32_bf16 v[2:5], v[208:211], v[250:253], v[2:5]
	s_setprio 0
	s_barrier
	s_add_i32 s90, s90, 2
	s_add_u32 s8, s8, 0x100
	s_addc_u32 s9, s9, 0
	s_add_u32 s68, s68, 0x100
	s_addc_u32 s69, s69, 0
	s_cmp_gt_u32 s90, 29
	s_cbranch_scc0 .LBB0_176

.LBB0_671:
	s_ashr_i32 s11, s10, 31
	s_lshl_b64 s[12:13], s[10:11], 20
	v_readlane_b32 s14, v254, 17
	v_readlane_b32 s15, v254, 18
	s_add_u32 s12, s14, s12
	s_addc_u32 s13, s15, s13
	s_and_b64 s[14:15], s[4:5], exec
	s_cselect_b32 s11, s13, s23
	s_cselect_b32 s18, s12, s22
	s_ashr_i32 s9, s8, 31
	s_lshl_b64 s[14:15], s[8:9], 20
	v_readlane_b32 s26, v254, 44
	v_readlane_b32 s27, v254, 45
	s_add_u32 s14, s26, s14
	s_addc_u32 s15, s27, s15
	s_and_b64 s[26:27], s[4:5], exec
	s_cselect_b32 s9, s15, s25
	s_cselect_b32 s19, s14, s24
	s_add_u32 s22, s22, 0x80080
	s_addc_u32 s23, s23, 0
	s_add_u32 s21, s24, 0x100
	s_addc_u32 s33, s25, 0
	s_mov_b32 s40, -2
	v_readlane_b32 s41, v255, 49
	s_nop 3
	s_cmp_eq_u32 s41, 2
	v_writelane_b32 v255, 2, 49
	s_cbranch_scc0 .Ltrip0_strict_1
	s_add_u32 s24, s22, 0xfff80080
	s_addc_u32 s25, s23, -1
	s_add_i32 s41, 0, 0x10000
	s_cmp_eq_u32 s40, 28
	s_cselect_b32 s27, s11, s25
	s_cselect_b32 s26, s18, s24
	s_cselect_b32 s25, s9, s33
	s_cselect_b32 s24, s19, s21
	s_add_i32 s46, 0, 0x14000
	v_add_u32_e32 v142, s41, v214
	v_add_u32_e32 v158, s46, v214
	ds_read_b128 v[130:133], v142
	ds_read_b128 v[134:137], v142 offset:1024
	ds_read_b128 v[138:141], v142 offset:2048
	ds_read_b128 v[142:145], v142 offset:3072
	ds_read_b128 v[146:149], v158
	ds_read_b128 v[150:153], v158 offset:1024
	ds_read_b128 v[154:157], v158 offset:2048
	ds_read_b128 v[158:161], v158 offset:3072
	v_lshl_add_u64 v[212:213], s[22:23], 0, v[182:183]
	s_add_i32 m0, s17, 0xc000
	ds_read_b128 v[162:165], v216
	ds_read_b128 v[166:169], v216 offset:1024
	ds_read_b128 v[170:173], v216 offset:2048
	ds_read_b128 v[186:189], v216 offset:3072
	ds_read_b128 v[196:199], v216 offset:4096
	ds_read_b128 v[200:203], v216 offset:5120
	ds_read_b128 v[204:207], v216 offset:6144
	ds_read_b128 v[208:211], v216 offset:7168
	global_load_lds_dwordx4 v[212:213], off
	v_lshl_add_u64 v[212:213], s[22:23], 0, v[184:185]
	s_add_i32 m0, s17, 0xe000
	s_nop 0
	global_load_lds_dwordx4 v[212:213], off
	s_waitcnt vmcnt(24)
	s_waitcnt lgkmcnt(0)
	s_barrier
	s_setprio 1
	v_mfma_f32_16x16x32_bf16 v[126:129], v[130:133], v[162:165], 0
	v_mfma_f32_16x16x32_bf16 v[122:125], v[138:141], v[162:165], 0
	v_mfma_f32_16x16x32_bf16 v[110:113], v[130:133], v[170:173], 0
	v_mfma_f32_16x16x32_bf16 v[106:109], v[138:141], v[170:173], 0
	v_mfma_f32_16x16x32_bf16 v[94:97], v[130:133], v[196:199], 0
	v_mfma_f32_16x16x32_bf16 v[90:93], v[138:141], v[196:199], 0
	v_mfma_f32_16x16x32_bf16 v[78:81], v[130:133], v[204:207], 0
	v_mfma_f32_16x16x32_bf16 v[74:77], v[138:141], v[204:207], 0
	v_mfma_f32_16x16x32_bf16 v[126:129], v[134:137], v[166:169], v[126:129]
	v_mfma_f32_16x16x32_bf16 v[122:125], v[142:145], v[166:169], v[122:125]
	v_mfma_f32_16x16x32_bf16 v[110:113], v[134:137], v[186:189], v[110:113]
	v_mfma_f32_16x16x32_bf16 v[106:109], v[142:145], v[186:189], v[106:109]
	v_mfma_f32_16x16x32_bf16 v[94:97], v[134:137], v[200:203], v[94:97]
	v_mfma_f32_16x16x32_bf16 v[90:93], v[142:145], v[200:203], v[90:93]
	v_mfma_f32_16x16x32_bf16 v[78:81], v[134:137], v[208:211], v[78:81]
	v_mfma_f32_16x16x32_bf16 v[74:77], v[142:145], v[208:211], v[74:77]
	s_setprio 0
	s_setprio 1
	v_mfma_f32_16x16x32_bf16 v[118:121], v[146:149], v[162:165], 0
	v_mfma_f32_16x16x32_bf16 v[114:117], v[154:157], v[162:165], 0
	v_mfma_f32_16x16x32_bf16 v[102:105], v[146:149], v[170:173], 0
	v_mfma_f32_16x16x32_bf16 v[98:101], v[154:157], v[170:173], 0
	v_mfma_f32_16x16x32_bf16 v[86:89], v[146:149], v[196:199], 0
	v_mfma_f32_16x16x32_bf16 v[82:85], v[154:157], v[196:199], 0
	v_mfma_f32_16x16x32_bf16 v[70:73], v[146:149], v[204:207], 0
	v_mfma_f32_16x16x32_bf16 v[66:69], v[154:157], v[204:207], 0
	v_mfma_f32_16x16x32_bf16 v[118:121], v[150:153], v[166:169], v[118:121]
	v_mfma_f32_16x16x32_bf16 v[114:117], v[158:161], v[166:169], v[114:117]
	v_mfma_f32_16x16x32_bf16 v[102:105], v[150:153], v[186:189], v[102:105]
	v_mfma_f32_16x16x32_bf16 v[98:101], v[158:161], v[186:189], v[98:101]
	v_mfma_f32_16x16x32_bf16 v[86:89], v[150:153], v[200:203], v[86:89]
	v_mfma_f32_16x16x32_bf16 v[82:85], v[158:161], v[200:203], v[82:85]
	v_mfma_f32_16x16x32_bf16 v[70:73], v[150:153], v[208:211], v[70:73]
	v_mfma_f32_16x16x32_bf16 v[66:69], v[158:161], v[208:211], v[66:69]
	s_setprio 0
	s_barrier
	s_add_i32 s41, s41, s29
	v_lshl_add_u64 v[212:213], s[24:25], 0, v[178:179]
	s_mov_b32 m0, s41
	ds_read_b128 v[162:165], v216 offset:16384
	ds_read_b128 v[166:169], v216 offset:17408
	ds_read_b128 v[170:173], v216 offset:18432
	ds_read_b128 v[186:189], v216 offset:19456
	ds_read_b128 v[196:199], v216 offset:20480
	ds_read_b128 v[200:203], v216 offset:21504
	ds_read_b128 v[204:207], v216 offset:22528
	ds_read_b128 v[208:211], v216 offset:23552
	global_load_lds_dwordx4 v[212:213], off
	s_add_i32 m0, s41, 0x2000
	s_add_u32 s42, s24, 0x80000
	v_lshl_add_u64 v[218:219], s[24:25], 0, v[174:175]
	s_addc_u32 s43, s25, 0
	s_add_i32 s41, s46, s29
	global_load_lds_dwordx4 v[218:219], off
	v_lshl_add_u64 v[220:221], s[42:43], 0, v[178:179]
	s_mov_b32 m0, s41
	v_lshl_add_u64 v[222:223], s[26:27], 0, v[176:177]
	global_load_lds_dwordx4 v[220:221], off
	v_lshl_add_u64 v[220:221], s[42:43], 0, v[174:175]
	s_add_i32 m0, s41, 0x2000
	s_nop 0
	global_load_lds_dwordx4 v[220:221], off
	v_lshl_add_u64 v[220:221], s[26:27], 0, v[180:181]
	s_mov_b32 m0, s17
	s_nop 0
	global_load_lds_dwordx4 v[220:221], off
	s_mov_b32 m0, s31
	s_nop 0
	global_load_lds_dwordx4 v[222:223], off
	s_waitcnt vmcnt(24)
	s_waitcnt lgkmcnt(0)
	s_barrier
	s_setprio 1
	v_mfma_f32_16x16x32_bf16 v[62:65], v[130:133], v[162:165], 0
	v_mfma_f32_16x16x32_bf16 v[58:61], v[138:141], v[162:165], 0
	v_mfma_f32_16x16x32_bf16 v[46:49], v[130:133], v[170:173], 0
	v_mfma_f32_16x16x32_bf16 v[42:45], v[138:141], v[170:173], 0
	v_mfma_f32_16x16x32_bf16 v[30:33], v[130:133], v[196:199], 0
	v_mfma_f32_16x16x32_bf16 v[26:29], v[138:141], v[196:199], 0
	v_mfma_f32_16x16x32_bf16 v[14:17], v[130:133], v[204:207], 0
	v_mfma_f32_16x16x32_bf16 v[10:13], v[138:141], v[204:207], 0
	v_mfma_f32_16x16x32_bf16 v[62:65], v[134:137], v[166:169], v[62:65]
	v_mfma_f32_16x16x32_bf16 v[58:61], v[142:145], v[166:169], v[58:61]
	v_mfma_f32_16x16x32_bf16 v[46:49], v[134:137], v[186:189], v[46:49]
	v_mfma_f32_16x16x32_bf16 v[42:45], v[142:145], v[186:189], v[42:45]
	v_mfma_f32_16x16x32_bf16 v[30:33], v[134:137], v[200:203], v[30:33]
	v_mfma_f32_16x16x32_bf16 v[26:29], v[142:145], v[200:203], v[26:29]
	v_mfma_f32_16x16x32_bf16 v[14:17], v[134:137], v[208:211], v[14:17]
	v_mfma_f32_16x16x32_bf16 v[10:13], v[142:145], v[208:211], v[10:13]
	s_setprio 0
	s_setprio 1
	v_mfma_f32_16x16x32_bf16 v[54:57], v[146:149], v[162:165], 0
	v_mfma_f32_16x16x32_bf16 v[50:53], v[154:157], v[162:165], 0
	v_mfma_f32_16x16x32_bf16 v[38:41], v[146:149], v[170:173], 0
	v_mfma_f32_16x16x32_bf16 v[34:37], v[154:157], v[170:173], 0
	v_mfma_f32_16x16x32_bf16 v[22:25], v[146:149], v[196:199], 0
	v_mfma_f32_16x16x32_bf16 v[18:21], v[154:157], v[196:199], 0
	v_mfma_f32_16x16x32_bf16 v[6:9], v[146:149], v[204:207], 0
	v_mfma_f32_16x16x32_bf16 v[2:5], v[154:157], v[204:207], 0
	v_mfma_f32_16x16x32_bf16 v[54:57], v[150:153], v[166:169], v[54:57]
	v_mfma_f32_16x16x32_bf16 v[50:53], v[158:161], v[166:169], v[50:53]
	v_mfma_f32_16x16x32_bf16 v[38:41], v[150:153], v[186:189], v[38:41]
	v_mfma_f32_16x16x32_bf16 v[34:37], v[158:161], v[186:189], v[34:37]
	v_mfma_f32_16x16x32_bf16 v[22:25], v[150:153], v[200:203], v[22:25]
	v_mfma_f32_16x16x32_bf16 v[18:21], v[158:161], v[200:203], v[18:21]
	v_mfma_f32_16x16x32_bf16 v[6:9], v[150:153], v[208:211], v[6:9]
	v_mfma_f32_16x16x32_bf16 v[2:5], v[158:161], v[208:211], v[2:5]
	s_setprio 0
	s_barrier
	s_add_i32 s41, 0, 0x18000
	s_add_i32 s42, 0, 0x1c000
	v_add_u32_e32 v142, s41, v214
	v_add_u32_e32 v158, s42, v214
	ds_read_b128 v[130:133], v142
	ds_read_b128 v[134:137], v142 offset:1024
	ds_read_b128 v[138:141], v142 offset:2048
	ds_read_b128 v[142:145], v142 offset:3072
	ds_read_b128 v[146:149], v158
	ds_read_b128 v[150:153], v158 offset:1024
	ds_read_b128 v[154:157], v158 offset:2048
	ds_read_b128 v[158:161], v158 offset:3072
	s_add_u32 s26, s26, 0x80000
	s_addc_u32 s27, s27, 0
	s_mov_b32 m0, s34
	v_lshl_add_u64 v[224:225], s[26:27], 0, v[180:181]
	ds_read_b128 v[162:165], v216 offset:32768
	ds_read_b128 v[166:169], v216 offset:33792
	ds_read_b128 v[170:173], v216 offset:34816
	ds_read_b128 v[186:189], v216 offset:35840
	ds_read_b128 v[196:199], v216 offset:36864
	ds_read_b128 v[200:203], v216 offset:37888
	ds_read_b128 v[204:207], v216 offset:38912
	ds_read_b128 v[208:211], v216 offset:39936
	global_load_lds_dwordx4 v[224:225], off
	v_lshl_add_u64 v[224:225], s[26:27], 0, v[176:177]
	s_mov_b32 m0, s35
	s_nop 0
	global_load_lds_dwordx4 v[224:225], off
	s_waitcnt vmcnt(8)
	s_waitcnt lgkmcnt(0)
	s_barrier
	s_setprio 1
	v_mfma_f32_16x16x32_bf16 v[126:129], v[130:133], v[162:165], v[126:129]
	v_mfma_f32_16x16x32_bf16 v[122:125], v[138:141], v[162:165], v[122:125]
	v_mfma_f32_16x16x32_bf16 v[110:113], v[130:133], v[170:173], v[110:113]
	v_mfma_f32_16x16x32_bf16 v[106:109], v[138:141], v[170:173], v[106:109]
	v_mfma_f32_16x16x32_bf16 v[94:97], v[130:133], v[196:199], v[94:97]
	v_mfma_f32_16x16x32_bf16 v[90:93], v[138:141], v[196:199], v[90:93]
	v_mfma_f32_16x16x32_bf16 v[78:81], v[130:133], v[204:207], v[78:81]
	v_mfma_f32_16x16x32_bf16 v[74:77], v[138:141], v[204:207], v[74:77]
	v_mfma_f32_16x16x32_bf16 v[126:129], v[134:137], v[166:169], v[126:129]
	v_mfma_f32_16x16x32_bf16 v[122:125], v[142:145], v[166:169], v[122:125]
	v_mfma_f32_16x16x32_bf16 v[110:113], v[134:137], v[186:189], v[110:113]
	v_mfma_f32_16x16x32_bf16 v[106:109], v[142:145], v[186:189], v[106:109]
	v_mfma_f32_16x16x32_bf16 v[94:97], v[134:137], v[200:203], v[94:97]
	v_mfma_f32_16x16x32_bf16 v[90:93], v[142:145], v[200:203], v[90:93]
	v_mfma_f32_16x16x32_bf16 v[78:81], v[134:137], v[208:211], v[78:81]
	v_mfma_f32_16x16x32_bf16 v[74:77], v[142:145], v[208:211], v[74:77]
	s_setprio 0
	s_setprio 1
	v_mfma_f32_16x16x32_bf16 v[118:121], v[146:149], v[162:165], v[118:121]
	v_mfma_f32_16x16x32_bf16 v[114:117], v[154:157], v[162:165], v[114:117]
	v_mfma_f32_16x16x32_bf16 v[102:105], v[146:149], v[170:173], v[102:105]
	v_mfma_f32_16x16x32_bf16 v[98:101], v[154:157], v[170:173], v[98:101]
	v_mfma_f32_16x16x32_bf16 v[86:89], v[146:149], v[196:199], v[86:89]
	v_mfma_f32_16x16x32_bf16 v[82:85], v[154:157], v[196:199], v[82:85]
	v_mfma_f32_16x16x32_bf16 v[70:73], v[146:149], v[204:207], v[70:73]
	v_mfma_f32_16x16x32_bf16 v[66:69], v[154:157], v[204:207], v[66:69]
	v_mfma_f32_16x16x32_bf16 v[118:121], v[150:153], v[166:169], v[118:121]
	v_mfma_f32_16x16x32_bf16 v[114:117], v[158:161], v[166:169], v[114:117]
	v_mfma_f32_16x16x32_bf16 v[102:105], v[150:153], v[186:189], v[102:105]
	v_mfma_f32_16x16x32_bf16 v[98:101], v[158:161], v[186:189], v[98:101]
	v_mfma_f32_16x16x32_bf16 v[86:89], v[150:153], v[200:203], v[86:89]
	v_mfma_f32_16x16x32_bf16 v[82:85], v[158:161], v[200:203], v[82:85]
	v_mfma_f32_16x16x32_bf16 v[70:73], v[150:153], v[208:211], v[70:73]
	v_mfma_f32_16x16x32_bf16 v[66:69], v[158:161], v[208:211], v[66:69]
	s_setprio 0
	s_barrier
	s_add_i32 s26, s41, s29
	v_lshl_add_u64 v[212:213], v[212:213], 0, s[58:59]
	s_mov_b32 m0, s26
	ds_read_b128 v[162:165], v216 offset:49152
	ds_read_b128 v[166:169], v216 offset:50176
	ds_read_b128 v[170:173], v216 offset:51200
	ds_read_b128 v[186:189], v216 offset:52224
	ds_read_b128 v[196:199], v216 offset:53248
	ds_read_b128 v[200:203], v216 offset:54272
	ds_read_b128 v[204:207], v216 offset:55296
	ds_read_b128 v[208:211], v216 offset:56320
	global_load_lds_dwordx4 v[212:213], off
	s_add_i32 m0, s26, 0x2000
	s_add_u32 s24, s24, 0x80080
	v_lshl_add_u64 v[212:213], v[218:219], 0, s[58:59]
	s_addc_u32 s25, s25, 0
	s_add_i32 s26, s42, s29
	global_load_lds_dwordx4 v[212:213], off
	v_lshl_add_u64 v[212:213], s[24:25], 0, v[178:179]
	s_mov_b32 m0, s26
	s_nop 0
	global_load_lds_dwordx4 v[212:213], off
	v_lshl_add_u64 v[212:213], s[24:25], 0, v[174:175]
	s_add_i32 m0, s26, 0x2000
	s_nop 0
	global_load_lds_dwordx4 v[212:213], off
	v_lshl_add_u64 v[212:213], v[220:221], 0, s[58:59]
	s_mov_b32 m0, s38
	s_nop 0
	global_load_lds_dwordx4 v[212:213], off
	v_lshl_add_u64 v[212:213], v[222:223], 0, s[58:59]
	s_mov_b32 m0, s39
	s_nop 0
	global_load_lds_dwordx4 v[212:213], off
	s_waitcnt vmcnt(8)
	s_waitcnt lgkmcnt(0)
	s_barrier
	s_setprio 1
	v_mfma_f32_16x16x32_bf16 v[62:65], v[130:133], v[162:165], v[62:65]
	v_mfma_f32_16x16x32_bf16 v[58:61], v[138:141], v[162:165], v[58:61]
	v_mfma_f32_16x16x32_bf16 v[46:49], v[130:133], v[170:173], v[46:49]
	v_mfma_f32_16x16x32_bf16 v[42:45], v[138:141], v[170:173], v[42:45]
	v_mfma_f32_16x16x32_bf16 v[30:33], v[130:133], v[196:199], v[30:33]
	v_mfma_f32_16x16x32_bf16 v[26:29], v[138:141], v[196:199], v[26:29]
	v_mfma_f32_16x16x32_bf16 v[14:17], v[130:133], v[204:207], v[14:17]
	v_mfma_f32_16x16x32_bf16 v[10:13], v[138:141], v[204:207], v[10:13]
	v_mfma_f32_16x16x32_bf16 v[62:65], v[134:137], v[166:169], v[62:65]
	v_mfma_f32_16x16x32_bf16 v[58:61], v[142:145], v[166:169], v[58:61]
	v_mfma_f32_16x16x32_bf16 v[46:49], v[134:137], v[186:189], v[46:49]
	v_mfma_f32_16x16x32_bf16 v[42:45], v[142:145], v[186:189], v[42:45]
	v_mfma_f32_16x16x32_bf16 v[30:33], v[134:137], v[200:203], v[30:33]
	v_mfma_f32_16x16x32_bf16 v[26:29], v[142:145], v[200:203], v[26:29]
	v_mfma_f32_16x16x32_bf16 v[14:17], v[134:137], v[208:211], v[14:17]
	v_mfma_f32_16x16x32_bf16 v[10:13], v[142:145], v[208:211], v[10:13]
	s_setprio 0
	s_setprio 1
	v_mfma_f32_16x16x32_bf16 v[54:57], v[146:149], v[162:165], v[54:57]
	v_mfma_f32_16x16x32_bf16 v[50:53], v[154:157], v[162:165], v[50:53]
	v_mfma_f32_16x16x32_bf16 v[38:41], v[146:149], v[170:173], v[38:41]
	v_mfma_f32_16x16x32_bf16 v[34:37], v[154:157], v[170:173], v[34:37]
	v_mfma_f32_16x16x32_bf16 v[22:25], v[146:149], v[196:199], v[22:25]
	v_mfma_f32_16x16x32_bf16 v[18:21], v[154:157], v[196:199], v[18:21]
	v_mfma_f32_16x16x32_bf16 v[6:9], v[146:149], v[204:207], v[6:9]
	v_mfma_f32_16x16x32_bf16 v[2:5], v[154:157], v[204:207], v[2:5]
	v_mfma_f32_16x16x32_bf16 v[54:57], v[150:153], v[166:169], v[54:57]
	v_mfma_f32_16x16x32_bf16 v[50:53], v[158:161], v[166:169], v[50:53]
	v_mfma_f32_16x16x32_bf16 v[38:41], v[150:153], v[186:189], v[38:41]
	v_mfma_f32_16x16x32_bf16 v[34:37], v[158:161], v[186:189], v[34:37]
	v_mfma_f32_16x16x32_bf16 v[22:25], v[150:153], v[200:203], v[22:25]
	v_mfma_f32_16x16x32_bf16 v[18:21], v[158:161], v[200:203], v[18:21]
	v_mfma_f32_16x16x32_bf16 v[6:9], v[150:153], v[208:211], v[6:9]
	v_mfma_f32_16x16x32_bf16 v[2:5], v[158:161], v[208:211], v[2:5]
	s_setprio 0
	s_barrier
	s_add_i32 s40, s40, 2
	s_add_u32 s22, s22, 0x100
	s_addc_u32 s23, s23, 0
	s_add_u32 s21, s21, 0x100
	s_addc_u32 s33, s33, 0
	s_cmp_gt_u32 s40, 29
	s_cbranch_scc1 .Lpeel_done_1
	s_branch .LBB0_672
.Ltrip0_strict_1:
	s_add_u32 s24, s22, 0xfff80080
	s_addc_u32 s25, s23, -1
	s_add_i32 s41, 0, 0x10000
	s_cmp_eq_u32 s40, 28
	s_cselect_b32 s27, s11, s25
	s_cselect_b32 s26, s18, s24
	s_cselect_b32 s25, s9, s33
	s_cselect_b32 s24, s19, s21
	s_add_i32 s46, 0, 0x14000
	v_add_u32_e32 v142, s41, v214
	v_add_u32_e32 v158, s46, v214
	ds_read_b128 v[130:133], v142
	ds_read_b128 v[134:137], v142 offset:1024
	ds_read_b128 v[138:141], v142 offset:2048
	ds_read_b128 v[142:145], v142 offset:3072
	ds_read_b128 v[146:149], v158
	ds_read_b128 v[150:153], v158 offset:1024
	ds_read_b128 v[154:157], v158 offset:2048
	ds_read_b128 v[158:161], v158 offset:3072
	v_lshl_add_u64 v[212:213], s[22:23], 0, v[182:183]
	s_add_i32 m0, s17, 0xc000
	ds_read_b128 v[162:165], v216
	ds_read_b128 v[166:169], v216 offset:1024
	ds_read_b128 v[170:173], v216 offset:2048
	ds_read_b128 v[186:189], v216 offset:3072
	ds_read_b128 v[196:199], v216 offset:4096
	ds_read_b128 v[200:203], v216 offset:5120
	ds_read_b128 v[204:207], v216 offset:6144
	ds_read_b128 v[208:211], v216 offset:7168
	global_load_lds_dwordx4 v[212:213], off
	v_lshl_add_u64 v[212:213], s[22:23], 0, v[184:185]
	s_add_i32 m0, s17, 0xe000
	s_nop 0
	global_load_lds_dwordx4 v[212:213], off
	s_waitcnt vmcnt(8)
	s_waitcnt lgkmcnt(0)
	s_barrier
	s_setprio 1
	v_mfma_f32_16x16x32_bf16 v[126:129], v[130:133], v[162:165], 0
	v_mfma_f32_16x16x32_bf16 v[122:125], v[138:141], v[162:165], 0
	v_mfma_f32_16x16x32_bf16 v[110:113], v[130:133], v[170:173], 0
	v_mfma_f32_16x16x32_bf16 v[106:109], v[138:141], v[170:173], 0
	v_mfma_f32_16x16x32_bf16 v[94:97], v[130:133], v[196:199], 0
	v_mfma_f32_16x16x32_bf16 v[90:93], v[138:141], v[196:199], 0
	v_mfma_f32_16x16x32_bf16 v[78:81], v[130:133], v[204:207], 0
	v_mfma_f32_16x16x32_bf16 v[74:77], v[138:141], v[204:207], 0
	v_mfma_f32_16x16x32_bf16 v[126:129], v[134:137], v[166:169], v[126:129]
	v_mfma_f32_16x16x32_bf16 v[122:125], v[142:145], v[166:169], v[122:125]
	v_mfma_f32_16x16x32_bf16 v[110:113], v[134:137], v[186:189], v[110:113]
	v_mfma_f32_16x16x32_bf16 v[106:109], v[142:145], v[186:189], v[106:109]
	v_mfma_f32_16x16x32_bf16 v[94:97], v[134:137], v[200:203], v[94:97]
	v_mfma_f32_16x16x32_bf16 v[90:93], v[142:145], v[200:203], v[90:93]
	v_mfma_f32_16x16x32_bf16 v[78:81], v[134:137], v[208:211], v[78:81]
	v_mfma_f32_16x16x32_bf16 v[74:77], v[142:145], v[208:211], v[74:77]
	s_setprio 0
	s_setprio 1
	v_mfma_f32_16x16x32_bf16 v[118:121], v[146:149], v[162:165], 0
	v_mfma_f32_16x16x32_bf16 v[114:117], v[154:157], v[162:165], 0
	v_mfma_f32_16x16x32_bf16 v[102:105], v[146:149], v[170:173], 0
	v_mfma_f32_16x16x32_bf16 v[98:101], v[154:157], v[170:173], 0
	v_mfma_f32_16x16x32_bf16 v[86:89], v[146:149], v[196:199], 0
	v_mfma_f32_16x16x32_bf16 v[82:85], v[154:157], v[196:199], 0
	v_mfma_f32_16x16x32_bf16 v[70:73], v[146:149], v[204:207], 0
	v_mfma_f32_16x16x32_bf16 v[66:69], v[154:157], v[204:207], 0
	v_mfma_f32_16x16x32_bf16 v[118:121], v[150:153], v[166:169], v[118:121]
	v_mfma_f32_16x16x32_bf16 v[114:117], v[158:161], v[166:169], v[114:117]
	v_mfma_f32_16x16x32_bf16 v[102:105], v[150:153], v[186:189], v[102:105]
	v_mfma_f32_16x16x32_bf16 v[98:101], v[158:161], v[186:189], v[98:101]
	v_mfma_f32_16x16x32_bf16 v[86:89], v[150:153], v[200:203], v[86:89]
	v_mfma_f32_16x16x32_bf16 v[82:85], v[158:161], v[200:203], v[82:85]
	v_mfma_f32_16x16x32_bf16 v[70:73], v[150:153], v[208:211], v[70:73]
	v_mfma_f32_16x16x32_bf16 v[66:69], v[158:161], v[208:211], v[66:69]
	s_setprio 0
	s_barrier
	s_add_i32 s41, s41, s29
	v_lshl_add_u64 v[212:213], s[24:25], 0, v[178:179]
	s_mov_b32 m0, s41
	ds_read_b128 v[162:165], v216 offset:16384
	ds_read_b128 v[166:169], v216 offset:17408
	ds_read_b128 v[170:173], v216 offset:18432
	ds_read_b128 v[186:189], v216 offset:19456
	ds_read_b128 v[196:199], v216 offset:20480
	ds_read_b128 v[200:203], v216 offset:21504
	ds_read_b128 v[204:207], v216 offset:22528
	ds_read_b128 v[208:211], v216 offset:23552
	global_load_lds_dwordx4 v[212:213], off
	s_add_i32 m0, s41, 0x2000
	s_add_u32 s42, s24, 0x80000
	v_lshl_add_u64 v[218:219], s[24:25], 0, v[174:175]
	s_addc_u32 s43, s25, 0
	s_add_i32 s41, s46, s29
	global_load_lds_dwordx4 v[218:219], off
	v_lshl_add_u64 v[220:221], s[42:43], 0, v[178:179]
	s_mov_b32 m0, s41
	v_lshl_add_u64 v[222:223], s[26:27], 0, v[176:177]
	global_load_lds_dwordx4 v[220:221], off
	v_lshl_add_u64 v[220:221], s[42:43], 0, v[174:175]
	s_add_i32 m0, s41, 0x2000
	s_nop 0
	global_load_lds_dwordx4 v[220:221], off
	v_lshl_add_u64 v[220:221], s[26:27], 0, v[180:181]
	s_mov_b32 m0, s17
	s_nop 0
	global_load_lds_dwordx4 v[220:221], off
	s_mov_b32 m0, s31
	s_nop 0
	global_load_lds_dwordx4 v[222:223], off
	s_waitcnt vmcnt(8)
	s_waitcnt lgkmcnt(0)
	s_barrier
	s_setprio 1
	v_mfma_f32_16x16x32_bf16 v[62:65], v[130:133], v[162:165], 0
	v_mfma_f32_16x16x32_bf16 v[58:61], v[138:141], v[162:165], 0
	v_mfma_f32_16x16x32_bf16 v[46:49], v[130:133], v[170:173], 0
	v_mfma_f32_16x16x32_bf16 v[42:45], v[138:141], v[170:173], 0
	v_mfma_f32_16x16x32_bf16 v[30:33], v[130:133], v[196:199], 0
	v_mfma_f32_16x16x32_bf16 v[26:29], v[138:141], v[196:199], 0
	v_mfma_f32_16x16x32_bf16 v[14:17], v[130:133], v[204:207], 0
	v_mfma_f32_16x16x32_bf16 v[10:13], v[138:141], v[204:207], 0
	v_mfma_f32_16x16x32_bf16 v[62:65], v[134:137], v[166:169], v[62:65]
	v_mfma_f32_16x16x32_bf16 v[58:61], v[142:145], v[166:169], v[58:61]
	v_mfma_f32_16x16x32_bf16 v[46:49], v[134:137], v[186:189], v[46:49]
	v_mfma_f32_16x16x32_bf16 v[42:45], v[142:145], v[186:189], v[42:45]
	v_mfma_f32_16x16x32_bf16 v[30:33], v[134:137], v[200:203], v[30:33]
	v_mfma_f32_16x16x32_bf16 v[26:29], v[142:145], v[200:203], v[26:29]
	v_mfma_f32_16x16x32_bf16 v[14:17], v[134:137], v[208:211], v[14:17]
	v_mfma_f32_16x16x32_bf16 v[10:13], v[142:145], v[208:211], v[10:13]
	s_setprio 0
	s_setprio 1
	v_mfma_f32_16x16x32_bf16 v[54:57], v[146:149], v[162:165], 0
	v_mfma_f32_16x16x32_bf16 v[50:53], v[154:157], v[162:165], 0
	v_mfma_f32_16x16x32_bf16 v[38:41], v[146:149], v[170:173], 0
	v_mfma_f32_16x16x32_bf16 v[34:37], v[154:157], v[170:173], 0
	v_mfma_f32_16x16x32_bf16 v[22:25], v[146:149], v[196:199], 0
	v_mfma_f32_16x16x32_bf16 v[18:21], v[154:157], v[196:199], 0
	v_mfma_f32_16x16x32_bf16 v[6:9], v[146:149], v[204:207], 0
	v_mfma_f32_16x16x32_bf16 v[2:5], v[154:157], v[204:207], 0
	v_mfma_f32_16x16x32_bf16 v[54:57], v[150:153], v[166:169], v[54:57]
	v_mfma_f32_16x16x32_bf16 v[50:53], v[158:161], v[166:169], v[50:53]
	v_mfma_f32_16x16x32_bf16 v[38:41], v[150:153], v[186:189], v[38:41]
	v_mfma_f32_16x16x32_bf16 v[34:37], v[158:161], v[186:189], v[34:37]
	v_mfma_f32_16x16x32_bf16 v[22:25], v[150:153], v[200:203], v[22:25]
	v_mfma_f32_16x16x32_bf16 v[18:21], v[158:161], v[200:203], v[18:21]
	v_mfma_f32_16x16x32_bf16 v[6:9], v[150:153], v[208:211], v[6:9]
	v_mfma_f32_16x16x32_bf16 v[2:5], v[158:161], v[208:211], v[2:5]
	s_setprio 0
	s_barrier
	s_add_i32 s41, 0, 0x18000
	s_add_i32 s42, 0, 0x1c000
	v_add_u32_e32 v142, s41, v214
	v_add_u32_e32 v158, s42, v214
	ds_read_b128 v[130:133], v142
	ds_read_b128 v[134:137], v142 offset:1024
	ds_read_b128 v[138:141], v142 offset:2048
	ds_read_b128 v[142:145], v142 offset:3072
	ds_read_b128 v[146:149], v158
	ds_read_b128 v[150:153], v158 offset:1024
	ds_read_b128 v[154:157], v158 offset:2048
	ds_read_b128 v[158:161], v158 offset:3072
	s_add_u32 s26, s26, 0x80000
	s_addc_u32 s27, s27, 0
	s_mov_b32 m0, s34
	v_lshl_add_u64 v[224:225], s[26:27], 0, v[180:181]
	ds_read_b128 v[162:165], v216 offset:32768
	ds_read_b128 v[166:169], v216 offset:33792
	ds_read_b128 v[170:173], v216 offset:34816
	ds_read_b128 v[186:189], v216 offset:35840
	ds_read_b128 v[196:199], v216 offset:36864
	ds_read_b128 v[200:203], v216 offset:37888
	ds_read_b128 v[204:207], v216 offset:38912
	ds_read_b128 v[208:211], v216 offset:39936
	global_load_lds_dwordx4 v[224:225], off
	v_lshl_add_u64 v[224:225], s[26:27], 0, v[176:177]
	s_mov_b32 m0, s35
	s_nop 0
	global_load_lds_dwordx4 v[224:225], off
	s_waitcnt vmcnt(8)
	s_waitcnt lgkmcnt(0)
	s_barrier
	s_setprio 1
	v_mfma_f32_16x16x32_bf16 v[126:129], v[130:133], v[162:165], v[126:129]
	v_mfma_f32_16x16x32_bf16 v[122:125], v[138:141], v[162:165], v[122:125]
	v_mfma_f32_16x16x32_bf16 v[110:113], v[130:133], v[170:173], v[110:113]
	v_mfma_f32_16x16x32_bf16 v[106:109], v[138:141], v[170:173], v[106:109]
	v_mfma_f32_16x16x32_bf16 v[94:97], v[130:133], v[196:199], v[94:97]
	v_mfma_f32_16x16x32_bf16 v[90:93], v[138:141], v[196:199], v[90:93]
	v_mfma_f32_16x16x32_bf16 v[78:81], v[130:133], v[204:207], v[78:81]
	v_mfma_f32_16x16x32_bf16 v[74:77], v[138:141], v[204:207], v[74:77]
	v_mfma_f32_16x16x32_bf16 v[126:129], v[134:137], v[166:169], v[126:129]
	v_mfma_f32_16x16x32_bf16 v[122:125], v[142:145], v[166:169], v[122:125]
	v_mfma_f32_16x16x32_bf16 v[110:113], v[134:137], v[186:189], v[110:113]
	v_mfma_f32_16x16x32_bf16 v[106:109], v[142:145], v[186:189], v[106:109]
	v_mfma_f32_16x16x32_bf16 v[94:97], v[134:137], v[200:203], v[94:97]
	v_mfma_f32_16x16x32_bf16 v[90:93], v[142:145], v[200:203], v[90:93]
	v_mfma_f32_16x16x32_bf16 v[78:81], v[134:137], v[208:211], v[78:81]
	v_mfma_f32_16x16x32_bf16 v[74:77], v[142:145], v[208:211], v[74:77]
	s_setprio 0
	s_setprio 1
	v_mfma_f32_16x16x32_bf16 v[118:121], v[146:149], v[162:165], v[118:121]
	v_mfma_f32_16x16x32_bf16 v[114:117], v[154:157], v[162:165], v[114:117]
	v_mfma_f32_16x16x32_bf16 v[102:105], v[146:149], v[170:173], v[102:105]
	v_mfma_f32_16x16x32_bf16 v[98:101], v[154:157], v[170:173], v[98:101]
	v_mfma_f32_16x16x32_bf16 v[86:89], v[146:149], v[196:199], v[86:89]
	v_mfma_f32_16x16x32_bf16 v[82:85], v[154:157], v[196:199], v[82:85]
	v_mfma_f32_16x16x32_bf16 v[70:73], v[146:149], v[204:207], v[70:73]
	v_mfma_f32_16x16x32_bf16 v[66:69], v[154:157], v[204:207], v[66:69]
	v_mfma_f32_16x16x32_bf16 v[118:121], v[150:153], v[166:169], v[118:121]
	v_mfma_f32_16x16x32_bf16 v[114:117], v[158:161], v[166:169], v[114:117]
	v_mfma_f32_16x16x32_bf16 v[102:105], v[150:153], v[186:189], v[102:105]
	v_mfma_f32_16x16x32_bf16 v[98:101], v[158:161], v[186:189], v[98:101]
	v_mfma_f32_16x16x32_bf16 v[86:89], v[150:153], v[200:203], v[86:89]
	v_mfma_f32_16x16x32_bf16 v[82:85], v[158:161], v[200:203], v[82:85]
	v_mfma_f32_16x16x32_bf16 v[70:73], v[150:153], v[208:211], v[70:73]
	v_mfma_f32_16x16x32_bf16 v[66:69], v[158:161], v[208:211], v[66:69]
	s_setprio 0
	s_barrier
	s_add_i32 s26, s41, s29
	v_lshl_add_u64 v[212:213], v[212:213], 0, s[58:59]
	s_mov_b32 m0, s26
	ds_read_b128 v[162:165], v216 offset:49152
	ds_read_b128 v[166:169], v216 offset:50176
	ds_read_b128 v[170:173], v216 offset:51200
	ds_read_b128 v[186:189], v216 offset:52224
	ds_read_b128 v[196:199], v216 offset:53248
	ds_read_b128 v[200:203], v216 offset:54272
	ds_read_b128 v[204:207], v216 offset:55296
	ds_read_b128 v[208:211], v216 offset:56320
	global_load_lds_dwordx4 v[212:213], off
	s_add_i32 m0, s26, 0x2000
	s_add_u32 s24, s24, 0x80080
	v_lshl_add_u64 v[212:213], v[218:219], 0, s[58:59]
	s_addc_u32 s25, s25, 0
	s_add_i32 s26, s42, s29
	global_load_lds_dwordx4 v[212:213], off
	v_lshl_add_u64 v[212:213], s[24:25], 0, v[178:179]
	s_mov_b32 m0, s26
	s_nop 0
	global_load_lds_dwordx4 v[212:213], off
	v_lshl_add_u64 v[212:213], s[24:25], 0, v[174:175]
	s_add_i32 m0, s26, 0x2000
	s_nop 0
	global_load_lds_dwordx4 v[212:213], off
	v_lshl_add_u64 v[212:213], v[220:221], 0, s[58:59]
	s_mov_b32 m0, s38
	s_nop 0
	global_load_lds_dwordx4 v[212:213], off
	v_lshl_add_u64 v[212:213], v[222:223], 0, s[58:59]
	s_mov_b32 m0, s39
	s_nop 0
	global_load_lds_dwordx4 v[212:213], off
	s_waitcnt vmcnt(8)
	s_waitcnt lgkmcnt(0)
	s_barrier
	s_setprio 1
	v_mfma_f32_16x16x32_bf16 v[62:65], v[130:133], v[162:165], v[62:65]
	v_mfma_f32_16x16x32_bf16 v[58:61], v[138:141], v[162:165], v[58:61]
	v_mfma_f32_16x16x32_bf16 v[46:49], v[130:133], v[170:173], v[46:49]
	v_mfma_f32_16x16x32_bf16 v[42:45], v[138:141], v[170:173], v[42:45]
	v_mfma_f32_16x16x32_bf16 v[30:33], v[130:133], v[196:199], v[30:33]
	v_mfma_f32_16x16x32_bf16 v[26:29], v[138:141], v[196:199], v[26:29]
	v_mfma_f32_16x16x32_bf16 v[14:17], v[130:133], v[204:207], v[14:17]
	v_mfma_f32_16x16x32_bf16 v[10:13], v[138:141], v[204:207], v[10:13]
	v_mfma_f32_16x16x32_bf16 v[62:65], v[134:137], v[166:169], v[62:65]
	v_mfma_f32_16x16x32_bf16 v[58:61], v[142:145], v[166:169], v[58:61]
	v_mfma_f32_16x16x32_bf16 v[46:49], v[134:137], v[186:189], v[46:49]
	v_mfma_f32_16x16x32_bf16 v[42:45], v[142:145], v[186:189], v[42:45]
	v_mfma_f32_16x16x32_bf16 v[30:33], v[134:137], v[200:203], v[30:33]
	v_mfma_f32_16x16x32_bf16 v[26:29], v[142:145], v[200:203], v[26:29]
	v_mfma_f32_16x16x32_bf16 v[14:17], v[134:137], v[208:211], v[14:17]
	v_mfma_f32_16x16x32_bf16 v[10:13], v[142:145], v[208:211], v[10:13]
	s_setprio 0
	s_setprio 1
	v_mfma_f32_16x16x32_bf16 v[54:57], v[146:149], v[162:165], v[54:57]
	v_mfma_f32_16x16x32_bf16 v[50:53], v[154:157], v[162:165], v[50:53]
	v_mfma_f32_16x16x32_bf16 v[38:41], v[146:149], v[170:173], v[38:41]
	v_mfma_f32_16x16x32_bf16 v[34:37], v[154:157], v[170:173], v[34:37]
	v_mfma_f32_16x16x32_bf16 v[22:25], v[146:149], v[196:199], v[22:25]
	v_mfma_f32_16x16x32_bf16 v[18:21], v[154:157], v[196:199], v[18:21]
	v_mfma_f32_16x16x32_bf16 v[6:9], v[146:149], v[204:207], v[6:9]
	v_mfma_f32_16x16x32_bf16 v[2:5], v[154:157], v[204:207], v[2:5]
	v_mfma_f32_16x16x32_bf16 v[54:57], v[150:153], v[166:169], v[54:57]
	v_mfma_f32_16x16x32_bf16 v[50:53], v[158:161], v[166:169], v[50:53]
	v_mfma_f32_16x16x32_bf16 v[38:41], v[150:153], v[186:189], v[38:41]
	v_mfma_f32_16x16x32_bf16 v[34:37], v[158:161], v[186:189], v[34:37]
	v_mfma_f32_16x16x32_bf16 v[22:25], v[150:153], v[200:203], v[22:25]
	v_mfma_f32_16x16x32_bf16 v[18:21], v[158:161], v[200:203], v[18:21]
	v_mfma_f32_16x16x32_bf16 v[6:9], v[150:153], v[208:211], v[6:9]
	v_mfma_f32_16x16x32_bf16 v[2:5], v[158:161], v[208:211], v[2:5]
	s_setprio 0
	s_barrier
	s_add_i32 s40, s40, 2
	s_add_u32 s22, s22, 0x100
	s_addc_u32 s23, s23, 0
	s_add_u32 s21, s21, 0x100
	s_addc_u32 s33, s33, 0
	s_cmp_gt_u32 s40, 29
	s_cbranch_scc1 .Lpeel_done_1
.LBB0_672:
	s_add_u32 s24, s22, 0xfff80080
	s_addc_u32 s25, s23, -1
	s_add_i32 s41, 0, 0x10000
	s_cmp_eq_u32 s40, 28
	s_cselect_b32 s27, s11, s25
	s_cselect_b32 s26, s18, s24
	s_cselect_b32 s25, s9, s33
	s_cselect_b32 s24, s19, s21
	s_add_i32 s46, 0, 0x14000
	v_add_u32_e32 v142, s41, v214
	v_add_u32_e32 v158, s46, v214
	ds_read_b128 v[130:133], v142
	ds_read_b128 v[134:137], v142 offset:1024
	ds_read_b128 v[138:141], v142 offset:2048
	ds_read_b128 v[142:145], v142 offset:3072
	ds_read_b128 v[146:149], v158
	ds_read_b128 v[150:153], v158 offset:1024
	ds_read_b128 v[154:157], v158 offset:2048
	ds_read_b128 v[158:161], v158 offset:3072
	v_lshl_add_u64 v[212:213], s[22:23], 0, v[182:183]
	s_add_i32 m0, s17, 0xc000
	ds_read_b128 v[162:165], v216
	ds_read_b128 v[166:169], v216 offset:1024
	ds_read_b128 v[170:173], v216 offset:2048
	ds_read_b128 v[186:189], v216 offset:3072
	ds_read_b128 v[196:199], v216 offset:4096
	ds_read_b128 v[200:203], v216 offset:5120
	ds_read_b128 v[204:207], v216 offset:6144
	ds_read_b128 v[208:211], v216 offset:7168
	global_load_lds_dwordx4 v[212:213], off
	v_lshl_add_u64 v[212:213], s[22:23], 0, v[184:185]
	s_add_i32 m0, s17, 0xe000
	s_nop 0
	global_load_lds_dwordx4 v[212:213], off
	s_waitcnt vmcnt(8)
	s_waitcnt lgkmcnt(0)
	s_barrier
	s_setprio 1
	v_mfma_f32_16x16x32_bf16 v[126:129], v[130:133], v[162:165], v[126:129]
	v_mfma_f32_16x16x32_bf16 v[122:125], v[138:141], v[162:165], v[122:125]
	v_mfma_f32_16x16x32_bf16 v[110:113], v[130:133], v[170:173], v[110:113]
	v_mfma_f32_16x16x32_bf16 v[106:109], v[138:141], v[170:173], v[106:109]
	v_mfma_f32_16x16x32_bf16 v[94:97], v[130:133], v[196:199], v[94:97]
	v_mfma_f32_16x16x32_bf16 v[90:93], v[138:141], v[196:199], v[90:93]
	v_mfma_f32_16x16x32_bf16 v[78:81], v[130:133], v[204:207], v[78:81]
	v_mfma_f32_16x16x32_bf16 v[74:77], v[138:141], v[204:207], v[74:77]
	v_mfma_f32_16x16x32_bf16 v[126:129], v[134:137], v[166:169], v[126:129]
	v_mfma_f32_16x16x32_bf16 v[122:125], v[142:145], v[166:169], v[122:125]
	v_mfma_f32_16x16x32_bf16 v[110:113], v[134:137], v[186:189], v[110:113]
	v_mfma_f32_16x16x32_bf16 v[106:109], v[142:145], v[186:189], v[106:109]
	v_mfma_f32_16x16x32_bf16 v[94:97], v[134:137], v[200:203], v[94:97]
	v_mfma_f32_16x16x32_bf16 v[90:93], v[142:145], v[200:203], v[90:93]
	v_mfma_f32_16x16x32_bf16 v[78:81], v[134:137], v[208:211], v[78:81]
	v_mfma_f32_16x16x32_bf16 v[74:77], v[142:145], v[208:211], v[74:77]
	s_setprio 0
	s_setprio 1
	v_mfma_f32_16x16x32_bf16 v[118:121], v[146:149], v[162:165], v[118:121]
	v_mfma_f32_16x16x32_bf16 v[114:117], v[154:157], v[162:165], v[114:117]
	v_mfma_f32_16x16x32_bf16 v[102:105], v[146:149], v[170:173], v[102:105]
	v_mfma_f32_16x16x32_bf16 v[98:101], v[154:157], v[170:173], v[98:101]
	v_mfma_f32_16x16x32_bf16 v[86:89], v[146:149], v[196:199], v[86:89]
	v_mfma_f32_16x16x32_bf16 v[82:85], v[154:157], v[196:199], v[82:85]
	v_mfma_f32_16x16x32_bf16 v[70:73], v[146:149], v[204:207], v[70:73]
	v_mfma_f32_16x16x32_bf16 v[66:69], v[154:157], v[204:207], v[66:69]
	v_mfma_f32_16x16x32_bf16 v[118:121], v[150:153], v[166:169], v[118:121]
	v_mfma_f32_16x16x32_bf16 v[114:117], v[158:161], v[166:169], v[114:117]
	v_mfma_f32_16x16x32_bf16 v[102:105], v[150:153], v[186:189], v[102:105]
	v_mfma_f32_16x16x32_bf16 v[98:101], v[158:161], v[186:189], v[98:101]
	v_mfma_f32_16x16x32_bf16 v[86:89], v[150:153], v[200:203], v[86:89]
	v_mfma_f32_16x16x32_bf16 v[82:85], v[158:161], v[200:203], v[82:85]
	v_mfma_f32_16x16x32_bf16 v[70:73], v[150:153], v[208:211], v[70:73]
	v_mfma_f32_16x16x32_bf16 v[66:69], v[158:161], v[208:211], v[66:69]
	s_setprio 0
	s_barrier
	s_add_i32 s41, s41, s29
	v_lshl_add_u64 v[212:213], s[24:25], 0, v[178:179]
	s_mov_b32 m0, s41
	ds_read_b128 v[162:165], v216 offset:16384
	ds_read_b128 v[166:169], v216 offset:17408
	ds_read_b128 v[170:173], v216 offset:18432
	ds_read_b128 v[186:189], v216 offset:19456
	ds_read_b128 v[196:199], v216 offset:20480
	ds_read_b128 v[200:203], v216 offset:21504
	ds_read_b128 v[204:207], v216 offset:22528
	ds_read_b128 v[208:211], v216 offset:23552
	global_load_lds_dwordx4 v[212:213], off
	s_add_i32 m0, s41, 0x2000
	s_add_u32 s42, s24, 0x80000
	v_lshl_add_u64 v[218:219], s[24:25], 0, v[174:175]
	s_addc_u32 s43, s25, 0
	s_add_i32 s41, s46, s29
	global_load_lds_dwordx4 v[218:219], off
	v_lshl_add_u64 v[220:221], s[42:43], 0, v[178:179]
	s_mov_b32 m0, s41
	v_lshl_add_u64 v[222:223], s[26:27], 0, v[176:177]
	global_load_lds_dwordx4 v[220:221], off
	v_lshl_add_u64 v[220:221], s[42:43], 0, v[174:175]
	s_add_i32 m0, s41, 0x2000
	s_nop 0
	global_load_lds_dwordx4 v[220:221], off
	v_lshl_add_u64 v[220:221], s[26:27], 0, v[180:181]
	s_mov_b32 m0, s17
	s_nop 0
	global_load_lds_dwordx4 v[220:221], off
	s_mov_b32 m0, s31
	s_nop 0
	global_load_lds_dwordx4 v[222:223], off
	s_waitcnt vmcnt(8)
	s_waitcnt lgkmcnt(0)
	s_barrier
	s_setprio 1
	v_mfma_f32_16x16x32_bf16 v[62:65], v[130:133], v[162:165], v[62:65]
	v_mfma_f32_16x16x32_bf16 v[58:61], v[138:141], v[162:165], v[58:61]
	v_mfma_f32_16x16x32_bf16 v[46:49], v[130:133], v[170:173], v[46:49]
	v_mfma_f32_16x16x32_bf16 v[42:45], v[138:141], v[170:173], v[42:45]
	v_mfma_f32_16x16x32_bf16 v[30:33], v[130:133], v[196:199], v[30:33]
	v_mfma_f32_16x16x32_bf16 v[26:29], v[138:141], v[196:199], v[26:29]
	v_mfma_f32_16x16x32_bf16 v[14:17], v[130:133], v[204:207], v[14:17]
	v_mfma_f32_16x16x32_bf16 v[10:13], v[138:141], v[204:207], v[10:13]
	v_mfma_f32_16x16x32_bf16 v[62:65], v[134:137], v[166:169], v[62:65]
	v_mfma_f32_16x16x32_bf16 v[58:61], v[142:145], v[166:169], v[58:61]
	v_mfma_f32_16x16x32_bf16 v[46:49], v[134:137], v[186:189], v[46:49]
	v_mfma_f32_16x16x32_bf16 v[42:45], v[142:145], v[186:189], v[42:45]
	v_mfma_f32_16x16x32_bf16 v[30:33], v[134:137], v[200:203], v[30:33]
	v_mfma_f32_16x16x32_bf16 v[26:29], v[142:145], v[200:203], v[26:29]
	v_mfma_f32_16x16x32_bf16 v[14:17], v[134:137], v[208:211], v[14:17]
	v_mfma_f32_16x16x32_bf16 v[10:13], v[142:145], v[208:211], v[10:13]
	s_setprio 0
	s_setprio 1
	v_mfma_f32_16x16x32_bf16 v[54:57], v[146:149], v[162:165], v[54:57]
	v_mfma_f32_16x16x32_bf16 v[50:53], v[154:157], v[162:165], v[50:53]
	v_mfma_f32_16x16x32_bf16 v[38:41], v[146:149], v[170:173], v[38:41]
	v_mfma_f32_16x16x32_bf16 v[34:37], v[154:157], v[170:173], v[34:37]
	v_mfma_f32_16x16x32_bf16 v[22:25], v[146:149], v[196:199], v[22:25]
	v_mfma_f32_16x16x32_bf16 v[18:21], v[154:157], v[196:199], v[18:21]
	v_mfma_f32_16x16x32_bf16 v[6:9], v[146:149], v[204:207], v[6:9]
	v_mfma_f32_16x16x32_bf16 v[2:5], v[154:157], v[204:207], v[2:5]
	v_mfma_f32_16x16x32_bf16 v[54:57], v[150:153], v[166:169], v[54:57]
	v_mfma_f32_16x16x32_bf16 v[50:53], v[158:161], v[166:169], v[50:53]
	v_mfma_f32_16x16x32_bf16 v[38:41], v[150:153], v[186:189], v[38:41]
	v_mfma_f32_16x16x32_bf16 v[34:37], v[158:161], v[186:189], v[34:37]
	v_mfma_f32_16x16x32_bf16 v[22:25], v[150:153], v[200:203], v[22:25]
	v_mfma_f32_16x16x32_bf16 v[18:21], v[158:161], v[200:203], v[18:21]
	v_mfma_f32_16x16x32_bf16 v[6:9], v[150:153], v[208:211], v[6:9]
	v_mfma_f32_16x16x32_bf16 v[2:5], v[158:161], v[208:211], v[2:5]
	s_setprio 0
	s_barrier
	s_add_i32 s41, 0, 0x18000
	s_add_i32 s42, 0, 0x1c000
	v_add_u32_e32 v142, s41, v214
	v_add_u32_e32 v158, s42, v214
	ds_read_b128 v[130:133], v142
	ds_read_b128 v[134:137], v142 offset:1024
	ds_read_b128 v[138:141], v142 offset:2048
	ds_read_b128 v[142:145], v142 offset:3072
	ds_read_b128 v[146:149], v158
	ds_read_b128 v[150:153], v158 offset:1024
	ds_read_b128 v[154:157], v158 offset:2048
	ds_read_b128 v[158:161], v158 offset:3072
	s_add_u32 s26, s26, 0x80000
	s_addc_u32 s27, s27, 0
	s_mov_b32 m0, s34
	v_lshl_add_u64 v[224:225], s[26:27], 0, v[180:181]
	ds_read_b128 v[162:165], v216 offset:32768
	ds_read_b128 v[166:169], v216 offset:33792
	ds_read_b128 v[170:173], v216 offset:34816
	ds_read_b128 v[186:189], v216 offset:35840
	ds_read_b128 v[196:199], v216 offset:36864
	ds_read_b128 v[200:203], v216 offset:37888
	ds_read_b128 v[204:207], v216 offset:38912
	ds_read_b128 v[208:211], v216 offset:39936
	global_load_lds_dwordx4 v[224:225], off
	v_lshl_add_u64 v[224:225], s[26:27], 0, v[176:177]
	s_mov_b32 m0, s35
	s_nop 0
	global_load_lds_dwordx4 v[224:225], off
	s_waitcnt vmcnt(8)
	s_waitcnt lgkmcnt(0)
	s_barrier
	s_setprio 1
	v_mfma_f32_16x16x32_bf16 v[126:129], v[130:133], v[162:165], v[126:129]
	v_mfma_f32_16x16x32_bf16 v[122:125], v[138:141], v[162:165], v[122:125]
	v_mfma_f32_16x16x32_bf16 v[110:113], v[130:133], v[170:173], v[110:113]
	v_mfma_f32_16x16x32_bf16 v[106:109], v[138:141], v[170:173], v[106:109]
	v_mfma_f32_16x16x32_bf16 v[94:97], v[130:133], v[196:199], v[94:97]
	v_mfma_f32_16x16x32_bf16 v[90:93], v[138:141], v[196:199], v[90:93]
	v_mfma_f32_16x16x32_bf16 v[78:81], v[130:133], v[204:207], v[78:81]
	v_mfma_f32_16x16x32_bf16 v[74:77], v[138:141], v[204:207], v[74:77]
	v_mfma_f32_16x16x32_bf16 v[126:129], v[134:137], v[166:169], v[126:129]
	v_mfma_f32_16x16x32_bf16 v[122:125], v[142:145], v[166:169], v[122:125]
	v_mfma_f32_16x16x32_bf16 v[110:113], v[134:137], v[186:189], v[110:113]
	v_mfma_f32_16x16x32_bf16 v[106:109], v[142:145], v[186:189], v[106:109]
	v_mfma_f32_16x16x32_bf16 v[94:97], v[134:137], v[200:203], v[94:97]
	v_mfma_f32_16x16x32_bf16 v[90:93], v[142:145], v[200:203], v[90:93]
	v_mfma_f32_16x16x32_bf16 v[78:81], v[134:137], v[208:211], v[78:81]
	v_mfma_f32_16x16x32_bf16 v[74:77], v[142:145], v[208:211], v[74:77]
	s_setprio 0
	s_setprio 1
	v_mfma_f32_16x16x32_bf16 v[118:121], v[146:149], v[162:165], v[118:121]
	v_mfma_f32_16x16x32_bf16 v[114:117], v[154:157], v[162:165], v[114:117]
	v_mfma_f32_16x16x32_bf16 v[102:105], v[146:149], v[170:173], v[102:105]
	v_mfma_f32_16x16x32_bf16 v[98:101], v[154:157], v[170:173], v[98:101]
	v_mfma_f32_16x16x32_bf16 v[86:89], v[146:149], v[196:199], v[86:89]
	v_mfma_f32_16x16x32_bf16 v[82:85], v[154:157], v[196:199], v[82:85]
	v_mfma_f32_16x16x32_bf16 v[70:73], v[146:149], v[204:207], v[70:73]
	v_mfma_f32_16x16x32_bf16 v[66:69], v[154:157], v[204:207], v[66:69]
	v_mfma_f32_16x16x32_bf16 v[118:121], v[150:153], v[166:169], v[118:121]
	v_mfma_f32_16x16x32_bf16 v[114:117], v[158:161], v[166:169], v[114:117]
	v_mfma_f32_16x16x32_bf16 v[102:105], v[150:153], v[186:189], v[102:105]
	v_mfma_f32_16x16x32_bf16 v[98:101], v[158:161], v[186:189], v[98:101]
	v_mfma_f32_16x16x32_bf16 v[86:89], v[150:153], v[200:203], v[86:89]
	v_mfma_f32_16x16x32_bf16 v[82:85], v[158:161], v[200:203], v[82:85]
	v_mfma_f32_16x16x32_bf16 v[70:73], v[150:153], v[208:211], v[70:73]
	v_mfma_f32_16x16x32_bf16 v[66:69], v[158:161], v[208:211], v[66:69]
	s_setprio 0
	s_barrier
	s_add_i32 s26, s41, s29
	v_lshl_add_u64 v[212:213], v[212:213], 0, s[58:59]
	s_mov_b32 m0, s26
	ds_read_b128 v[162:165], v216 offset:49152
	ds_read_b128 v[166:169], v216 offset:50176
	ds_read_b128 v[170:173], v216 offset:51200
	ds_read_b128 v[186:189], v216 offset:52224
	ds_read_b128 v[196:199], v216 offset:53248
	ds_read_b128 v[200:203], v216 offset:54272
	ds_read_b128 v[204:207], v216 offset:55296
	ds_read_b128 v[208:211], v216 offset:56320
	global_load_lds_dwordx4 v[212:213], off
	s_add_i32 m0, s26, 0x2000
	s_add_u32 s24, s24, 0x80080
	v_lshl_add_u64 v[212:213], v[218:219], 0, s[58:59]
	s_addc_u32 s25, s25, 0
	s_add_i32 s26, s42, s29
	global_load_lds_dwordx4 v[212:213], off
	v_lshl_add_u64 v[212:213], s[24:25], 0, v[178:179]
	s_mov_b32 m0, s26
	s_nop 0
	global_load_lds_dwordx4 v[212:213], off
	v_lshl_add_u64 v[212:213], s[24:25], 0, v[174:175]
	s_add_i32 m0, s26, 0x2000
	s_nop 0
	global_load_lds_dwordx4 v[212:213], off
	v_lshl_add_u64 v[212:213], v[220:221], 0, s[58:59]
	s_mov_b32 m0, s38
	s_nop 0
	global_load_lds_dwordx4 v[212:213], off
	v_lshl_add_u64 v[212:213], v[222:223], 0, s[58:59]
	s_mov_b32 m0, s39
	s_nop 0
	global_load_lds_dwordx4 v[212:213], off
	s_waitcnt vmcnt(8)
	s_waitcnt lgkmcnt(0)
	s_barrier
	s_setprio 1
	v_mfma_f32_16x16x32_bf16 v[62:65], v[130:133], v[162:165], v[62:65]
	v_mfma_f32_16x16x32_bf16 v[58:61], v[138:141], v[162:165], v[58:61]
	v_mfma_f32_16x16x32_bf16 v[46:49], v[130:133], v[170:173], v[46:49]
	v_mfma_f32_16x16x32_bf16 v[42:45], v[138:141], v[170:173], v[42:45]
	v_mfma_f32_16x16x32_bf16 v[30:33], v[130:133], v[196:199], v[30:33]
	v_mfma_f32_16x16x32_bf16 v[26:29], v[138:141], v[196:199], v[26:29]
	v_mfma_f32_16x16x32_bf16 v[14:17], v[130:133], v[204:207], v[14:17]
	v_mfma_f32_16x16x32_bf16 v[10:13], v[138:141], v[204:207], v[10:13]
	v_mfma_f32_16x16x32_bf16 v[62:65], v[134:137], v[166:169], v[62:65]
	v_mfma_f32_16x16x32_bf16 v[58:61], v[142:145], v[166:169], v[58:61]
	v_mfma_f32_16x16x32_bf16 v[46:49], v[134:137], v[186:189], v[46:49]
	v_mfma_f32_16x16x32_bf16 v[42:45], v[142:145], v[186:189], v[42:45]
	v_mfma_f32_16x16x32_bf16 v[30:33], v[134:137], v[200:203], v[30:33]
	v_mfma_f32_16x16x32_bf16 v[26:29], v[142:145], v[200:203], v[26:29]
	v_mfma_f32_16x16x32_bf16 v[14:17], v[134:137], v[208:211], v[14:17]
	v_mfma_f32_16x16x32_bf16 v[10:13], v[142:145], v[208:211], v[10:13]
	s_setprio 0
	s_setprio 1
	v_mfma_f32_16x16x32_bf16 v[54:57], v[146:149], v[162:165], v[54:57]
	v_mfma_f32_16x16x32_bf16 v[50:53], v[154:157], v[162:165], v[50:53]
	v_mfma_f32_16x16x32_bf16 v[38:41], v[146:149], v[170:173], v[38:41]
	v_mfma_f32_16x16x32_bf16 v[34:37], v[154:157], v[170:173], v[34:37]
	v_mfma_f32_16x16x32_bf16 v[22:25], v[146:149], v[196:199], v[22:25]
	v_mfma_f32_16x16x32_bf16 v[18:21], v[154:157], v[196:199], v[18:21]
	v_mfma_f32_16x16x32_bf16 v[6:9], v[146:149], v[204:207], v[6:9]
	v_mfma_f32_16x16x32_bf16 v[2:5], v[154:157], v[204:207], v[2:5]
	v_mfma_f32_16x16x32_bf16 v[54:57], v[150:153], v[166:169], v[54:57]
	v_mfma_f32_16x16x32_bf16 v[50:53], v[158:161], v[166:169], v[50:53]
	v_mfma_f32_16x16x32_bf16 v[38:41], v[150:153], v[186:189], v[38:41]
	v_mfma_f32_16x16x32_bf16 v[34:37], v[158:161], v[186:189], v[34:37]
	v_mfma_f32_16x16x32_bf16 v[22:25], v[150:153], v[200:203], v[22:25]
	v_mfma_f32_16x16x32_bf16 v[18:21], v[158:161], v[200:203], v[18:21]
	v_mfma_f32_16x16x32_bf16 v[6:9], v[150:153], v[208:211], v[6:9]
	v_mfma_f32_16x16x32_bf16 v[2:5], v[158:161], v[208:211], v[2:5]
	s_setprio 0
	s_barrier
	s_add_i32 s40, s40, 2
	s_add_u32 s22, s22, 0x100
	s_addc_u32 s23, s23, 0
	s_add_u32 s21, s21, 0x100
	s_addc_u32 s33, s33, 0
	s_cmp_gt_u32 s40, 29
	s_cbranch_scc0 .LBB0_672

.LBB0_747:
	s_ashr_i32 s9, s8, 31
	s_lshl_b64 s[10:11], s[8:9], 20
	s_add_u32 s10, s69, s10
	s_addc_u32 s11, s77, s11
	s_and_b64 s[12:13], s[4:5], exec
	s_cselect_b32 s9, s11, s17
	s_cselect_b32 s31, s10, s16
	s_ashr_i32 s7, s6, 31
	s_lshl_b64 s[12:13], s[6:7], 20
	v_readlane_b32 s22, v254, 42
	v_readlane_b32 s23, v254, 43
	s_add_u32 s12, s22, s12
	s_addc_u32 s13, s23, s13
	s_and_b64 s[22:23], s[4:5], exec
	s_cselect_b32 s7, s13, s21
	s_cselect_b32 s33, s12, s20
	s_add_u32 s16, s16, 0x80080
	s_addc_u32 s17, s17, 0
	s_add_u32 s34, s20, 0x100
	s_addc_u32 s35, s21, 0
	s_mov_b32 s36, -2
	v_readlane_b32 s37, v255, 49
	s_nop 3
	s_cmp_eq_u32 s37, 3
	v_writelane_b32 v255, 3, 49
	s_cbranch_scc0 .Ltrip0_strict_2
	s_add_u32 s20, s16, 0xfff80080
	s_addc_u32 s21, s17, -1
	s_add_i32 s37, 0, 0x10000
	s_cmp_eq_u32 s36, 28
	s_cselect_b32 s23, s9, s21
	s_cselect_b32 s22, s31, s20
	s_cselect_b32 s21, s7, s35
	s_cselect_b32 s20, s33, s34
	s_add_i32 s40, 0, 0x14000
	v_add_u32_e32 v142, s37, v238
	v_add_u32_e32 v158, s40, v238
	ds_read_b128 v[130:133], v142
	ds_read_b128 v[134:137], v142 offset:1024
	ds_read_b128 v[138:141], v142 offset:2048
	ds_read_b128 v[142:145], v142 offset:3072
	ds_read_b128 v[146:149], v158
	ds_read_b128 v[150:153], v158 offset:1024
	ds_read_b128 v[154:157], v158 offset:2048
	ds_read_b128 v[158:161], v158 offset:3072
	v_lshl_add_u64 v[210:211], s[16:17], 0, v[206:207]
	s_add_i32 m0, s25, 0xc000
	ds_read_b128 v[162:165], v240
	ds_read_b128 v[166:169], v240 offset:1024
	ds_read_b128 v[170:173], v240 offset:2048
	ds_read_b128 v[174:177], v240 offset:3072
	ds_read_b128 v[178:181], v240 offset:4096
	ds_read_b128 v[182:185], v240 offset:5120
	ds_read_b128 v[186:189], v240 offset:6144
	ds_read_b128 v[196:199], v240 offset:7168
	global_load_lds_dwordx4 v[210:211], off
	v_lshl_add_u64 v[210:211], s[16:17], 0, v[208:209]
	s_add_i32 m0, s25, 0xe000
	s_nop 0
	global_load_lds_dwordx4 v[210:211], off
	s_waitcnt vmcnt(24)
	s_waitcnt lgkmcnt(0)
	s_barrier
	s_setprio 1
	v_mfma_f32_16x16x32_bf16 v[126:129], v[130:133], v[162:165], 0
	v_mfma_f32_16x16x32_bf16 v[122:125], v[138:141], v[162:165], 0
	v_mfma_f32_16x16x32_bf16 v[110:113], v[130:133], v[170:173], 0
	v_mfma_f32_16x16x32_bf16 v[106:109], v[138:141], v[170:173], 0
	v_mfma_f32_16x16x32_bf16 v[98:101], v[130:133], v[178:181], 0
	v_mfma_f32_16x16x32_bf16 v[90:93], v[138:141], v[178:181], 0
	v_mfma_f32_16x16x32_bf16 v[82:85], v[130:133], v[186:189], 0
	v_mfma_f32_16x16x32_bf16 v[74:77], v[138:141], v[186:189], 0
	v_mfma_f32_16x16x32_bf16 v[126:129], v[134:137], v[166:169], v[126:129]
	v_mfma_f32_16x16x32_bf16 v[122:125], v[142:145], v[166:169], v[122:125]
	v_mfma_f32_16x16x32_bf16 v[110:113], v[134:137], v[174:177], v[110:113]
	v_mfma_f32_16x16x32_bf16 v[106:109], v[142:145], v[174:177], v[106:109]
	v_mfma_f32_16x16x32_bf16 v[98:101], v[134:137], v[182:185], v[98:101]
	v_mfma_f32_16x16x32_bf16 v[90:93], v[142:145], v[182:185], v[90:93]
	v_mfma_f32_16x16x32_bf16 v[82:85], v[134:137], v[196:199], v[82:85]
	v_mfma_f32_16x16x32_bf16 v[74:77], v[142:145], v[196:199], v[74:77]
	s_setprio 0
	s_setprio 1
	v_mfma_f32_16x16x32_bf16 v[118:121], v[146:149], v[162:165], 0
	v_mfma_f32_16x16x32_bf16 v[114:117], v[154:157], v[162:165], 0
	v_mfma_f32_16x16x32_bf16 v[102:105], v[146:149], v[170:173], 0
	v_mfma_f32_16x16x32_bf16 v[94:97], v[154:157], v[170:173], 0
	v_mfma_f32_16x16x32_bf16 v[86:89], v[146:149], v[178:181], 0
	v_mfma_f32_16x16x32_bf16 v[78:81], v[154:157], v[178:181], 0
	v_mfma_f32_16x16x32_bf16 v[70:73], v[146:149], v[186:189], 0
	v_mfma_f32_16x16x32_bf16 v[66:69], v[154:157], v[186:189], 0
	v_mfma_f32_16x16x32_bf16 v[118:121], v[150:153], v[166:169], v[118:121]
	v_mfma_f32_16x16x32_bf16 v[114:117], v[158:161], v[166:169], v[114:117]
	v_mfma_f32_16x16x32_bf16 v[102:105], v[150:153], v[174:177], v[102:105]
	v_mfma_f32_16x16x32_bf16 v[94:97], v[158:161], v[174:177], v[94:97]
	v_mfma_f32_16x16x32_bf16 v[86:89], v[150:153], v[182:185], v[86:89]
	v_mfma_f32_16x16x32_bf16 v[78:81], v[158:161], v[182:185], v[78:81]
	v_mfma_f32_16x16x32_bf16 v[70:73], v[150:153], v[196:199], v[70:73]
	v_mfma_f32_16x16x32_bf16 v[66:69], v[158:161], v[196:199], v[66:69]
	s_setprio 0
	s_barrier
	s_add_i32 s37, s37, s24
	v_lshl_add_u64 v[210:211], s[20:21], 0, v[190:191]
	s_mov_b32 m0, s37
	ds_read_b128 v[162:165], v240 offset:16384
	ds_read_b128 v[166:169], v240 offset:17408
	ds_read_b128 v[170:173], v240 offset:18432
	ds_read_b128 v[174:177], v240 offset:19456
	ds_read_b128 v[178:181], v240 offset:20480
	ds_read_b128 v[182:185], v240 offset:21504
	ds_read_b128 v[186:189], v240 offset:22528
	ds_read_b128 v[196:199], v240 offset:23552
	global_load_lds_dwordx4 v[210:211], off
	s_add_i32 m0, s37, 0x2000
	s_add_u32 s38, s20, 0x80000
	v_lshl_add_u64 v[212:213], s[20:21], 0, v[204:205]
	s_addc_u32 s39, s21, 0
	s_add_i32 s37, s40, s24
	global_load_lds_dwordx4 v[212:213], off
	v_lshl_add_u64 v[214:215], s[38:39], 0, v[190:191]
	s_mov_b32 m0, s37
	v_lshl_add_u64 v[216:217], s[22:23], 0, v[202:203]
	global_load_lds_dwordx4 v[214:215], off
	v_lshl_add_u64 v[214:215], s[38:39], 0, v[204:205]
	s_add_i32 m0, s37, 0x2000
	s_nop 0
	global_load_lds_dwordx4 v[214:215], off
	v_lshl_add_u64 v[214:215], s[22:23], 0, v[200:201]
	s_mov_b32 m0, s25
	s_nop 0
	global_load_lds_dwordx4 v[214:215], off
	s_mov_b32 m0, s26
	s_nop 0
	global_load_lds_dwordx4 v[216:217], off
	s_waitcnt vmcnt(24)
	s_waitcnt lgkmcnt(0)
	s_barrier
	s_setprio 1
	v_mfma_f32_16x16x32_bf16 v[62:65], v[130:133], v[162:165], 0
	v_mfma_f32_16x16x32_bf16 v[58:61], v[138:141], v[162:165], 0
	v_mfma_f32_16x16x32_bf16 v[50:53], v[130:133], v[170:173], 0
	v_mfma_f32_16x16x32_bf16 v[42:45], v[138:141], v[170:173], 0
	v_mfma_f32_16x16x32_bf16 v[34:37], v[130:133], v[178:181], 0
	v_mfma_f32_16x16x32_bf16 v[26:29], v[138:141], v[178:181], 0
	v_mfma_f32_16x16x32_bf16 v[18:21], v[130:133], v[186:189], 0
	v_mfma_f32_16x16x32_bf16 v[10:13], v[138:141], v[186:189], 0
	v_mfma_f32_16x16x32_bf16 v[62:65], v[134:137], v[166:169], v[62:65]
	v_mfma_f32_16x16x32_bf16 v[58:61], v[142:145], v[166:169], v[58:61]
	v_mfma_f32_16x16x32_bf16 v[50:53], v[134:137], v[174:177], v[50:53]
	v_mfma_f32_16x16x32_bf16 v[42:45], v[142:145], v[174:177], v[42:45]
	v_mfma_f32_16x16x32_bf16 v[34:37], v[134:137], v[182:185], v[34:37]
	v_mfma_f32_16x16x32_bf16 v[26:29], v[142:145], v[182:185], v[26:29]
	v_mfma_f32_16x16x32_bf16 v[18:21], v[134:137], v[196:199], v[18:21]
	v_mfma_f32_16x16x32_bf16 v[10:13], v[142:145], v[196:199], v[10:13]
	s_setprio 0
	s_setprio 1
	v_mfma_f32_16x16x32_bf16 v[54:57], v[146:149], v[162:165], 0
	v_mfma_f32_16x16x32_bf16 v[46:49], v[154:157], v[162:165], 0
	v_mfma_f32_16x16x32_bf16 v[38:41], v[146:149], v[170:173], 0
	v_mfma_f32_16x16x32_bf16 v[30:33], v[154:157], v[170:173], 0
	v_mfma_f32_16x16x32_bf16 v[22:25], v[146:149], v[178:181], 0
	v_mfma_f32_16x16x32_bf16 v[14:17], v[154:157], v[178:181], 0
	v_mfma_f32_16x16x32_bf16 v[6:9], v[146:149], v[186:189], 0
	v_mfma_f32_16x16x32_bf16 v[2:5], v[154:157], v[186:189], 0
	v_mfma_f32_16x16x32_bf16 v[54:57], v[150:153], v[166:169], v[54:57]
	v_mfma_f32_16x16x32_bf16 v[46:49], v[158:161], v[166:169], v[46:49]
	v_mfma_f32_16x16x32_bf16 v[38:41], v[150:153], v[174:177], v[38:41]
	v_mfma_f32_16x16x32_bf16 v[30:33], v[158:161], v[174:177], v[30:33]
	v_mfma_f32_16x16x32_bf16 v[22:25], v[150:153], v[182:185], v[22:25]
	v_mfma_f32_16x16x32_bf16 v[14:17], v[158:161], v[182:185], v[14:17]
	v_mfma_f32_16x16x32_bf16 v[6:9], v[150:153], v[196:199], v[6:9]
	v_mfma_f32_16x16x32_bf16 v[2:5], v[158:161], v[196:199], v[2:5]
	s_setprio 0
	s_barrier
	s_add_i32 s37, 0, 0x18000
	s_add_i32 s38, 0, 0x1c000
	v_add_u32_e32 v142, s37, v238
	v_add_u32_e32 v158, s38, v238
	ds_read_b128 v[130:133], v142
	ds_read_b128 v[134:137], v142 offset:1024
	ds_read_b128 v[138:141], v142 offset:2048
	ds_read_b128 v[142:145], v142 offset:3072
	ds_read_b128 v[146:149], v158
	ds_read_b128 v[150:153], v158 offset:1024
	ds_read_b128 v[154:157], v158 offset:2048
	ds_read_b128 v[158:161], v158 offset:3072
	s_add_u32 s22, s22, 0x80000
	s_addc_u32 s23, s23, 0
	s_mov_b32 m0, s27
	v_lshl_add_u64 v[218:219], s[22:23], 0, v[200:201]
	ds_read_b128 v[162:165], v240 offset:32768
	ds_read_b128 v[166:169], v240 offset:33792
	ds_read_b128 v[170:173], v240 offset:34816
	ds_read_b128 v[174:177], v240 offset:35840
	ds_read_b128 v[178:181], v240 offset:36864
	ds_read_b128 v[182:185], v240 offset:37888
	ds_read_b128 v[186:189], v240 offset:38912
	ds_read_b128 v[196:199], v240 offset:39936
	global_load_lds_dwordx4 v[218:219], off
	v_lshl_add_u64 v[218:219], s[22:23], 0, v[202:203]
	s_mov_b32 m0, s28
	s_nop 0
	global_load_lds_dwordx4 v[218:219], off
	s_waitcnt vmcnt(8)
	s_waitcnt lgkmcnt(0)
	s_barrier
	s_setprio 1
	v_mfma_f32_16x16x32_bf16 v[126:129], v[130:133], v[162:165], v[126:129]
	v_mfma_f32_16x16x32_bf16 v[122:125], v[138:141], v[162:165], v[122:125]
	v_mfma_f32_16x16x32_bf16 v[110:113], v[130:133], v[170:173], v[110:113]
	v_mfma_f32_16x16x32_bf16 v[106:109], v[138:141], v[170:173], v[106:109]
	v_mfma_f32_16x16x32_bf16 v[98:101], v[130:133], v[178:181], v[98:101]
	v_mfma_f32_16x16x32_bf16 v[90:93], v[138:141], v[178:181], v[90:93]
	v_mfma_f32_16x16x32_bf16 v[82:85], v[130:133], v[186:189], v[82:85]
	v_mfma_f32_16x16x32_bf16 v[74:77], v[138:141], v[186:189], v[74:77]
	v_mfma_f32_16x16x32_bf16 v[126:129], v[134:137], v[166:169], v[126:129]
	v_mfma_f32_16x16x32_bf16 v[122:125], v[142:145], v[166:169], v[122:125]
	v_mfma_f32_16x16x32_bf16 v[110:113], v[134:137], v[174:177], v[110:113]
	v_mfma_f32_16x16x32_bf16 v[106:109], v[142:145], v[174:177], v[106:109]
	v_mfma_f32_16x16x32_bf16 v[98:101], v[134:137], v[182:185], v[98:101]
	v_mfma_f32_16x16x32_bf16 v[90:93], v[142:145], v[182:185], v[90:93]
	v_mfma_f32_16x16x32_bf16 v[82:85], v[134:137], v[196:199], v[82:85]
	v_mfma_f32_16x16x32_bf16 v[74:77], v[142:145], v[196:199], v[74:77]
	s_setprio 0
	s_setprio 1
	v_mfma_f32_16x16x32_bf16 v[118:121], v[146:149], v[162:165], v[118:121]
	v_mfma_f32_16x16x32_bf16 v[114:117], v[154:157], v[162:165], v[114:117]
	v_mfma_f32_16x16x32_bf16 v[102:105], v[146:149], v[170:173], v[102:105]
	v_mfma_f32_16x16x32_bf16 v[94:97], v[154:157], v[170:173], v[94:97]
	v_mfma_f32_16x16x32_bf16 v[86:89], v[146:149], v[178:181], v[86:89]
	v_mfma_f32_16x16x32_bf16 v[78:81], v[154:157], v[178:181], v[78:81]
	v_mfma_f32_16x16x32_bf16 v[70:73], v[146:149], v[186:189], v[70:73]
	v_mfma_f32_16x16x32_bf16 v[66:69], v[154:157], v[186:189], v[66:69]
	v_mfma_f32_16x16x32_bf16 v[118:121], v[150:153], v[166:169], v[118:121]
	v_mfma_f32_16x16x32_bf16 v[114:117], v[158:161], v[166:169], v[114:117]
	v_mfma_f32_16x16x32_bf16 v[102:105], v[150:153], v[174:177], v[102:105]
	v_mfma_f32_16x16x32_bf16 v[94:97], v[158:161], v[174:177], v[94:97]
	v_mfma_f32_16x16x32_bf16 v[86:89], v[150:153], v[182:185], v[86:89]
	v_mfma_f32_16x16x32_bf16 v[78:81], v[158:161], v[182:185], v[78:81]
	v_mfma_f32_16x16x32_bf16 v[70:73], v[150:153], v[196:199], v[70:73]
	v_mfma_f32_16x16x32_bf16 v[66:69], v[158:161], v[196:199], v[66:69]
	s_setprio 0
	s_barrier
	s_add_i32 s22, s37, s24
	v_lshl_add_u64 v[210:211], v[210:211], 0, s[58:59]
	s_mov_b32 m0, s22
	ds_read_b128 v[162:165], v240 offset:49152
	ds_read_b128 v[166:169], v240 offset:50176
	ds_read_b128 v[170:173], v240 offset:51200
	ds_read_b128 v[174:177], v240 offset:52224
	ds_read_b128 v[178:181], v240 offset:53248
	ds_read_b128 v[182:185], v240 offset:54272
	ds_read_b128 v[186:189], v240 offset:55296
	ds_read_b128 v[196:199], v240 offset:56320
	global_load_lds_dwordx4 v[210:211], off
	s_add_i32 m0, s22, 0x2000
	s_add_u32 s20, s20, 0x80080
	v_lshl_add_u64 v[210:211], v[212:213], 0, s[58:59]
	s_addc_u32 s21, s21, 0
	s_add_i32 s22, s38, s24
	global_load_lds_dwordx4 v[210:211], off
	v_lshl_add_u64 v[210:211], s[20:21], 0, v[190:191]
	s_mov_b32 m0, s22
	s_nop 0
	global_load_lds_dwordx4 v[210:211], off
	v_lshl_add_u64 v[210:211], s[20:21], 0, v[204:205]
	s_add_i32 m0, s22, 0x2000
	s_nop 0
	global_load_lds_dwordx4 v[210:211], off
	v_lshl_add_u64 v[210:211], v[214:215], 0, s[58:59]
	s_mov_b32 m0, s29
	s_nop 0
	global_load_lds_dwordx4 v[210:211], off
	v_lshl_add_u64 v[210:211], v[216:217], 0, s[58:59]
	s_mov_b32 m0, s30
	s_nop 0
	global_load_lds_dwordx4 v[210:211], off
	s_waitcnt vmcnt(8)
	s_waitcnt lgkmcnt(0)
	s_barrier
	s_setprio 1
	v_mfma_f32_16x16x32_bf16 v[62:65], v[130:133], v[162:165], v[62:65]
	v_mfma_f32_16x16x32_bf16 v[58:61], v[138:141], v[162:165], v[58:61]
	v_mfma_f32_16x16x32_bf16 v[50:53], v[130:133], v[170:173], v[50:53]
	v_mfma_f32_16x16x32_bf16 v[42:45], v[138:141], v[170:173], v[42:45]
	v_mfma_f32_16x16x32_bf16 v[34:37], v[130:133], v[178:181], v[34:37]
	v_mfma_f32_16x16x32_bf16 v[26:29], v[138:141], v[178:181], v[26:29]
	v_mfma_f32_16x16x32_bf16 v[18:21], v[130:133], v[186:189], v[18:21]
	v_mfma_f32_16x16x32_bf16 v[10:13], v[138:141], v[186:189], v[10:13]
	v_mfma_f32_16x16x32_bf16 v[62:65], v[134:137], v[166:169], v[62:65]
	v_mfma_f32_16x16x32_bf16 v[58:61], v[142:145], v[166:169], v[58:61]
	v_mfma_f32_16x16x32_bf16 v[50:53], v[134:137], v[174:177], v[50:53]
	v_mfma_f32_16x16x32_bf16 v[42:45], v[142:145], v[174:177], v[42:45]
	v_mfma_f32_16x16x32_bf16 v[34:37], v[134:137], v[182:185], v[34:37]
	v_mfma_f32_16x16x32_bf16 v[26:29], v[142:145], v[182:185], v[26:29]
	v_mfma_f32_16x16x32_bf16 v[18:21], v[134:137], v[196:199], v[18:21]
	v_mfma_f32_16x16x32_bf16 v[10:13], v[142:145], v[196:199], v[10:13]
	s_setprio 0
	s_setprio 1
	v_mfma_f32_16x16x32_bf16 v[54:57], v[146:149], v[162:165], v[54:57]
	v_mfma_f32_16x16x32_bf16 v[46:49], v[154:157], v[162:165], v[46:49]
	v_mfma_f32_16x16x32_bf16 v[38:41], v[146:149], v[170:173], v[38:41]
	v_mfma_f32_16x16x32_bf16 v[30:33], v[154:157], v[170:173], v[30:33]
	v_mfma_f32_16x16x32_bf16 v[22:25], v[146:149], v[178:181], v[22:25]
	v_mfma_f32_16x16x32_bf16 v[14:17], v[154:157], v[178:181], v[14:17]
	v_mfma_f32_16x16x32_bf16 v[6:9], v[146:149], v[186:189], v[6:9]
	v_mfma_f32_16x16x32_bf16 v[2:5], v[154:157], v[186:189], v[2:5]
	v_mfma_f32_16x16x32_bf16 v[54:57], v[150:153], v[166:169], v[54:57]
	v_mfma_f32_16x16x32_bf16 v[46:49], v[158:161], v[166:169], v[46:49]
	v_mfma_f32_16x16x32_bf16 v[38:41], v[150:153], v[174:177], v[38:41]
	v_mfma_f32_16x16x32_bf16 v[30:33], v[158:161], v[174:177], v[30:33]
	v_mfma_f32_16x16x32_bf16 v[22:25], v[150:153], v[182:185], v[22:25]
	v_mfma_f32_16x16x32_bf16 v[14:17], v[158:161], v[182:185], v[14:17]
	v_mfma_f32_16x16x32_bf16 v[6:9], v[150:153], v[196:199], v[6:9]
	v_mfma_f32_16x16x32_bf16 v[2:5], v[158:161], v[196:199], v[2:5]
	s_setprio 0
	s_barrier
	s_add_i32 s36, s36, 2
	s_add_u32 s16, s16, 0x100
	s_addc_u32 s17, s17, 0
	s_add_u32 s34, s34, 0x100
	s_addc_u32 s35, s35, 0
	s_cmp_gt_u32 s36, 29
	s_cbranch_scc1 .Lpeel_done_2
	s_branch .LBB0_748
.Ltrip0_strict_2:
	s_add_u32 s20, s16, 0xfff80080
	s_addc_u32 s21, s17, -1
	s_add_i32 s37, 0, 0x10000
	s_cmp_eq_u32 s36, 28
	s_cselect_b32 s23, s9, s21
	s_cselect_b32 s22, s31, s20
	s_cselect_b32 s21, s7, s35
	s_cselect_b32 s20, s33, s34
	s_add_i32 s40, 0, 0x14000
	v_add_u32_e32 v142, s37, v238
	v_add_u32_e32 v158, s40, v238
	ds_read_b128 v[130:133], v142
	ds_read_b128 v[134:137], v142 offset:1024
	ds_read_b128 v[138:141], v142 offset:2048
	ds_read_b128 v[142:145], v142 offset:3072
	ds_read_b128 v[146:149], v158
	ds_read_b128 v[150:153], v158 offset:1024
	ds_read_b128 v[154:157], v158 offset:2048
	ds_read_b128 v[158:161], v158 offset:3072
	v_lshl_add_u64 v[210:211], s[16:17], 0, v[206:207]
	s_add_i32 m0, s25, 0xc000
	ds_read_b128 v[162:165], v240
	ds_read_b128 v[166:169], v240 offset:1024
	ds_read_b128 v[170:173], v240 offset:2048
	ds_read_b128 v[174:177], v240 offset:3072
	ds_read_b128 v[178:181], v240 offset:4096
	ds_read_b128 v[182:185], v240 offset:5120
	ds_read_b128 v[186:189], v240 offset:6144
	ds_read_b128 v[196:199], v240 offset:7168
	global_load_lds_dwordx4 v[210:211], off
	v_lshl_add_u64 v[210:211], s[16:17], 0, v[208:209]
	s_add_i32 m0, s25, 0xe000
	s_nop 0
	global_load_lds_dwordx4 v[210:211], off
	s_waitcnt vmcnt(8)
	s_waitcnt lgkmcnt(0)
	s_barrier
	s_setprio 1
	v_mfma_f32_16x16x32_bf16 v[126:129], v[130:133], v[162:165], 0
	v_mfma_f32_16x16x32_bf16 v[122:125], v[138:141], v[162:165], 0
	v_mfma_f32_16x16x32_bf16 v[110:113], v[130:133], v[170:173], 0
	v_mfma_f32_16x16x32_bf16 v[106:109], v[138:141], v[170:173], 0
	v_mfma_f32_16x16x32_bf16 v[98:101], v[130:133], v[178:181], 0
	v_mfma_f32_16x16x32_bf16 v[90:93], v[138:141], v[178:181], 0
	v_mfma_f32_16x16x32_bf16 v[82:85], v[130:133], v[186:189], 0
	v_mfma_f32_16x16x32_bf16 v[74:77], v[138:141], v[186:189], 0
	v_mfma_f32_16x16x32_bf16 v[126:129], v[134:137], v[166:169], v[126:129]
	v_mfma_f32_16x16x32_bf16 v[122:125], v[142:145], v[166:169], v[122:125]
	v_mfma_f32_16x16x32_bf16 v[110:113], v[134:137], v[174:177], v[110:113]
	v_mfma_f32_16x16x32_bf16 v[106:109], v[142:145], v[174:177], v[106:109]
	v_mfma_f32_16x16x32_bf16 v[98:101], v[134:137], v[182:185], v[98:101]
	v_mfma_f32_16x16x32_bf16 v[90:93], v[142:145], v[182:185], v[90:93]
	v_mfma_f32_16x16x32_bf16 v[82:85], v[134:137], v[196:199], v[82:85]
	v_mfma_f32_16x16x32_bf16 v[74:77], v[142:145], v[196:199], v[74:77]
	s_setprio 0
	s_setprio 1
	v_mfma_f32_16x16x32_bf16 v[118:121], v[146:149], v[162:165], 0
	v_mfma_f32_16x16x32_bf16 v[114:117], v[154:157], v[162:165], 0
	v_mfma_f32_16x16x32_bf16 v[102:105], v[146:149], v[170:173], 0
	v_mfma_f32_16x16x32_bf16 v[94:97], v[154:157], v[170:173], 0
	v_mfma_f32_16x16x32_bf16 v[86:89], v[146:149], v[178:181], 0
	v_mfma_f32_16x16x32_bf16 v[78:81], v[154:157], v[178:181], 0
	v_mfma_f32_16x16x32_bf16 v[70:73], v[146:149], v[186:189], 0
	v_mfma_f32_16x16x32_bf16 v[66:69], v[154:157], v[186:189], 0
	v_mfma_f32_16x16x32_bf16 v[118:121], v[150:153], v[166:169], v[118:121]
	v_mfma_f32_16x16x32_bf16 v[114:117], v[158:161], v[166:169], v[114:117]
	v_mfma_f32_16x16x32_bf16 v[102:105], v[150:153], v[174:177], v[102:105]
	v_mfma_f32_16x16x32_bf16 v[94:97], v[158:161], v[174:177], v[94:97]
	v_mfma_f32_16x16x32_bf16 v[86:89], v[150:153], v[182:185], v[86:89]
	v_mfma_f32_16x16x32_bf16 v[78:81], v[158:161], v[182:185], v[78:81]
	v_mfma_f32_16x16x32_bf16 v[70:73], v[150:153], v[196:199], v[70:73]
	v_mfma_f32_16x16x32_bf16 v[66:69], v[158:161], v[196:199], v[66:69]
	s_setprio 0
	s_barrier
	s_add_i32 s37, s37, s24
	v_lshl_add_u64 v[210:211], s[20:21], 0, v[190:191]
	s_mov_b32 m0, s37
	ds_read_b128 v[162:165], v240 offset:16384
	ds_read_b128 v[166:169], v240 offset:17408
	ds_read_b128 v[170:173], v240 offset:18432
	ds_read_b128 v[174:177], v240 offset:19456
	ds_read_b128 v[178:181], v240 offset:20480
	ds_read_b128 v[182:185], v240 offset:21504
	ds_read_b128 v[186:189], v240 offset:22528
	ds_read_b128 v[196:199], v240 offset:23552
	global_load_lds_dwordx4 v[210:211], off
	s_add_i32 m0, s37, 0x2000
	s_add_u32 s38, s20, 0x80000
	v_lshl_add_u64 v[212:213], s[20:21], 0, v[204:205]
	s_addc_u32 s39, s21, 0
	s_add_i32 s37, s40, s24
	global_load_lds_dwordx4 v[212:213], off
	v_lshl_add_u64 v[214:215], s[38:39], 0, v[190:191]
	s_mov_b32 m0, s37
	v_lshl_add_u64 v[216:217], s[22:23], 0, v[202:203]
	global_load_lds_dwordx4 v[214:215], off
	v_lshl_add_u64 v[214:215], s[38:39], 0, v[204:205]
	s_add_i32 m0, s37, 0x2000
	s_nop 0
	global_load_lds_dwordx4 v[214:215], off
	v_lshl_add_u64 v[214:215], s[22:23], 0, v[200:201]
	s_mov_b32 m0, s25
	s_nop 0
	global_load_lds_dwordx4 v[214:215], off
	s_mov_b32 m0, s26
	s_nop 0
	global_load_lds_dwordx4 v[216:217], off
	s_waitcnt vmcnt(8)
	s_waitcnt lgkmcnt(0)
	s_barrier
	s_setprio 1
	v_mfma_f32_16x16x32_bf16 v[62:65], v[130:133], v[162:165], 0
	v_mfma_f32_16x16x32_bf16 v[58:61], v[138:141], v[162:165], 0
	v_mfma_f32_16x16x32_bf16 v[50:53], v[130:133], v[170:173], 0
	v_mfma_f32_16x16x32_bf16 v[42:45], v[138:141], v[170:173], 0
	v_mfma_f32_16x16x32_bf16 v[34:37], v[130:133], v[178:181], 0
	v_mfma_f32_16x16x32_bf16 v[26:29], v[138:141], v[178:181], 0
	v_mfma_f32_16x16x32_bf16 v[18:21], v[130:133], v[186:189], 0
	v_mfma_f32_16x16x32_bf16 v[10:13], v[138:141], v[186:189], 0
	v_mfma_f32_16x16x32_bf16 v[62:65], v[134:137], v[166:169], v[62:65]
	v_mfma_f32_16x16x32_bf16 v[58:61], v[142:145], v[166:169], v[58:61]
	v_mfma_f32_16x16x32_bf16 v[50:53], v[134:137], v[174:177], v[50:53]
	v_mfma_f32_16x16x32_bf16 v[42:45], v[142:145], v[174:177], v[42:45]
	v_mfma_f32_16x16x32_bf16 v[34:37], v[134:137], v[182:185], v[34:37]
	v_mfma_f32_16x16x32_bf16 v[26:29], v[142:145], v[182:185], v[26:29]
	v_mfma_f32_16x16x32_bf16 v[18:21], v[134:137], v[196:199], v[18:21]
	v_mfma_f32_16x16x32_bf16 v[10:13], v[142:145], v[196:199], v[10:13]
	s_setprio 0
	s_setprio 1
	v_mfma_f32_16x16x32_bf16 v[54:57], v[146:149], v[162:165], 0
	v_mfma_f32_16x16x32_bf16 v[46:49], v[154:157], v[162:165], 0
	v_mfma_f32_16x16x32_bf16 v[38:41], v[146:149], v[170:173], 0
	v_mfma_f32_16x16x32_bf16 v[30:33], v[154:157], v[170:173], 0
	v_mfma_f32_16x16x32_bf16 v[22:25], v[146:149], v[178:181], 0
	v_mfma_f32_16x16x32_bf16 v[14:17], v[154:157], v[178:181], 0
	v_mfma_f32_16x16x32_bf16 v[6:9], v[146:149], v[186:189], 0
	v_mfma_f32_16x16x32_bf16 v[2:5], v[154:157], v[186:189], 0
	v_mfma_f32_16x16x32_bf16 v[54:57], v[150:153], v[166:169], v[54:57]
	v_mfma_f32_16x16x32_bf16 v[46:49], v[158:161], v[166:169], v[46:49]
	v_mfma_f32_16x16x32_bf16 v[38:41], v[150:153], v[174:177], v[38:41]
	v_mfma_f32_16x16x32_bf16 v[30:33], v[158:161], v[174:177], v[30:33]
	v_mfma_f32_16x16x32_bf16 v[22:25], v[150:153], v[182:185], v[22:25]
	v_mfma_f32_16x16x32_bf16 v[14:17], v[158:161], v[182:185], v[14:17]
	v_mfma_f32_16x16x32_bf16 v[6:9], v[150:153], v[196:199], v[6:9]
	v_mfma_f32_16x16x32_bf16 v[2:5], v[158:161], v[196:199], v[2:5]
	s_setprio 0
	s_barrier
	s_add_i32 s37, 0, 0x18000
	s_add_i32 s38, 0, 0x1c000
	v_add_u32_e32 v142, s37, v238
	v_add_u32_e32 v158, s38, v238
	ds_read_b128 v[130:133], v142
	ds_read_b128 v[134:137], v142 offset:1024
	ds_read_b128 v[138:141], v142 offset:2048
	ds_read_b128 v[142:145], v142 offset:3072
	ds_read_b128 v[146:149], v158
	ds_read_b128 v[150:153], v158 offset:1024
	ds_read_b128 v[154:157], v158 offset:2048
	ds_read_b128 v[158:161], v158 offset:3072
	s_add_u32 s22, s22, 0x80000
	s_addc_u32 s23, s23, 0
	s_mov_b32 m0, s27
	v_lshl_add_u64 v[218:219], s[22:23], 0, v[200:201]
	ds_read_b128 v[162:165], v240 offset:32768
	ds_read_b128 v[166:169], v240 offset:33792
	ds_read_b128 v[170:173], v240 offset:34816
	ds_read_b128 v[174:177], v240 offset:35840
	ds_read_b128 v[178:181], v240 offset:36864
	ds_read_b128 v[182:185], v240 offset:37888
	ds_read_b128 v[186:189], v240 offset:38912
	ds_read_b128 v[196:199], v240 offset:39936
	global_load_lds_dwordx4 v[218:219], off
	v_lshl_add_u64 v[218:219], s[22:23], 0, v[202:203]
	s_mov_b32 m0, s28
	s_nop 0
	global_load_lds_dwordx4 v[218:219], off
	s_waitcnt vmcnt(8)
	s_waitcnt lgkmcnt(0)
	s_barrier
	s_setprio 1
	v_mfma_f32_16x16x32_bf16 v[126:129], v[130:133], v[162:165], v[126:129]
	v_mfma_f32_16x16x32_bf16 v[122:125], v[138:141], v[162:165], v[122:125]
	v_mfma_f32_16x16x32_bf16 v[110:113], v[130:133], v[170:173], v[110:113]
	v_mfma_f32_16x16x32_bf16 v[106:109], v[138:141], v[170:173], v[106:109]
	v_mfma_f32_16x16x32_bf16 v[98:101], v[130:133], v[178:181], v[98:101]
	v_mfma_f32_16x16x32_bf16 v[90:93], v[138:141], v[178:181], v[90:93]
	v_mfma_f32_16x16x32_bf16 v[82:85], v[130:133], v[186:189], v[82:85]
	v_mfma_f32_16x16x32_bf16 v[74:77], v[138:141], v[186:189], v[74:77]
	v_mfma_f32_16x16x32_bf16 v[126:129], v[134:137], v[166:169], v[126:129]
	v_mfma_f32_16x16x32_bf16 v[122:125], v[142:145], v[166:169], v[122:125]
	v_mfma_f32_16x16x32_bf16 v[110:113], v[134:137], v[174:177], v[110:113]
	v_mfma_f32_16x16x32_bf16 v[106:109], v[142:145], v[174:177], v[106:109]
	v_mfma_f32_16x16x32_bf16 v[98:101], v[134:137], v[182:185], v[98:101]
	v_mfma_f32_16x16x32_bf16 v[90:93], v[142:145], v[182:185], v[90:93]
	v_mfma_f32_16x16x32_bf16 v[82:85], v[134:137], v[196:199], v[82:85]
	v_mfma_f32_16x16x32_bf16 v[74:77], v[142:145], v[196:199], v[74:77]
	s_setprio 0
	s_setprio 1
	v_mfma_f32_16x16x32_bf16 v[118:121], v[146:149], v[162:165], v[118:121]
	v_mfma_f32_16x16x32_bf16 v[114:117], v[154:157], v[162:165], v[114:117]
	v_mfma_f32_16x16x32_bf16 v[102:105], v[146:149], v[170:173], v[102:105]
	v_mfma_f32_16x16x32_bf16 v[94:97], v[154:157], v[170:173], v[94:97]
	v_mfma_f32_16x16x32_bf16 v[86:89], v[146:149], v[178:181], v[86:89]
	v_mfma_f32_16x16x32_bf16 v[78:81], v[154:157], v[178:181], v[78:81]
	v_mfma_f32_16x16x32_bf16 v[70:73], v[146:149], v[186:189], v[70:73]
	v_mfma_f32_16x16x32_bf16 v[66:69], v[154:157], v[186:189], v[66:69]
	v_mfma_f32_16x16x32_bf16 v[118:121], v[150:153], v[166:169], v[118:121]
	v_mfma_f32_16x16x32_bf16 v[114:117], v[158:161], v[166:169], v[114:117]
	v_mfma_f32_16x16x32_bf16 v[102:105], v[150:153], v[174:177], v[102:105]
	v_mfma_f32_16x16x32_bf16 v[94:97], v[158:161], v[174:177], v[94:97]
	v_mfma_f32_16x16x32_bf16 v[86:89], v[150:153], v[182:185], v[86:89]
	v_mfma_f32_16x16x32_bf16 v[78:81], v[158:161], v[182:185], v[78:81]
	v_mfma_f32_16x16x32_bf16 v[70:73], v[150:153], v[196:199], v[70:73]
	v_mfma_f32_16x16x32_bf16 v[66:69], v[158:161], v[196:199], v[66:69]
	s_setprio 0
	s_barrier
	s_add_i32 s22, s37, s24
	v_lshl_add_u64 v[210:211], v[210:211], 0, s[58:59]
	s_mov_b32 m0, s22
	ds_read_b128 v[162:165], v240 offset:49152
	ds_read_b128 v[166:169], v240 offset:50176
	ds_read_b128 v[170:173], v240 offset:51200
	ds_read_b128 v[174:177], v240 offset:52224
	ds_read_b128 v[178:181], v240 offset:53248
	ds_read_b128 v[182:185], v240 offset:54272
	ds_read_b128 v[186:189], v240 offset:55296
	ds_read_b128 v[196:199], v240 offset:56320
	global_load_lds_dwordx4 v[210:211], off
	s_add_i32 m0, s22, 0x2000
	s_add_u32 s20, s20, 0x80080
	v_lshl_add_u64 v[210:211], v[212:213], 0, s[58:59]
	s_addc_u32 s21, s21, 0
	s_add_i32 s22, s38, s24
	global_load_lds_dwordx4 v[210:211], off
	v_lshl_add_u64 v[210:211], s[20:21], 0, v[190:191]
	s_mov_b32 m0, s22
	s_nop 0
	global_load_lds_dwordx4 v[210:211], off
	v_lshl_add_u64 v[210:211], s[20:21], 0, v[204:205]
	s_add_i32 m0, s22, 0x2000
	s_nop 0
	global_load_lds_dwordx4 v[210:211], off
	v_lshl_add_u64 v[210:211], v[214:215], 0, s[58:59]
	s_mov_b32 m0, s29
	s_nop 0
	global_load_lds_dwordx4 v[210:211], off
	v_lshl_add_u64 v[210:211], v[216:217], 0, s[58:59]
	s_mov_b32 m0, s30
	s_nop 0
	global_load_lds_dwordx4 v[210:211], off
	s_waitcnt vmcnt(8)
	s_waitcnt lgkmcnt(0)
	s_barrier
	s_setprio 1
	v_mfma_f32_16x16x32_bf16 v[62:65], v[130:133], v[162:165], v[62:65]
	v_mfma_f32_16x16x32_bf16 v[58:61], v[138:141], v[162:165], v[58:61]
	v_mfma_f32_16x16x32_bf16 v[50:53], v[130:133], v[170:173], v[50:53]
	v_mfma_f32_16x16x32_bf16 v[42:45], v[138:141], v[170:173], v[42:45]
	v_mfma_f32_16x16x32_bf16 v[34:37], v[130:133], v[178:181], v[34:37]
	v_mfma_f32_16x16x32_bf16 v[26:29], v[138:141], v[178:181], v[26:29]
	v_mfma_f32_16x16x32_bf16 v[18:21], v[130:133], v[186:189], v[18:21]
	v_mfma_f32_16x16x32_bf16 v[10:13], v[138:141], v[186:189], v[10:13]
	v_mfma_f32_16x16x32_bf16 v[62:65], v[134:137], v[166:169], v[62:65]
	v_mfma_f32_16x16x32_bf16 v[58:61], v[142:145], v[166:169], v[58:61]
	v_mfma_f32_16x16x32_bf16 v[50:53], v[134:137], v[174:177], v[50:53]
	v_mfma_f32_16x16x32_bf16 v[42:45], v[142:145], v[174:177], v[42:45]
	v_mfma_f32_16x16x32_bf16 v[34:37], v[134:137], v[182:185], v[34:37]
	v_mfma_f32_16x16x32_bf16 v[26:29], v[142:145], v[182:185], v[26:29]
	v_mfma_f32_16x16x32_bf16 v[18:21], v[134:137], v[196:199], v[18:21]
	v_mfma_f32_16x16x32_bf16 v[10:13], v[142:145], v[196:199], v[10:13]
	s_setprio 0
	s_setprio 1
	v_mfma_f32_16x16x32_bf16 v[54:57], v[146:149], v[162:165], v[54:57]
	v_mfma_f32_16x16x32_bf16 v[46:49], v[154:157], v[162:165], v[46:49]
	v_mfma_f32_16x16x32_bf16 v[38:41], v[146:149], v[170:173], v[38:41]
	v_mfma_f32_16x16x32_bf16 v[30:33], v[154:157], v[170:173], v[30:33]
	v_mfma_f32_16x16x32_bf16 v[22:25], v[146:149], v[178:181], v[22:25]
	v_mfma_f32_16x16x32_bf16 v[14:17], v[154:157], v[178:181], v[14:17]
	v_mfma_f32_16x16x32_bf16 v[6:9], v[146:149], v[186:189], v[6:9]
	v_mfma_f32_16x16x32_bf16 v[2:5], v[154:157], v[186:189], v[2:5]
	v_mfma_f32_16x16x32_bf16 v[54:57], v[150:153], v[166:169], v[54:57]
	v_mfma_f32_16x16x32_bf16 v[46:49], v[158:161], v[166:169], v[46:49]
	v_mfma_f32_16x16x32_bf16 v[38:41], v[150:153], v[174:177], v[38:41]
	v_mfma_f32_16x16x32_bf16 v[30:33], v[158:161], v[174:177], v[30:33]
	v_mfma_f32_16x16x32_bf16 v[22:25], v[150:153], v[182:185], v[22:25]
	v_mfma_f32_16x16x32_bf16 v[14:17], v[158:161], v[182:185], v[14:17]
	v_mfma_f32_16x16x32_bf16 v[6:9], v[150:153], v[196:199], v[6:9]
	v_mfma_f32_16x16x32_bf16 v[2:5], v[158:161], v[196:199], v[2:5]
	s_setprio 0
	s_barrier
	s_add_i32 s36, s36, 2
	s_add_u32 s16, s16, 0x100
	s_addc_u32 s17, s17, 0
	s_add_u32 s34, s34, 0x100
	s_addc_u32 s35, s35, 0
	s_cmp_gt_u32 s36, 29
	s_cbranch_scc1 .Lpeel_done_2
.LBB0_748:
	s_add_u32 s20, s16, 0xfff80080
	s_addc_u32 s21, s17, -1
	s_add_i32 s37, 0, 0x10000
	s_cmp_eq_u32 s36, 28
	s_cselect_b32 s23, s9, s21
	s_cselect_b32 s22, s31, s20
	s_cselect_b32 s21, s7, s35
	s_cselect_b32 s20, s33, s34
	s_add_i32 s40, 0, 0x14000
	v_add_u32_e32 v142, s37, v238
	v_add_u32_e32 v158, s40, v238
	ds_read_b128 v[130:133], v142
	ds_read_b128 v[134:137], v142 offset:1024
	ds_read_b128 v[138:141], v142 offset:2048
	ds_read_b128 v[142:145], v142 offset:3072
	ds_read_b128 v[146:149], v158
	ds_read_b128 v[150:153], v158 offset:1024
	ds_read_b128 v[154:157], v158 offset:2048
	ds_read_b128 v[158:161], v158 offset:3072
	v_lshl_add_u64 v[210:211], s[16:17], 0, v[206:207]
	s_add_i32 m0, s25, 0xc000
	ds_read_b128 v[162:165], v240
	ds_read_b128 v[166:169], v240 offset:1024
	ds_read_b128 v[170:173], v240 offset:2048
	ds_read_b128 v[174:177], v240 offset:3072
	ds_read_b128 v[178:181], v240 offset:4096
	ds_read_b128 v[182:185], v240 offset:5120
	ds_read_b128 v[186:189], v240 offset:6144
	ds_read_b128 v[196:199], v240 offset:7168
	global_load_lds_dwordx4 v[210:211], off
	v_lshl_add_u64 v[210:211], s[16:17], 0, v[208:209]
	s_add_i32 m0, s25, 0xe000
	s_nop 0
	global_load_lds_dwordx4 v[210:211], off
	s_waitcnt vmcnt(8)
	s_waitcnt lgkmcnt(0)
	s_barrier
	s_setprio 1
	v_mfma_f32_16x16x32_bf16 v[126:129], v[130:133], v[162:165], v[126:129]
	v_mfma_f32_16x16x32_bf16 v[122:125], v[138:141], v[162:165], v[122:125]
	v_mfma_f32_16x16x32_bf16 v[110:113], v[130:133], v[170:173], v[110:113]
	v_mfma_f32_16x16x32_bf16 v[106:109], v[138:141], v[170:173], v[106:109]
	v_mfma_f32_16x16x32_bf16 v[98:101], v[130:133], v[178:181], v[98:101]
	v_mfma_f32_16x16x32_bf16 v[90:93], v[138:141], v[178:181], v[90:93]
	v_mfma_f32_16x16x32_bf16 v[82:85], v[130:133], v[186:189], v[82:85]
	v_mfma_f32_16x16x32_bf16 v[74:77], v[138:141], v[186:189], v[74:77]
	v_mfma_f32_16x16x32_bf16 v[126:129], v[134:137], v[166:169], v[126:129]
	v_mfma_f32_16x16x32_bf16 v[122:125], v[142:145], v[166:169], v[122:125]
	v_mfma_f32_16x16x32_bf16 v[110:113], v[134:137], v[174:177], v[110:113]
	v_mfma_f32_16x16x32_bf16 v[106:109], v[142:145], v[174:177], v[106:109]
	v_mfma_f32_16x16x32_bf16 v[98:101], v[134:137], v[182:185], v[98:101]
	v_mfma_f32_16x16x32_bf16 v[90:93], v[142:145], v[182:185], v[90:93]
	v_mfma_f32_16x16x32_bf16 v[82:85], v[134:137], v[196:199], v[82:85]
	v_mfma_f32_16x16x32_bf16 v[74:77], v[142:145], v[196:199], v[74:77]
	s_setprio 0
	s_setprio 1
	v_mfma_f32_16x16x32_bf16 v[118:121], v[146:149], v[162:165], v[118:121]
	v_mfma_f32_16x16x32_bf16 v[114:117], v[154:157], v[162:165], v[114:117]
	v_mfma_f32_16x16x32_bf16 v[102:105], v[146:149], v[170:173], v[102:105]
	v_mfma_f32_16x16x32_bf16 v[94:97], v[154:157], v[170:173], v[94:97]
	v_mfma_f32_16x16x32_bf16 v[86:89], v[146:149], v[178:181], v[86:89]
	v_mfma_f32_16x16x32_bf16 v[78:81], v[154:157], v[178:181], v[78:81]
	v_mfma_f32_16x16x32_bf16 v[70:73], v[146:149], v[186:189], v[70:73]
	v_mfma_f32_16x16x32_bf16 v[66:69], v[154:157], v[186:189], v[66:69]
	v_mfma_f32_16x16x32_bf16 v[118:121], v[150:153], v[166:169], v[118:121]
	v_mfma_f32_16x16x32_bf16 v[114:117], v[158:161], v[166:169], v[114:117]
	v_mfma_f32_16x16x32_bf16 v[102:105], v[150:153], v[174:177], v[102:105]
	v_mfma_f32_16x16x32_bf16 v[94:97], v[158:161], v[174:177], v[94:97]
	v_mfma_f32_16x16x32_bf16 v[86:89], v[150:153], v[182:185], v[86:89]
	v_mfma_f32_16x16x32_bf16 v[78:81], v[158:161], v[182:185], v[78:81]
	v_mfma_f32_16x16x32_bf16 v[70:73], v[150:153], v[196:199], v[70:73]
	v_mfma_f32_16x16x32_bf16 v[66:69], v[158:161], v[196:199], v[66:69]
	s_setprio 0
	s_barrier
	s_add_i32 s37, s37, s24
	v_lshl_add_u64 v[210:211], s[20:21], 0, v[190:191]
	s_mov_b32 m0, s37
	ds_read_b128 v[162:165], v240 offset:16384
	ds_read_b128 v[166:169], v240 offset:17408
	ds_read_b128 v[170:173], v240 offset:18432
	ds_read_b128 v[174:177], v240 offset:19456
	ds_read_b128 v[178:181], v240 offset:20480
	ds_read_b128 v[182:185], v240 offset:21504
	ds_read_b128 v[186:189], v240 offset:22528
	ds_read_b128 v[196:199], v240 offset:23552
	global_load_lds_dwordx4 v[210:211], off
	s_add_i32 m0, s37, 0x2000
	s_add_u32 s38, s20, 0x80000
	v_lshl_add_u64 v[212:213], s[20:21], 0, v[204:205]
	s_addc_u32 s39, s21, 0
	s_add_i32 s37, s40, s24
	global_load_lds_dwordx4 v[212:213], off
	v_lshl_add_u64 v[214:215], s[38:39], 0, v[190:191]
	s_mov_b32 m0, s37
	v_lshl_add_u64 v[216:217], s[22:23], 0, v[202:203]
	global_load_lds_dwordx4 v[214:215], off
	v_lshl_add_u64 v[214:215], s[38:39], 0, v[204:205]
	s_add_i32 m0, s37, 0x2000
	s_nop 0
	global_load_lds_dwordx4 v[214:215], off
	v_lshl_add_u64 v[214:215], s[22:23], 0, v[200:201]
	s_mov_b32 m0, s25
	s_nop 0
	global_load_lds_dwordx4 v[214:215], off
	s_mov_b32 m0, s26
	s_nop 0
	global_load_lds_dwordx4 v[216:217], off
	s_waitcnt vmcnt(8)
	s_waitcnt lgkmcnt(0)
	s_barrier
	s_setprio 1
	v_mfma_f32_16x16x32_bf16 v[62:65], v[130:133], v[162:165], v[62:65]
	v_mfma_f32_16x16x32_bf16 v[58:61], v[138:141], v[162:165], v[58:61]
	v_mfma_f32_16x16x32_bf16 v[50:53], v[130:133], v[170:173], v[50:53]
	v_mfma_f32_16x16x32_bf16 v[42:45], v[138:141], v[170:173], v[42:45]
	v_mfma_f32_16x16x32_bf16 v[34:37], v[130:133], v[178:181], v[34:37]
	v_mfma_f32_16x16x32_bf16 v[26:29], v[138:141], v[178:181], v[26:29]
	v_mfma_f32_16x16x32_bf16 v[18:21], v[130:133], v[186:189], v[18:21]
	v_mfma_f32_16x16x32_bf16 v[10:13], v[138:141], v[186:189], v[10:13]
	v_mfma_f32_16x16x32_bf16 v[62:65], v[134:137], v[166:169], v[62:65]
	v_mfma_f32_16x16x32_bf16 v[58:61], v[142:145], v[166:169], v[58:61]
	v_mfma_f32_16x16x32_bf16 v[50:53], v[134:137], v[174:177], v[50:53]
	v_mfma_f32_16x16x32_bf16 v[42:45], v[142:145], v[174:177], v[42:45]
	v_mfma_f32_16x16x32_bf16 v[34:37], v[134:137], v[182:185], v[34:37]
	v_mfma_f32_16x16x32_bf16 v[26:29], v[142:145], v[182:185], v[26:29]
	v_mfma_f32_16x16x32_bf16 v[18:21], v[134:137], v[196:199], v[18:21]
	v_mfma_f32_16x16x32_bf16 v[10:13], v[142:145], v[196:199], v[10:13]
	s_setprio 0
	s_setprio 1
	v_mfma_f32_16x16x32_bf16 v[54:57], v[146:149], v[162:165], v[54:57]
	v_mfma_f32_16x16x32_bf16 v[46:49], v[154:157], v[162:165], v[46:49]
	v_mfma_f32_16x16x32_bf16 v[38:41], v[146:149], v[170:173], v[38:41]
	v_mfma_f32_16x16x32_bf16 v[30:33], v[154:157], v[170:173], v[30:33]
	v_mfma_f32_16x16x32_bf16 v[22:25], v[146:149], v[178:181], v[22:25]
	v_mfma_f32_16x16x32_bf16 v[14:17], v[154:157], v[178:181], v[14:17]
	v_mfma_f32_16x16x32_bf16 v[6:9], v[146:149], v[186:189], v[6:9]
	v_mfma_f32_16x16x32_bf16 v[2:5], v[154:157], v[186:189], v[2:5]
	v_mfma_f32_16x16x32_bf16 v[54:57], v[150:153], v[166:169], v[54:57]
	v_mfma_f32_16x16x32_bf16 v[46:49], v[158:161], v[166:169], v[46:49]
	v_mfma_f32_16x16x32_bf16 v[38:41], v[150:153], v[174:177], v[38:41]
	v_mfma_f32_16x16x32_bf16 v[30:33], v[158:161], v[174:177], v[30:33]
	v_mfma_f32_16x16x32_bf16 v[22:25], v[150:153], v[182:185], v[22:25]
	v_mfma_f32_16x16x32_bf16 v[14:17], v[158:161], v[182:185], v[14:17]
	v_mfma_f32_16x16x32_bf16 v[6:9], v[150:153], v[196:199], v[6:9]
	v_mfma_f32_16x16x32_bf16 v[2:5], v[158:161], v[196:199], v[2:5]
	s_setprio 0
	s_barrier
	s_add_i32 s37, 0, 0x18000
	s_add_i32 s38, 0, 0x1c000
	v_add_u32_e32 v142, s37, v238
	v_add_u32_e32 v158, s38, v238
	ds_read_b128 v[130:133], v142
	ds_read_b128 v[134:137], v142 offset:1024
	ds_read_b128 v[138:141], v142 offset:2048
	ds_read_b128 v[142:145], v142 offset:3072
	ds_read_b128 v[146:149], v158
	ds_read_b128 v[150:153], v158 offset:1024
	ds_read_b128 v[154:157], v158 offset:2048
	ds_read_b128 v[158:161], v158 offset:3072
	s_add_u32 s22, s22, 0x80000
	s_addc_u32 s23, s23, 0
	s_mov_b32 m0, s27
	v_lshl_add_u64 v[218:219], s[22:23], 0, v[200:201]
	ds_read_b128 v[162:165], v240 offset:32768
	ds_read_b128 v[166:169], v240 offset:33792
	ds_read_b128 v[170:173], v240 offset:34816
	ds_read_b128 v[174:177], v240 offset:35840
	ds_read_b128 v[178:181], v240 offset:36864
	ds_read_b128 v[182:185], v240 offset:37888
	ds_read_b128 v[186:189], v240 offset:38912
	ds_read_b128 v[196:199], v240 offset:39936
	global_load_lds_dwordx4 v[218:219], off
	v_lshl_add_u64 v[218:219], s[22:23], 0, v[202:203]
	s_mov_b32 m0, s28
	s_nop 0
	global_load_lds_dwordx4 v[218:219], off
	s_waitcnt vmcnt(8)
	s_waitcnt lgkmcnt(0)
	s_barrier
	s_setprio 1
	v_mfma_f32_16x16x32_bf16 v[126:129], v[130:133], v[162:165], v[126:129]
	v_mfma_f32_16x16x32_bf16 v[122:125], v[138:141], v[162:165], v[122:125]
	v_mfma_f32_16x16x32_bf16 v[110:113], v[130:133], v[170:173], v[110:113]
	v_mfma_f32_16x16x32_bf16 v[106:109], v[138:141], v[170:173], v[106:109]
	v_mfma_f32_16x16x32_bf16 v[98:101], v[130:133], v[178:181], v[98:101]
	v_mfma_f32_16x16x32_bf16 v[90:93], v[138:141], v[178:181], v[90:93]
	v_mfma_f32_16x16x32_bf16 v[82:85], v[130:133], v[186:189], v[82:85]
	v_mfma_f32_16x16x32_bf16 v[74:77], v[138:141], v[186:189], v[74:77]
	v_mfma_f32_16x16x32_bf16 v[126:129], v[134:137], v[166:169], v[126:129]
	v_mfma_f32_16x16x32_bf16 v[122:125], v[142:145], v[166:169], v[122:125]
	v_mfma_f32_16x16x32_bf16 v[110:113], v[134:137], v[174:177], v[110:113]
	v_mfma_f32_16x16x32_bf16 v[106:109], v[142:145], v[174:177], v[106:109]
	v_mfma_f32_16x16x32_bf16 v[98:101], v[134:137], v[182:185], v[98:101]
	v_mfma_f32_16x16x32_bf16 v[90:93], v[142:145], v[182:185], v[90:93]
	v_mfma_f32_16x16x32_bf16 v[82:85], v[134:137], v[196:199], v[82:85]
	v_mfma_f32_16x16x32_bf16 v[74:77], v[142:145], v[196:199], v[74:77]
	s_setprio 0
	s_setprio 1
	v_mfma_f32_16x16x32_bf16 v[118:121], v[146:149], v[162:165], v[118:121]
	v_mfma_f32_16x16x32_bf16 v[114:117], v[154:157], v[162:165], v[114:117]
	v_mfma_f32_16x16x32_bf16 v[102:105], v[146:149], v[170:173], v[102:105]
	v_mfma_f32_16x16x32_bf16 v[94:97], v[154:157], v[170:173], v[94:97]
	v_mfma_f32_16x16x32_bf16 v[86:89], v[146:149], v[178:181], v[86:89]
	v_mfma_f32_16x16x32_bf16 v[78:81], v[154:157], v[178:181], v[78:81]
	v_mfma_f32_16x16x32_bf16 v[70:73], v[146:149], v[186:189], v[70:73]
	v_mfma_f32_16x16x32_bf16 v[66:69], v[154:157], v[186:189], v[66:69]
	v_mfma_f32_16x16x32_bf16 v[118:121], v[150:153], v[166:169], v[118:121]
	v_mfma_f32_16x16x32_bf16 v[114:117], v[158:161], v[166:169], v[114:117]
	v_mfma_f32_16x16x32_bf16 v[102:105], v[150:153], v[174:177], v[102:105]
	v_mfma_f32_16x16x32_bf16 v[94:97], v[158:161], v[174:177], v[94:97]
	v_mfma_f32_16x16x32_bf16 v[86:89], v[150:153], v[182:185], v[86:89]
	v_mfma_f32_16x16x32_bf16 v[78:81], v[158:161], v[182:185], v[78:81]
	v_mfma_f32_16x16x32_bf16 v[70:73], v[150:153], v[196:199], v[70:73]
	v_mfma_f32_16x16x32_bf16 v[66:69], v[158:161], v[196:199], v[66:69]
	s_setprio 0
	s_barrier
	s_add_i32 s22, s37, s24
	v_lshl_add_u64 v[210:211], v[210:211], 0, s[58:59]
	s_mov_b32 m0, s22
	ds_read_b128 v[162:165], v240 offset:49152
	ds_read_b128 v[166:169], v240 offset:50176
	ds_read_b128 v[170:173], v240 offset:51200
	ds_read_b128 v[174:177], v240 offset:52224
	ds_read_b128 v[178:181], v240 offset:53248
	ds_read_b128 v[182:185], v240 offset:54272
	ds_read_b128 v[186:189], v240 offset:55296
	ds_read_b128 v[196:199], v240 offset:56320
	global_load_lds_dwordx4 v[210:211], off
	s_add_i32 m0, s22, 0x2000
	s_add_u32 s20, s20, 0x80080
	v_lshl_add_u64 v[210:211], v[212:213], 0, s[58:59]
	s_addc_u32 s21, s21, 0
	s_add_i32 s22, s38, s24
	global_load_lds_dwordx4 v[210:211], off
	v_lshl_add_u64 v[210:211], s[20:21], 0, v[190:191]
	s_mov_b32 m0, s22
	s_nop 0
	global_load_lds_dwordx4 v[210:211], off
	v_lshl_add_u64 v[210:211], s[20:21], 0, v[204:205]
	s_add_i32 m0, s22, 0x2000
	s_nop 0
	global_load_lds_dwordx4 v[210:211], off
	v_lshl_add_u64 v[210:211], v[214:215], 0, s[58:59]
	s_mov_b32 m0, s29
	s_nop 0
	global_load_lds_dwordx4 v[210:211], off
	v_lshl_add_u64 v[210:211], v[216:217], 0, s[58:59]
	s_mov_b32 m0, s30
	s_nop 0
	global_load_lds_dwordx4 v[210:211], off
	s_waitcnt vmcnt(8)
	s_waitcnt lgkmcnt(0)
	s_barrier
	s_setprio 1
	v_mfma_f32_16x16x32_bf16 v[62:65], v[130:133], v[162:165], v[62:65]
	v_mfma_f32_16x16x32_bf16 v[58:61], v[138:141], v[162:165], v[58:61]
	v_mfma_f32_16x16x32_bf16 v[50:53], v[130:133], v[170:173], v[50:53]
	v_mfma_f32_16x16x32_bf16 v[42:45], v[138:141], v[170:173], v[42:45]
	v_mfma_f32_16x16x32_bf16 v[34:37], v[130:133], v[178:181], v[34:37]
	v_mfma_f32_16x16x32_bf16 v[26:29], v[138:141], v[178:181], v[26:29]
	v_mfma_f32_16x16x32_bf16 v[18:21], v[130:133], v[186:189], v[18:21]
	v_mfma_f32_16x16x32_bf16 v[10:13], v[138:141], v[186:189], v[10:13]
	v_mfma_f32_16x16x32_bf16 v[62:65], v[134:137], v[166:169], v[62:65]
	v_mfma_f32_16x16x32_bf16 v[58:61], v[142:145], v[166:169], v[58:61]
	v_mfma_f32_16x16x32_bf16 v[50:53], v[134:137], v[174:177], v[50:53]
	v_mfma_f32_16x16x32_bf16 v[42:45], v[142:145], v[174:177], v[42:45]
	v_mfma_f32_16x16x32_bf16 v[34:37], v[134:137], v[182:185], v[34:37]
	v_mfma_f32_16x16x32_bf16 v[26:29], v[142:145], v[182:185], v[26:29]
	v_mfma_f32_16x16x32_bf16 v[18:21], v[134:137], v[196:199], v[18:21]
	v_mfma_f32_16x16x32_bf16 v[10:13], v[142:145], v[196:199], v[10:13]
	s_setprio 0
	s_setprio 1
	v_mfma_f32_16x16x32_bf16 v[54:57], v[146:149], v[162:165], v[54:57]
	v_mfma_f32_16x16x32_bf16 v[46:49], v[154:157], v[162:165], v[46:49]
	v_mfma_f32_16x16x32_bf16 v[38:41], v[146:149], v[170:173], v[38:41]
	v_mfma_f32_16x16x32_bf16 v[30:33], v[154:157], v[170:173], v[30:33]
	v_mfma_f32_16x16x32_bf16 v[22:25], v[146:149], v[178:181], v[22:25]
	v_mfma_f32_16x16x32_bf16 v[14:17], v[154:157], v[178:181], v[14:17]
	v_mfma_f32_16x16x32_bf16 v[6:9], v[146:149], v[186:189], v[6:9]
	v_mfma_f32_16x16x32_bf16 v[2:5], v[154:157], v[186:189], v[2:5]
	v_mfma_f32_16x16x32_bf16 v[54:57], v[150:153], v[166:169], v[54:57]
	v_mfma_f32_16x16x32_bf16 v[46:49], v[158:161], v[166:169], v[46:49]
	v_mfma_f32_16x16x32_bf16 v[38:41], v[150:153], v[174:177], v[38:41]
	v_mfma_f32_16x16x32_bf16 v[30:33], v[158:161], v[174:177], v[30:33]
	v_mfma_f32_16x16x32_bf16 v[22:25], v[150:153], v[182:185], v[22:25]
	v_mfma_f32_16x16x32_bf16 v[14:17], v[158:161], v[182:185], v[14:17]
	v_mfma_f32_16x16x32_bf16 v[6:9], v[150:153], v[196:199], v[6:9]
	v_mfma_f32_16x16x32_bf16 v[2:5], v[158:161], v[196:199], v[2:5]
	s_setprio 0
	s_barrier
	s_add_i32 s36, s36, 2
	s_add_u32 s16, s16, 0x100
	s_addc_u32 s17, s17, 0
	s_add_u32 s34, s34, 0x100
	s_addc_u32 s35, s35, 0
	s_cmp_gt_u32 s36, 29
	s_cbranch_scc0 .LBB0_748

.LBB0_771:
	s_ashr_i32 s17, s16, 31
	s_lshl_b64 s[20:21], s[16:17], 20
	v_readlane_b32 s0, v254, 60
	s_add_u32 s20, s0, s20
	v_readlane_b32 s0, v254, 61
	s_addc_u32 s21, s0, s21
	s_and_b64 s[22:23], s[6:7], exec
	s_cselect_b32 s17, s21, s27
	s_cselect_b32 s40, s20, s26
	s_ashr_i32 s15, s14, 31
	s_lshl_b64 s[22:23], s[14:15], 20
	v_readlane_b32 s0, v254, 40
	v_readlane_b32 s1, v254, 41
	s_add_u32 s22, s0, s22
	s_addc_u32 s23, s1, s23
	s_and_b64 s[30:31], s[6:7], exec
	s_cselect_b32 s15, s23, s29
	s_cselect_b32 s41, s22, s28
	s_add_u32 s26, s26, 0x80080
	s_addc_u32 s27, s27, 0
	s_add_u32 s42, s28, 0x100
	s_addc_u32 s43, s29, 0
	s_mov_b32 s46, -2
	v_readlane_b32 s47, v255, 49
	s_nop 3
	s_cmp_eq_u32 s47, 4
	v_writelane_b32 v255, 4, 49
	s_cbranch_scc0 .Ltrip0_strict_3
	s_add_u32 s28, s26, 0xfff80080
	s_addc_u32 s29, s27, -1
	s_add_i32 s47, 0, 0x10000
	s_cmp_eq_u32 s46, 28
	s_cselect_b32 s31, s17, s29
	s_cselect_b32 s30, s40, s28
	s_cselect_b32 s29, s15, s43
	s_cselect_b32 s28, s41, s42
	s_add_i32 s55, 0, 0x14000
	v_add_u32_e32 v142, s47, v220
	v_add_u32_e32 v158, s55, v220
	ds_read_b128 v[130:133], v142
	ds_read_b128 v[134:137], v142 offset:1024
	ds_read_b128 v[138:141], v142 offset:2048
	ds_read_b128 v[142:145], v142 offset:3072
	ds_read_b128 v[146:149], v158
	ds_read_b128 v[150:153], v158 offset:1024
	ds_read_b128 v[154:157], v158 offset:2048
	ds_read_b128 v[158:161], v158 offset:3072
	v_lshl_add_u64 v[210:211], s[26:27], 0, v[202:203]
	s_add_i32 m0, s34, 0xc000
	ds_read_b128 v[162:165], v222
	ds_read_b128 v[166:169], v222 offset:1024
	ds_read_b128 v[170:173], v222 offset:2048
	ds_read_b128 v[174:177], v222 offset:3072
	ds_read_b128 v[178:181], v222 offset:4096
	ds_read_b128 v[182:185], v222 offset:5120
	ds_read_b128 v[196:199], v222 offset:6144
	ds_read_b128 v[206:209], v222 offset:7168
	global_load_lds_dwordx4 v[210:211], off
	v_lshl_add_u64 v[210:211], s[26:27], 0, v[204:205]
	s_add_i32 m0, s34, 0xe000
	s_nop 0
	global_load_lds_dwordx4 v[210:211], off
	s_waitcnt vmcnt(24)
	s_waitcnt lgkmcnt(0)
	s_barrier
	s_setprio 1
	v_mfma_f32_16x16x32_bf16 v[126:129], v[130:133], v[162:165], 0
	v_mfma_f32_16x16x32_bf16 v[122:125], v[138:141], v[162:165], 0
	v_mfma_f32_16x16x32_bf16 v[110:113], v[130:133], v[170:173], 0
	v_mfma_f32_16x16x32_bf16 v[106:109], v[138:141], v[170:173], 0
	v_mfma_f32_16x16x32_bf16 v[94:97], v[130:133], v[178:181], 0
	v_mfma_f32_16x16x32_bf16 v[90:93], v[138:141], v[178:181], 0
	v_mfma_f32_16x16x32_bf16 v[78:81], v[130:133], v[196:199], 0
	v_mfma_f32_16x16x32_bf16 v[74:77], v[138:141], v[196:199], 0
	v_mfma_f32_16x16x32_bf16 v[126:129], v[134:137], v[166:169], v[126:129]
	v_mfma_f32_16x16x32_bf16 v[122:125], v[142:145], v[166:169], v[122:125]
	v_mfma_f32_16x16x32_bf16 v[110:113], v[134:137], v[174:177], v[110:113]
	v_mfma_f32_16x16x32_bf16 v[106:109], v[142:145], v[174:177], v[106:109]
	v_mfma_f32_16x16x32_bf16 v[94:97], v[134:137], v[182:185], v[94:97]
	v_mfma_f32_16x16x32_bf16 v[90:93], v[142:145], v[182:185], v[90:93]
	v_mfma_f32_16x16x32_bf16 v[78:81], v[134:137], v[206:209], v[78:81]
	v_mfma_f32_16x16x32_bf16 v[74:77], v[142:145], v[206:209], v[74:77]
	s_setprio 0
	s_setprio 1
	v_mfma_f32_16x16x32_bf16 v[118:121], v[146:149], v[162:165], 0
	v_mfma_f32_16x16x32_bf16 v[114:117], v[154:157], v[162:165], 0
	v_mfma_f32_16x16x32_bf16 v[102:105], v[146:149], v[170:173], 0
	v_mfma_f32_16x16x32_bf16 v[98:101], v[154:157], v[170:173], 0
	v_mfma_f32_16x16x32_bf16 v[86:89], v[146:149], v[178:181], 0
	v_mfma_f32_16x16x32_bf16 v[82:85], v[154:157], v[178:181], 0
	v_mfma_f32_16x16x32_bf16 v[70:73], v[146:149], v[196:199], 0
	v_mfma_f32_16x16x32_bf16 v[66:69], v[154:157], v[196:199], 0
	v_mfma_f32_16x16x32_bf16 v[118:121], v[150:153], v[166:169], v[118:121]
	v_mfma_f32_16x16x32_bf16 v[114:117], v[158:161], v[166:169], v[114:117]
	v_mfma_f32_16x16x32_bf16 v[102:105], v[150:153], v[174:177], v[102:105]
	v_mfma_f32_16x16x32_bf16 v[98:101], v[158:161], v[174:177], v[98:101]
	v_mfma_f32_16x16x32_bf16 v[86:89], v[150:153], v[182:185], v[86:89]
	v_mfma_f32_16x16x32_bf16 v[82:85], v[158:161], v[182:185], v[82:85]
	v_mfma_f32_16x16x32_bf16 v[70:73], v[150:153], v[206:209], v[70:73]
	v_mfma_f32_16x16x32_bf16 v[66:69], v[158:161], v[206:209], v[66:69]
	s_setprio 0
	s_barrier
	s_add_i32 s47, s47, s33
	v_lshl_add_u64 v[210:211], s[28:29], 0, v[190:191]
	s_mov_b32 m0, s47
	ds_read_b128 v[162:165], v222 offset:16384
	ds_read_b128 v[166:169], v222 offset:17408
	ds_read_b128 v[170:173], v222 offset:18432
	ds_read_b128 v[174:177], v222 offset:19456
	ds_read_b128 v[178:181], v222 offset:20480
	ds_read_b128 v[182:185], v222 offset:21504
	ds_read_b128 v[196:199], v222 offset:22528
	ds_read_b128 v[206:209], v222 offset:23552
	global_load_lds_dwordx4 v[210:211], off
	s_add_i32 m0, s47, 0x2000
	s_add_u32 s52, s28, 0x80000
	v_lshl_add_u64 v[212:213], s[28:29], 0, v[200:201]
	s_addc_u32 s53, s29, 0
	s_add_i32 s47, s55, s33
	global_load_lds_dwordx4 v[212:213], off
	v_lshl_add_u64 v[214:215], s[52:53], 0, v[190:191]
	s_mov_b32 m0, s47
	v_lshl_add_u64 v[216:217], s[30:31], 0, v[188:189]
	global_load_lds_dwordx4 v[214:215], off
	v_lshl_add_u64 v[214:215], s[52:53], 0, v[200:201]
	s_add_i32 m0, s47, 0x2000
	s_nop 0
	global_load_lds_dwordx4 v[214:215], off
	v_lshl_add_u64 v[214:215], s[30:31], 0, v[186:187]
	s_mov_b32 m0, s34
	s_nop 0
	global_load_lds_dwordx4 v[214:215], off
	s_mov_b32 m0, s35
	s_nop 0
	global_load_lds_dwordx4 v[216:217], off
	s_waitcnt vmcnt(24)
	s_waitcnt lgkmcnt(0)
	s_barrier
	s_setprio 1
	v_mfma_f32_16x16x32_bf16 v[62:65], v[130:133], v[162:165], 0
	v_mfma_f32_16x16x32_bf16 v[58:61], v[138:141], v[162:165], 0
	v_mfma_f32_16x16x32_bf16 v[46:49], v[130:133], v[170:173], 0
	v_mfma_f32_16x16x32_bf16 v[42:45], v[138:141], v[170:173], 0
	v_mfma_f32_16x16x32_bf16 v[30:33], v[130:133], v[178:181], 0
	v_mfma_f32_16x16x32_bf16 v[26:29], v[138:141], v[178:181], 0
	v_mfma_f32_16x16x32_bf16 v[14:17], v[130:133], v[196:199], 0
	v_mfma_f32_16x16x32_bf16 v[10:13], v[138:141], v[196:199], 0
	v_mfma_f32_16x16x32_bf16 v[62:65], v[134:137], v[166:169], v[62:65]
	v_mfma_f32_16x16x32_bf16 v[58:61], v[142:145], v[166:169], v[58:61]
	v_mfma_f32_16x16x32_bf16 v[46:49], v[134:137], v[174:177], v[46:49]
	v_mfma_f32_16x16x32_bf16 v[42:45], v[142:145], v[174:177], v[42:45]
	v_mfma_f32_16x16x32_bf16 v[30:33], v[134:137], v[182:185], v[30:33]
	v_mfma_f32_16x16x32_bf16 v[26:29], v[142:145], v[182:185], v[26:29]
	v_mfma_f32_16x16x32_bf16 v[14:17], v[134:137], v[206:209], v[14:17]
	v_mfma_f32_16x16x32_bf16 v[10:13], v[142:145], v[206:209], v[10:13]
	s_setprio 0
	s_setprio 1
	v_mfma_f32_16x16x32_bf16 v[54:57], v[146:149], v[162:165], 0
	v_mfma_f32_16x16x32_bf16 v[50:53], v[154:157], v[162:165], 0
	v_mfma_f32_16x16x32_bf16 v[38:41], v[146:149], v[170:173], 0
	v_mfma_f32_16x16x32_bf16 v[34:37], v[154:157], v[170:173], 0
	v_mfma_f32_16x16x32_bf16 v[22:25], v[146:149], v[178:181], 0
	v_mfma_f32_16x16x32_bf16 v[18:21], v[154:157], v[178:181], 0
	v_mfma_f32_16x16x32_bf16 v[6:9], v[146:149], v[196:199], 0
	v_mfma_f32_16x16x32_bf16 v[2:5], v[154:157], v[196:199], 0
	v_mfma_f32_16x16x32_bf16 v[54:57], v[150:153], v[166:169], v[54:57]
	v_mfma_f32_16x16x32_bf16 v[50:53], v[158:161], v[166:169], v[50:53]
	v_mfma_f32_16x16x32_bf16 v[38:41], v[150:153], v[174:177], v[38:41]
	v_mfma_f32_16x16x32_bf16 v[34:37], v[158:161], v[174:177], v[34:37]
	v_mfma_f32_16x16x32_bf16 v[22:25], v[150:153], v[182:185], v[22:25]
	v_mfma_f32_16x16x32_bf16 v[18:21], v[158:161], v[182:185], v[18:21]
	v_mfma_f32_16x16x32_bf16 v[6:9], v[150:153], v[206:209], v[6:9]
	v_mfma_f32_16x16x32_bf16 v[2:5], v[158:161], v[206:209], v[2:5]
	s_setprio 0
	s_barrier
	s_add_i32 s47, 0, 0x18000
	s_add_i32 s52, 0, 0x1c000
	v_add_u32_e32 v142, s47, v220
	v_add_u32_e32 v158, s52, v220
	ds_read_b128 v[130:133], v142
	ds_read_b128 v[134:137], v142 offset:1024
	ds_read_b128 v[138:141], v142 offset:2048
	ds_read_b128 v[142:145], v142 offset:3072
	ds_read_b128 v[146:149], v158
	ds_read_b128 v[150:153], v158 offset:1024
	ds_read_b128 v[154:157], v158 offset:2048
	ds_read_b128 v[158:161], v158 offset:3072
	s_add_u32 s30, s30, 0x80000
	s_addc_u32 s31, s31, 0
	s_mov_b32 m0, s36
	v_lshl_add_u64 v[218:219], s[30:31], 0, v[186:187]
	ds_read_b128 v[162:165], v222 offset:32768
	ds_read_b128 v[166:169], v222 offset:33792
	ds_read_b128 v[170:173], v222 offset:34816
	ds_read_b128 v[174:177], v222 offset:35840
	ds_read_b128 v[178:181], v222 offset:36864
	ds_read_b128 v[182:185], v222 offset:37888
	ds_read_b128 v[196:199], v222 offset:38912
	ds_read_b128 v[206:209], v222 offset:39936
	global_load_lds_dwordx4 v[218:219], off
	v_lshl_add_u64 v[218:219], s[30:31], 0, v[188:189]
	s_mov_b32 m0, s37
	s_nop 0
	global_load_lds_dwordx4 v[218:219], off
	s_waitcnt vmcnt(8)
	s_waitcnt lgkmcnt(0)
	s_barrier
	s_setprio 1
	v_mfma_f32_16x16x32_bf16 v[126:129], v[130:133], v[162:165], v[126:129]
	v_mfma_f32_16x16x32_bf16 v[122:125], v[138:141], v[162:165], v[122:125]
	v_mfma_f32_16x16x32_bf16 v[110:113], v[130:133], v[170:173], v[110:113]
	v_mfma_f32_16x16x32_bf16 v[106:109], v[138:141], v[170:173], v[106:109]
	v_mfma_f32_16x16x32_bf16 v[94:97], v[130:133], v[178:181], v[94:97]
	v_mfma_f32_16x16x32_bf16 v[90:93], v[138:141], v[178:181], v[90:93]
	v_mfma_f32_16x16x32_bf16 v[78:81], v[130:133], v[196:199], v[78:81]
	v_mfma_f32_16x16x32_bf16 v[74:77], v[138:141], v[196:199], v[74:77]
	v_mfma_f32_16x16x32_bf16 v[126:129], v[134:137], v[166:169], v[126:129]
	v_mfma_f32_16x16x32_bf16 v[122:125], v[142:145], v[166:169], v[122:125]
	v_mfma_f32_16x16x32_bf16 v[110:113], v[134:137], v[174:177], v[110:113]
	v_mfma_f32_16x16x32_bf16 v[106:109], v[142:145], v[174:177], v[106:109]
	v_mfma_f32_16x16x32_bf16 v[94:97], v[134:137], v[182:185], v[94:97]
	v_mfma_f32_16x16x32_bf16 v[90:93], v[142:145], v[182:185], v[90:93]
	v_mfma_f32_16x16x32_bf16 v[78:81], v[134:137], v[206:209], v[78:81]
	v_mfma_f32_16x16x32_bf16 v[74:77], v[142:145], v[206:209], v[74:77]
	s_setprio 0
	s_setprio 1
	v_mfma_f32_16x16x32_bf16 v[118:121], v[146:149], v[162:165], v[118:121]
	v_mfma_f32_16x16x32_bf16 v[114:117], v[154:157], v[162:165], v[114:117]
	v_mfma_f32_16x16x32_bf16 v[102:105], v[146:149], v[170:173], v[102:105]
	v_mfma_f32_16x16x32_bf16 v[98:101], v[154:157], v[170:173], v[98:101]
	v_mfma_f32_16x16x32_bf16 v[86:89], v[146:149], v[178:181], v[86:89]
	v_mfma_f32_16x16x32_bf16 v[82:85], v[154:157], v[178:181], v[82:85]
	v_mfma_f32_16x16x32_bf16 v[70:73], v[146:149], v[196:199], v[70:73]
	v_mfma_f32_16x16x32_bf16 v[66:69], v[154:157], v[196:199], v[66:69]
	v_mfma_f32_16x16x32_bf16 v[118:121], v[150:153], v[166:169], v[118:121]
	v_mfma_f32_16x16x32_bf16 v[114:117], v[158:161], v[166:169], v[114:117]
	v_mfma_f32_16x16x32_bf16 v[102:105], v[150:153], v[174:177], v[102:105]
	v_mfma_f32_16x16x32_bf16 v[98:101], v[158:161], v[174:177], v[98:101]
	v_mfma_f32_16x16x32_bf16 v[86:89], v[150:153], v[182:185], v[86:89]
	v_mfma_f32_16x16x32_bf16 v[82:85], v[158:161], v[182:185], v[82:85]
	v_mfma_f32_16x16x32_bf16 v[70:73], v[150:153], v[206:209], v[70:73]
	v_mfma_f32_16x16x32_bf16 v[66:69], v[158:161], v[206:209], v[66:69]
	s_setprio 0
	s_barrier
	s_add_i32 s30, s47, s33
	v_lshl_add_u64 v[210:211], v[210:211], 0, s[58:59]
	s_mov_b32 m0, s30
	ds_read_b128 v[162:165], v222 offset:49152
	ds_read_b128 v[166:169], v222 offset:50176
	ds_read_b128 v[170:173], v222 offset:51200
	ds_read_b128 v[174:177], v222 offset:52224
	ds_read_b128 v[178:181], v222 offset:53248
	ds_read_b128 v[182:185], v222 offset:54272
	ds_read_b128 v[196:199], v222 offset:55296
	ds_read_b128 v[206:209], v222 offset:56320
	global_load_lds_dwordx4 v[210:211], off
	s_add_i32 m0, s30, 0x2000
	s_add_u32 s28, s28, 0x80080
	v_lshl_add_u64 v[210:211], v[212:213], 0, s[58:59]
	s_addc_u32 s29, s29, 0
	s_add_i32 s30, s52, s33
	global_load_lds_dwordx4 v[210:211], off
	v_lshl_add_u64 v[210:211], s[28:29], 0, v[190:191]
	s_mov_b32 m0, s30
	s_nop 0
	global_load_lds_dwordx4 v[210:211], off
	v_lshl_add_u64 v[210:211], s[28:29], 0, v[200:201]
	s_add_i32 m0, s30, 0x2000
	s_nop 0
	global_load_lds_dwordx4 v[210:211], off
	v_lshl_add_u64 v[210:211], v[214:215], 0, s[58:59]
	s_mov_b32 m0, s38
	s_nop 0
	global_load_lds_dwordx4 v[210:211], off
	v_lshl_add_u64 v[210:211], v[216:217], 0, s[58:59]
	s_mov_b32 m0, s39
	s_nop 0
	global_load_lds_dwordx4 v[210:211], off
	s_waitcnt vmcnt(8)
	s_waitcnt lgkmcnt(0)
	s_barrier
	s_setprio 1
	v_mfma_f32_16x16x32_bf16 v[62:65], v[130:133], v[162:165], v[62:65]
	v_mfma_f32_16x16x32_bf16 v[58:61], v[138:141], v[162:165], v[58:61]
	v_mfma_f32_16x16x32_bf16 v[46:49], v[130:133], v[170:173], v[46:49]
	v_mfma_f32_16x16x32_bf16 v[42:45], v[138:141], v[170:173], v[42:45]
	v_mfma_f32_16x16x32_bf16 v[30:33], v[130:133], v[178:181], v[30:33]
	v_mfma_f32_16x16x32_bf16 v[26:29], v[138:141], v[178:181], v[26:29]
	v_mfma_f32_16x16x32_bf16 v[14:17], v[130:133], v[196:199], v[14:17]
	v_mfma_f32_16x16x32_bf16 v[10:13], v[138:141], v[196:199], v[10:13]
	v_mfma_f32_16x16x32_bf16 v[62:65], v[134:137], v[166:169], v[62:65]
	v_mfma_f32_16x16x32_bf16 v[58:61], v[142:145], v[166:169], v[58:61]
	v_mfma_f32_16x16x32_bf16 v[46:49], v[134:137], v[174:177], v[46:49]
	v_mfma_f32_16x16x32_bf16 v[42:45], v[142:145], v[174:177], v[42:45]
	v_mfma_f32_16x16x32_bf16 v[30:33], v[134:137], v[182:185], v[30:33]
	v_mfma_f32_16x16x32_bf16 v[26:29], v[142:145], v[182:185], v[26:29]
	v_mfma_f32_16x16x32_bf16 v[14:17], v[134:137], v[206:209], v[14:17]
	v_mfma_f32_16x16x32_bf16 v[10:13], v[142:145], v[206:209], v[10:13]
	s_setprio 0
	s_setprio 1
	v_mfma_f32_16x16x32_bf16 v[54:57], v[146:149], v[162:165], v[54:57]
	v_mfma_f32_16x16x32_bf16 v[50:53], v[154:157], v[162:165], v[50:53]
	v_mfma_f32_16x16x32_bf16 v[38:41], v[146:149], v[170:173], v[38:41]
	v_mfma_f32_16x16x32_bf16 v[34:37], v[154:157], v[170:173], v[34:37]
	v_mfma_f32_16x16x32_bf16 v[22:25], v[146:149], v[178:181], v[22:25]
	v_mfma_f32_16x16x32_bf16 v[18:21], v[154:157], v[178:181], v[18:21]
	v_mfma_f32_16x16x32_bf16 v[6:9], v[146:149], v[196:199], v[6:9]
	v_mfma_f32_16x16x32_bf16 v[2:5], v[154:157], v[196:199], v[2:5]
	v_mfma_f32_16x16x32_bf16 v[54:57], v[150:153], v[166:169], v[54:57]
	v_mfma_f32_16x16x32_bf16 v[50:53], v[158:161], v[166:169], v[50:53]
	v_mfma_f32_16x16x32_bf16 v[38:41], v[150:153], v[174:177], v[38:41]
	v_mfma_f32_16x16x32_bf16 v[34:37], v[158:161], v[174:177], v[34:37]
	v_mfma_f32_16x16x32_bf16 v[22:25], v[150:153], v[182:185], v[22:25]
	v_mfma_f32_16x16x32_bf16 v[18:21], v[158:161], v[182:185], v[18:21]
	v_mfma_f32_16x16x32_bf16 v[6:9], v[150:153], v[206:209], v[6:9]
	v_mfma_f32_16x16x32_bf16 v[2:5], v[158:161], v[206:209], v[2:5]
	s_setprio 0
	s_barrier
	s_add_i32 s46, s46, 2
	s_add_u32 s26, s26, 0x100
	s_addc_u32 s27, s27, 0
	s_add_u32 s42, s42, 0x100
	s_addc_u32 s43, s43, 0
	s_cmp_gt_u32 s46, 29
	s_cbranch_scc1 .Lpeel_done_3
	s_branch .LBB0_772
.Ltrip0_strict_3:
	s_add_u32 s28, s26, 0xfff80080
	s_addc_u32 s29, s27, -1
	s_add_i32 s47, 0, 0x10000
	s_cmp_eq_u32 s46, 28
	s_cselect_b32 s31, s17, s29
	s_cselect_b32 s30, s40, s28
	s_cselect_b32 s29, s15, s43
	s_cselect_b32 s28, s41, s42
	s_add_i32 s55, 0, 0x14000
	v_add_u32_e32 v142, s47, v220
	v_add_u32_e32 v158, s55, v220
	ds_read_b128 v[130:133], v142
	ds_read_b128 v[134:137], v142 offset:1024
	ds_read_b128 v[138:141], v142 offset:2048
	ds_read_b128 v[142:145], v142 offset:3072
	ds_read_b128 v[146:149], v158
	ds_read_b128 v[150:153], v158 offset:1024
	ds_read_b128 v[154:157], v158 offset:2048
	ds_read_b128 v[158:161], v158 offset:3072
	v_lshl_add_u64 v[210:211], s[26:27], 0, v[202:203]
	s_add_i32 m0, s34, 0xc000
	ds_read_b128 v[162:165], v222
	ds_read_b128 v[166:169], v222 offset:1024
	ds_read_b128 v[170:173], v222 offset:2048
	ds_read_b128 v[174:177], v222 offset:3072
	ds_read_b128 v[178:181], v222 offset:4096
	ds_read_b128 v[182:185], v222 offset:5120
	ds_read_b128 v[196:199], v222 offset:6144
	ds_read_b128 v[206:209], v222 offset:7168
	global_load_lds_dwordx4 v[210:211], off
	v_lshl_add_u64 v[210:211], s[26:27], 0, v[204:205]
	s_add_i32 m0, s34, 0xe000
	s_nop 0
	global_load_lds_dwordx4 v[210:211], off
	s_waitcnt vmcnt(8)
	s_waitcnt lgkmcnt(0)
	s_barrier
	s_setprio 1
	v_mfma_f32_16x16x32_bf16 v[126:129], v[130:133], v[162:165], 0
	v_mfma_f32_16x16x32_bf16 v[122:125], v[138:141], v[162:165], 0
	v_mfma_f32_16x16x32_bf16 v[110:113], v[130:133], v[170:173], 0
	v_mfma_f32_16x16x32_bf16 v[106:109], v[138:141], v[170:173], 0
	v_mfma_f32_16x16x32_bf16 v[94:97], v[130:133], v[178:181], 0
	v_mfma_f32_16x16x32_bf16 v[90:93], v[138:141], v[178:181], 0
	v_mfma_f32_16x16x32_bf16 v[78:81], v[130:133], v[196:199], 0
	v_mfma_f32_16x16x32_bf16 v[74:77], v[138:141], v[196:199], 0
	v_mfma_f32_16x16x32_bf16 v[126:129], v[134:137], v[166:169], v[126:129]
	v_mfma_f32_16x16x32_bf16 v[122:125], v[142:145], v[166:169], v[122:125]
	v_mfma_f32_16x16x32_bf16 v[110:113], v[134:137], v[174:177], v[110:113]
	v_mfma_f32_16x16x32_bf16 v[106:109], v[142:145], v[174:177], v[106:109]
	v_mfma_f32_16x16x32_bf16 v[94:97], v[134:137], v[182:185], v[94:97]
	v_mfma_f32_16x16x32_bf16 v[90:93], v[142:145], v[182:185], v[90:93]
	v_mfma_f32_16x16x32_bf16 v[78:81], v[134:137], v[206:209], v[78:81]
	v_mfma_f32_16x16x32_bf16 v[74:77], v[142:145], v[206:209], v[74:77]
	s_setprio 0
	s_setprio 1
	v_mfma_f32_16x16x32_bf16 v[118:121], v[146:149], v[162:165], 0
	v_mfma_f32_16x16x32_bf16 v[114:117], v[154:157], v[162:165], 0
	v_mfma_f32_16x16x32_bf16 v[102:105], v[146:149], v[170:173], 0
	v_mfma_f32_16x16x32_bf16 v[98:101], v[154:157], v[170:173], 0
	v_mfma_f32_16x16x32_bf16 v[86:89], v[146:149], v[178:181], 0
	v_mfma_f32_16x16x32_bf16 v[82:85], v[154:157], v[178:181], 0
	v_mfma_f32_16x16x32_bf16 v[70:73], v[146:149], v[196:199], 0
	v_mfma_f32_16x16x32_bf16 v[66:69], v[154:157], v[196:199], 0
	v_mfma_f32_16x16x32_bf16 v[118:121], v[150:153], v[166:169], v[118:121]
	v_mfma_f32_16x16x32_bf16 v[114:117], v[158:161], v[166:169], v[114:117]
	v_mfma_f32_16x16x32_bf16 v[102:105], v[150:153], v[174:177], v[102:105]
	v_mfma_f32_16x16x32_bf16 v[98:101], v[158:161], v[174:177], v[98:101]
	v_mfma_f32_16x16x32_bf16 v[86:89], v[150:153], v[182:185], v[86:89]
	v_mfma_f32_16x16x32_bf16 v[82:85], v[158:161], v[182:185], v[82:85]
	v_mfma_f32_16x16x32_bf16 v[70:73], v[150:153], v[206:209], v[70:73]
	v_mfma_f32_16x16x32_bf16 v[66:69], v[158:161], v[206:209], v[66:69]
	s_setprio 0
	s_barrier
	s_add_i32 s47, s47, s33
	v_lshl_add_u64 v[210:211], s[28:29], 0, v[190:191]
	s_mov_b32 m0, s47
	ds_read_b128 v[162:165], v222 offset:16384
	ds_read_b128 v[166:169], v222 offset:17408
	ds_read_b128 v[170:173], v222 offset:18432
	ds_read_b128 v[174:177], v222 offset:19456
	ds_read_b128 v[178:181], v222 offset:20480
	ds_read_b128 v[182:185], v222 offset:21504
	ds_read_b128 v[196:199], v222 offset:22528
	ds_read_b128 v[206:209], v222 offset:23552
	global_load_lds_dwordx4 v[210:211], off
	s_add_i32 m0, s47, 0x2000
	s_add_u32 s52, s28, 0x80000
	v_lshl_add_u64 v[212:213], s[28:29], 0, v[200:201]
	s_addc_u32 s53, s29, 0
	s_add_i32 s47, s55, s33
	global_load_lds_dwordx4 v[212:213], off
	v_lshl_add_u64 v[214:215], s[52:53], 0, v[190:191]
	s_mov_b32 m0, s47
	v_lshl_add_u64 v[216:217], s[30:31], 0, v[188:189]
	global_load_lds_dwordx4 v[214:215], off
	v_lshl_add_u64 v[214:215], s[52:53], 0, v[200:201]
	s_add_i32 m0, s47, 0x2000
	s_nop 0
	global_load_lds_dwordx4 v[214:215], off
	v_lshl_add_u64 v[214:215], s[30:31], 0, v[186:187]
	s_mov_b32 m0, s34
	s_nop 0
	global_load_lds_dwordx4 v[214:215], off
	s_mov_b32 m0, s35
	s_nop 0
	global_load_lds_dwordx4 v[216:217], off
	s_waitcnt vmcnt(8)
	s_waitcnt lgkmcnt(0)
	s_barrier
	s_setprio 1
	v_mfma_f32_16x16x32_bf16 v[62:65], v[130:133], v[162:165], 0
	v_mfma_f32_16x16x32_bf16 v[58:61], v[138:141], v[162:165], 0
	v_mfma_f32_16x16x32_bf16 v[46:49], v[130:133], v[170:173], 0
	v_mfma_f32_16x16x32_bf16 v[42:45], v[138:141], v[170:173], 0
	v_mfma_f32_16x16x32_bf16 v[30:33], v[130:133], v[178:181], 0
	v_mfma_f32_16x16x32_bf16 v[26:29], v[138:141], v[178:181], 0
	v_mfma_f32_16x16x32_bf16 v[14:17], v[130:133], v[196:199], 0
	v_mfma_f32_16x16x32_bf16 v[10:13], v[138:141], v[196:199], 0
	v_mfma_f32_16x16x32_bf16 v[62:65], v[134:137], v[166:169], v[62:65]
	v_mfma_f32_16x16x32_bf16 v[58:61], v[142:145], v[166:169], v[58:61]
	v_mfma_f32_16x16x32_bf16 v[46:49], v[134:137], v[174:177], v[46:49]
	v_mfma_f32_16x16x32_bf16 v[42:45], v[142:145], v[174:177], v[42:45]
	v_mfma_f32_16x16x32_bf16 v[30:33], v[134:137], v[182:185], v[30:33]
	v_mfma_f32_16x16x32_bf16 v[26:29], v[142:145], v[182:185], v[26:29]
	v_mfma_f32_16x16x32_bf16 v[14:17], v[134:137], v[206:209], v[14:17]
	v_mfma_f32_16x16x32_bf16 v[10:13], v[142:145], v[206:209], v[10:13]
	s_setprio 0
	s_setprio 1
	v_mfma_f32_16x16x32_bf16 v[54:57], v[146:149], v[162:165], 0
	v_mfma_f32_16x16x32_bf16 v[50:53], v[154:157], v[162:165], 0
	v_mfma_f32_16x16x32_bf16 v[38:41], v[146:149], v[170:173], 0
	v_mfma_f32_16x16x32_bf16 v[34:37], v[154:157], v[170:173], 0
	v_mfma_f32_16x16x32_bf16 v[22:25], v[146:149], v[178:181], 0
	v_mfma_f32_16x16x32_bf16 v[18:21], v[154:157], v[178:181], 0
	v_mfma_f32_16x16x32_bf16 v[6:9], v[146:149], v[196:199], 0
	v_mfma_f32_16x16x32_bf16 v[2:5], v[154:157], v[196:199], 0
	v_mfma_f32_16x16x32_bf16 v[54:57], v[150:153], v[166:169], v[54:57]
	v_mfma_f32_16x16x32_bf16 v[50:53], v[158:161], v[166:169], v[50:53]
	v_mfma_f32_16x16x32_bf16 v[38:41], v[150:153], v[174:177], v[38:41]
	v_mfma_f32_16x16x32_bf16 v[34:37], v[158:161], v[174:177], v[34:37]
	v_mfma_f32_16x16x32_bf16 v[22:25], v[150:153], v[182:185], v[22:25]
	v_mfma_f32_16x16x32_bf16 v[18:21], v[158:161], v[182:185], v[18:21]
	v_mfma_f32_16x16x32_bf16 v[6:9], v[150:153], v[206:209], v[6:9]
	v_mfma_f32_16x16x32_bf16 v[2:5], v[158:161], v[206:209], v[2:5]
	s_setprio 0
	s_barrier
	s_add_i32 s47, 0, 0x18000
	s_add_i32 s52, 0, 0x1c000
	v_add_u32_e32 v142, s47, v220
	v_add_u32_e32 v158, s52, v220
	ds_read_b128 v[130:133], v142
	ds_read_b128 v[134:137], v142 offset:1024
	ds_read_b128 v[138:141], v142 offset:2048
	ds_read_b128 v[142:145], v142 offset:3072
	ds_read_b128 v[146:149], v158
	ds_read_b128 v[150:153], v158 offset:1024
	ds_read_b128 v[154:157], v158 offset:2048
	ds_read_b128 v[158:161], v158 offset:3072
	s_add_u32 s30, s30, 0x80000
	s_addc_u32 s31, s31, 0
	s_mov_b32 m0, s36
	v_lshl_add_u64 v[218:219], s[30:31], 0, v[186:187]
	ds_read_b128 v[162:165], v222 offset:32768
	ds_read_b128 v[166:169], v222 offset:33792
	ds_read_b128 v[170:173], v222 offset:34816
	ds_read_b128 v[174:177], v222 offset:35840
	ds_read_b128 v[178:181], v222 offset:36864
	ds_read_b128 v[182:185], v222 offset:37888
	ds_read_b128 v[196:199], v222 offset:38912
	ds_read_b128 v[206:209], v222 offset:39936
	global_load_lds_dwordx4 v[218:219], off
	v_lshl_add_u64 v[218:219], s[30:31], 0, v[188:189]
	s_mov_b32 m0, s37
	s_nop 0
	global_load_lds_dwordx4 v[218:219], off
	s_waitcnt vmcnt(8)
	s_waitcnt lgkmcnt(0)
	s_barrier
	s_setprio 1
	v_mfma_f32_16x16x32_bf16 v[126:129], v[130:133], v[162:165], v[126:129]
	v_mfma_f32_16x16x32_bf16 v[122:125], v[138:141], v[162:165], v[122:125]
	v_mfma_f32_16x16x32_bf16 v[110:113], v[130:133], v[170:173], v[110:113]
	v_mfma_f32_16x16x32_bf16 v[106:109], v[138:141], v[170:173], v[106:109]
	v_mfma_f32_16x16x32_bf16 v[94:97], v[130:133], v[178:181], v[94:97]
	v_mfma_f32_16x16x32_bf16 v[90:93], v[138:141], v[178:181], v[90:93]
	v_mfma_f32_16x16x32_bf16 v[78:81], v[130:133], v[196:199], v[78:81]
	v_mfma_f32_16x16x32_bf16 v[74:77], v[138:141], v[196:199], v[74:77]
	v_mfma_f32_16x16x32_bf16 v[126:129], v[134:137], v[166:169], v[126:129]
	v_mfma_f32_16x16x32_bf16 v[122:125], v[142:145], v[166:169], v[122:125]
	v_mfma_f32_16x16x32_bf16 v[110:113], v[134:137], v[174:177], v[110:113]
	v_mfma_f32_16x16x32_bf16 v[106:109], v[142:145], v[174:177], v[106:109]
	v_mfma_f32_16x16x32_bf16 v[94:97], v[134:137], v[182:185], v[94:97]
	v_mfma_f32_16x16x32_bf16 v[90:93], v[142:145], v[182:185], v[90:93]
	v_mfma_f32_16x16x32_bf16 v[78:81], v[134:137], v[206:209], v[78:81]
	v_mfma_f32_16x16x32_bf16 v[74:77], v[142:145], v[206:209], v[74:77]
	s_setprio 0
	s_setprio 1
	v_mfma_f32_16x16x32_bf16 v[118:121], v[146:149], v[162:165], v[118:121]
	v_mfma_f32_16x16x32_bf16 v[114:117], v[154:157], v[162:165], v[114:117]
	v_mfma_f32_16x16x32_bf16 v[102:105], v[146:149], v[170:173], v[102:105]
	v_mfma_f32_16x16x32_bf16 v[98:101], v[154:157], v[170:173], v[98:101]
	v_mfma_f32_16x16x32_bf16 v[86:89], v[146:149], v[178:181], v[86:89]
	v_mfma_f32_16x16x32_bf16 v[82:85], v[154:157], v[178:181], v[82:85]
	v_mfma_f32_16x16x32_bf16 v[70:73], v[146:149], v[196:199], v[70:73]
	v_mfma_f32_16x16x32_bf16 v[66:69], v[154:157], v[196:199], v[66:69]
	v_mfma_f32_16x16x32_bf16 v[118:121], v[150:153], v[166:169], v[118:121]
	v_mfma_f32_16x16x32_bf16 v[114:117], v[158:161], v[166:169], v[114:117]
	v_mfma_f32_16x16x32_bf16 v[102:105], v[150:153], v[174:177], v[102:105]
	v_mfma_f32_16x16x32_bf16 v[98:101], v[158:161], v[174:177], v[98:101]
	v_mfma_f32_16x16x32_bf16 v[86:89], v[150:153], v[182:185], v[86:89]
	v_mfma_f32_16x16x32_bf16 v[82:85], v[158:161], v[182:185], v[82:85]
	v_mfma_f32_16x16x32_bf16 v[70:73], v[150:153], v[206:209], v[70:73]
	v_mfma_f32_16x16x32_bf16 v[66:69], v[158:161], v[206:209], v[66:69]
	s_setprio 0
	s_barrier
	s_add_i32 s30, s47, s33
	v_lshl_add_u64 v[210:211], v[210:211], 0, s[58:59]
	s_mov_b32 m0, s30
	ds_read_b128 v[162:165], v222 offset:49152
	ds_read_b128 v[166:169], v222 offset:50176
	ds_read_b128 v[170:173], v222 offset:51200
	ds_read_b128 v[174:177], v222 offset:52224
	ds_read_b128 v[178:181], v222 offset:53248
	ds_read_b128 v[182:185], v222 offset:54272
	ds_read_b128 v[196:199], v222 offset:55296
	ds_read_b128 v[206:209], v222 offset:56320
	global_load_lds_dwordx4 v[210:211], off
	s_add_i32 m0, s30, 0x2000
	s_add_u32 s28, s28, 0x80080
	v_lshl_add_u64 v[210:211], v[212:213], 0, s[58:59]
	s_addc_u32 s29, s29, 0
	s_add_i32 s30, s52, s33
	global_load_lds_dwordx4 v[210:211], off
	v_lshl_add_u64 v[210:211], s[28:29], 0, v[190:191]
	s_mov_b32 m0, s30
	s_nop 0
	global_load_lds_dwordx4 v[210:211], off
	v_lshl_add_u64 v[210:211], s[28:29], 0, v[200:201]
	s_add_i32 m0, s30, 0x2000
	s_nop 0
	global_load_lds_dwordx4 v[210:211], off
	v_lshl_add_u64 v[210:211], v[214:215], 0, s[58:59]
	s_mov_b32 m0, s38
	s_nop 0
	global_load_lds_dwordx4 v[210:211], off
	v_lshl_add_u64 v[210:211], v[216:217], 0, s[58:59]
	s_mov_b32 m0, s39
	s_nop 0
	global_load_lds_dwordx4 v[210:211], off
	s_waitcnt vmcnt(8)
	s_waitcnt lgkmcnt(0)
	s_barrier
	s_setprio 1
	v_mfma_f32_16x16x32_bf16 v[62:65], v[130:133], v[162:165], v[62:65]
	v_mfma_f32_16x16x32_bf16 v[58:61], v[138:141], v[162:165], v[58:61]
	v_mfma_f32_16x16x32_bf16 v[46:49], v[130:133], v[170:173], v[46:49]
	v_mfma_f32_16x16x32_bf16 v[42:45], v[138:141], v[170:173], v[42:45]
	v_mfma_f32_16x16x32_bf16 v[30:33], v[130:133], v[178:181], v[30:33]
	v_mfma_f32_16x16x32_bf16 v[26:29], v[138:141], v[178:181], v[26:29]
	v_mfma_f32_16x16x32_bf16 v[14:17], v[130:133], v[196:199], v[14:17]
	v_mfma_f32_16x16x32_bf16 v[10:13], v[138:141], v[196:199], v[10:13]
	v_mfma_f32_16x16x32_bf16 v[62:65], v[134:137], v[166:169], v[62:65]
	v_mfma_f32_16x16x32_bf16 v[58:61], v[142:145], v[166:169], v[58:61]
	v_mfma_f32_16x16x32_bf16 v[46:49], v[134:137], v[174:177], v[46:49]
	v_mfma_f32_16x16x32_bf16 v[42:45], v[142:145], v[174:177], v[42:45]
	v_mfma_f32_16x16x32_bf16 v[30:33], v[134:137], v[182:185], v[30:33]
	v_mfma_f32_16x16x32_bf16 v[26:29], v[142:145], v[182:185], v[26:29]
	v_mfma_f32_16x16x32_bf16 v[14:17], v[134:137], v[206:209], v[14:17]
	v_mfma_f32_16x16x32_bf16 v[10:13], v[142:145], v[206:209], v[10:13]
	s_setprio 0
	s_setprio 1
	v_mfma_f32_16x16x32_bf16 v[54:57], v[146:149], v[162:165], v[54:57]
	v_mfma_f32_16x16x32_bf16 v[50:53], v[154:157], v[162:165], v[50:53]
	v_mfma_f32_16x16x32_bf16 v[38:41], v[146:149], v[170:173], v[38:41]
	v_mfma_f32_16x16x32_bf16 v[34:37], v[154:157], v[170:173], v[34:37]
	v_mfma_f32_16x16x32_bf16 v[22:25], v[146:149], v[178:181], v[22:25]
	v_mfma_f32_16x16x32_bf16 v[18:21], v[154:157], v[178:181], v[18:21]
	v_mfma_f32_16x16x32_bf16 v[6:9], v[146:149], v[196:199], v[6:9]
	v_mfma_f32_16x16x32_bf16 v[2:5], v[154:157], v[196:199], v[2:5]
	v_mfma_f32_16x16x32_bf16 v[54:57], v[150:153], v[166:169], v[54:57]
	v_mfma_f32_16x16x32_bf16 v[50:53], v[158:161], v[166:169], v[50:53]
	v_mfma_f32_16x16x32_bf16 v[38:41], v[150:153], v[174:177], v[38:41]
	v_mfma_f32_16x16x32_bf16 v[34:37], v[158:161], v[174:177], v[34:37]
	v_mfma_f32_16x16x32_bf16 v[22:25], v[150:153], v[182:185], v[22:25]
	v_mfma_f32_16x16x32_bf16 v[18:21], v[158:161], v[182:185], v[18:21]
	v_mfma_f32_16x16x32_bf16 v[6:9], v[150:153], v[206:209], v[6:9]
	v_mfma_f32_16x16x32_bf16 v[2:5], v[158:161], v[206:209], v[2:5]
	s_setprio 0
	s_barrier
	s_add_i32 s46, s46, 2
	s_add_u32 s26, s26, 0x100
	s_addc_u32 s27, s27, 0
	s_add_u32 s42, s42, 0x100
	s_addc_u32 s43, s43, 0
	s_cmp_gt_u32 s46, 29
	s_cbranch_scc1 .Lpeel_done_3
.LBB0_772:
	s_add_u32 s28, s26, 0xfff80080
	s_addc_u32 s29, s27, -1
	s_add_i32 s47, 0, 0x10000
	s_cmp_eq_u32 s46, 28
	s_cselect_b32 s31, s17, s29
	s_cselect_b32 s30, s40, s28
	s_cselect_b32 s29, s15, s43
	s_cselect_b32 s28, s41, s42
	s_add_i32 s55, 0, 0x14000
	v_add_u32_e32 v142, s47, v220
	v_add_u32_e32 v158, s55, v220
	ds_read_b128 v[130:133], v142
	ds_read_b128 v[134:137], v142 offset:1024
	ds_read_b128 v[138:141], v142 offset:2048
	ds_read_b128 v[142:145], v142 offset:3072
	ds_read_b128 v[146:149], v158
	ds_read_b128 v[150:153], v158 offset:1024
	ds_read_b128 v[154:157], v158 offset:2048
	ds_read_b128 v[158:161], v158 offset:3072
	v_lshl_add_u64 v[210:211], s[26:27], 0, v[202:203]
	s_add_i32 m0, s34, 0xc000
	ds_read_b128 v[162:165], v222
	ds_read_b128 v[166:169], v222 offset:1024
	ds_read_b128 v[170:173], v222 offset:2048
	ds_read_b128 v[174:177], v222 offset:3072
	ds_read_b128 v[178:181], v222 offset:4096
	ds_read_b128 v[182:185], v222 offset:5120
	ds_read_b128 v[196:199], v222 offset:6144
	ds_read_b128 v[206:209], v222 offset:7168
	global_load_lds_dwordx4 v[210:211], off
	v_lshl_add_u64 v[210:211], s[26:27], 0, v[204:205]
	s_add_i32 m0, s34, 0xe000
	s_nop 0
	global_load_lds_dwordx4 v[210:211], off
	s_waitcnt vmcnt(8)
	s_waitcnt lgkmcnt(0)
	s_barrier
	s_setprio 1
	v_mfma_f32_16x16x32_bf16 v[126:129], v[130:133], v[162:165], v[126:129]
	v_mfma_f32_16x16x32_bf16 v[122:125], v[138:141], v[162:165], v[122:125]
	v_mfma_f32_16x16x32_bf16 v[110:113], v[130:133], v[170:173], v[110:113]
	v_mfma_f32_16x16x32_bf16 v[106:109], v[138:141], v[170:173], v[106:109]
	v_mfma_f32_16x16x32_bf16 v[94:97], v[130:133], v[178:181], v[94:97]
	v_mfma_f32_16x16x32_bf16 v[90:93], v[138:141], v[178:181], v[90:93]
	v_mfma_f32_16x16x32_bf16 v[78:81], v[130:133], v[196:199], v[78:81]
	v_mfma_f32_16x16x32_bf16 v[74:77], v[138:141], v[196:199], v[74:77]
	v_mfma_f32_16x16x32_bf16 v[126:129], v[134:137], v[166:169], v[126:129]
	v_mfma_f32_16x16x32_bf16 v[122:125], v[142:145], v[166:169], v[122:125]
	v_mfma_f32_16x16x32_bf16 v[110:113], v[134:137], v[174:177], v[110:113]
	v_mfma_f32_16x16x32_bf16 v[106:109], v[142:145], v[174:177], v[106:109]
	v_mfma_f32_16x16x32_bf16 v[94:97], v[134:137], v[182:185], v[94:97]
	v_mfma_f32_16x16x32_bf16 v[90:93], v[142:145], v[182:185], v[90:93]
	v_mfma_f32_16x16x32_bf16 v[78:81], v[134:137], v[206:209], v[78:81]
	v_mfma_f32_16x16x32_bf16 v[74:77], v[142:145], v[206:209], v[74:77]
	s_setprio 0
	s_setprio 1
	v_mfma_f32_16x16x32_bf16 v[118:121], v[146:149], v[162:165], v[118:121]
	v_mfma_f32_16x16x32_bf16 v[114:117], v[154:157], v[162:165], v[114:117]
	v_mfma_f32_16x16x32_bf16 v[102:105], v[146:149], v[170:173], v[102:105]
	v_mfma_f32_16x16x32_bf16 v[98:101], v[154:157], v[170:173], v[98:101]
	v_mfma_f32_16x16x32_bf16 v[86:89], v[146:149], v[178:181], v[86:89]
	v_mfma_f32_16x16x32_bf16 v[82:85], v[154:157], v[178:181], v[82:85]
	v_mfma_f32_16x16x32_bf16 v[70:73], v[146:149], v[196:199], v[70:73]
	v_mfma_f32_16x16x32_bf16 v[66:69], v[154:157], v[196:199], v[66:69]
	v_mfma_f32_16x16x32_bf16 v[118:121], v[150:153], v[166:169], v[118:121]
	v_mfma_f32_16x16x32_bf16 v[114:117], v[158:161], v[166:169], v[114:117]
	v_mfma_f32_16x16x32_bf16 v[102:105], v[150:153], v[174:177], v[102:105]
	v_mfma_f32_16x16x32_bf16 v[98:101], v[158:161], v[174:177], v[98:101]
	v_mfma_f32_16x16x32_bf16 v[86:89], v[150:153], v[182:185], v[86:89]
	v_mfma_f32_16x16x32_bf16 v[82:85], v[158:161], v[182:185], v[82:85]
	v_mfma_f32_16x16x32_bf16 v[70:73], v[150:153], v[206:209], v[70:73]
	v_mfma_f32_16x16x32_bf16 v[66:69], v[158:161], v[206:209], v[66:69]
	s_setprio 0
	s_barrier
	s_add_i32 s47, s47, s33
	v_lshl_add_u64 v[210:211], s[28:29], 0, v[190:191]
	s_mov_b32 m0, s47
	ds_read_b128 v[162:165], v222 offset:16384
	ds_read_b128 v[166:169], v222 offset:17408
	ds_read_b128 v[170:173], v222 offset:18432
	ds_read_b128 v[174:177], v222 offset:19456
	ds_read_b128 v[178:181], v222 offset:20480
	ds_read_b128 v[182:185], v222 offset:21504
	ds_read_b128 v[196:199], v222 offset:22528
	ds_read_b128 v[206:209], v222 offset:23552
	global_load_lds_dwordx4 v[210:211], off
	s_add_i32 m0, s47, 0x2000
	s_add_u32 s52, s28, 0x80000
	v_lshl_add_u64 v[212:213], s[28:29], 0, v[200:201]
	s_addc_u32 s53, s29, 0
	s_add_i32 s47, s55, s33
	global_load_lds_dwordx4 v[212:213], off
	v_lshl_add_u64 v[214:215], s[52:53], 0, v[190:191]
	s_mov_b32 m0, s47
	v_lshl_add_u64 v[216:217], s[30:31], 0, v[188:189]
	global_load_lds_dwordx4 v[214:215], off
	v_lshl_add_u64 v[214:215], s[52:53], 0, v[200:201]
	s_add_i32 m0, s47, 0x2000
	s_nop 0
	global_load_lds_dwordx4 v[214:215], off
	v_lshl_add_u64 v[214:215], s[30:31], 0, v[186:187]
	s_mov_b32 m0, s34
	s_nop 0
	global_load_lds_dwordx4 v[214:215], off
	s_mov_b32 m0, s35
	s_nop 0
	global_load_lds_dwordx4 v[216:217], off
	s_waitcnt vmcnt(8)
	s_waitcnt lgkmcnt(0)
	s_barrier
	s_setprio 1
	v_mfma_f32_16x16x32_bf16 v[62:65], v[130:133], v[162:165], v[62:65]
	v_mfma_f32_16x16x32_bf16 v[58:61], v[138:141], v[162:165], v[58:61]
	v_mfma_f32_16x16x32_bf16 v[46:49], v[130:133], v[170:173], v[46:49]
	v_mfma_f32_16x16x32_bf16 v[42:45], v[138:141], v[170:173], v[42:45]
	v_mfma_f32_16x16x32_bf16 v[30:33], v[130:133], v[178:181], v[30:33]
	v_mfma_f32_16x16x32_bf16 v[26:29], v[138:141], v[178:181], v[26:29]
	v_mfma_f32_16x16x32_bf16 v[14:17], v[130:133], v[196:199], v[14:17]
	v_mfma_f32_16x16x32_bf16 v[10:13], v[138:141], v[196:199], v[10:13]
	v_mfma_f32_16x16x32_bf16 v[62:65], v[134:137], v[166:169], v[62:65]
	v_mfma_f32_16x16x32_bf16 v[58:61], v[142:145], v[166:169], v[58:61]
	v_mfma_f32_16x16x32_bf16 v[46:49], v[134:137], v[174:177], v[46:49]
	v_mfma_f32_16x16x32_bf16 v[42:45], v[142:145], v[174:177], v[42:45]
	v_mfma_f32_16x16x32_bf16 v[30:33], v[134:137], v[182:185], v[30:33]
	v_mfma_f32_16x16x32_bf16 v[26:29], v[142:145], v[182:185], v[26:29]
	v_mfma_f32_16x16x32_bf16 v[14:17], v[134:137], v[206:209], v[14:17]
	v_mfma_f32_16x16x32_bf16 v[10:13], v[142:145], v[206:209], v[10:13]
	s_setprio 0
	s_setprio 1
	v_mfma_f32_16x16x32_bf16 v[54:57], v[146:149], v[162:165], v[54:57]
	v_mfma_f32_16x16x32_bf16 v[50:53], v[154:157], v[162:165], v[50:53]
	v_mfma_f32_16x16x32_bf16 v[38:41], v[146:149], v[170:173], v[38:41]
	v_mfma_f32_16x16x32_bf16 v[34:37], v[154:157], v[170:173], v[34:37]
	v_mfma_f32_16x16x32_bf16 v[22:25], v[146:149], v[178:181], v[22:25]
	v_mfma_f32_16x16x32_bf16 v[18:21], v[154:157], v[178:181], v[18:21]
	v_mfma_f32_16x16x32_bf16 v[6:9], v[146:149], v[196:199], v[6:9]
	v_mfma_f32_16x16x32_bf16 v[2:5], v[154:157], v[196:199], v[2:5]
	v_mfma_f32_16x16x32_bf16 v[54:57], v[150:153], v[166:169], v[54:57]
	v_mfma_f32_16x16x32_bf16 v[50:53], v[158:161], v[166:169], v[50:53]
	v_mfma_f32_16x16x32_bf16 v[38:41], v[150:153], v[174:177], v[38:41]
	v_mfma_f32_16x16x32_bf16 v[34:37], v[158:161], v[174:177], v[34:37]
	v_mfma_f32_16x16x32_bf16 v[22:25], v[150:153], v[182:185], v[22:25]
	v_mfma_f32_16x16x32_bf16 v[18:21], v[158:161], v[182:185], v[18:21]
	v_mfma_f32_16x16x32_bf16 v[6:9], v[150:153], v[206:209], v[6:9]
	v_mfma_f32_16x16x32_bf16 v[2:5], v[158:161], v[206:209], v[2:5]
	s_setprio 0
	s_barrier
	s_add_i32 s47, 0, 0x18000
	s_add_i32 s52, 0, 0x1c000
	v_add_u32_e32 v142, s47, v220
	v_add_u32_e32 v158, s52, v220
	ds_read_b128 v[130:133], v142
	ds_read_b128 v[134:137], v142 offset:1024
	ds_read_b128 v[138:141], v142 offset:2048
	ds_read_b128 v[142:145], v142 offset:3072
	ds_read_b128 v[146:149], v158
	ds_read_b128 v[150:153], v158 offset:1024
	ds_read_b128 v[154:157], v158 offset:2048
	ds_read_b128 v[158:161], v158 offset:3072
	s_add_u32 s30, s30, 0x80000
	s_addc_u32 s31, s31, 0
	s_mov_b32 m0, s36
	v_lshl_add_u64 v[218:219], s[30:31], 0, v[186:187]
	ds_read_b128 v[162:165], v222 offset:32768
	ds_read_b128 v[166:169], v222 offset:33792
	ds_read_b128 v[170:173], v222 offset:34816
	ds_read_b128 v[174:177], v222 offset:35840
	ds_read_b128 v[178:181], v222 offset:36864
	ds_read_b128 v[182:185], v222 offset:37888
	ds_read_b128 v[196:199], v222 offset:38912
	ds_read_b128 v[206:209], v222 offset:39936
	global_load_lds_dwordx4 v[218:219], off
	v_lshl_add_u64 v[218:219], s[30:31], 0, v[188:189]
	s_mov_b32 m0, s37
	s_nop 0
	global_load_lds_dwordx4 v[218:219], off
	s_waitcnt vmcnt(8)
	s_waitcnt lgkmcnt(0)
	s_barrier
	s_setprio 1
	v_mfma_f32_16x16x32_bf16 v[126:129], v[130:133], v[162:165], v[126:129]
	v_mfma_f32_16x16x32_bf16 v[122:125], v[138:141], v[162:165], v[122:125]
	v_mfma_f32_16x16x32_bf16 v[110:113], v[130:133], v[170:173], v[110:113]
	v_mfma_f32_16x16x32_bf16 v[106:109], v[138:141], v[170:173], v[106:109]
	v_mfma_f32_16x16x32_bf16 v[94:97], v[130:133], v[178:181], v[94:97]
	v_mfma_f32_16x16x32_bf16 v[90:93], v[138:141], v[178:181], v[90:93]
	v_mfma_f32_16x16x32_bf16 v[78:81], v[130:133], v[196:199], v[78:81]
	v_mfma_f32_16x16x32_bf16 v[74:77], v[138:141], v[196:199], v[74:77]
	v_mfma_f32_16x16x32_bf16 v[126:129], v[134:137], v[166:169], v[126:129]
	v_mfma_f32_16x16x32_bf16 v[122:125], v[142:145], v[166:169], v[122:125]
	v_mfma_f32_16x16x32_bf16 v[110:113], v[134:137], v[174:177], v[110:113]
	v_mfma_f32_16x16x32_bf16 v[106:109], v[142:145], v[174:177], v[106:109]
	v_mfma_f32_16x16x32_bf16 v[94:97], v[134:137], v[182:185], v[94:97]
	v_mfma_f32_16x16x32_bf16 v[90:93], v[142:145], v[182:185], v[90:93]
	v_mfma_f32_16x16x32_bf16 v[78:81], v[134:137], v[206:209], v[78:81]
	v_mfma_f32_16x16x32_bf16 v[74:77], v[142:145], v[206:209], v[74:77]
	s_setprio 0
	s_setprio 1
	v_mfma_f32_16x16x32_bf16 v[118:121], v[146:149], v[162:165], v[118:121]
	v_mfma_f32_16x16x32_bf16 v[114:117], v[154:157], v[162:165], v[114:117]
	v_mfma_f32_16x16x32_bf16 v[102:105], v[146:149], v[170:173], v[102:105]
	v_mfma_f32_16x16x32_bf16 v[98:101], v[154:157], v[170:173], v[98:101]
	v_mfma_f32_16x16x32_bf16 v[86:89], v[146:149], v[178:181], v[86:89]
	v_mfma_f32_16x16x32_bf16 v[82:85], v[154:157], v[178:181], v[82:85]
	v_mfma_f32_16x16x32_bf16 v[70:73], v[146:149], v[196:199], v[70:73]
	v_mfma_f32_16x16x32_bf16 v[66:69], v[154:157], v[196:199], v[66:69]
	v_mfma_f32_16x16x32_bf16 v[118:121], v[150:153], v[166:169], v[118:121]
	v_mfma_f32_16x16x32_bf16 v[114:117], v[158:161], v[166:169], v[114:117]
	v_mfma_f32_16x16x32_bf16 v[102:105], v[150:153], v[174:177], v[102:105]
	v_mfma_f32_16x16x32_bf16 v[98:101], v[158:161], v[174:177], v[98:101]
	v_mfma_f32_16x16x32_bf16 v[86:89], v[150:153], v[182:185], v[86:89]
	v_mfma_f32_16x16x32_bf16 v[82:85], v[158:161], v[182:185], v[82:85]
	v_mfma_f32_16x16x32_bf16 v[70:73], v[150:153], v[206:209], v[70:73]
	v_mfma_f32_16x16x32_bf16 v[66:69], v[158:161], v[206:209], v[66:69]
	s_setprio 0
	s_barrier
	s_add_i32 s30, s47, s33
	v_lshl_add_u64 v[210:211], v[210:211], 0, s[58:59]
	s_mov_b32 m0, s30
	ds_read_b128 v[162:165], v222 offset:49152
	ds_read_b128 v[166:169], v222 offset:50176
	ds_read_b128 v[170:173], v222 offset:51200
	ds_read_b128 v[174:177], v222 offset:52224
	ds_read_b128 v[178:181], v222 offset:53248
	ds_read_b128 v[182:185], v222 offset:54272
	ds_read_b128 v[196:199], v222 offset:55296
	ds_read_b128 v[206:209], v222 offset:56320
	global_load_lds_dwordx4 v[210:211], off
	s_add_i32 m0, s30, 0x2000
	s_add_u32 s28, s28, 0x80080
	v_lshl_add_u64 v[210:211], v[212:213], 0, s[58:59]
	s_addc_u32 s29, s29, 0
	s_add_i32 s30, s52, s33
	global_load_lds_dwordx4 v[210:211], off
	v_lshl_add_u64 v[210:211], s[28:29], 0, v[190:191]
	s_mov_b32 m0, s30
	s_nop 0
	global_load_lds_dwordx4 v[210:211], off
	v_lshl_add_u64 v[210:211], s[28:29], 0, v[200:201]
	s_add_i32 m0, s30, 0x2000
	s_nop 0
	global_load_lds_dwordx4 v[210:211], off
	v_lshl_add_u64 v[210:211], v[214:215], 0, s[58:59]
	s_mov_b32 m0, s38
	s_nop 0
	global_load_lds_dwordx4 v[210:211], off
	v_lshl_add_u64 v[210:211], v[216:217], 0, s[58:59]
	s_mov_b32 m0, s39
	s_nop 0
	global_load_lds_dwordx4 v[210:211], off
	s_waitcnt vmcnt(8)
	s_waitcnt lgkmcnt(0)
	s_barrier
	s_setprio 1
	v_mfma_f32_16x16x32_bf16 v[62:65], v[130:133], v[162:165], v[62:65]
	v_mfma_f32_16x16x32_bf16 v[58:61], v[138:141], v[162:165], v[58:61]
	v_mfma_f32_16x16x32_bf16 v[46:49], v[130:133], v[170:173], v[46:49]
	v_mfma_f32_16x16x32_bf16 v[42:45], v[138:141], v[170:173], v[42:45]
	v_mfma_f32_16x16x32_bf16 v[30:33], v[130:133], v[178:181], v[30:33]
	v_mfma_f32_16x16x32_bf16 v[26:29], v[138:141], v[178:181], v[26:29]
	v_mfma_f32_16x16x32_bf16 v[14:17], v[130:133], v[196:199], v[14:17]
	v_mfma_f32_16x16x32_bf16 v[10:13], v[138:141], v[196:199], v[10:13]
	v_mfma_f32_16x16x32_bf16 v[62:65], v[134:137], v[166:169], v[62:65]
	v_mfma_f32_16x16x32_bf16 v[58:61], v[142:145], v[166:169], v[58:61]
	v_mfma_f32_16x16x32_bf16 v[46:49], v[134:137], v[174:177], v[46:49]
	v_mfma_f32_16x16x32_bf16 v[42:45], v[142:145], v[174:177], v[42:45]
	v_mfma_f32_16x16x32_bf16 v[30:33], v[134:137], v[182:185], v[30:33]
	v_mfma_f32_16x16x32_bf16 v[26:29], v[142:145], v[182:185], v[26:29]
	v_mfma_f32_16x16x32_bf16 v[14:17], v[134:137], v[206:209], v[14:17]
	v_mfma_f32_16x16x32_bf16 v[10:13], v[142:145], v[206:209], v[10:13]
	s_setprio 0
	s_setprio 1
	v_mfma_f32_16x16x32_bf16 v[54:57], v[146:149], v[162:165], v[54:57]
	v_mfma_f32_16x16x32_bf16 v[50:53], v[154:157], v[162:165], v[50:53]
	v_mfma_f32_16x16x32_bf16 v[38:41], v[146:149], v[170:173], v[38:41]
	v_mfma_f32_16x16x32_bf16 v[34:37], v[154:157], v[170:173], v[34:37]
	v_mfma_f32_16x16x32_bf16 v[22:25], v[146:149], v[178:181], v[22:25]
	v_mfma_f32_16x16x32_bf16 v[18:21], v[154:157], v[178:181], v[18:21]
	v_mfma_f32_16x16x32_bf16 v[6:9], v[146:149], v[196:199], v[6:9]
	v_mfma_f32_16x16x32_bf16 v[2:5], v[154:157], v[196:199], v[2:5]
	v_mfma_f32_16x16x32_bf16 v[54:57], v[150:153], v[166:169], v[54:57]
	v_mfma_f32_16x16x32_bf16 v[50:53], v[158:161], v[166:169], v[50:53]
	v_mfma_f32_16x16x32_bf16 v[38:41], v[150:153], v[174:177], v[38:41]
	v_mfma_f32_16x16x32_bf16 v[34:37], v[158:161], v[174:177], v[34:37]
	v_mfma_f32_16x16x32_bf16 v[22:25], v[150:153], v[182:185], v[22:25]
	v_mfma_f32_16x16x32_bf16 v[18:21], v[158:161], v[182:185], v[18:21]
	v_mfma_f32_16x16x32_bf16 v[6:9], v[150:153], v[206:209], v[6:9]
	v_mfma_f32_16x16x32_bf16 v[2:5], v[158:161], v[206:209], v[2:5]
	s_setprio 0
	s_barrier
	s_add_i32 s46, s46, 2
	s_add_u32 s26, s26, 0x100
	s_addc_u32 s27, s27, 0
	s_add_u32 s42, s42, 0x100
	s_addc_u32 s43, s43, 0
	s_cmp_gt_u32 s46, 29
	s_cbranch_scc0 .LBB0_772

.LBB0_799:
	s_ashr_i32 s11, s10, 31
	s_lshl_b64 s[14:15], s[10:11], 20
	s_add_u32 s14, s69, s14
	s_addc_u32 s15, s77, s15
	s_and_b64 s[16:17], s[12:13], exec
	s_cselect_b32 s11, s15, s25
	s_cselect_b32 s21, s14, s24
	s_ashr_i32 s9, s8, 31
	s_lshl_b64 s[16:17], s[8:9], 20
	v_readlane_b32 s0, v254, 42
	v_readlane_b32 s1, v254, 43
	s_add_u32 s16, s0, s16
	s_addc_u32 s17, s1, s17
	s_and_b64 s[28:29], s[12:13], exec
	s_cselect_b32 s9, s17, s27
	s_cselect_b32 s47, s16, s26
	s_add_u32 s24, s24, 0x80080
	s_addc_u32 s25, s25, 0
	s_add_u32 s52, s26, 0x100
	s_addc_u32 s53, s27, 0
	s_mov_b32 s55, -2
	v_readlane_b32 s56, v255, 49
	s_nop 3
	s_cmp_eq_u32 s56, 5
	v_writelane_b32 v255, 5, 49
	s_cbranch_scc0 .Ltrip0_strict_4
	s_add_u32 s26, s24, 0xfff80080
	s_addc_u32 s27, s25, -1
	s_add_i32 s56, 0, 0x10000
	s_cmp_eq_u32 s55, 28
	s_cselect_b32 s29, s11, s27
	s_cselect_b32 s28, s21, s26
	s_cselect_b32 s27, s9, s53
	s_cselect_b32 s26, s47, s52
	s_add_i32 s60, 0, 0x14000
	v_add_u32_e32 v142, s56, v238
	v_add_u32_e32 v158, s60, v238
	ds_read_b128 v[130:133], v142
	ds_read_b128 v[134:137], v142 offset:1024
	ds_read_b128 v[138:141], v142 offset:2048
	ds_read_b128 v[142:145], v142 offset:3072
	ds_read_b128 v[146:149], v158
	ds_read_b128 v[150:153], v158 offset:1024
	ds_read_b128 v[154:157], v158 offset:2048
	ds_read_b128 v[158:161], v158 offset:3072
	v_lshl_add_u64 v[210:211], s[24:25], 0, v[206:207]
	s_add_i32 m0, s23, 0xc000
	ds_read_b128 v[162:165], v240
	ds_read_b128 v[166:169], v240 offset:1024
	ds_read_b128 v[170:173], v240 offset:2048
	ds_read_b128 v[174:177], v240 offset:3072
	ds_read_b128 v[178:181], v240 offset:4096
	ds_read_b128 v[182:185], v240 offset:5120
	ds_read_b128 v[186:189], v240 offset:6144
	ds_read_b128 v[196:199], v240 offset:7168
	global_load_lds_dwordx4 v[210:211], off
	v_lshl_add_u64 v[210:211], s[24:25], 0, v[208:209]
	s_add_i32 m0, s23, 0xe000
	s_nop 0
	global_load_lds_dwordx4 v[210:211], off
	s_waitcnt vmcnt(24)
	s_waitcnt lgkmcnt(0)
	s_barrier
	s_setprio 1
	v_mfma_f32_16x16x32_bf16 v[126:129], v[130:133], v[162:165], 0
	v_mfma_f32_16x16x32_bf16 v[122:125], v[138:141], v[162:165], 0
	v_mfma_f32_16x16x32_bf16 v[110:113], v[130:133], v[170:173], 0
	v_mfma_f32_16x16x32_bf16 v[106:109], v[138:141], v[170:173], 0
	v_mfma_f32_16x16x32_bf16 v[98:101], v[130:133], v[178:181], 0
	v_mfma_f32_16x16x32_bf16 v[90:93], v[138:141], v[178:181], 0
	v_mfma_f32_16x16x32_bf16 v[82:85], v[130:133], v[186:189], 0
	v_mfma_f32_16x16x32_bf16 v[74:77], v[138:141], v[186:189], 0
	v_mfma_f32_16x16x32_bf16 v[126:129], v[134:137], v[166:169], v[126:129]
	v_mfma_f32_16x16x32_bf16 v[122:125], v[142:145], v[166:169], v[122:125]
	v_mfma_f32_16x16x32_bf16 v[110:113], v[134:137], v[174:177], v[110:113]
	v_mfma_f32_16x16x32_bf16 v[106:109], v[142:145], v[174:177], v[106:109]
	v_mfma_f32_16x16x32_bf16 v[98:101], v[134:137], v[182:185], v[98:101]
	v_mfma_f32_16x16x32_bf16 v[90:93], v[142:145], v[182:185], v[90:93]
	v_mfma_f32_16x16x32_bf16 v[82:85], v[134:137], v[196:199], v[82:85]
	v_mfma_f32_16x16x32_bf16 v[74:77], v[142:145], v[196:199], v[74:77]
	s_setprio 0
	s_setprio 1
	v_mfma_f32_16x16x32_bf16 v[118:121], v[146:149], v[162:165], 0
	v_mfma_f32_16x16x32_bf16 v[114:117], v[154:157], v[162:165], 0
	v_mfma_f32_16x16x32_bf16 v[102:105], v[146:149], v[170:173], 0
	v_mfma_f32_16x16x32_bf16 v[94:97], v[154:157], v[170:173], 0
	v_mfma_f32_16x16x32_bf16 v[86:89], v[146:149], v[178:181], 0
	v_mfma_f32_16x16x32_bf16 v[78:81], v[154:157], v[178:181], 0
	v_mfma_f32_16x16x32_bf16 v[70:73], v[146:149], v[186:189], 0
	v_mfma_f32_16x16x32_bf16 v[66:69], v[154:157], v[186:189], 0
	v_mfma_f32_16x16x32_bf16 v[118:121], v[150:153], v[166:169], v[118:121]
	v_mfma_f32_16x16x32_bf16 v[114:117], v[158:161], v[166:169], v[114:117]
	v_mfma_f32_16x16x32_bf16 v[102:105], v[150:153], v[174:177], v[102:105]
	v_mfma_f32_16x16x32_bf16 v[94:97], v[158:161], v[174:177], v[94:97]
	v_mfma_f32_16x16x32_bf16 v[86:89], v[150:153], v[182:185], v[86:89]
	v_mfma_f32_16x16x32_bf16 v[78:81], v[158:161], v[182:185], v[78:81]
	v_mfma_f32_16x16x32_bf16 v[70:73], v[150:153], v[196:199], v[70:73]
	v_mfma_f32_16x16x32_bf16 v[66:69], v[158:161], v[196:199], v[66:69]
	s_setprio 0
	s_barrier
	s_add_i32 s56, s56, s34
	v_lshl_add_u64 v[210:211], s[26:27], 0, v[190:191]
	s_mov_b32 m0, s56
	ds_read_b128 v[162:165], v240 offset:16384
	ds_read_b128 v[166:169], v240 offset:17408
	ds_read_b128 v[170:173], v240 offset:18432
	ds_read_b128 v[174:177], v240 offset:19456
	ds_read_b128 v[178:181], v240 offset:20480
	ds_read_b128 v[182:185], v240 offset:21504
	ds_read_b128 v[186:189], v240 offset:22528
	ds_read_b128 v[196:199], v240 offset:23552
	global_load_lds_dwordx4 v[210:211], off
	s_add_i32 m0, s56, 0x2000
	s_add_u32 s56, s26, 0x80000
	v_lshl_add_u64 v[212:213], s[26:27], 0, v[204:205]
	s_addc_u32 s57, s27, 0
	s_add_i32 s60, s60, s34
	global_load_lds_dwordx4 v[212:213], off
	v_lshl_add_u64 v[214:215], s[56:57], 0, v[190:191]
	s_mov_b32 m0, s60
	v_lshl_add_u64 v[216:217], s[28:29], 0, v[202:203]
	global_load_lds_dwordx4 v[214:215], off
	v_lshl_add_u64 v[214:215], s[56:57], 0, v[204:205]
	s_add_i32 m0, s60, 0x2000
	s_nop 0
	global_load_lds_dwordx4 v[214:215], off
	v_lshl_add_u64 v[214:215], s[28:29], 0, v[200:201]
	s_mov_b32 m0, s23
	s_nop 0
	global_load_lds_dwordx4 v[214:215], off
	s_mov_b32 m0, s35
	s_nop 0
	global_load_lds_dwordx4 v[216:217], off
	s_waitcnt vmcnt(24)
	s_waitcnt lgkmcnt(0)
	s_barrier
	s_setprio 1
	v_mfma_f32_16x16x32_bf16 v[62:65], v[130:133], v[162:165], 0
	v_mfma_f32_16x16x32_bf16 v[58:61], v[138:141], v[162:165], 0
	v_mfma_f32_16x16x32_bf16 v[50:53], v[130:133], v[170:173], 0
	v_mfma_f32_16x16x32_bf16 v[42:45], v[138:141], v[170:173], 0
	v_mfma_f32_16x16x32_bf16 v[34:37], v[130:133], v[178:181], 0
	v_mfma_f32_16x16x32_bf16 v[26:29], v[138:141], v[178:181], 0
	v_mfma_f32_16x16x32_bf16 v[18:21], v[130:133], v[186:189], 0
	v_mfma_f32_16x16x32_bf16 v[10:13], v[138:141], v[186:189], 0
	v_mfma_f32_16x16x32_bf16 v[62:65], v[134:137], v[166:169], v[62:65]
	v_mfma_f32_16x16x32_bf16 v[58:61], v[142:145], v[166:169], v[58:61]
	v_mfma_f32_16x16x32_bf16 v[50:53], v[134:137], v[174:177], v[50:53]
	v_mfma_f32_16x16x32_bf16 v[42:45], v[142:145], v[174:177], v[42:45]
	v_mfma_f32_16x16x32_bf16 v[34:37], v[134:137], v[182:185], v[34:37]
	v_mfma_f32_16x16x32_bf16 v[26:29], v[142:145], v[182:185], v[26:29]
	v_mfma_f32_16x16x32_bf16 v[18:21], v[134:137], v[196:199], v[18:21]
	v_mfma_f32_16x16x32_bf16 v[10:13], v[142:145], v[196:199], v[10:13]
	s_setprio 0
	s_setprio 1
	v_mfma_f32_16x16x32_bf16 v[54:57], v[146:149], v[162:165], 0
	v_mfma_f32_16x16x32_bf16 v[46:49], v[154:157], v[162:165], 0
	v_mfma_f32_16x16x32_bf16 v[38:41], v[146:149], v[170:173], 0
	v_mfma_f32_16x16x32_bf16 v[30:33], v[154:157], v[170:173], 0
	v_mfma_f32_16x16x32_bf16 v[22:25], v[146:149], v[178:181], 0
	v_mfma_f32_16x16x32_bf16 v[14:17], v[154:157], v[178:181], 0
	v_mfma_f32_16x16x32_bf16 v[6:9], v[146:149], v[186:189], 0
	v_mfma_f32_16x16x32_bf16 v[2:5], v[154:157], v[186:189], 0
	v_mfma_f32_16x16x32_bf16 v[54:57], v[150:153], v[166:169], v[54:57]
	v_mfma_f32_16x16x32_bf16 v[46:49], v[158:161], v[166:169], v[46:49]
	v_mfma_f32_16x16x32_bf16 v[38:41], v[150:153], v[174:177], v[38:41]
	v_mfma_f32_16x16x32_bf16 v[30:33], v[158:161], v[174:177], v[30:33]
	v_mfma_f32_16x16x32_bf16 v[22:25], v[150:153], v[182:185], v[22:25]
	v_mfma_f32_16x16x32_bf16 v[14:17], v[158:161], v[182:185], v[14:17]
	v_mfma_f32_16x16x32_bf16 v[6:9], v[150:153], v[196:199], v[6:9]
	v_mfma_f32_16x16x32_bf16 v[2:5], v[158:161], v[196:199], v[2:5]
	s_setprio 0
	s_barrier
	s_add_i32 s56, 0, 0x18000
	s_add_i32 s57, 0, 0x1c000
	v_add_u32_e32 v142, s56, v238
	v_add_u32_e32 v158, s57, v238
	ds_read_b128 v[130:133], v142
	ds_read_b128 v[134:137], v142 offset:1024
	ds_read_b128 v[138:141], v142 offset:2048
	ds_read_b128 v[142:145], v142 offset:3072
	ds_read_b128 v[146:149], v158
	ds_read_b128 v[150:153], v158 offset:1024
	ds_read_b128 v[154:157], v158 offset:2048
	ds_read_b128 v[158:161], v158 offset:3072
	s_add_u32 s28, s28, 0x80000
	s_addc_u32 s29, s29, 0
	s_mov_b32 m0, s41
	v_lshl_add_u64 v[218:219], s[28:29], 0, v[200:201]
	ds_read_b128 v[162:165], v240 offset:32768
	ds_read_b128 v[166:169], v240 offset:33792
	ds_read_b128 v[170:173], v240 offset:34816
	ds_read_b128 v[174:177], v240 offset:35840
	ds_read_b128 v[178:181], v240 offset:36864
	ds_read_b128 v[182:185], v240 offset:37888
	ds_read_b128 v[186:189], v240 offset:38912
	ds_read_b128 v[196:199], v240 offset:39936
	global_load_lds_dwordx4 v[218:219], off
	v_lshl_add_u64 v[218:219], s[28:29], 0, v[202:203]
	s_mov_b32 m0, s42
	s_nop 0
	global_load_lds_dwordx4 v[218:219], off
	s_waitcnt vmcnt(8)
	s_waitcnt lgkmcnt(0)
	s_barrier
	s_setprio 1
	v_mfma_f32_16x16x32_bf16 v[126:129], v[130:133], v[162:165], v[126:129]
	v_mfma_f32_16x16x32_bf16 v[122:125], v[138:141], v[162:165], v[122:125]
	v_mfma_f32_16x16x32_bf16 v[110:113], v[130:133], v[170:173], v[110:113]
	v_mfma_f32_16x16x32_bf16 v[106:109], v[138:141], v[170:173], v[106:109]
	v_mfma_f32_16x16x32_bf16 v[98:101], v[130:133], v[178:181], v[98:101]
	v_mfma_f32_16x16x32_bf16 v[90:93], v[138:141], v[178:181], v[90:93]
	v_mfma_f32_16x16x32_bf16 v[82:85], v[130:133], v[186:189], v[82:85]
	v_mfma_f32_16x16x32_bf16 v[74:77], v[138:141], v[186:189], v[74:77]
	v_mfma_f32_16x16x32_bf16 v[126:129], v[134:137], v[166:169], v[126:129]
	v_mfma_f32_16x16x32_bf16 v[122:125], v[142:145], v[166:169], v[122:125]
	v_mfma_f32_16x16x32_bf16 v[110:113], v[134:137], v[174:177], v[110:113]
	v_mfma_f32_16x16x32_bf16 v[106:109], v[142:145], v[174:177], v[106:109]
	v_mfma_f32_16x16x32_bf16 v[98:101], v[134:137], v[182:185], v[98:101]
	v_mfma_f32_16x16x32_bf16 v[90:93], v[142:145], v[182:185], v[90:93]
	v_mfma_f32_16x16x32_bf16 v[82:85], v[134:137], v[196:199], v[82:85]
	v_mfma_f32_16x16x32_bf16 v[74:77], v[142:145], v[196:199], v[74:77]
	s_setprio 0
	s_setprio 1
	v_mfma_f32_16x16x32_bf16 v[118:121], v[146:149], v[162:165], v[118:121]
	v_mfma_f32_16x16x32_bf16 v[114:117], v[154:157], v[162:165], v[114:117]
	v_mfma_f32_16x16x32_bf16 v[102:105], v[146:149], v[170:173], v[102:105]
	v_mfma_f32_16x16x32_bf16 v[94:97], v[154:157], v[170:173], v[94:97]
	v_mfma_f32_16x16x32_bf16 v[86:89], v[146:149], v[178:181], v[86:89]
	v_mfma_f32_16x16x32_bf16 v[78:81], v[154:157], v[178:181], v[78:81]
	v_mfma_f32_16x16x32_bf16 v[70:73], v[146:149], v[186:189], v[70:73]
	v_mfma_f32_16x16x32_bf16 v[66:69], v[154:157], v[186:189], v[66:69]
	v_mfma_f32_16x16x32_bf16 v[118:121], v[150:153], v[166:169], v[118:121]
	v_mfma_f32_16x16x32_bf16 v[114:117], v[158:161], v[166:169], v[114:117]
	v_mfma_f32_16x16x32_bf16 v[102:105], v[150:153], v[174:177], v[102:105]
	v_mfma_f32_16x16x32_bf16 v[94:97], v[158:161], v[174:177], v[94:97]
	v_mfma_f32_16x16x32_bf16 v[86:89], v[150:153], v[182:185], v[86:89]
	v_mfma_f32_16x16x32_bf16 v[78:81], v[158:161], v[182:185], v[78:81]
	v_mfma_f32_16x16x32_bf16 v[70:73], v[150:153], v[196:199], v[70:73]
	v_mfma_f32_16x16x32_bf16 v[66:69], v[158:161], v[196:199], v[66:69]
	s_setprio 0
	s_barrier
	s_add_i32 s28, s56, s34
	v_lshl_add_u64 v[210:211], v[210:211], 0, s[58:59]
	s_mov_b32 m0, s28
	ds_read_b128 v[162:165], v240 offset:49152
	ds_read_b128 v[166:169], v240 offset:50176
	ds_read_b128 v[170:173], v240 offset:51200
	ds_read_b128 v[174:177], v240 offset:52224
	ds_read_b128 v[178:181], v240 offset:53248
	ds_read_b128 v[182:185], v240 offset:54272
	ds_read_b128 v[186:189], v240 offset:55296
	ds_read_b128 v[196:199], v240 offset:56320
	global_load_lds_dwordx4 v[210:211], off
	s_add_i32 m0, s28, 0x2000
	s_add_u32 s26, s26, 0x80080
	v_lshl_add_u64 v[210:211], v[212:213], 0, s[58:59]
	s_addc_u32 s27, s27, 0
	s_add_i32 s28, s57, s34
	global_load_lds_dwordx4 v[210:211], off
	v_lshl_add_u64 v[210:211], s[26:27], 0, v[190:191]
	s_mov_b32 m0, s28
	s_nop 0
	global_load_lds_dwordx4 v[210:211], off
	v_lshl_add_u64 v[210:211], s[26:27], 0, v[204:205]
	s_add_i32 m0, s28, 0x2000
	s_nop 0
	global_load_lds_dwordx4 v[210:211], off
	v_lshl_add_u64 v[210:211], v[214:215], 0, s[58:59]
	s_mov_b32 m0, s43
	s_nop 0
	global_load_lds_dwordx4 v[210:211], off
	v_lshl_add_u64 v[210:211], v[216:217], 0, s[58:59]
	s_mov_b32 m0, s46
	s_nop 0
	global_load_lds_dwordx4 v[210:211], off
	s_waitcnt vmcnt(8)
	s_waitcnt lgkmcnt(0)
	s_barrier
	s_setprio 1
	v_mfma_f32_16x16x32_bf16 v[62:65], v[130:133], v[162:165], v[62:65]
	v_mfma_f32_16x16x32_bf16 v[58:61], v[138:141], v[162:165], v[58:61]
	v_mfma_f32_16x16x32_bf16 v[50:53], v[130:133], v[170:173], v[50:53]
	v_mfma_f32_16x16x32_bf16 v[42:45], v[138:141], v[170:173], v[42:45]
	v_mfma_f32_16x16x32_bf16 v[34:37], v[130:133], v[178:181], v[34:37]
	v_mfma_f32_16x16x32_bf16 v[26:29], v[138:141], v[178:181], v[26:29]
	v_mfma_f32_16x16x32_bf16 v[18:21], v[130:133], v[186:189], v[18:21]
	v_mfma_f32_16x16x32_bf16 v[10:13], v[138:141], v[186:189], v[10:13]
	v_mfma_f32_16x16x32_bf16 v[62:65], v[134:137], v[166:169], v[62:65]
	v_mfma_f32_16x16x32_bf16 v[58:61], v[142:145], v[166:169], v[58:61]
	v_mfma_f32_16x16x32_bf16 v[50:53], v[134:137], v[174:177], v[50:53]
	v_mfma_f32_16x16x32_bf16 v[42:45], v[142:145], v[174:177], v[42:45]
	v_mfma_f32_16x16x32_bf16 v[34:37], v[134:137], v[182:185], v[34:37]
	v_mfma_f32_16x16x32_bf16 v[26:29], v[142:145], v[182:185], v[26:29]
	v_mfma_f32_16x16x32_bf16 v[18:21], v[134:137], v[196:199], v[18:21]
	v_mfma_f32_16x16x32_bf16 v[10:13], v[142:145], v[196:199], v[10:13]
	s_setprio 0
	s_setprio 1
	v_mfma_f32_16x16x32_bf16 v[54:57], v[146:149], v[162:165], v[54:57]
	v_mfma_f32_16x16x32_bf16 v[46:49], v[154:157], v[162:165], v[46:49]
	v_mfma_f32_16x16x32_bf16 v[38:41], v[146:149], v[170:173], v[38:41]
	v_mfma_f32_16x16x32_bf16 v[30:33], v[154:157], v[170:173], v[30:33]
	v_mfma_f32_16x16x32_bf16 v[22:25], v[146:149], v[178:181], v[22:25]
	v_mfma_f32_16x16x32_bf16 v[14:17], v[154:157], v[178:181], v[14:17]
	v_mfma_f32_16x16x32_bf16 v[6:9], v[146:149], v[186:189], v[6:9]
	v_mfma_f32_16x16x32_bf16 v[2:5], v[154:157], v[186:189], v[2:5]
	v_mfma_f32_16x16x32_bf16 v[54:57], v[150:153], v[166:169], v[54:57]
	v_mfma_f32_16x16x32_bf16 v[46:49], v[158:161], v[166:169], v[46:49]
	v_mfma_f32_16x16x32_bf16 v[38:41], v[150:153], v[174:177], v[38:41]
	v_mfma_f32_16x16x32_bf16 v[30:33], v[158:161], v[174:177], v[30:33]
	v_mfma_f32_16x16x32_bf16 v[22:25], v[150:153], v[182:185], v[22:25]
	v_mfma_f32_16x16x32_bf16 v[14:17], v[158:161], v[182:185], v[14:17]
	v_mfma_f32_16x16x32_bf16 v[6:9], v[150:153], v[196:199], v[6:9]
	v_mfma_f32_16x16x32_bf16 v[2:5], v[158:161], v[196:199], v[2:5]
	s_setprio 0
	s_barrier
	s_add_i32 s55, s55, 2
	s_add_u32 s24, s24, 0x100
	s_addc_u32 s25, s25, 0
	s_add_u32 s52, s52, 0x100
	s_addc_u32 s53, s53, 0
	s_cmp_gt_u32 s55, 29
	s_cbranch_scc1 .Lpeel_done_4
	s_branch .LBB0_800
.Ltrip0_strict_4:
	s_add_u32 s26, s24, 0xfff80080
	s_addc_u32 s27, s25, -1
	s_add_i32 s56, 0, 0x10000
	s_cmp_eq_u32 s55, 28
	s_cselect_b32 s29, s11, s27
	s_cselect_b32 s28, s21, s26
	s_cselect_b32 s27, s9, s53
	s_cselect_b32 s26, s47, s52
	s_add_i32 s60, 0, 0x14000
	v_add_u32_e32 v142, s56, v238
	v_add_u32_e32 v158, s60, v238
	ds_read_b128 v[130:133], v142
	ds_read_b128 v[134:137], v142 offset:1024
	ds_read_b128 v[138:141], v142 offset:2048
	ds_read_b128 v[142:145], v142 offset:3072
	ds_read_b128 v[146:149], v158
	ds_read_b128 v[150:153], v158 offset:1024
	ds_read_b128 v[154:157], v158 offset:2048
	ds_read_b128 v[158:161], v158 offset:3072
	v_lshl_add_u64 v[210:211], s[24:25], 0, v[206:207]
	s_add_i32 m0, s23, 0xc000
	ds_read_b128 v[162:165], v240
	ds_read_b128 v[166:169], v240 offset:1024
	ds_read_b128 v[170:173], v240 offset:2048
	ds_read_b128 v[174:177], v240 offset:3072
	ds_read_b128 v[178:181], v240 offset:4096
	ds_read_b128 v[182:185], v240 offset:5120
	ds_read_b128 v[186:189], v240 offset:6144
	ds_read_b128 v[196:199], v240 offset:7168
	global_load_lds_dwordx4 v[210:211], off
	v_lshl_add_u64 v[210:211], s[24:25], 0, v[208:209]
	s_add_i32 m0, s23, 0xe000
	s_nop 0
	global_load_lds_dwordx4 v[210:211], off
	s_waitcnt vmcnt(8)
	s_waitcnt lgkmcnt(0)
	s_barrier
	s_setprio 1
	v_mfma_f32_16x16x32_bf16 v[126:129], v[130:133], v[162:165], 0
	v_mfma_f32_16x16x32_bf16 v[122:125], v[138:141], v[162:165], 0
	v_mfma_f32_16x16x32_bf16 v[110:113], v[130:133], v[170:173], 0
	v_mfma_f32_16x16x32_bf16 v[106:109], v[138:141], v[170:173], 0
	v_mfma_f32_16x16x32_bf16 v[98:101], v[130:133], v[178:181], 0
	v_mfma_f32_16x16x32_bf16 v[90:93], v[138:141], v[178:181], 0
	v_mfma_f32_16x16x32_bf16 v[82:85], v[130:133], v[186:189], 0
	v_mfma_f32_16x16x32_bf16 v[74:77], v[138:141], v[186:189], 0
	v_mfma_f32_16x16x32_bf16 v[126:129], v[134:137], v[166:169], v[126:129]
	v_mfma_f32_16x16x32_bf16 v[122:125], v[142:145], v[166:169], v[122:125]
	v_mfma_f32_16x16x32_bf16 v[110:113], v[134:137], v[174:177], v[110:113]
	v_mfma_f32_16x16x32_bf16 v[106:109], v[142:145], v[174:177], v[106:109]
	v_mfma_f32_16x16x32_bf16 v[98:101], v[134:137], v[182:185], v[98:101]
	v_mfma_f32_16x16x32_bf16 v[90:93], v[142:145], v[182:185], v[90:93]
	v_mfma_f32_16x16x32_bf16 v[82:85], v[134:137], v[196:199], v[82:85]
	v_mfma_f32_16x16x32_bf16 v[74:77], v[142:145], v[196:199], v[74:77]
	s_setprio 0
	s_setprio 1
	v_mfma_f32_16x16x32_bf16 v[118:121], v[146:149], v[162:165], 0
	v_mfma_f32_16x16x32_bf16 v[114:117], v[154:157], v[162:165], 0
	v_mfma_f32_16x16x32_bf16 v[102:105], v[146:149], v[170:173], 0
	v_mfma_f32_16x16x32_bf16 v[94:97], v[154:157], v[170:173], 0
	v_mfma_f32_16x16x32_bf16 v[86:89], v[146:149], v[178:181], 0
	v_mfma_f32_16x16x32_bf16 v[78:81], v[154:157], v[178:181], 0
	v_mfma_f32_16x16x32_bf16 v[70:73], v[146:149], v[186:189], 0
	v_mfma_f32_16x16x32_bf16 v[66:69], v[154:157], v[186:189], 0
	v_mfma_f32_16x16x32_bf16 v[118:121], v[150:153], v[166:169], v[118:121]
	v_mfma_f32_16x16x32_bf16 v[114:117], v[158:161], v[166:169], v[114:117]
	v_mfma_f32_16x16x32_bf16 v[102:105], v[150:153], v[174:177], v[102:105]
	v_mfma_f32_16x16x32_bf16 v[94:97], v[158:161], v[174:177], v[94:97]
	v_mfma_f32_16x16x32_bf16 v[86:89], v[150:153], v[182:185], v[86:89]
	v_mfma_f32_16x16x32_bf16 v[78:81], v[158:161], v[182:185], v[78:81]
	v_mfma_f32_16x16x32_bf16 v[70:73], v[150:153], v[196:199], v[70:73]
	v_mfma_f32_16x16x32_bf16 v[66:69], v[158:161], v[196:199], v[66:69]
	s_setprio 0
	s_barrier
	s_add_i32 s56, s56, s34
	v_lshl_add_u64 v[210:211], s[26:27], 0, v[190:191]
	s_mov_b32 m0, s56
	ds_read_b128 v[162:165], v240 offset:16384
	ds_read_b128 v[166:169], v240 offset:17408
	ds_read_b128 v[170:173], v240 offset:18432
	ds_read_b128 v[174:177], v240 offset:19456
	ds_read_b128 v[178:181], v240 offset:20480
	ds_read_b128 v[182:185], v240 offset:21504
	ds_read_b128 v[186:189], v240 offset:22528
	ds_read_b128 v[196:199], v240 offset:23552
	global_load_lds_dwordx4 v[210:211], off
	s_add_i32 m0, s56, 0x2000
	s_add_u32 s56, s26, 0x80000
	v_lshl_add_u64 v[212:213], s[26:27], 0, v[204:205]
	s_addc_u32 s57, s27, 0
	s_add_i32 s60, s60, s34
	global_load_lds_dwordx4 v[212:213], off
	v_lshl_add_u64 v[214:215], s[56:57], 0, v[190:191]
	s_mov_b32 m0, s60
	v_lshl_add_u64 v[216:217], s[28:29], 0, v[202:203]
	global_load_lds_dwordx4 v[214:215], off
	v_lshl_add_u64 v[214:215], s[56:57], 0, v[204:205]
	s_add_i32 m0, s60, 0x2000
	s_nop 0
	global_load_lds_dwordx4 v[214:215], off
	v_lshl_add_u64 v[214:215], s[28:29], 0, v[200:201]
	s_mov_b32 m0, s23
	s_nop 0
	global_load_lds_dwordx4 v[214:215], off
	s_mov_b32 m0, s35
	s_nop 0
	global_load_lds_dwordx4 v[216:217], off
	s_waitcnt vmcnt(8)
	s_waitcnt lgkmcnt(0)
	s_barrier
	s_setprio 1
	v_mfma_f32_16x16x32_bf16 v[62:65], v[130:133], v[162:165], 0
	v_mfma_f32_16x16x32_bf16 v[58:61], v[138:141], v[162:165], 0
	v_mfma_f32_16x16x32_bf16 v[50:53], v[130:133], v[170:173], 0
	v_mfma_f32_16x16x32_bf16 v[42:45], v[138:141], v[170:173], 0
	v_mfma_f32_16x16x32_bf16 v[34:37], v[130:133], v[178:181], 0
	v_mfma_f32_16x16x32_bf16 v[26:29], v[138:141], v[178:181], 0
	v_mfma_f32_16x16x32_bf16 v[18:21], v[130:133], v[186:189], 0
	v_mfma_f32_16x16x32_bf16 v[10:13], v[138:141], v[186:189], 0
	v_mfma_f32_16x16x32_bf16 v[62:65], v[134:137], v[166:169], v[62:65]
	v_mfma_f32_16x16x32_bf16 v[58:61], v[142:145], v[166:169], v[58:61]
	v_mfma_f32_16x16x32_bf16 v[50:53], v[134:137], v[174:177], v[50:53]
	v_mfma_f32_16x16x32_bf16 v[42:45], v[142:145], v[174:177], v[42:45]
	v_mfma_f32_16x16x32_bf16 v[34:37], v[134:137], v[182:185], v[34:37]
	v_mfma_f32_16x16x32_bf16 v[26:29], v[142:145], v[182:185], v[26:29]
	v_mfma_f32_16x16x32_bf16 v[18:21], v[134:137], v[196:199], v[18:21]
	v_mfma_f32_16x16x32_bf16 v[10:13], v[142:145], v[196:199], v[10:13]
	s_setprio 0
	s_setprio 1
	v_mfma_f32_16x16x32_bf16 v[54:57], v[146:149], v[162:165], 0
	v_mfma_f32_16x16x32_bf16 v[46:49], v[154:157], v[162:165], 0
	v_mfma_f32_16x16x32_bf16 v[38:41], v[146:149], v[170:173], 0
	v_mfma_f32_16x16x32_bf16 v[30:33], v[154:157], v[170:173], 0
	v_mfma_f32_16x16x32_bf16 v[22:25], v[146:149], v[178:181], 0
	v_mfma_f32_16x16x32_bf16 v[14:17], v[154:157], v[178:181], 0
	v_mfma_f32_16x16x32_bf16 v[6:9], v[146:149], v[186:189], 0
	v_mfma_f32_16x16x32_bf16 v[2:5], v[154:157], v[186:189], 0
	v_mfma_f32_16x16x32_bf16 v[54:57], v[150:153], v[166:169], v[54:57]
	v_mfma_f32_16x16x32_bf16 v[46:49], v[158:161], v[166:169], v[46:49]
	v_mfma_f32_16x16x32_bf16 v[38:41], v[150:153], v[174:177], v[38:41]
	v_mfma_f32_16x16x32_bf16 v[30:33], v[158:161], v[174:177], v[30:33]
	v_mfma_f32_16x16x32_bf16 v[22:25], v[150:153], v[182:185], v[22:25]
	v_mfma_f32_16x16x32_bf16 v[14:17], v[158:161], v[182:185], v[14:17]
	v_mfma_f32_16x16x32_bf16 v[6:9], v[150:153], v[196:199], v[6:9]
	v_mfma_f32_16x16x32_bf16 v[2:5], v[158:161], v[196:199], v[2:5]
	s_setprio 0
	s_barrier
	s_add_i32 s56, 0, 0x18000
	s_add_i32 s57, 0, 0x1c000
	v_add_u32_e32 v142, s56, v238
	v_add_u32_e32 v158, s57, v238
	ds_read_b128 v[130:133], v142
	ds_read_b128 v[134:137], v142 offset:1024
	ds_read_b128 v[138:141], v142 offset:2048
	ds_read_b128 v[142:145], v142 offset:3072
	ds_read_b128 v[146:149], v158
	ds_read_b128 v[150:153], v158 offset:1024
	ds_read_b128 v[154:157], v158 offset:2048
	ds_read_b128 v[158:161], v158 offset:3072
	s_add_u32 s28, s28, 0x80000
	s_addc_u32 s29, s29, 0
	s_mov_b32 m0, s41
	v_lshl_add_u64 v[218:219], s[28:29], 0, v[200:201]
	ds_read_b128 v[162:165], v240 offset:32768
	ds_read_b128 v[166:169], v240 offset:33792
	ds_read_b128 v[170:173], v240 offset:34816
	ds_read_b128 v[174:177], v240 offset:35840
	ds_read_b128 v[178:181], v240 offset:36864
	ds_read_b128 v[182:185], v240 offset:37888
	ds_read_b128 v[186:189], v240 offset:38912
	ds_read_b128 v[196:199], v240 offset:39936
	global_load_lds_dwordx4 v[218:219], off
	v_lshl_add_u64 v[218:219], s[28:29], 0, v[202:203]
	s_mov_b32 m0, s42
	s_nop 0
	global_load_lds_dwordx4 v[218:219], off
	s_waitcnt vmcnt(8)
	s_waitcnt lgkmcnt(0)
	s_barrier
	s_setprio 1
	v_mfma_f32_16x16x32_bf16 v[126:129], v[130:133], v[162:165], v[126:129]
	v_mfma_f32_16x16x32_bf16 v[122:125], v[138:141], v[162:165], v[122:125]
	v_mfma_f32_16x16x32_bf16 v[110:113], v[130:133], v[170:173], v[110:113]
	v_mfma_f32_16x16x32_bf16 v[106:109], v[138:141], v[170:173], v[106:109]
	v_mfma_f32_16x16x32_bf16 v[98:101], v[130:133], v[178:181], v[98:101]
	v_mfma_f32_16x16x32_bf16 v[90:93], v[138:141], v[178:181], v[90:93]
	v_mfma_f32_16x16x32_bf16 v[82:85], v[130:133], v[186:189], v[82:85]
	v_mfma_f32_16x16x32_bf16 v[74:77], v[138:141], v[186:189], v[74:77]
	v_mfma_f32_16x16x32_bf16 v[126:129], v[134:137], v[166:169], v[126:129]
	v_mfma_f32_16x16x32_bf16 v[122:125], v[142:145], v[166:169], v[122:125]
	v_mfma_f32_16x16x32_bf16 v[110:113], v[134:137], v[174:177], v[110:113]
	v_mfma_f32_16x16x32_bf16 v[106:109], v[142:145], v[174:177], v[106:109]
	v_mfma_f32_16x16x32_bf16 v[98:101], v[134:137], v[182:185], v[98:101]
	v_mfma_f32_16x16x32_bf16 v[90:93], v[142:145], v[182:185], v[90:93]
	v_mfma_f32_16x16x32_bf16 v[82:85], v[134:137], v[196:199], v[82:85]
	v_mfma_f32_16x16x32_bf16 v[74:77], v[142:145], v[196:199], v[74:77]
	s_setprio 0
	s_setprio 1
	v_mfma_f32_16x16x32_bf16 v[118:121], v[146:149], v[162:165], v[118:121]
	v_mfma_f32_16x16x32_bf16 v[114:117], v[154:157], v[162:165], v[114:117]
	v_mfma_f32_16x16x32_bf16 v[102:105], v[146:149], v[170:173], v[102:105]
	v_mfma_f32_16x16x32_bf16 v[94:97], v[154:157], v[170:173], v[94:97]
	v_mfma_f32_16x16x32_bf16 v[86:89], v[146:149], v[178:181], v[86:89]
	v_mfma_f32_16x16x32_bf16 v[78:81], v[154:157], v[178:181], v[78:81]
	v_mfma_f32_16x16x32_bf16 v[70:73], v[146:149], v[186:189], v[70:73]
	v_mfma_f32_16x16x32_bf16 v[66:69], v[154:157], v[186:189], v[66:69]
	v_mfma_f32_16x16x32_bf16 v[118:121], v[150:153], v[166:169], v[118:121]
	v_mfma_f32_16x16x32_bf16 v[114:117], v[158:161], v[166:169], v[114:117]
	v_mfma_f32_16x16x32_bf16 v[102:105], v[150:153], v[174:177], v[102:105]
	v_mfma_f32_16x16x32_bf16 v[94:97], v[158:161], v[174:177], v[94:97]
	v_mfma_f32_16x16x32_bf16 v[86:89], v[150:153], v[182:185], v[86:89]
	v_mfma_f32_16x16x32_bf16 v[78:81], v[158:161], v[182:185], v[78:81]
	v_mfma_f32_16x16x32_bf16 v[70:73], v[150:153], v[196:199], v[70:73]
	v_mfma_f32_16x16x32_bf16 v[66:69], v[158:161], v[196:199], v[66:69]
	s_setprio 0
	s_barrier
	s_add_i32 s28, s56, s34
	v_lshl_add_u64 v[210:211], v[210:211], 0, s[58:59]
	s_mov_b32 m0, s28
	ds_read_b128 v[162:165], v240 offset:49152
	ds_read_b128 v[166:169], v240 offset:50176
	ds_read_b128 v[170:173], v240 offset:51200
	ds_read_b128 v[174:177], v240 offset:52224
	ds_read_b128 v[178:181], v240 offset:53248
	ds_read_b128 v[182:185], v240 offset:54272
	ds_read_b128 v[186:189], v240 offset:55296
	ds_read_b128 v[196:199], v240 offset:56320
	global_load_lds_dwordx4 v[210:211], off
	s_add_i32 m0, s28, 0x2000
	s_add_u32 s26, s26, 0x80080
	v_lshl_add_u64 v[210:211], v[212:213], 0, s[58:59]
	s_addc_u32 s27, s27, 0
	s_add_i32 s28, s57, s34
	global_load_lds_dwordx4 v[210:211], off
	v_lshl_add_u64 v[210:211], s[26:27], 0, v[190:191]
	s_mov_b32 m0, s28
	s_nop 0
	global_load_lds_dwordx4 v[210:211], off
	v_lshl_add_u64 v[210:211], s[26:27], 0, v[204:205]
	s_add_i32 m0, s28, 0x2000
	s_nop 0
	global_load_lds_dwordx4 v[210:211], off
	v_lshl_add_u64 v[210:211], v[214:215], 0, s[58:59]
	s_mov_b32 m0, s43
	s_nop 0
	global_load_lds_dwordx4 v[210:211], off
	v_lshl_add_u64 v[210:211], v[216:217], 0, s[58:59]
	s_mov_b32 m0, s46
	s_nop 0
	global_load_lds_dwordx4 v[210:211], off
	s_waitcnt vmcnt(8)
	s_waitcnt lgkmcnt(0)
	s_barrier
	s_setprio 1
	v_mfma_f32_16x16x32_bf16 v[62:65], v[130:133], v[162:165], v[62:65]
	v_mfma_f32_16x16x32_bf16 v[58:61], v[138:141], v[162:165], v[58:61]
	v_mfma_f32_16x16x32_bf16 v[50:53], v[130:133], v[170:173], v[50:53]
	v_mfma_f32_16x16x32_bf16 v[42:45], v[138:141], v[170:173], v[42:45]
	v_mfma_f32_16x16x32_bf16 v[34:37], v[130:133], v[178:181], v[34:37]
	v_mfma_f32_16x16x32_bf16 v[26:29], v[138:141], v[178:181], v[26:29]
	v_mfma_f32_16x16x32_bf16 v[18:21], v[130:133], v[186:189], v[18:21]
	v_mfma_f32_16x16x32_bf16 v[10:13], v[138:141], v[186:189], v[10:13]
	v_mfma_f32_16x16x32_bf16 v[62:65], v[134:137], v[166:169], v[62:65]
	v_mfma_f32_16x16x32_bf16 v[58:61], v[142:145], v[166:169], v[58:61]
	v_mfma_f32_16x16x32_bf16 v[50:53], v[134:137], v[174:177], v[50:53]
	v_mfma_f32_16x16x32_bf16 v[42:45], v[142:145], v[174:177], v[42:45]
	v_mfma_f32_16x16x32_bf16 v[34:37], v[134:137], v[182:185], v[34:37]
	v_mfma_f32_16x16x32_bf16 v[26:29], v[142:145], v[182:185], v[26:29]
	v_mfma_f32_16x16x32_bf16 v[18:21], v[134:137], v[196:199], v[18:21]
	v_mfma_f32_16x16x32_bf16 v[10:13], v[142:145], v[196:199], v[10:13]
	s_setprio 0
	s_setprio 1
	v_mfma_f32_16x16x32_bf16 v[54:57], v[146:149], v[162:165], v[54:57]
	v_mfma_f32_16x16x32_bf16 v[46:49], v[154:157], v[162:165], v[46:49]
	v_mfma_f32_16x16x32_bf16 v[38:41], v[146:149], v[170:173], v[38:41]
	v_mfma_f32_16x16x32_bf16 v[30:33], v[154:157], v[170:173], v[30:33]
	v_mfma_f32_16x16x32_bf16 v[22:25], v[146:149], v[178:181], v[22:25]
	v_mfma_f32_16x16x32_bf16 v[14:17], v[154:157], v[178:181], v[14:17]
	v_mfma_f32_16x16x32_bf16 v[6:9], v[146:149], v[186:189], v[6:9]
	v_mfma_f32_16x16x32_bf16 v[2:5], v[154:157], v[186:189], v[2:5]
	v_mfma_f32_16x16x32_bf16 v[54:57], v[150:153], v[166:169], v[54:57]
	v_mfma_f32_16x16x32_bf16 v[46:49], v[158:161], v[166:169], v[46:49]
	v_mfma_f32_16x16x32_bf16 v[38:41], v[150:153], v[174:177], v[38:41]
	v_mfma_f32_16x16x32_bf16 v[30:33], v[158:161], v[174:177], v[30:33]
	v_mfma_f32_16x16x32_bf16 v[22:25], v[150:153], v[182:185], v[22:25]
	v_mfma_f32_16x16x32_bf16 v[14:17], v[158:161], v[182:185], v[14:17]
	v_mfma_f32_16x16x32_bf16 v[6:9], v[150:153], v[196:199], v[6:9]
	v_mfma_f32_16x16x32_bf16 v[2:5], v[158:161], v[196:199], v[2:5]
	s_setprio 0
	s_barrier
	s_add_i32 s55, s55, 2
	s_add_u32 s24, s24, 0x100
	s_addc_u32 s25, s25, 0
	s_add_u32 s52, s52, 0x100
	s_addc_u32 s53, s53, 0
	s_cmp_gt_u32 s55, 29
	s_cbranch_scc1 .Lpeel_done_4
.LBB0_800:
	s_add_u32 s26, s24, 0xfff80080
	s_addc_u32 s27, s25, -1
	s_add_i32 s56, 0, 0x10000
	s_cmp_eq_u32 s55, 28
	s_cselect_b32 s29, s11, s27
	s_cselect_b32 s28, s21, s26
	s_cselect_b32 s27, s9, s53
	s_cselect_b32 s26, s47, s52
	s_add_i32 s60, 0, 0x14000
	v_add_u32_e32 v142, s56, v238
	v_add_u32_e32 v158, s60, v238
	ds_read_b128 v[130:133], v142
	ds_read_b128 v[134:137], v142 offset:1024
	ds_read_b128 v[138:141], v142 offset:2048
	ds_read_b128 v[142:145], v142 offset:3072
	ds_read_b128 v[146:149], v158
	ds_read_b128 v[150:153], v158 offset:1024
	ds_read_b128 v[154:157], v158 offset:2048
	ds_read_b128 v[158:161], v158 offset:3072
	v_lshl_add_u64 v[210:211], s[24:25], 0, v[206:207]
	s_add_i32 m0, s23, 0xc000
	ds_read_b128 v[162:165], v240
	ds_read_b128 v[166:169], v240 offset:1024
	ds_read_b128 v[170:173], v240 offset:2048
	ds_read_b128 v[174:177], v240 offset:3072
	ds_read_b128 v[178:181], v240 offset:4096
	ds_read_b128 v[182:185], v240 offset:5120
	ds_read_b128 v[186:189], v240 offset:6144
	ds_read_b128 v[196:199], v240 offset:7168
	global_load_lds_dwordx4 v[210:211], off
	v_lshl_add_u64 v[210:211], s[24:25], 0, v[208:209]
	s_add_i32 m0, s23, 0xe000
	s_nop 0
	global_load_lds_dwordx4 v[210:211], off
	s_waitcnt vmcnt(8)
	s_waitcnt lgkmcnt(0)
	s_barrier
	s_setprio 1
	v_mfma_f32_16x16x32_bf16 v[126:129], v[130:133], v[162:165], v[126:129]
	v_mfma_f32_16x16x32_bf16 v[122:125], v[138:141], v[162:165], v[122:125]
	v_mfma_f32_16x16x32_bf16 v[110:113], v[130:133], v[170:173], v[110:113]
	v_mfma_f32_16x16x32_bf16 v[106:109], v[138:141], v[170:173], v[106:109]
	v_mfma_f32_16x16x32_bf16 v[98:101], v[130:133], v[178:181], v[98:101]
	v_mfma_f32_16x16x32_bf16 v[90:93], v[138:141], v[178:181], v[90:93]
	v_mfma_f32_16x16x32_bf16 v[82:85], v[130:133], v[186:189], v[82:85]
	v_mfma_f32_16x16x32_bf16 v[74:77], v[138:141], v[186:189], v[74:77]
	v_mfma_f32_16x16x32_bf16 v[126:129], v[134:137], v[166:169], v[126:129]
	v_mfma_f32_16x16x32_bf16 v[122:125], v[142:145], v[166:169], v[122:125]
	v_mfma_f32_16x16x32_bf16 v[110:113], v[134:137], v[174:177], v[110:113]
	v_mfma_f32_16x16x32_bf16 v[106:109], v[142:145], v[174:177], v[106:109]
	v_mfma_f32_16x16x32_bf16 v[98:101], v[134:137], v[182:185], v[98:101]
	v_mfma_f32_16x16x32_bf16 v[90:93], v[142:145], v[182:185], v[90:93]
	v_mfma_f32_16x16x32_bf16 v[82:85], v[134:137], v[196:199], v[82:85]
	v_mfma_f32_16x16x32_bf16 v[74:77], v[142:145], v[196:199], v[74:77]
	s_setprio 0
	s_setprio 1
	v_mfma_f32_16x16x32_bf16 v[118:121], v[146:149], v[162:165], v[118:121]
	v_mfma_f32_16x16x32_bf16 v[114:117], v[154:157], v[162:165], v[114:117]
	v_mfma_f32_16x16x32_bf16 v[102:105], v[146:149], v[170:173], v[102:105]
	v_mfma_f32_16x16x32_bf16 v[94:97], v[154:157], v[170:173], v[94:97]
	v_mfma_f32_16x16x32_bf16 v[86:89], v[146:149], v[178:181], v[86:89]
	v_mfma_f32_16x16x32_bf16 v[78:81], v[154:157], v[178:181], v[78:81]
	v_mfma_f32_16x16x32_bf16 v[70:73], v[146:149], v[186:189], v[70:73]
	v_mfma_f32_16x16x32_bf16 v[66:69], v[154:157], v[186:189], v[66:69]
	v_mfma_f32_16x16x32_bf16 v[118:121], v[150:153], v[166:169], v[118:121]
	v_mfma_f32_16x16x32_bf16 v[114:117], v[158:161], v[166:169], v[114:117]
	v_mfma_f32_16x16x32_bf16 v[102:105], v[150:153], v[174:177], v[102:105]
	v_mfma_f32_16x16x32_bf16 v[94:97], v[158:161], v[174:177], v[94:97]
	v_mfma_f32_16x16x32_bf16 v[86:89], v[150:153], v[182:185], v[86:89]
	v_mfma_f32_16x16x32_bf16 v[78:81], v[158:161], v[182:185], v[78:81]
	v_mfma_f32_16x16x32_bf16 v[70:73], v[150:153], v[196:199], v[70:73]
	v_mfma_f32_16x16x32_bf16 v[66:69], v[158:161], v[196:199], v[66:69]
	s_setprio 0
	s_barrier
	s_add_i32 s56, s56, s34
	v_lshl_add_u64 v[210:211], s[26:27], 0, v[190:191]
	s_mov_b32 m0, s56
	ds_read_b128 v[162:165], v240 offset:16384
	ds_read_b128 v[166:169], v240 offset:17408
	ds_read_b128 v[170:173], v240 offset:18432
	ds_read_b128 v[174:177], v240 offset:19456
	ds_read_b128 v[178:181], v240 offset:20480
	ds_read_b128 v[182:185], v240 offset:21504
	ds_read_b128 v[186:189], v240 offset:22528
	ds_read_b128 v[196:199], v240 offset:23552
	global_load_lds_dwordx4 v[210:211], off
	s_add_i32 m0, s56, 0x2000
	s_add_u32 s56, s26, 0x80000
	v_lshl_add_u64 v[212:213], s[26:27], 0, v[204:205]
	s_addc_u32 s57, s27, 0
	s_add_i32 s60, s60, s34
	global_load_lds_dwordx4 v[212:213], off
	v_lshl_add_u64 v[214:215], s[56:57], 0, v[190:191]
	s_mov_b32 m0, s60
	v_lshl_add_u64 v[216:217], s[28:29], 0, v[202:203]
	global_load_lds_dwordx4 v[214:215], off
	v_lshl_add_u64 v[214:215], s[56:57], 0, v[204:205]
	s_add_i32 m0, s60, 0x2000
	s_nop 0
	global_load_lds_dwordx4 v[214:215], off
	v_lshl_add_u64 v[214:215], s[28:29], 0, v[200:201]
	s_mov_b32 m0, s23
	s_nop 0
	global_load_lds_dwordx4 v[214:215], off
	s_mov_b32 m0, s35
	s_nop 0
	global_load_lds_dwordx4 v[216:217], off
	s_waitcnt vmcnt(8)
	s_waitcnt lgkmcnt(0)
	s_barrier
	s_setprio 1
	v_mfma_f32_16x16x32_bf16 v[62:65], v[130:133], v[162:165], v[62:65]
	v_mfma_f32_16x16x32_bf16 v[58:61], v[138:141], v[162:165], v[58:61]
	v_mfma_f32_16x16x32_bf16 v[50:53], v[130:133], v[170:173], v[50:53]
	v_mfma_f32_16x16x32_bf16 v[42:45], v[138:141], v[170:173], v[42:45]
	v_mfma_f32_16x16x32_bf16 v[34:37], v[130:133], v[178:181], v[34:37]
	v_mfma_f32_16x16x32_bf16 v[26:29], v[138:141], v[178:181], v[26:29]
	v_mfma_f32_16x16x32_bf16 v[18:21], v[130:133], v[186:189], v[18:21]
	v_mfma_f32_16x16x32_bf16 v[10:13], v[138:141], v[186:189], v[10:13]
	v_mfma_f32_16x16x32_bf16 v[62:65], v[134:137], v[166:169], v[62:65]
	v_mfma_f32_16x16x32_bf16 v[58:61], v[142:145], v[166:169], v[58:61]
	v_mfma_f32_16x16x32_bf16 v[50:53], v[134:137], v[174:177], v[50:53]
	v_mfma_f32_16x16x32_bf16 v[42:45], v[142:145], v[174:177], v[42:45]
	v_mfma_f32_16x16x32_bf16 v[34:37], v[134:137], v[182:185], v[34:37]
	v_mfma_f32_16x16x32_bf16 v[26:29], v[142:145], v[182:185], v[26:29]
	v_mfma_f32_16x16x32_bf16 v[18:21], v[134:137], v[196:199], v[18:21]
	v_mfma_f32_16x16x32_bf16 v[10:13], v[142:145], v[196:199], v[10:13]
	s_setprio 0
	s_setprio 1
	v_mfma_f32_16x16x32_bf16 v[54:57], v[146:149], v[162:165], v[54:57]
	v_mfma_f32_16x16x32_bf16 v[46:49], v[154:157], v[162:165], v[46:49]
	v_mfma_f32_16x16x32_bf16 v[38:41], v[146:149], v[170:173], v[38:41]
	v_mfma_f32_16x16x32_bf16 v[30:33], v[154:157], v[170:173], v[30:33]
	v_mfma_f32_16x16x32_bf16 v[22:25], v[146:149], v[178:181], v[22:25]
	v_mfma_f32_16x16x32_bf16 v[14:17], v[154:157], v[178:181], v[14:17]
	v_mfma_f32_16x16x32_bf16 v[6:9], v[146:149], v[186:189], v[6:9]
	v_mfma_f32_16x16x32_bf16 v[2:5], v[154:157], v[186:189], v[2:5]
	v_mfma_f32_16x16x32_bf16 v[54:57], v[150:153], v[166:169], v[54:57]
	v_mfma_f32_16x16x32_bf16 v[46:49], v[158:161], v[166:169], v[46:49]
	v_mfma_f32_16x16x32_bf16 v[38:41], v[150:153], v[174:177], v[38:41]
	v_mfma_f32_16x16x32_bf16 v[30:33], v[158:161], v[174:177], v[30:33]
	v_mfma_f32_16x16x32_bf16 v[22:25], v[150:153], v[182:185], v[22:25]
	v_mfma_f32_16x16x32_bf16 v[14:17], v[158:161], v[182:185], v[14:17]
	v_mfma_f32_16x16x32_bf16 v[6:9], v[150:153], v[196:199], v[6:9]
	v_mfma_f32_16x16x32_bf16 v[2:5], v[158:161], v[196:199], v[2:5]
	s_setprio 0
	s_barrier
	s_add_i32 s56, 0, 0x18000
	s_add_i32 s57, 0, 0x1c000
	v_add_u32_e32 v142, s56, v238
	v_add_u32_e32 v158, s57, v238
	ds_read_b128 v[130:133], v142
	ds_read_b128 v[134:137], v142 offset:1024
	ds_read_b128 v[138:141], v142 offset:2048
	ds_read_b128 v[142:145], v142 offset:3072
	ds_read_b128 v[146:149], v158
	ds_read_b128 v[150:153], v158 offset:1024
	ds_read_b128 v[154:157], v158 offset:2048
	ds_read_b128 v[158:161], v158 offset:3072
	s_add_u32 s28, s28, 0x80000
	s_addc_u32 s29, s29, 0
	s_mov_b32 m0, s41
	v_lshl_add_u64 v[218:219], s[28:29], 0, v[200:201]
	ds_read_b128 v[162:165], v240 offset:32768
	ds_read_b128 v[166:169], v240 offset:33792
	ds_read_b128 v[170:173], v240 offset:34816
	ds_read_b128 v[174:177], v240 offset:35840
	ds_read_b128 v[178:181], v240 offset:36864
	ds_read_b128 v[182:185], v240 offset:37888
	ds_read_b128 v[186:189], v240 offset:38912
	ds_read_b128 v[196:199], v240 offset:39936
	global_load_lds_dwordx4 v[218:219], off
	v_lshl_add_u64 v[218:219], s[28:29], 0, v[202:203]
	s_mov_b32 m0, s42
	s_nop 0
	global_load_lds_dwordx4 v[218:219], off
	s_waitcnt vmcnt(8)
	s_waitcnt lgkmcnt(0)
	s_barrier
	s_setprio 1
	v_mfma_f32_16x16x32_bf16 v[126:129], v[130:133], v[162:165], v[126:129]
	v_mfma_f32_16x16x32_bf16 v[122:125], v[138:141], v[162:165], v[122:125]
	v_mfma_f32_16x16x32_bf16 v[110:113], v[130:133], v[170:173], v[110:113]
	v_mfma_f32_16x16x32_bf16 v[106:109], v[138:141], v[170:173], v[106:109]
	v_mfma_f32_16x16x32_bf16 v[98:101], v[130:133], v[178:181], v[98:101]
	v_mfma_f32_16x16x32_bf16 v[90:93], v[138:141], v[178:181], v[90:93]
	v_mfma_f32_16x16x32_bf16 v[82:85], v[130:133], v[186:189], v[82:85]
	v_mfma_f32_16x16x32_bf16 v[74:77], v[138:141], v[186:189], v[74:77]
	v_mfma_f32_16x16x32_bf16 v[126:129], v[134:137], v[166:169], v[126:129]
	v_mfma_f32_16x16x32_bf16 v[122:125], v[142:145], v[166:169], v[122:125]
	v_mfma_f32_16x16x32_bf16 v[110:113], v[134:137], v[174:177], v[110:113]
	v_mfma_f32_16x16x32_bf16 v[106:109], v[142:145], v[174:177], v[106:109]
	v_mfma_f32_16x16x32_bf16 v[98:101], v[134:137], v[182:185], v[98:101]
	v_mfma_f32_16x16x32_bf16 v[90:93], v[142:145], v[182:185], v[90:93]
	v_mfma_f32_16x16x32_bf16 v[82:85], v[134:137], v[196:199], v[82:85]
	v_mfma_f32_16x16x32_bf16 v[74:77], v[142:145], v[196:199], v[74:77]
	s_setprio 0
	s_setprio 1
	v_mfma_f32_16x16x32_bf16 v[118:121], v[146:149], v[162:165], v[118:121]
	v_mfma_f32_16x16x32_bf16 v[114:117], v[154:157], v[162:165], v[114:117]
	v_mfma_f32_16x16x32_bf16 v[102:105], v[146:149], v[170:173], v[102:105]
	v_mfma_f32_16x16x32_bf16 v[94:97], v[154:157], v[170:173], v[94:97]
	v_mfma_f32_16x16x32_bf16 v[86:89], v[146:149], v[178:181], v[86:89]
	v_mfma_f32_16x16x32_bf16 v[78:81], v[154:157], v[178:181], v[78:81]
	v_mfma_f32_16x16x32_bf16 v[70:73], v[146:149], v[186:189], v[70:73]
	v_mfma_f32_16x16x32_bf16 v[66:69], v[154:157], v[186:189], v[66:69]
	v_mfma_f32_16x16x32_bf16 v[118:121], v[150:153], v[166:169], v[118:121]
	v_mfma_f32_16x16x32_bf16 v[114:117], v[158:161], v[166:169], v[114:117]
	v_mfma_f32_16x16x32_bf16 v[102:105], v[150:153], v[174:177], v[102:105]
	v_mfma_f32_16x16x32_bf16 v[94:97], v[158:161], v[174:177], v[94:97]
	v_mfma_f32_16x16x32_bf16 v[86:89], v[150:153], v[182:185], v[86:89]
	v_mfma_f32_16x16x32_bf16 v[78:81], v[158:161], v[182:185], v[78:81]
	v_mfma_f32_16x16x32_bf16 v[70:73], v[150:153], v[196:199], v[70:73]
	v_mfma_f32_16x16x32_bf16 v[66:69], v[158:161], v[196:199], v[66:69]
	s_setprio 0
	s_barrier
	s_add_i32 s28, s56, s34
	v_lshl_add_u64 v[210:211], v[210:211], 0, s[58:59]
	s_mov_b32 m0, s28
	ds_read_b128 v[162:165], v240 offset:49152
	ds_read_b128 v[166:169], v240 offset:50176
	ds_read_b128 v[170:173], v240 offset:51200
	ds_read_b128 v[174:177], v240 offset:52224
	ds_read_b128 v[178:181], v240 offset:53248
	ds_read_b128 v[182:185], v240 offset:54272
	ds_read_b128 v[186:189], v240 offset:55296
	ds_read_b128 v[196:199], v240 offset:56320
	global_load_lds_dwordx4 v[210:211], off
	s_add_i32 m0, s28, 0x2000
	s_add_u32 s26, s26, 0x80080
	v_lshl_add_u64 v[210:211], v[212:213], 0, s[58:59]
	s_addc_u32 s27, s27, 0
	s_add_i32 s28, s57, s34
	global_load_lds_dwordx4 v[210:211], off
	v_lshl_add_u64 v[210:211], s[26:27], 0, v[190:191]
	s_mov_b32 m0, s28
	s_nop 0
	global_load_lds_dwordx4 v[210:211], off
	v_lshl_add_u64 v[210:211], s[26:27], 0, v[204:205]
	s_add_i32 m0, s28, 0x2000
	s_nop 0
	global_load_lds_dwordx4 v[210:211], off
	v_lshl_add_u64 v[210:211], v[214:215], 0, s[58:59]
	s_mov_b32 m0, s43
	s_nop 0
	global_load_lds_dwordx4 v[210:211], off
	v_lshl_add_u64 v[210:211], v[216:217], 0, s[58:59]
	s_mov_b32 m0, s46
	s_nop 0
	global_load_lds_dwordx4 v[210:211], off
	s_waitcnt vmcnt(8)
	s_waitcnt lgkmcnt(0)
	s_barrier
	s_setprio 1
	v_mfma_f32_16x16x32_bf16 v[62:65], v[130:133], v[162:165], v[62:65]
	v_mfma_f32_16x16x32_bf16 v[58:61], v[138:141], v[162:165], v[58:61]
	v_mfma_f32_16x16x32_bf16 v[50:53], v[130:133], v[170:173], v[50:53]
	v_mfma_f32_16x16x32_bf16 v[42:45], v[138:141], v[170:173], v[42:45]
	v_mfma_f32_16x16x32_bf16 v[34:37], v[130:133], v[178:181], v[34:37]
	v_mfma_f32_16x16x32_bf16 v[26:29], v[138:141], v[178:181], v[26:29]
	v_mfma_f32_16x16x32_bf16 v[18:21], v[130:133], v[186:189], v[18:21]
	v_mfma_f32_16x16x32_bf16 v[10:13], v[138:141], v[186:189], v[10:13]
	v_mfma_f32_16x16x32_bf16 v[62:65], v[134:137], v[166:169], v[62:65]
	v_mfma_f32_16x16x32_bf16 v[58:61], v[142:145], v[166:169], v[58:61]
	v_mfma_f32_16x16x32_bf16 v[50:53], v[134:137], v[174:177], v[50:53]
	v_mfma_f32_16x16x32_bf16 v[42:45], v[142:145], v[174:177], v[42:45]
	v_mfma_f32_16x16x32_bf16 v[34:37], v[134:137], v[182:185], v[34:37]
	v_mfma_f32_16x16x32_bf16 v[26:29], v[142:145], v[182:185], v[26:29]
	v_mfma_f32_16x16x32_bf16 v[18:21], v[134:137], v[196:199], v[18:21]
	v_mfma_f32_16x16x32_bf16 v[10:13], v[142:145], v[196:199], v[10:13]
	s_setprio 0
	s_setprio 1
	v_mfma_f32_16x16x32_bf16 v[54:57], v[146:149], v[162:165], v[54:57]
	v_mfma_f32_16x16x32_bf16 v[46:49], v[154:157], v[162:165], v[46:49]
	v_mfma_f32_16x16x32_bf16 v[38:41], v[146:149], v[170:173], v[38:41]
	v_mfma_f32_16x16x32_bf16 v[30:33], v[154:157], v[170:173], v[30:33]
	v_mfma_f32_16x16x32_bf16 v[22:25], v[146:149], v[178:181], v[22:25]
	v_mfma_f32_16x16x32_bf16 v[14:17], v[154:157], v[178:181], v[14:17]
	v_mfma_f32_16x16x32_bf16 v[6:9], v[146:149], v[186:189], v[6:9]
	v_mfma_f32_16x16x32_bf16 v[2:5], v[154:157], v[186:189], v[2:5]
	v_mfma_f32_16x16x32_bf16 v[54:57], v[150:153], v[166:169], v[54:57]
	v_mfma_f32_16x16x32_bf16 v[46:49], v[158:161], v[166:169], v[46:49]
	v_mfma_f32_16x16x32_bf16 v[38:41], v[150:153], v[174:177], v[38:41]
	v_mfma_f32_16x16x32_bf16 v[30:33], v[158:161], v[174:177], v[30:33]
	v_mfma_f32_16x16x32_bf16 v[22:25], v[150:153], v[182:185], v[22:25]
	v_mfma_f32_16x16x32_bf16 v[14:17], v[158:161], v[182:185], v[14:17]
	v_mfma_f32_16x16x32_bf16 v[6:9], v[150:153], v[196:199], v[6:9]
	v_mfma_f32_16x16x32_bf16 v[2:5], v[158:161], v[196:199], v[2:5]
	s_setprio 0
	s_barrier
	s_add_i32 s55, s55, 2
	s_add_u32 s24, s24, 0x100
	s_addc_u32 s25, s25, 0
	s_add_u32 s52, s52, 0x100
	s_addc_u32 s53, s53, 0
	s_cmp_gt_u32 s55, 29
	s_cbranch_scc0 .LBB0_800

.LBB0_822:
	s_ashr_i32 s17, s16, 31
	s_lshl_b64 s[22:23], s[16:17], 20
	v_readlane_b32 s0, v254, 60
	s_add_u32 s22, s0, s22
	v_readlane_b32 s0, v254, 61
	s_addc_u32 s23, s0, s23
	s_and_b64 s[24:25], s[20:21], exec
	s_cselect_b32 s17, s23, s31
	s_cselect_b32 s27, s22, s30
	s_ashr_i32 s15, s14, 31
	s_lshl_b64 s[24:25], s[14:15], 20
	v_readlane_b32 s0, v254, 40
	v_readlane_b32 s1, v254, 41
	s_add_u32 s24, s0, s24
	s_addc_u32 s25, s1, s25
	s_and_b64 s[52:53], s[20:21], exec
	s_cselect_b32 s15, s25, s35
	s_cselect_b32 s29, s24, s34
	s_add_u32 s30, s30, 0x80080
	s_addc_u32 s31, s31, 0
	s_add_u32 s81, s34, 0x100
	s_addc_u32 s88, s35, 0
	s_mov_b32 s89, -2
	v_readlane_b32 s90, v255, 49
	s_nop 3
	s_cmp_eq_u32 s90, 6
	v_writelane_b32 v255, 6, 49
	s_cbranch_scc0 .Ltrip0_strict_5
	s_add_u32 s34, s30, 0xfff80080
	s_addc_u32 s35, s31, -1
	s_add_i32 s90, 0, 0x10000
	s_cmp_eq_u32 s89, 28
	s_cselect_b32 s53, s17, s35
	s_cselect_b32 s52, s27, s34
	s_cselect_b32 s35, s15, s88
	s_cselect_b32 s34, s29, s81
	s_add_i32 s96, 0, 0x14000
	v_add_u32_e32 v142, s90, v220
	v_add_u32_e32 v158, s96, v220
	ds_read_b128 v[130:133], v142
	ds_read_b128 v[134:137], v142 offset:1024
	ds_read_b128 v[138:141], v142 offset:2048
	ds_read_b128 v[142:145], v142 offset:3072
	ds_read_b128 v[146:149], v158
	ds_read_b128 v[150:153], v158 offset:1024
	ds_read_b128 v[154:157], v158 offset:2048
	ds_read_b128 v[158:161], v158 offset:3072
	v_lshl_add_u64 v[210:211], s[30:31], 0, v[202:203]
	s_add_i32 m0, s55, 0xc000
	ds_read_b128 v[162:165], v222
	ds_read_b128 v[166:169], v222 offset:1024
	ds_read_b128 v[170:173], v222 offset:2048
	ds_read_b128 v[174:177], v222 offset:3072
	ds_read_b128 v[178:181], v222 offset:4096
	ds_read_b128 v[182:185], v222 offset:5120
	ds_read_b128 v[196:199], v222 offset:6144
	ds_read_b128 v[206:209], v222 offset:7168
	global_load_lds_dwordx4 v[210:211], off
	v_lshl_add_u64 v[210:211], s[30:31], 0, v[204:205]
	s_add_i32 m0, s55, 0xe000
	s_nop 0
	global_load_lds_dwordx4 v[210:211], off
	s_waitcnt vmcnt(24)
	s_waitcnt lgkmcnt(0)
	s_barrier
	s_setprio 1
	v_mfma_f32_16x16x32_bf16 v[126:129], v[130:133], v[162:165], 0
	v_mfma_f32_16x16x32_bf16 v[122:125], v[138:141], v[162:165], 0
	v_mfma_f32_16x16x32_bf16 v[110:113], v[130:133], v[170:173], 0
	v_mfma_f32_16x16x32_bf16 v[106:109], v[138:141], v[170:173], 0
	v_mfma_f32_16x16x32_bf16 v[94:97], v[130:133], v[178:181], 0
	v_mfma_f32_16x16x32_bf16 v[90:93], v[138:141], v[178:181], 0
	v_mfma_f32_16x16x32_bf16 v[78:81], v[130:133], v[196:199], 0
	v_mfma_f32_16x16x32_bf16 v[74:77], v[138:141], v[196:199], 0
	v_mfma_f32_16x16x32_bf16 v[126:129], v[134:137], v[166:169], v[126:129]
	v_mfma_f32_16x16x32_bf16 v[122:125], v[142:145], v[166:169], v[122:125]
	v_mfma_f32_16x16x32_bf16 v[110:113], v[134:137], v[174:177], v[110:113]
	v_mfma_f32_16x16x32_bf16 v[106:109], v[142:145], v[174:177], v[106:109]
	v_mfma_f32_16x16x32_bf16 v[94:97], v[134:137], v[182:185], v[94:97]
	v_mfma_f32_16x16x32_bf16 v[90:93], v[142:145], v[182:185], v[90:93]
	v_mfma_f32_16x16x32_bf16 v[78:81], v[134:137], v[206:209], v[78:81]
	v_mfma_f32_16x16x32_bf16 v[74:77], v[142:145], v[206:209], v[74:77]
	s_setprio 0
	s_setprio 1
	v_mfma_f32_16x16x32_bf16 v[118:121], v[146:149], v[162:165], 0
	v_mfma_f32_16x16x32_bf16 v[114:117], v[154:157], v[162:165], 0
	v_mfma_f32_16x16x32_bf16 v[102:105], v[146:149], v[170:173], 0
	v_mfma_f32_16x16x32_bf16 v[98:101], v[154:157], v[170:173], 0
	v_mfma_f32_16x16x32_bf16 v[86:89], v[146:149], v[178:181], 0
	v_mfma_f32_16x16x32_bf16 v[82:85], v[154:157], v[178:181], 0
	v_mfma_f32_16x16x32_bf16 v[70:73], v[146:149], v[196:199], 0
	v_mfma_f32_16x16x32_bf16 v[66:69], v[154:157], v[196:199], 0
	v_mfma_f32_16x16x32_bf16 v[118:121], v[150:153], v[166:169], v[118:121]
	v_mfma_f32_16x16x32_bf16 v[114:117], v[158:161], v[166:169], v[114:117]
	v_mfma_f32_16x16x32_bf16 v[102:105], v[150:153], v[174:177], v[102:105]
	v_mfma_f32_16x16x32_bf16 v[98:101], v[158:161], v[174:177], v[98:101]
	v_mfma_f32_16x16x32_bf16 v[86:89], v[150:153], v[182:185], v[86:89]
	v_mfma_f32_16x16x32_bf16 v[82:85], v[158:161], v[182:185], v[82:85]
	v_mfma_f32_16x16x32_bf16 v[70:73], v[150:153], v[206:209], v[70:73]
	v_mfma_f32_16x16x32_bf16 v[66:69], v[158:161], v[206:209], v[66:69]
	s_setprio 0
	s_barrier
	s_add_i32 s90, s90, s47
	v_lshl_add_u64 v[210:211], s[34:35], 0, v[190:191]
	s_mov_b32 m0, s90
	ds_read_b128 v[162:165], v222 offset:16384
	ds_read_b128 v[166:169], v222 offset:17408
	ds_read_b128 v[170:173], v222 offset:18432
	ds_read_b128 v[174:177], v222 offset:19456
	ds_read_b128 v[178:181], v222 offset:20480
	ds_read_b128 v[182:185], v222 offset:21504
	ds_read_b128 v[196:199], v222 offset:22528
	ds_read_b128 v[206:209], v222 offset:23552
	global_load_lds_dwordx4 v[210:211], off
	s_add_i32 m0, s90, 0x2000
	s_add_u32 s90, s34, 0x80000
	v_lshl_add_u64 v[212:213], s[34:35], 0, v[200:201]
	s_addc_u32 s91, s35, 0
	s_add_i32 s96, s96, s47
	global_load_lds_dwordx4 v[212:213], off
	v_lshl_add_u64 v[214:215], s[90:91], 0, v[190:191]
	s_mov_b32 m0, s96
	v_lshl_add_u64 v[216:217], s[52:53], 0, v[188:189]
	global_load_lds_dwordx4 v[214:215], off
	v_lshl_add_u64 v[214:215], s[90:91], 0, v[200:201]
	s_add_i32 m0, s96, 0x2000
	s_nop 0
	global_load_lds_dwordx4 v[214:215], off
	v_lshl_add_u64 v[214:215], s[52:53], 0, v[186:187]
	s_mov_b32 m0, s55
	s_nop 0
	global_load_lds_dwordx4 v[214:215], off
	s_mov_b32 m0, s56
	s_nop 0
	global_load_lds_dwordx4 v[216:217], off
	s_waitcnt vmcnt(24)
	s_waitcnt lgkmcnt(0)
	s_barrier
	s_setprio 1
	v_mfma_f32_16x16x32_bf16 v[62:65], v[130:133], v[162:165], 0
	v_mfma_f32_16x16x32_bf16 v[58:61], v[138:141], v[162:165], 0
	v_mfma_f32_16x16x32_bf16 v[46:49], v[130:133], v[170:173], 0
	v_mfma_f32_16x16x32_bf16 v[42:45], v[138:141], v[170:173], 0
	v_mfma_f32_16x16x32_bf16 v[30:33], v[130:133], v[178:181], 0
	v_mfma_f32_16x16x32_bf16 v[26:29], v[138:141], v[178:181], 0
	v_mfma_f32_16x16x32_bf16 v[14:17], v[130:133], v[196:199], 0
	v_mfma_f32_16x16x32_bf16 v[10:13], v[138:141], v[196:199], 0
	v_mfma_f32_16x16x32_bf16 v[62:65], v[134:137], v[166:169], v[62:65]
	v_mfma_f32_16x16x32_bf16 v[58:61], v[142:145], v[166:169], v[58:61]
	v_mfma_f32_16x16x32_bf16 v[46:49], v[134:137], v[174:177], v[46:49]
	v_mfma_f32_16x16x32_bf16 v[42:45], v[142:145], v[174:177], v[42:45]
	v_mfma_f32_16x16x32_bf16 v[30:33], v[134:137], v[182:185], v[30:33]
	v_mfma_f32_16x16x32_bf16 v[26:29], v[142:145], v[182:185], v[26:29]
	v_mfma_f32_16x16x32_bf16 v[14:17], v[134:137], v[206:209], v[14:17]
	v_mfma_f32_16x16x32_bf16 v[10:13], v[142:145], v[206:209], v[10:13]
	s_setprio 0
	s_setprio 1
	v_mfma_f32_16x16x32_bf16 v[54:57], v[146:149], v[162:165], 0
	v_mfma_f32_16x16x32_bf16 v[50:53], v[154:157], v[162:165], 0
	v_mfma_f32_16x16x32_bf16 v[38:41], v[146:149], v[170:173], 0
	v_mfma_f32_16x16x32_bf16 v[34:37], v[154:157], v[170:173], 0
	v_mfma_f32_16x16x32_bf16 v[22:25], v[146:149], v[178:181], 0
	v_mfma_f32_16x16x32_bf16 v[18:21], v[154:157], v[178:181], 0
	v_mfma_f32_16x16x32_bf16 v[6:9], v[146:149], v[196:199], 0
	v_mfma_f32_16x16x32_bf16 v[2:5], v[154:157], v[196:199], 0
	v_mfma_f32_16x16x32_bf16 v[54:57], v[150:153], v[166:169], v[54:57]
	v_mfma_f32_16x16x32_bf16 v[50:53], v[158:161], v[166:169], v[50:53]
	v_mfma_f32_16x16x32_bf16 v[38:41], v[150:153], v[174:177], v[38:41]
	v_mfma_f32_16x16x32_bf16 v[34:37], v[158:161], v[174:177], v[34:37]
	v_mfma_f32_16x16x32_bf16 v[22:25], v[150:153], v[182:185], v[22:25]
	v_mfma_f32_16x16x32_bf16 v[18:21], v[158:161], v[182:185], v[18:21]
	v_mfma_f32_16x16x32_bf16 v[6:9], v[150:153], v[206:209], v[6:9]
	v_mfma_f32_16x16x32_bf16 v[2:5], v[158:161], v[206:209], v[2:5]
	s_setprio 0
	s_barrier
	s_add_i32 s90, 0, 0x18000
	s_add_i32 s91, 0, 0x1c000
	v_add_u32_e32 v142, s90, v220
	v_add_u32_e32 v158, s91, v220
	ds_read_b128 v[130:133], v142
	ds_read_b128 v[134:137], v142 offset:1024
	ds_read_b128 v[138:141], v142 offset:2048
	ds_read_b128 v[142:145], v142 offset:3072
	ds_read_b128 v[146:149], v158
	ds_read_b128 v[150:153], v158 offset:1024
	ds_read_b128 v[154:157], v158 offset:2048
	ds_read_b128 v[158:161], v158 offset:3072
	s_add_u32 s52, s52, 0x80000
	s_addc_u32 s53, s53, 0
	s_mov_b32 m0, s57
	v_lshl_add_u64 v[218:219], s[52:53], 0, v[186:187]
	ds_read_b128 v[162:165], v222 offset:32768
	ds_read_b128 v[166:169], v222 offset:33792
	ds_read_b128 v[170:173], v222 offset:34816
	ds_read_b128 v[174:177], v222 offset:35840
	ds_read_b128 v[178:181], v222 offset:36864
	ds_read_b128 v[182:185], v222 offset:37888
	ds_read_b128 v[196:199], v222 offset:38912
	ds_read_b128 v[206:209], v222 offset:39936
	global_load_lds_dwordx4 v[218:219], off
	v_lshl_add_u64 v[218:219], s[52:53], 0, v[188:189]
	s_mov_b32 m0, s60
	s_nop 0
	global_load_lds_dwordx4 v[218:219], off
	s_waitcnt vmcnt(8)
	s_waitcnt lgkmcnt(0)
	s_barrier
	s_setprio 1
	v_mfma_f32_16x16x32_bf16 v[126:129], v[130:133], v[162:165], v[126:129]
	v_mfma_f32_16x16x32_bf16 v[122:125], v[138:141], v[162:165], v[122:125]
	v_mfma_f32_16x16x32_bf16 v[110:113], v[130:133], v[170:173], v[110:113]
	v_mfma_f32_16x16x32_bf16 v[106:109], v[138:141], v[170:173], v[106:109]
	v_mfma_f32_16x16x32_bf16 v[94:97], v[130:133], v[178:181], v[94:97]
	v_mfma_f32_16x16x32_bf16 v[90:93], v[138:141], v[178:181], v[90:93]
	v_mfma_f32_16x16x32_bf16 v[78:81], v[130:133], v[196:199], v[78:81]
	v_mfma_f32_16x16x32_bf16 v[74:77], v[138:141], v[196:199], v[74:77]
	v_mfma_f32_16x16x32_bf16 v[126:129], v[134:137], v[166:169], v[126:129]
	v_mfma_f32_16x16x32_bf16 v[122:125], v[142:145], v[166:169], v[122:125]
	v_mfma_f32_16x16x32_bf16 v[110:113], v[134:137], v[174:177], v[110:113]
	v_mfma_f32_16x16x32_bf16 v[106:109], v[142:145], v[174:177], v[106:109]
	v_mfma_f32_16x16x32_bf16 v[94:97], v[134:137], v[182:185], v[94:97]
	v_mfma_f32_16x16x32_bf16 v[90:93], v[142:145], v[182:185], v[90:93]
	v_mfma_f32_16x16x32_bf16 v[78:81], v[134:137], v[206:209], v[78:81]
	v_mfma_f32_16x16x32_bf16 v[74:77], v[142:145], v[206:209], v[74:77]
	s_setprio 0
	s_setprio 1
	v_mfma_f32_16x16x32_bf16 v[118:121], v[146:149], v[162:165], v[118:121]
	v_mfma_f32_16x16x32_bf16 v[114:117], v[154:157], v[162:165], v[114:117]
	v_mfma_f32_16x16x32_bf16 v[102:105], v[146:149], v[170:173], v[102:105]
	v_mfma_f32_16x16x32_bf16 v[98:101], v[154:157], v[170:173], v[98:101]
	v_mfma_f32_16x16x32_bf16 v[86:89], v[146:149], v[178:181], v[86:89]
	v_mfma_f32_16x16x32_bf16 v[82:85], v[154:157], v[178:181], v[82:85]
	v_mfma_f32_16x16x32_bf16 v[70:73], v[146:149], v[196:199], v[70:73]
	v_mfma_f32_16x16x32_bf16 v[66:69], v[154:157], v[196:199], v[66:69]
	v_mfma_f32_16x16x32_bf16 v[118:121], v[150:153], v[166:169], v[118:121]
	v_mfma_f32_16x16x32_bf16 v[114:117], v[158:161], v[166:169], v[114:117]
	v_mfma_f32_16x16x32_bf16 v[102:105], v[150:153], v[174:177], v[102:105]
	v_mfma_f32_16x16x32_bf16 v[98:101], v[158:161], v[174:177], v[98:101]
	v_mfma_f32_16x16x32_bf16 v[86:89], v[150:153], v[182:185], v[86:89]
	v_mfma_f32_16x16x32_bf16 v[82:85], v[158:161], v[182:185], v[82:85]
	v_mfma_f32_16x16x32_bf16 v[70:73], v[150:153], v[206:209], v[70:73]
	v_mfma_f32_16x16x32_bf16 v[66:69], v[158:161], v[206:209], v[66:69]
	s_setprio 0
	s_barrier
	s_add_i32 s52, s90, s47
	v_lshl_add_u64 v[210:211], v[210:211], 0, s[58:59]
	s_mov_b32 m0, s52
	ds_read_b128 v[162:165], v222 offset:49152
	ds_read_b128 v[166:169], v222 offset:50176
	ds_read_b128 v[170:173], v222 offset:51200
	ds_read_b128 v[174:177], v222 offset:52224
	ds_read_b128 v[178:181], v222 offset:53248
	ds_read_b128 v[182:185], v222 offset:54272
	ds_read_b128 v[196:199], v222 offset:55296
	ds_read_b128 v[206:209], v222 offset:56320
	global_load_lds_dwordx4 v[210:211], off
	s_add_i32 m0, s52, 0x2000
	s_add_u32 s34, s34, 0x80080
	v_lshl_add_u64 v[210:211], v[212:213], 0, s[58:59]
	s_addc_u32 s35, s35, 0
	s_add_i32 s52, s91, s47
	global_load_lds_dwordx4 v[210:211], off
	v_lshl_add_u64 v[210:211], s[34:35], 0, v[190:191]
	s_mov_b32 m0, s52
	s_nop 0
	global_load_lds_dwordx4 v[210:211], off
	v_lshl_add_u64 v[210:211], s[34:35], 0, v[200:201]
	s_add_i32 m0, s52, 0x2000
	s_nop 0
	global_load_lds_dwordx4 v[210:211], off
	v_lshl_add_u64 v[210:211], v[214:215], 0, s[58:59]
	s_mov_b32 m0, s61
	s_nop 0
	global_load_lds_dwordx4 v[210:211], off
	v_lshl_add_u64 v[210:211], v[216:217], 0, s[58:59]
	s_mov_b32 m0, s69
	s_nop 0
	global_load_lds_dwordx4 v[210:211], off
	s_waitcnt vmcnt(8)
	s_waitcnt lgkmcnt(0)
	s_barrier
	s_setprio 1
	v_mfma_f32_16x16x32_bf16 v[62:65], v[130:133], v[162:165], v[62:65]
	v_mfma_f32_16x16x32_bf16 v[58:61], v[138:141], v[162:165], v[58:61]
	v_mfma_f32_16x16x32_bf16 v[46:49], v[130:133], v[170:173], v[46:49]
	v_mfma_f32_16x16x32_bf16 v[42:45], v[138:141], v[170:173], v[42:45]
	v_mfma_f32_16x16x32_bf16 v[30:33], v[130:133], v[178:181], v[30:33]
	v_mfma_f32_16x16x32_bf16 v[26:29], v[138:141], v[178:181], v[26:29]
	v_mfma_f32_16x16x32_bf16 v[14:17], v[130:133], v[196:199], v[14:17]
	v_mfma_f32_16x16x32_bf16 v[10:13], v[138:141], v[196:199], v[10:13]
	v_mfma_f32_16x16x32_bf16 v[62:65], v[134:137], v[166:169], v[62:65]
	v_mfma_f32_16x16x32_bf16 v[58:61], v[142:145], v[166:169], v[58:61]
	v_mfma_f32_16x16x32_bf16 v[46:49], v[134:137], v[174:177], v[46:49]
	v_mfma_f32_16x16x32_bf16 v[42:45], v[142:145], v[174:177], v[42:45]
	v_mfma_f32_16x16x32_bf16 v[30:33], v[134:137], v[182:185], v[30:33]
	v_mfma_f32_16x16x32_bf16 v[26:29], v[142:145], v[182:185], v[26:29]
	v_mfma_f32_16x16x32_bf16 v[14:17], v[134:137], v[206:209], v[14:17]
	v_mfma_f32_16x16x32_bf16 v[10:13], v[142:145], v[206:209], v[10:13]
	s_setprio 0
	s_setprio 1
	v_mfma_f32_16x16x32_bf16 v[54:57], v[146:149], v[162:165], v[54:57]
	v_mfma_f32_16x16x32_bf16 v[50:53], v[154:157], v[162:165], v[50:53]
	v_mfma_f32_16x16x32_bf16 v[38:41], v[146:149], v[170:173], v[38:41]
	v_mfma_f32_16x16x32_bf16 v[34:37], v[154:157], v[170:173], v[34:37]
	v_mfma_f32_16x16x32_bf16 v[22:25], v[146:149], v[178:181], v[22:25]
	v_mfma_f32_16x16x32_bf16 v[18:21], v[154:157], v[178:181], v[18:21]
	v_mfma_f32_16x16x32_bf16 v[6:9], v[146:149], v[196:199], v[6:9]
	v_mfma_f32_16x16x32_bf16 v[2:5], v[154:157], v[196:199], v[2:5]
	v_mfma_f32_16x16x32_bf16 v[54:57], v[150:153], v[166:169], v[54:57]
	v_mfma_f32_16x16x32_bf16 v[50:53], v[158:161], v[166:169], v[50:53]
	v_mfma_f32_16x16x32_bf16 v[38:41], v[150:153], v[174:177], v[38:41]
	v_mfma_f32_16x16x32_bf16 v[34:37], v[158:161], v[174:177], v[34:37]
	v_mfma_f32_16x16x32_bf16 v[22:25], v[150:153], v[182:185], v[22:25]
	v_mfma_f32_16x16x32_bf16 v[18:21], v[158:161], v[182:185], v[18:21]
	v_mfma_f32_16x16x32_bf16 v[6:9], v[150:153], v[206:209], v[6:9]
	v_mfma_f32_16x16x32_bf16 v[2:5], v[158:161], v[206:209], v[2:5]
	s_setprio 0
	s_barrier
	s_add_i32 s89, s89, 2
	s_add_u32 s30, s30, 0x100
	s_addc_u32 s31, s31, 0
	s_add_u32 s81, s81, 0x100
	s_addc_u32 s88, s88, 0
	s_cmp_gt_u32 s89, 29
	s_cbranch_scc1 .Lpeel_done_5
	s_branch .LBB0_823
.Ltrip0_strict_5:
	s_add_u32 s34, s30, 0xfff80080
	s_addc_u32 s35, s31, -1
	s_add_i32 s90, 0, 0x10000
	s_cmp_eq_u32 s89, 28
	s_cselect_b32 s53, s17, s35
	s_cselect_b32 s52, s27, s34
	s_cselect_b32 s35, s15, s88
	s_cselect_b32 s34, s29, s81
	s_add_i32 s96, 0, 0x14000
	v_add_u32_e32 v142, s90, v220
	v_add_u32_e32 v158, s96, v220
	ds_read_b128 v[130:133], v142
	ds_read_b128 v[134:137], v142 offset:1024
	ds_read_b128 v[138:141], v142 offset:2048
	ds_read_b128 v[142:145], v142 offset:3072
	ds_read_b128 v[146:149], v158
	ds_read_b128 v[150:153], v158 offset:1024
	ds_read_b128 v[154:157], v158 offset:2048
	ds_read_b128 v[158:161], v158 offset:3072
	v_lshl_add_u64 v[210:211], s[30:31], 0, v[202:203]
	s_add_i32 m0, s55, 0xc000
	ds_read_b128 v[162:165], v222
	ds_read_b128 v[166:169], v222 offset:1024
	ds_read_b128 v[170:173], v222 offset:2048
	ds_read_b128 v[174:177], v222 offset:3072
	ds_read_b128 v[178:181], v222 offset:4096
	ds_read_b128 v[182:185], v222 offset:5120
	ds_read_b128 v[196:199], v222 offset:6144
	ds_read_b128 v[206:209], v222 offset:7168
	global_load_lds_dwordx4 v[210:211], off
	v_lshl_add_u64 v[210:211], s[30:31], 0, v[204:205]
	s_add_i32 m0, s55, 0xe000
	s_nop 0
	global_load_lds_dwordx4 v[210:211], off
	s_waitcnt vmcnt(8)
	s_waitcnt lgkmcnt(0)
	s_barrier
	s_setprio 1
	v_mfma_f32_16x16x32_bf16 v[126:129], v[130:133], v[162:165], 0
	v_mfma_f32_16x16x32_bf16 v[122:125], v[138:141], v[162:165], 0
	v_mfma_f32_16x16x32_bf16 v[110:113], v[130:133], v[170:173], 0
	v_mfma_f32_16x16x32_bf16 v[106:109], v[138:141], v[170:173], 0
	v_mfma_f32_16x16x32_bf16 v[94:97], v[130:133], v[178:181], 0
	v_mfma_f32_16x16x32_bf16 v[90:93], v[138:141], v[178:181], 0
	v_mfma_f32_16x16x32_bf16 v[78:81], v[130:133], v[196:199], 0
	v_mfma_f32_16x16x32_bf16 v[74:77], v[138:141], v[196:199], 0
	v_mfma_f32_16x16x32_bf16 v[126:129], v[134:137], v[166:169], v[126:129]
	v_mfma_f32_16x16x32_bf16 v[122:125], v[142:145], v[166:169], v[122:125]
	v_mfma_f32_16x16x32_bf16 v[110:113], v[134:137], v[174:177], v[110:113]
	v_mfma_f32_16x16x32_bf16 v[106:109], v[142:145], v[174:177], v[106:109]
	v_mfma_f32_16x16x32_bf16 v[94:97], v[134:137], v[182:185], v[94:97]
	v_mfma_f32_16x16x32_bf16 v[90:93], v[142:145], v[182:185], v[90:93]
	v_mfma_f32_16x16x32_bf16 v[78:81], v[134:137], v[206:209], v[78:81]
	v_mfma_f32_16x16x32_bf16 v[74:77], v[142:145], v[206:209], v[74:77]
	s_setprio 0
	s_setprio 1
	v_mfma_f32_16x16x32_bf16 v[118:121], v[146:149], v[162:165], 0
	v_mfma_f32_16x16x32_bf16 v[114:117], v[154:157], v[162:165], 0
	v_mfma_f32_16x16x32_bf16 v[102:105], v[146:149], v[170:173], 0
	v_mfma_f32_16x16x32_bf16 v[98:101], v[154:157], v[170:173], 0
	v_mfma_f32_16x16x32_bf16 v[86:89], v[146:149], v[178:181], 0
	v_mfma_f32_16x16x32_bf16 v[82:85], v[154:157], v[178:181], 0
	v_mfma_f32_16x16x32_bf16 v[70:73], v[146:149], v[196:199], 0
	v_mfma_f32_16x16x32_bf16 v[66:69], v[154:157], v[196:199], 0
	v_mfma_f32_16x16x32_bf16 v[118:121], v[150:153], v[166:169], v[118:121]
	v_mfma_f32_16x16x32_bf16 v[114:117], v[158:161], v[166:169], v[114:117]
	v_mfma_f32_16x16x32_bf16 v[102:105], v[150:153], v[174:177], v[102:105]
	v_mfma_f32_16x16x32_bf16 v[98:101], v[158:161], v[174:177], v[98:101]
	v_mfma_f32_16x16x32_bf16 v[86:89], v[150:153], v[182:185], v[86:89]
	v_mfma_f32_16x16x32_bf16 v[82:85], v[158:161], v[182:185], v[82:85]
	v_mfma_f32_16x16x32_bf16 v[70:73], v[150:153], v[206:209], v[70:73]
	v_mfma_f32_16x16x32_bf16 v[66:69], v[158:161], v[206:209], v[66:69]
	s_setprio 0
	s_barrier
	s_add_i32 s90, s90, s47
	v_lshl_add_u64 v[210:211], s[34:35], 0, v[190:191]
	s_mov_b32 m0, s90
	ds_read_b128 v[162:165], v222 offset:16384
	ds_read_b128 v[166:169], v222 offset:17408
	ds_read_b128 v[170:173], v222 offset:18432
	ds_read_b128 v[174:177], v222 offset:19456
	ds_read_b128 v[178:181], v222 offset:20480
	ds_read_b128 v[182:185], v222 offset:21504
	ds_read_b128 v[196:199], v222 offset:22528
	ds_read_b128 v[206:209], v222 offset:23552
	global_load_lds_dwordx4 v[210:211], off
	s_add_i32 m0, s90, 0x2000
	s_add_u32 s90, s34, 0x80000
	v_lshl_add_u64 v[212:213], s[34:35], 0, v[200:201]
	s_addc_u32 s91, s35, 0
	s_add_i32 s96, s96, s47
	global_load_lds_dwordx4 v[212:213], off
	v_lshl_add_u64 v[214:215], s[90:91], 0, v[190:191]
	s_mov_b32 m0, s96
	v_lshl_add_u64 v[216:217], s[52:53], 0, v[188:189]
	global_load_lds_dwordx4 v[214:215], off
	v_lshl_add_u64 v[214:215], s[90:91], 0, v[200:201]
	s_add_i32 m0, s96, 0x2000
	s_nop 0
	global_load_lds_dwordx4 v[214:215], off
	v_lshl_add_u64 v[214:215], s[52:53], 0, v[186:187]
	s_mov_b32 m0, s55
	s_nop 0
	global_load_lds_dwordx4 v[214:215], off
	s_mov_b32 m0, s56
	s_nop 0
	global_load_lds_dwordx4 v[216:217], off
	s_waitcnt vmcnt(8)
	s_waitcnt lgkmcnt(0)
	s_barrier
	s_setprio 1
	v_mfma_f32_16x16x32_bf16 v[62:65], v[130:133], v[162:165], 0
	v_mfma_f32_16x16x32_bf16 v[58:61], v[138:141], v[162:165], 0
	v_mfma_f32_16x16x32_bf16 v[46:49], v[130:133], v[170:173], 0
	v_mfma_f32_16x16x32_bf16 v[42:45], v[138:141], v[170:173], 0
	v_mfma_f32_16x16x32_bf16 v[30:33], v[130:133], v[178:181], 0
	v_mfma_f32_16x16x32_bf16 v[26:29], v[138:141], v[178:181], 0
	v_mfma_f32_16x16x32_bf16 v[14:17], v[130:133], v[196:199], 0
	v_mfma_f32_16x16x32_bf16 v[10:13], v[138:141], v[196:199], 0
	v_mfma_f32_16x16x32_bf16 v[62:65], v[134:137], v[166:169], v[62:65]
	v_mfma_f32_16x16x32_bf16 v[58:61], v[142:145], v[166:169], v[58:61]
	v_mfma_f32_16x16x32_bf16 v[46:49], v[134:137], v[174:177], v[46:49]
	v_mfma_f32_16x16x32_bf16 v[42:45], v[142:145], v[174:177], v[42:45]
	v_mfma_f32_16x16x32_bf16 v[30:33], v[134:137], v[182:185], v[30:33]
	v_mfma_f32_16x16x32_bf16 v[26:29], v[142:145], v[182:185], v[26:29]
	v_mfma_f32_16x16x32_bf16 v[14:17], v[134:137], v[206:209], v[14:17]
	v_mfma_f32_16x16x32_bf16 v[10:13], v[142:145], v[206:209], v[10:13]
	s_setprio 0
	s_setprio 1
	v_mfma_f32_16x16x32_bf16 v[54:57], v[146:149], v[162:165], 0
	v_mfma_f32_16x16x32_bf16 v[50:53], v[154:157], v[162:165], 0
	v_mfma_f32_16x16x32_bf16 v[38:41], v[146:149], v[170:173], 0
	v_mfma_f32_16x16x32_bf16 v[34:37], v[154:157], v[170:173], 0
	v_mfma_f32_16x16x32_bf16 v[22:25], v[146:149], v[178:181], 0
	v_mfma_f32_16x16x32_bf16 v[18:21], v[154:157], v[178:181], 0
	v_mfma_f32_16x16x32_bf16 v[6:9], v[146:149], v[196:199], 0
	v_mfma_f32_16x16x32_bf16 v[2:5], v[154:157], v[196:199], 0
	v_mfma_f32_16x16x32_bf16 v[54:57], v[150:153], v[166:169], v[54:57]
	v_mfma_f32_16x16x32_bf16 v[50:53], v[158:161], v[166:169], v[50:53]
	v_mfma_f32_16x16x32_bf16 v[38:41], v[150:153], v[174:177], v[38:41]
	v_mfma_f32_16x16x32_bf16 v[34:37], v[158:161], v[174:177], v[34:37]
	v_mfma_f32_16x16x32_bf16 v[22:25], v[150:153], v[182:185], v[22:25]
	v_mfma_f32_16x16x32_bf16 v[18:21], v[158:161], v[182:185], v[18:21]
	v_mfma_f32_16x16x32_bf16 v[6:9], v[150:153], v[206:209], v[6:9]
	v_mfma_f32_16x16x32_bf16 v[2:5], v[158:161], v[206:209], v[2:5]
	s_setprio 0
	s_barrier
	s_add_i32 s90, 0, 0x18000
	s_add_i32 s91, 0, 0x1c000
	v_add_u32_e32 v142, s90, v220
	v_add_u32_e32 v158, s91, v220
	ds_read_b128 v[130:133], v142
	ds_read_b128 v[134:137], v142 offset:1024
	ds_read_b128 v[138:141], v142 offset:2048
	ds_read_b128 v[142:145], v142 offset:3072
	ds_read_b128 v[146:149], v158
	ds_read_b128 v[150:153], v158 offset:1024
	ds_read_b128 v[154:157], v158 offset:2048
	ds_read_b128 v[158:161], v158 offset:3072
	s_add_u32 s52, s52, 0x80000
	s_addc_u32 s53, s53, 0
	s_mov_b32 m0, s57
	v_lshl_add_u64 v[218:219], s[52:53], 0, v[186:187]
	ds_read_b128 v[162:165], v222 offset:32768
	ds_read_b128 v[166:169], v222 offset:33792
	ds_read_b128 v[170:173], v222 offset:34816
	ds_read_b128 v[174:177], v222 offset:35840
	ds_read_b128 v[178:181], v222 offset:36864
	ds_read_b128 v[182:185], v222 offset:37888
	ds_read_b128 v[196:199], v222 offset:38912
	ds_read_b128 v[206:209], v222 offset:39936
	global_load_lds_dwordx4 v[218:219], off
	v_lshl_add_u64 v[218:219], s[52:53], 0, v[188:189]
	s_mov_b32 m0, s60
	s_nop 0
	global_load_lds_dwordx4 v[218:219], off
	s_waitcnt vmcnt(8)
	s_waitcnt lgkmcnt(0)
	s_barrier
	s_setprio 1
	v_mfma_f32_16x16x32_bf16 v[126:129], v[130:133], v[162:165], v[126:129]
	v_mfma_f32_16x16x32_bf16 v[122:125], v[138:141], v[162:165], v[122:125]
	v_mfma_f32_16x16x32_bf16 v[110:113], v[130:133], v[170:173], v[110:113]
	v_mfma_f32_16x16x32_bf16 v[106:109], v[138:141], v[170:173], v[106:109]
	v_mfma_f32_16x16x32_bf16 v[94:97], v[130:133], v[178:181], v[94:97]
	v_mfma_f32_16x16x32_bf16 v[90:93], v[138:141], v[178:181], v[90:93]
	v_mfma_f32_16x16x32_bf16 v[78:81], v[130:133], v[196:199], v[78:81]
	v_mfma_f32_16x16x32_bf16 v[74:77], v[138:141], v[196:199], v[74:77]
	v_mfma_f32_16x16x32_bf16 v[126:129], v[134:137], v[166:169], v[126:129]
	v_mfma_f32_16x16x32_bf16 v[122:125], v[142:145], v[166:169], v[122:125]
	v_mfma_f32_16x16x32_bf16 v[110:113], v[134:137], v[174:177], v[110:113]
	v_mfma_f32_16x16x32_bf16 v[106:109], v[142:145], v[174:177], v[106:109]
	v_mfma_f32_16x16x32_bf16 v[94:97], v[134:137], v[182:185], v[94:97]
	v_mfma_f32_16x16x32_bf16 v[90:93], v[142:145], v[182:185], v[90:93]
	v_mfma_f32_16x16x32_bf16 v[78:81], v[134:137], v[206:209], v[78:81]
	v_mfma_f32_16x16x32_bf16 v[74:77], v[142:145], v[206:209], v[74:77]
	s_setprio 0
	s_setprio 1
	v_mfma_f32_16x16x32_bf16 v[118:121], v[146:149], v[162:165], v[118:121]
	v_mfma_f32_16x16x32_bf16 v[114:117], v[154:157], v[162:165], v[114:117]
	v_mfma_f32_16x16x32_bf16 v[102:105], v[146:149], v[170:173], v[102:105]
	v_mfma_f32_16x16x32_bf16 v[98:101], v[154:157], v[170:173], v[98:101]
	v_mfma_f32_16x16x32_bf16 v[86:89], v[146:149], v[178:181], v[86:89]
	v_mfma_f32_16x16x32_bf16 v[82:85], v[154:157], v[178:181], v[82:85]
	v_mfma_f32_16x16x32_bf16 v[70:73], v[146:149], v[196:199], v[70:73]
	v_mfma_f32_16x16x32_bf16 v[66:69], v[154:157], v[196:199], v[66:69]
	v_mfma_f32_16x16x32_bf16 v[118:121], v[150:153], v[166:169], v[118:121]
	v_mfma_f32_16x16x32_bf16 v[114:117], v[158:161], v[166:169], v[114:117]
	v_mfma_f32_16x16x32_bf16 v[102:105], v[150:153], v[174:177], v[102:105]
	v_mfma_f32_16x16x32_bf16 v[98:101], v[158:161], v[174:177], v[98:101]
	v_mfma_f32_16x16x32_bf16 v[86:89], v[150:153], v[182:185], v[86:89]
	v_mfma_f32_16x16x32_bf16 v[82:85], v[158:161], v[182:185], v[82:85]
	v_mfma_f32_16x16x32_bf16 v[70:73], v[150:153], v[206:209], v[70:73]
	v_mfma_f32_16x16x32_bf16 v[66:69], v[158:161], v[206:209], v[66:69]
	s_setprio 0
	s_barrier
	s_add_i32 s52, s90, s47
	v_lshl_add_u64 v[210:211], v[210:211], 0, s[58:59]
	s_mov_b32 m0, s52
	ds_read_b128 v[162:165], v222 offset:49152
	ds_read_b128 v[166:169], v222 offset:50176
	ds_read_b128 v[170:173], v222 offset:51200
	ds_read_b128 v[174:177], v222 offset:52224
	ds_read_b128 v[178:181], v222 offset:53248
	ds_read_b128 v[182:185], v222 offset:54272
	ds_read_b128 v[196:199], v222 offset:55296
	ds_read_b128 v[206:209], v222 offset:56320
	global_load_lds_dwordx4 v[210:211], off
	s_add_i32 m0, s52, 0x2000
	s_add_u32 s34, s34, 0x80080
	v_lshl_add_u64 v[210:211], v[212:213], 0, s[58:59]
	s_addc_u32 s35, s35, 0
	s_add_i32 s52, s91, s47
	global_load_lds_dwordx4 v[210:211], off
	v_lshl_add_u64 v[210:211], s[34:35], 0, v[190:191]
	s_mov_b32 m0, s52
	s_nop 0
	global_load_lds_dwordx4 v[210:211], off
	v_lshl_add_u64 v[210:211], s[34:35], 0, v[200:201]
	s_add_i32 m0, s52, 0x2000
	s_nop 0
	global_load_lds_dwordx4 v[210:211], off
	v_lshl_add_u64 v[210:211], v[214:215], 0, s[58:59]
	s_mov_b32 m0, s61
	s_nop 0
	global_load_lds_dwordx4 v[210:211], off
	v_lshl_add_u64 v[210:211], v[216:217], 0, s[58:59]
	s_mov_b32 m0, s69
	s_nop 0
	global_load_lds_dwordx4 v[210:211], off
	s_waitcnt vmcnt(8)
	s_waitcnt lgkmcnt(0)
	s_barrier
	s_setprio 1
	v_mfma_f32_16x16x32_bf16 v[62:65], v[130:133], v[162:165], v[62:65]
	v_mfma_f32_16x16x32_bf16 v[58:61], v[138:141], v[162:165], v[58:61]
	v_mfma_f32_16x16x32_bf16 v[46:49], v[130:133], v[170:173], v[46:49]
	v_mfma_f32_16x16x32_bf16 v[42:45], v[138:141], v[170:173], v[42:45]
	v_mfma_f32_16x16x32_bf16 v[30:33], v[130:133], v[178:181], v[30:33]
	v_mfma_f32_16x16x32_bf16 v[26:29], v[138:141], v[178:181], v[26:29]
	v_mfma_f32_16x16x32_bf16 v[14:17], v[130:133], v[196:199], v[14:17]
	v_mfma_f32_16x16x32_bf16 v[10:13], v[138:141], v[196:199], v[10:13]
	v_mfma_f32_16x16x32_bf16 v[62:65], v[134:137], v[166:169], v[62:65]
	v_mfma_f32_16x16x32_bf16 v[58:61], v[142:145], v[166:169], v[58:61]
	v_mfma_f32_16x16x32_bf16 v[46:49], v[134:137], v[174:177], v[46:49]
	v_mfma_f32_16x16x32_bf16 v[42:45], v[142:145], v[174:177], v[42:45]
	v_mfma_f32_16x16x32_bf16 v[30:33], v[134:137], v[182:185], v[30:33]
	v_mfma_f32_16x16x32_bf16 v[26:29], v[142:145], v[182:185], v[26:29]
	v_mfma_f32_16x16x32_bf16 v[14:17], v[134:137], v[206:209], v[14:17]
	v_mfma_f32_16x16x32_bf16 v[10:13], v[142:145], v[206:209], v[10:13]
	s_setprio 0
	s_setprio 1
	v_mfma_f32_16x16x32_bf16 v[54:57], v[146:149], v[162:165], v[54:57]
	v_mfma_f32_16x16x32_bf16 v[50:53], v[154:157], v[162:165], v[50:53]
	v_mfma_f32_16x16x32_bf16 v[38:41], v[146:149], v[170:173], v[38:41]
	v_mfma_f32_16x16x32_bf16 v[34:37], v[154:157], v[170:173], v[34:37]
	v_mfma_f32_16x16x32_bf16 v[22:25], v[146:149], v[178:181], v[22:25]
	v_mfma_f32_16x16x32_bf16 v[18:21], v[154:157], v[178:181], v[18:21]
	v_mfma_f32_16x16x32_bf16 v[6:9], v[146:149], v[196:199], v[6:9]
	v_mfma_f32_16x16x32_bf16 v[2:5], v[154:157], v[196:199], v[2:5]
	v_mfma_f32_16x16x32_bf16 v[54:57], v[150:153], v[166:169], v[54:57]
	v_mfma_f32_16x16x32_bf16 v[50:53], v[158:161], v[166:169], v[50:53]
	v_mfma_f32_16x16x32_bf16 v[38:41], v[150:153], v[174:177], v[38:41]
	v_mfma_f32_16x16x32_bf16 v[34:37], v[158:161], v[174:177], v[34:37]
	v_mfma_f32_16x16x32_bf16 v[22:25], v[150:153], v[182:185], v[22:25]
	v_mfma_f32_16x16x32_bf16 v[18:21], v[158:161], v[182:185], v[18:21]
	v_mfma_f32_16x16x32_bf16 v[6:9], v[150:153], v[206:209], v[6:9]
	v_mfma_f32_16x16x32_bf16 v[2:5], v[158:161], v[206:209], v[2:5]
	s_setprio 0
	s_barrier
	s_add_i32 s89, s89, 2
	s_add_u32 s30, s30, 0x100
	s_addc_u32 s31, s31, 0
	s_add_u32 s81, s81, 0x100
	s_addc_u32 s88, s88, 0
	s_cmp_gt_u32 s89, 29
	s_cbranch_scc1 .Lpeel_done_5
.LBB0_823:
	s_add_u32 s34, s30, 0xfff80080
	s_addc_u32 s35, s31, -1
	s_add_i32 s90, 0, 0x10000
	s_cmp_eq_u32 s89, 28
	s_cselect_b32 s53, s17, s35
	s_cselect_b32 s52, s27, s34
	s_cselect_b32 s35, s15, s88
	s_cselect_b32 s34, s29, s81
	s_add_i32 s96, 0, 0x14000
	v_add_u32_e32 v142, s90, v220
	v_add_u32_e32 v158, s96, v220
	ds_read_b128 v[130:133], v142
	ds_read_b128 v[134:137], v142 offset:1024
	ds_read_b128 v[138:141], v142 offset:2048
	ds_read_b128 v[142:145], v142 offset:3072
	ds_read_b128 v[146:149], v158
	ds_read_b128 v[150:153], v158 offset:1024
	ds_read_b128 v[154:157], v158 offset:2048
	ds_read_b128 v[158:161], v158 offset:3072
	v_lshl_add_u64 v[210:211], s[30:31], 0, v[202:203]
	s_add_i32 m0, s55, 0xc000
	ds_read_b128 v[162:165], v222
	ds_read_b128 v[166:169], v222 offset:1024
	ds_read_b128 v[170:173], v222 offset:2048
	ds_read_b128 v[174:177], v222 offset:3072
	ds_read_b128 v[178:181], v222 offset:4096
	ds_read_b128 v[182:185], v222 offset:5120
	ds_read_b128 v[196:199], v222 offset:6144
	ds_read_b128 v[206:209], v222 offset:7168
	global_load_lds_dwordx4 v[210:211], off
	v_lshl_add_u64 v[210:211], s[30:31], 0, v[204:205]
	s_add_i32 m0, s55, 0xe000
	s_nop 0
	global_load_lds_dwordx4 v[210:211], off
	s_waitcnt vmcnt(8)
	s_waitcnt lgkmcnt(0)
	s_barrier
	s_setprio 1
	v_mfma_f32_16x16x32_bf16 v[126:129], v[130:133], v[162:165], v[126:129]
	v_mfma_f32_16x16x32_bf16 v[122:125], v[138:141], v[162:165], v[122:125]
	v_mfma_f32_16x16x32_bf16 v[110:113], v[130:133], v[170:173], v[110:113]
	v_mfma_f32_16x16x32_bf16 v[106:109], v[138:141], v[170:173], v[106:109]
	v_mfma_f32_16x16x32_bf16 v[94:97], v[130:133], v[178:181], v[94:97]
	v_mfma_f32_16x16x32_bf16 v[90:93], v[138:141], v[178:181], v[90:93]
	v_mfma_f32_16x16x32_bf16 v[78:81], v[130:133], v[196:199], v[78:81]
	v_mfma_f32_16x16x32_bf16 v[74:77], v[138:141], v[196:199], v[74:77]
	v_mfma_f32_16x16x32_bf16 v[126:129], v[134:137], v[166:169], v[126:129]
	v_mfma_f32_16x16x32_bf16 v[122:125], v[142:145], v[166:169], v[122:125]
	v_mfma_f32_16x16x32_bf16 v[110:113], v[134:137], v[174:177], v[110:113]
	v_mfma_f32_16x16x32_bf16 v[106:109], v[142:145], v[174:177], v[106:109]
	v_mfma_f32_16x16x32_bf16 v[94:97], v[134:137], v[182:185], v[94:97]
	v_mfma_f32_16x16x32_bf16 v[90:93], v[142:145], v[182:185], v[90:93]
	v_mfma_f32_16x16x32_bf16 v[78:81], v[134:137], v[206:209], v[78:81]
	v_mfma_f32_16x16x32_bf16 v[74:77], v[142:145], v[206:209], v[74:77]
	s_setprio 0
	s_setprio 1
	v_mfma_f32_16x16x32_bf16 v[118:121], v[146:149], v[162:165], v[118:121]
	v_mfma_f32_16x16x32_bf16 v[114:117], v[154:157], v[162:165], v[114:117]
	v_mfma_f32_16x16x32_bf16 v[102:105], v[146:149], v[170:173], v[102:105]
	v_mfma_f32_16x16x32_bf16 v[98:101], v[154:157], v[170:173], v[98:101]
	v_mfma_f32_16x16x32_bf16 v[86:89], v[146:149], v[178:181], v[86:89]
	v_mfma_f32_16x16x32_bf16 v[82:85], v[154:157], v[178:181], v[82:85]
	v_mfma_f32_16x16x32_bf16 v[70:73], v[146:149], v[196:199], v[70:73]
	v_mfma_f32_16x16x32_bf16 v[66:69], v[154:157], v[196:199], v[66:69]
	v_mfma_f32_16x16x32_bf16 v[118:121], v[150:153], v[166:169], v[118:121]
	v_mfma_f32_16x16x32_bf16 v[114:117], v[158:161], v[166:169], v[114:117]
	v_mfma_f32_16x16x32_bf16 v[102:105], v[150:153], v[174:177], v[102:105]
	v_mfma_f32_16x16x32_bf16 v[98:101], v[158:161], v[174:177], v[98:101]
	v_mfma_f32_16x16x32_bf16 v[86:89], v[150:153], v[182:185], v[86:89]
	v_mfma_f32_16x16x32_bf16 v[82:85], v[158:161], v[182:185], v[82:85]
	v_mfma_f32_16x16x32_bf16 v[70:73], v[150:153], v[206:209], v[70:73]
	v_mfma_f32_16x16x32_bf16 v[66:69], v[158:161], v[206:209], v[66:69]
	s_setprio 0
	s_barrier
	s_add_i32 s90, s90, s47
	v_lshl_add_u64 v[210:211], s[34:35], 0, v[190:191]
	s_mov_b32 m0, s90
	ds_read_b128 v[162:165], v222 offset:16384
	ds_read_b128 v[166:169], v222 offset:17408
	ds_read_b128 v[170:173], v222 offset:18432
	ds_read_b128 v[174:177], v222 offset:19456
	ds_read_b128 v[178:181], v222 offset:20480
	ds_read_b128 v[182:185], v222 offset:21504
	ds_read_b128 v[196:199], v222 offset:22528
	ds_read_b128 v[206:209], v222 offset:23552
	global_load_lds_dwordx4 v[210:211], off
	s_add_i32 m0, s90, 0x2000
	s_add_u32 s90, s34, 0x80000
	v_lshl_add_u64 v[212:213], s[34:35], 0, v[200:201]
	s_addc_u32 s91, s35, 0
	s_add_i32 s96, s96, s47
	global_load_lds_dwordx4 v[212:213], off
	v_lshl_add_u64 v[214:215], s[90:91], 0, v[190:191]
	s_mov_b32 m0, s96
	v_lshl_add_u64 v[216:217], s[52:53], 0, v[188:189]
	global_load_lds_dwordx4 v[214:215], off
	v_lshl_add_u64 v[214:215], s[90:91], 0, v[200:201]
	s_add_i32 m0, s96, 0x2000
	s_nop 0
	global_load_lds_dwordx4 v[214:215], off
	v_lshl_add_u64 v[214:215], s[52:53], 0, v[186:187]
	s_mov_b32 m0, s55
	s_nop 0
	global_load_lds_dwordx4 v[214:215], off
	s_mov_b32 m0, s56
	s_nop 0
	global_load_lds_dwordx4 v[216:217], off
	s_waitcnt vmcnt(8)
	s_waitcnt lgkmcnt(0)
	s_barrier
	s_setprio 1
	v_mfma_f32_16x16x32_bf16 v[62:65], v[130:133], v[162:165], v[62:65]
	v_mfma_f32_16x16x32_bf16 v[58:61], v[138:141], v[162:165], v[58:61]
	v_mfma_f32_16x16x32_bf16 v[46:49], v[130:133], v[170:173], v[46:49]
	v_mfma_f32_16x16x32_bf16 v[42:45], v[138:141], v[170:173], v[42:45]
	v_mfma_f32_16x16x32_bf16 v[30:33], v[130:133], v[178:181], v[30:33]
	v_mfma_f32_16x16x32_bf16 v[26:29], v[138:141], v[178:181], v[26:29]
	v_mfma_f32_16x16x32_bf16 v[14:17], v[130:133], v[196:199], v[14:17]
	v_mfma_f32_16x16x32_bf16 v[10:13], v[138:141], v[196:199], v[10:13]
	v_mfma_f32_16x16x32_bf16 v[62:65], v[134:137], v[166:169], v[62:65]
	v_mfma_f32_16x16x32_bf16 v[58:61], v[142:145], v[166:169], v[58:61]
	v_mfma_f32_16x16x32_bf16 v[46:49], v[134:137], v[174:177], v[46:49]
	v_mfma_f32_16x16x32_bf16 v[42:45], v[142:145], v[174:177], v[42:45]
	v_mfma_f32_16x16x32_bf16 v[30:33], v[134:137], v[182:185], v[30:33]
	v_mfma_f32_16x16x32_bf16 v[26:29], v[142:145], v[182:185], v[26:29]
	v_mfma_f32_16x16x32_bf16 v[14:17], v[134:137], v[206:209], v[14:17]
	v_mfma_f32_16x16x32_bf16 v[10:13], v[142:145], v[206:209], v[10:13]
	s_setprio 0
	s_setprio 1
	v_mfma_f32_16x16x32_bf16 v[54:57], v[146:149], v[162:165], v[54:57]
	v_mfma_f32_16x16x32_bf16 v[50:53], v[154:157], v[162:165], v[50:53]
	v_mfma_f32_16x16x32_bf16 v[38:41], v[146:149], v[170:173], v[38:41]
	v_mfma_f32_16x16x32_bf16 v[34:37], v[154:157], v[170:173], v[34:37]
	v_mfma_f32_16x16x32_bf16 v[22:25], v[146:149], v[178:181], v[22:25]
	v_mfma_f32_16x16x32_bf16 v[18:21], v[154:157], v[178:181], v[18:21]
	v_mfma_f32_16x16x32_bf16 v[6:9], v[146:149], v[196:199], v[6:9]
	v_mfma_f32_16x16x32_bf16 v[2:5], v[154:157], v[196:199], v[2:5]
	v_mfma_f32_16x16x32_bf16 v[54:57], v[150:153], v[166:169], v[54:57]
	v_mfma_f32_16x16x32_bf16 v[50:53], v[158:161], v[166:169], v[50:53]
	v_mfma_f32_16x16x32_bf16 v[38:41], v[150:153], v[174:177], v[38:41]
	v_mfma_f32_16x16x32_bf16 v[34:37], v[158:161], v[174:177], v[34:37]
	v_mfma_f32_16x16x32_bf16 v[22:25], v[150:153], v[182:185], v[22:25]
	v_mfma_f32_16x16x32_bf16 v[18:21], v[158:161], v[182:185], v[18:21]
	v_mfma_f32_16x16x32_bf16 v[6:9], v[150:153], v[206:209], v[6:9]
	v_mfma_f32_16x16x32_bf16 v[2:5], v[158:161], v[206:209], v[2:5]
	s_setprio 0
	s_barrier
	s_add_i32 s90, 0, 0x18000
	s_add_i32 s91, 0, 0x1c000
	v_add_u32_e32 v142, s90, v220
	v_add_u32_e32 v158, s91, v220
	ds_read_b128 v[130:133], v142
	ds_read_b128 v[134:137], v142 offset:1024
	ds_read_b128 v[138:141], v142 offset:2048
	ds_read_b128 v[142:145], v142 offset:3072
	ds_read_b128 v[146:149], v158
	ds_read_b128 v[150:153], v158 offset:1024
	ds_read_b128 v[154:157], v158 offset:2048
	ds_read_b128 v[158:161], v158 offset:3072
	s_add_u32 s52, s52, 0x80000
	s_addc_u32 s53, s53, 0
	s_mov_b32 m0, s57
	v_lshl_add_u64 v[218:219], s[52:53], 0, v[186:187]
	ds_read_b128 v[162:165], v222 offset:32768
	ds_read_b128 v[166:169], v222 offset:33792
	ds_read_b128 v[170:173], v222 offset:34816
	ds_read_b128 v[174:177], v222 offset:35840
	ds_read_b128 v[178:181], v222 offset:36864
	ds_read_b128 v[182:185], v222 offset:37888
	ds_read_b128 v[196:199], v222 offset:38912
	ds_read_b128 v[206:209], v222 offset:39936
	global_load_lds_dwordx4 v[218:219], off
	v_lshl_add_u64 v[218:219], s[52:53], 0, v[188:189]
	s_mov_b32 m0, s60
	s_nop 0
	global_load_lds_dwordx4 v[218:219], off
	s_waitcnt vmcnt(8)
	s_waitcnt lgkmcnt(0)
	s_barrier
	s_setprio 1
	v_mfma_f32_16x16x32_bf16 v[126:129], v[130:133], v[162:165], v[126:129]
	v_mfma_f32_16x16x32_bf16 v[122:125], v[138:141], v[162:165], v[122:125]
	v_mfma_f32_16x16x32_bf16 v[110:113], v[130:133], v[170:173], v[110:113]
	v_mfma_f32_16x16x32_bf16 v[106:109], v[138:141], v[170:173], v[106:109]
	v_mfma_f32_16x16x32_bf16 v[94:97], v[130:133], v[178:181], v[94:97]
	v_mfma_f32_16x16x32_bf16 v[90:93], v[138:141], v[178:181], v[90:93]
	v_mfma_f32_16x16x32_bf16 v[78:81], v[130:133], v[196:199], v[78:81]
	v_mfma_f32_16x16x32_bf16 v[74:77], v[138:141], v[196:199], v[74:77]
	v_mfma_f32_16x16x32_bf16 v[126:129], v[134:137], v[166:169], v[126:129]
	v_mfma_f32_16x16x32_bf16 v[122:125], v[142:145], v[166:169], v[122:125]
	v_mfma_f32_16x16x32_bf16 v[110:113], v[134:137], v[174:177], v[110:113]
	v_mfma_f32_16x16x32_bf16 v[106:109], v[142:145], v[174:177], v[106:109]
	v_mfma_f32_16x16x32_bf16 v[94:97], v[134:137], v[182:185], v[94:97]
	v_mfma_f32_16x16x32_bf16 v[90:93], v[142:145], v[182:185], v[90:93]
	v_mfma_f32_16x16x32_bf16 v[78:81], v[134:137], v[206:209], v[78:81]
	v_mfma_f32_16x16x32_bf16 v[74:77], v[142:145], v[206:209], v[74:77]
	s_setprio 0
	s_setprio 1
	v_mfma_f32_16x16x32_bf16 v[118:121], v[146:149], v[162:165], v[118:121]
	v_mfma_f32_16x16x32_bf16 v[114:117], v[154:157], v[162:165], v[114:117]
	v_mfma_f32_16x16x32_bf16 v[102:105], v[146:149], v[170:173], v[102:105]
	v_mfma_f32_16x16x32_bf16 v[98:101], v[154:157], v[170:173], v[98:101]
	v_mfma_f32_16x16x32_bf16 v[86:89], v[146:149], v[178:181], v[86:89]
	v_mfma_f32_16x16x32_bf16 v[82:85], v[154:157], v[178:181], v[82:85]
	v_mfma_f32_16x16x32_bf16 v[70:73], v[146:149], v[196:199], v[70:73]
	v_mfma_f32_16x16x32_bf16 v[66:69], v[154:157], v[196:199], v[66:69]
	v_mfma_f32_16x16x32_bf16 v[118:121], v[150:153], v[166:169], v[118:121]
	v_mfma_f32_16x16x32_bf16 v[114:117], v[158:161], v[166:169], v[114:117]
	v_mfma_f32_16x16x32_bf16 v[102:105], v[150:153], v[174:177], v[102:105]
	v_mfma_f32_16x16x32_bf16 v[98:101], v[158:161], v[174:177], v[98:101]
	v_mfma_f32_16x16x32_bf16 v[86:89], v[150:153], v[182:185], v[86:89]
	v_mfma_f32_16x16x32_bf16 v[82:85], v[158:161], v[182:185], v[82:85]
	v_mfma_f32_16x16x32_bf16 v[70:73], v[150:153], v[206:209], v[70:73]
	v_mfma_f32_16x16x32_bf16 v[66:69], v[158:161], v[206:209], v[66:69]
	s_setprio 0
	s_barrier
	s_add_i32 s52, s90, s47
	v_lshl_add_u64 v[210:211], v[210:211], 0, s[58:59]
	s_mov_b32 m0, s52
	ds_read_b128 v[162:165], v222 offset:49152
	ds_read_b128 v[166:169], v222 offset:50176
	ds_read_b128 v[170:173], v222 offset:51200
	ds_read_b128 v[174:177], v222 offset:52224
	ds_read_b128 v[178:181], v222 offset:53248
	ds_read_b128 v[182:185], v222 offset:54272
	ds_read_b128 v[196:199], v222 offset:55296
	ds_read_b128 v[206:209], v222 offset:56320
	global_load_lds_dwordx4 v[210:211], off
	s_add_i32 m0, s52, 0x2000
	s_add_u32 s34, s34, 0x80080
	v_lshl_add_u64 v[210:211], v[212:213], 0, s[58:59]
	s_addc_u32 s35, s35, 0
	s_add_i32 s52, s91, s47
	global_load_lds_dwordx4 v[210:211], off
	v_lshl_add_u64 v[210:211], s[34:35], 0, v[190:191]
	s_mov_b32 m0, s52
	s_nop 0
	global_load_lds_dwordx4 v[210:211], off
	v_lshl_add_u64 v[210:211], s[34:35], 0, v[200:201]
	s_add_i32 m0, s52, 0x2000
	s_nop 0
	global_load_lds_dwordx4 v[210:211], off
	v_lshl_add_u64 v[210:211], v[214:215], 0, s[58:59]
	s_mov_b32 m0, s61
	s_nop 0
	global_load_lds_dwordx4 v[210:211], off
	v_lshl_add_u64 v[210:211], v[216:217], 0, s[58:59]
	s_mov_b32 m0, s69
	s_nop 0
	global_load_lds_dwordx4 v[210:211], off
	s_waitcnt vmcnt(8)
	s_waitcnt lgkmcnt(0)
	s_barrier
	s_setprio 1
	v_mfma_f32_16x16x32_bf16 v[62:65], v[130:133], v[162:165], v[62:65]
	v_mfma_f32_16x16x32_bf16 v[58:61], v[138:141], v[162:165], v[58:61]
	v_mfma_f32_16x16x32_bf16 v[46:49], v[130:133], v[170:173], v[46:49]
	v_mfma_f32_16x16x32_bf16 v[42:45], v[138:141], v[170:173], v[42:45]
	v_mfma_f32_16x16x32_bf16 v[30:33], v[130:133], v[178:181], v[30:33]
	v_mfma_f32_16x16x32_bf16 v[26:29], v[138:141], v[178:181], v[26:29]
	v_mfma_f32_16x16x32_bf16 v[14:17], v[130:133], v[196:199], v[14:17]
	v_mfma_f32_16x16x32_bf16 v[10:13], v[138:141], v[196:199], v[10:13]
	v_mfma_f32_16x16x32_bf16 v[62:65], v[134:137], v[166:169], v[62:65]
	v_mfma_f32_16x16x32_bf16 v[58:61], v[142:145], v[166:169], v[58:61]
	v_mfma_f32_16x16x32_bf16 v[46:49], v[134:137], v[174:177], v[46:49]
	v_mfma_f32_16x16x32_bf16 v[42:45], v[142:145], v[174:177], v[42:45]
	v_mfma_f32_16x16x32_bf16 v[30:33], v[134:137], v[182:185], v[30:33]
	v_mfma_f32_16x16x32_bf16 v[26:29], v[142:145], v[182:185], v[26:29]
	v_mfma_f32_16x16x32_bf16 v[14:17], v[134:137], v[206:209], v[14:17]
	v_mfma_f32_16x16x32_bf16 v[10:13], v[142:145], v[206:209], v[10:13]
	s_setprio 0
	s_setprio 1
	v_mfma_f32_16x16x32_bf16 v[54:57], v[146:149], v[162:165], v[54:57]
	v_mfma_f32_16x16x32_bf16 v[50:53], v[154:157], v[162:165], v[50:53]
	v_mfma_f32_16x16x32_bf16 v[38:41], v[146:149], v[170:173], v[38:41]
	v_mfma_f32_16x16x32_bf16 v[34:37], v[154:157], v[170:173], v[34:37]
	v_mfma_f32_16x16x32_bf16 v[22:25], v[146:149], v[178:181], v[22:25]
	v_mfma_f32_16x16x32_bf16 v[18:21], v[154:157], v[178:181], v[18:21]
	v_mfma_f32_16x16x32_bf16 v[6:9], v[146:149], v[196:199], v[6:9]
	v_mfma_f32_16x16x32_bf16 v[2:5], v[154:157], v[196:199], v[2:5]
	v_mfma_f32_16x16x32_bf16 v[54:57], v[150:153], v[166:169], v[54:57]
	v_mfma_f32_16x16x32_bf16 v[50:53], v[158:161], v[166:169], v[50:53]
	v_mfma_f32_16x16x32_bf16 v[38:41], v[150:153], v[174:177], v[38:41]
	v_mfma_f32_16x16x32_bf16 v[34:37], v[158:161], v[174:177], v[34:37]
	v_mfma_f32_16x16x32_bf16 v[22:25], v[150:153], v[182:185], v[22:25]
	v_mfma_f32_16x16x32_bf16 v[18:21], v[158:161], v[182:185], v[18:21]
	v_mfma_f32_16x16x32_bf16 v[6:9], v[150:153], v[206:209], v[6:9]
	v_mfma_f32_16x16x32_bf16 v[2:5], v[158:161], v[206:209], v[2:5]
	s_setprio 0
	s_barrier
	s_add_i32 s89, s89, 2
	s_add_u32 s30, s30, 0x100
	s_addc_u32 s31, s31, 0
	s_add_u32 s81, s81, 0x100
	s_addc_u32 s88, s88, 0
	s_cmp_gt_u32 s89, 29
	s_cbranch_scc0 .LBB0_823

.LBB0_937:
	s_ashr_i32 s23, s22, 31
	s_lshl_b64 s[4:5], s[22:23], 20
	s_add_u32 s4, s86, s4
	s_addc_u32 s5, s87, s5
	s_and_b64 s[26:27], s[24:25], exec
	s_cselect_b32 s11, s5, s29
	s_cselect_b32 s23, s4, s28
	s_ashr_i32 s21, s20, 31
	s_lshl_b64 s[26:27], s[20:21], 20
	v_readlane_b32 s0, v254, 38
	v_readlane_b32 s1, v254, 39
	s_add_u32 s26, s0, s26
	s_addc_u32 s27, s1, s27
	s_and_b64 s[34:35], s[24:25], exec
	s_cselect_b32 s21, s27, s31
	s_cselect_b32 s53, s26, s30
	s_add_u32 s28, s28, 0x80080
	s_addc_u32 s29, s29, 0
	s_add_u32 s55, s30, 0x100
	s_addc_u32 s56, s31, 0
	s_mov_b32 s57, -2
	v_readlane_b32 s60, v255, 49
	s_nop 3
	s_cmp_eq_u32 s60, 7
	v_writelane_b32 v255, 7, 49
	s_cbranch_scc0 .Ltrip0_strict_6
	s_add_u32 s30, s28, 0xfff80080
	s_addc_u32 s31, s29, -1
	s_add_i32 s60, 0, 0x10000
	s_cmp_eq_u32 s57, 28
	s_cselect_b32 s35, s11, s31
	s_cselect_b32 s34, s23, s30
	s_cselect_b32 s31, s21, s56
	s_cselect_b32 s30, s53, s55
	s_add_i32 s66, 0, 0x14000
	v_add_u32_e32 v154, s60, v139
	v_add_u32_e32 v170, s66, v139
	ds_read_b128 v[142:145], v154
	ds_read_b128 v[146:149], v154 offset:1024
	ds_read_b128 v[150:153], v154 offset:2048
	ds_read_b128 v[154:157], v154 offset:3072
	ds_read_b128 v[158:161], v170
	ds_read_b128 v[162:165], v170 offset:1024
	ds_read_b128 v[166:169], v170 offset:2048
	ds_read_b128 v[170:173], v170 offset:3072
	v_lshl_add_u64 v[186:187], s[28:29], 0, v[134:135]
	s_add_i32 m0, s13, 0xc000
	ds_read_b128 v[174:177], v141
	ds_read_b128 v[178:181], v141 offset:1024
	ds_read_b128 v[182:185], v141 offset:2048
	ds_read_b128 v[196:199], v141 offset:3072
	ds_read_b128 v[200:203], v141 offset:4096
	ds_read_b128 v[204:207], v141 offset:5120
	ds_read_b128 v[208:211], v141 offset:6144
	ds_read_b128 v[212:215], v141 offset:7168
	global_load_lds_dwordx4 v[186:187], off
	v_lshl_add_u64 v[186:187], s[28:29], 0, v[136:137]
	s_add_i32 m0, s13, 0xe000
	s_nop 0
	global_load_lds_dwordx4 v[186:187], off
	s_waitcnt vmcnt(24)
	s_waitcnt lgkmcnt(0)
	s_barrier
	s_setprio 1
	v_mfma_f32_16x16x32_bf16 v[124:127], v[142:145], v[174:177], 0
	v_mfma_f32_16x16x32_bf16 v[120:123], v[150:153], v[174:177], 0
	v_mfma_f32_16x16x32_bf16 v[116:119], v[142:145], v[182:185], 0
	v_mfma_f32_16x16x32_bf16 v[112:115], v[150:153], v[182:185], 0
	v_mfma_f32_16x16x32_bf16 v[100:103], v[142:145], v[200:203], 0
	v_mfma_f32_16x16x32_bf16 v[96:99], v[150:153], v[200:203], 0
	v_mfma_f32_16x16x32_bf16 v[84:87], v[142:145], v[208:211], 0
	v_mfma_f32_16x16x32_bf16 v[80:83], v[150:153], v[208:211], 0
	v_mfma_f32_16x16x32_bf16 v[124:127], v[146:149], v[178:181], v[124:127]
	v_mfma_f32_16x16x32_bf16 v[120:123], v[154:157], v[178:181], v[120:123]
	v_mfma_f32_16x16x32_bf16 v[116:119], v[146:149], v[196:199], v[116:119]
	v_mfma_f32_16x16x32_bf16 v[112:115], v[154:157], v[196:199], v[112:115]
	v_mfma_f32_16x16x32_bf16 v[100:103], v[146:149], v[204:207], v[100:103]
	v_mfma_f32_16x16x32_bf16 v[96:99], v[154:157], v[204:207], v[96:99]
	v_mfma_f32_16x16x32_bf16 v[84:87], v[146:149], v[212:215], v[84:87]
	v_mfma_f32_16x16x32_bf16 v[80:83], v[154:157], v[212:215], v[80:83]
	s_setprio 0
	s_setprio 1
	v_mfma_f32_16x16x32_bf16 v[108:111], v[158:161], v[174:177], 0
	v_mfma_f32_16x16x32_bf16 v[104:107], v[166:169], v[174:177], 0
	v_mfma_f32_16x16x32_bf16 v[92:95], v[158:161], v[182:185], 0
	v_mfma_f32_16x16x32_bf16 v[88:91], v[166:169], v[182:185], 0
	v_mfma_f32_16x16x32_bf16 v[76:79], v[158:161], v[200:203], 0
	v_mfma_f32_16x16x32_bf16 v[72:75], v[166:169], v[200:203], 0
	v_mfma_f32_16x16x32_bf16 v[68:71], v[158:161], v[208:211], 0
	v_mfma_f32_16x16x32_bf16 v[64:67], v[166:169], v[208:211], 0
	v_mfma_f32_16x16x32_bf16 v[108:111], v[162:165], v[178:181], v[108:111]
	v_mfma_f32_16x16x32_bf16 v[104:107], v[170:173], v[178:181], v[104:107]
	v_mfma_f32_16x16x32_bf16 v[92:95], v[162:165], v[196:199], v[92:95]
	v_mfma_f32_16x16x32_bf16 v[88:91], v[170:173], v[196:199], v[88:91]
	v_mfma_f32_16x16x32_bf16 v[76:79], v[162:165], v[204:207], v[76:79]
	v_mfma_f32_16x16x32_bf16 v[72:75], v[170:173], v[204:207], v[72:75]
	v_mfma_f32_16x16x32_bf16 v[68:71], v[162:165], v[212:215], v[68:71]
	v_mfma_f32_16x16x32_bf16 v[64:67], v[170:173], v[212:215], v[64:67]
	s_setprio 0
	s_barrier
	s_add_i32 s60, s60, s38
	v_lshl_add_u64 v[186:187], s[30:31], 0, v[190:191]
	s_mov_b32 m0, s60
	ds_read_b128 v[174:177], v141 offset:16384
	ds_read_b128 v[178:181], v141 offset:17408
	ds_read_b128 v[182:185], v141 offset:18432
	ds_read_b128 v[196:199], v141 offset:19456
	ds_read_b128 v[200:203], v141 offset:20480
	ds_read_b128 v[204:207], v141 offset:21504
	ds_read_b128 v[208:211], v141 offset:22528
	ds_read_b128 v[212:215], v141 offset:23552
	global_load_lds_dwordx4 v[186:187], off
	s_add_i32 m0, s60, 0x2000
	s_add_u32 s60, s30, 0x80000
	v_lshl_add_u64 v[216:217], s[30:31], 0, v[132:133]
	s_addc_u32 s61, s31, 0
	s_add_i32 s66, s66, s38
	global_load_lds_dwordx4 v[216:217], off
	v_lshl_add_u64 v[218:219], s[60:61], 0, v[190:191]
	s_mov_b32 m0, s66
	v_lshl_add_u64 v[220:221], s[34:35], 0, v[130:131]
	global_load_lds_dwordx4 v[218:219], off
	v_lshl_add_u64 v[218:219], s[60:61], 0, v[132:133]
	s_add_i32 m0, s66, 0x2000
	s_nop 0
	global_load_lds_dwordx4 v[218:219], off
	v_lshl_add_u64 v[218:219], s[34:35], 0, v[128:129]
	s_mov_b32 m0, s13
	s_nop 0
	global_load_lds_dwordx4 v[218:219], off
	s_mov_b32 m0, s39
	s_nop 0
	global_load_lds_dwordx4 v[220:221], off
	s_waitcnt vmcnt(24)
	s_waitcnt lgkmcnt(0)
	s_barrier
	s_setprio 1
	v_mfma_f32_16x16x32_bf16 v[60:63], v[142:145], v[174:177], 0
	v_mfma_f32_16x16x32_bf16 v[56:59], v[150:153], v[174:177], 0
	v_mfma_f32_16x16x32_bf16 v[52:55], v[142:145], v[182:185], 0
	v_mfma_f32_16x16x32_bf16 v[48:51], v[150:153], v[182:185], 0
	v_mfma_f32_16x16x32_bf16 v[36:39], v[142:145], v[200:203], 0
	v_mfma_f32_16x16x32_bf16 v[32:35], v[150:153], v[200:203], 0
	v_mfma_f32_16x16x32_bf16 v[20:23], v[142:145], v[208:211], 0
	v_mfma_f32_16x16x32_bf16 v[16:19], v[150:153], v[208:211], 0
	v_mfma_f32_16x16x32_bf16 v[60:63], v[146:149], v[178:181], v[60:63]
	v_mfma_f32_16x16x32_bf16 v[56:59], v[154:157], v[178:181], v[56:59]
	v_mfma_f32_16x16x32_bf16 v[52:55], v[146:149], v[196:199], v[52:55]
	v_mfma_f32_16x16x32_bf16 v[48:51], v[154:157], v[196:199], v[48:51]
	v_mfma_f32_16x16x32_bf16 v[36:39], v[146:149], v[204:207], v[36:39]
	v_mfma_f32_16x16x32_bf16 v[32:35], v[154:157], v[204:207], v[32:35]
	v_mfma_f32_16x16x32_bf16 v[20:23], v[146:149], v[212:215], v[20:23]
	v_mfma_f32_16x16x32_bf16 v[16:19], v[154:157], v[212:215], v[16:19]
	s_setprio 0
	s_setprio 1
	v_mfma_f32_16x16x32_bf16 v[44:47], v[158:161], v[174:177], 0
	v_mfma_f32_16x16x32_bf16 v[40:43], v[166:169], v[174:177], 0
	v_mfma_f32_16x16x32_bf16 v[28:31], v[158:161], v[182:185], 0
	v_mfma_f32_16x16x32_bf16 v[24:27], v[166:169], v[182:185], 0
	v_mfma_f32_16x16x32_bf16 v[12:15], v[158:161], v[200:203], 0
	v_mfma_f32_16x16x32_bf16 v[8:11], v[166:169], v[200:203], 0
	v_mfma_f32_16x16x32_bf16 v[4:7], v[158:161], v[208:211], 0
	v_mfma_f32_16x16x32_bf16 v[0:3], v[166:169], v[208:211], 0
	v_mfma_f32_16x16x32_bf16 v[44:47], v[162:165], v[178:181], v[44:47]
	v_mfma_f32_16x16x32_bf16 v[40:43], v[170:173], v[178:181], v[40:43]
	v_mfma_f32_16x16x32_bf16 v[28:31], v[162:165], v[196:199], v[28:31]
	v_mfma_f32_16x16x32_bf16 v[24:27], v[170:173], v[196:199], v[24:27]
	v_mfma_f32_16x16x32_bf16 v[12:15], v[162:165], v[204:207], v[12:15]
	v_mfma_f32_16x16x32_bf16 v[8:11], v[170:173], v[204:207], v[8:11]
	v_mfma_f32_16x16x32_bf16 v[4:7], v[162:165], v[212:215], v[4:7]
	v_mfma_f32_16x16x32_bf16 v[0:3], v[170:173], v[212:215], v[0:3]
	s_setprio 0
	s_barrier
	s_add_i32 s60, 0, 0x18000
	s_add_i32 s61, 0, 0x1c000
	v_add_u32_e32 v154, s60, v139
	v_add_u32_e32 v170, s61, v139
	ds_read_b128 v[142:145], v154
	ds_read_b128 v[146:149], v154 offset:1024
	ds_read_b128 v[150:153], v154 offset:2048
	ds_read_b128 v[154:157], v154 offset:3072
	ds_read_b128 v[158:161], v170
	ds_read_b128 v[162:165], v170 offset:1024
	ds_read_b128 v[166:169], v170 offset:2048
	ds_read_b128 v[170:173], v170 offset:3072
	s_add_u32 s34, s34, 0x80000
	s_addc_u32 s35, s35, 0
	s_mov_b32 m0, s41
	v_lshl_add_u64 v[222:223], s[34:35], 0, v[128:129]
	ds_read_b128 v[174:177], v141 offset:32768
	ds_read_b128 v[178:181], v141 offset:33792
	ds_read_b128 v[182:185], v141 offset:34816
	ds_read_b128 v[196:199], v141 offset:35840
	ds_read_b128 v[200:203], v141 offset:36864
	ds_read_b128 v[204:207], v141 offset:37888
	ds_read_b128 v[208:211], v141 offset:38912
	ds_read_b128 v[212:215], v141 offset:39936
	global_load_lds_dwordx4 v[222:223], off
	v_lshl_add_u64 v[222:223], s[34:35], 0, v[130:131]
	s_mov_b32 m0, s42
	s_nop 0
	global_load_lds_dwordx4 v[222:223], off
	s_waitcnt vmcnt(8)
	s_waitcnt lgkmcnt(0)
	s_barrier
	s_setprio 1
	v_mfma_f32_16x16x32_bf16 v[124:127], v[142:145], v[174:177], v[124:127]
	v_mfma_f32_16x16x32_bf16 v[120:123], v[150:153], v[174:177], v[120:123]
	v_mfma_f32_16x16x32_bf16 v[116:119], v[142:145], v[182:185], v[116:119]
	v_mfma_f32_16x16x32_bf16 v[112:115], v[150:153], v[182:185], v[112:115]
	v_mfma_f32_16x16x32_bf16 v[100:103], v[142:145], v[200:203], v[100:103]
	v_mfma_f32_16x16x32_bf16 v[96:99], v[150:153], v[200:203], v[96:99]
	v_mfma_f32_16x16x32_bf16 v[84:87], v[142:145], v[208:211], v[84:87]
	v_mfma_f32_16x16x32_bf16 v[80:83], v[150:153], v[208:211], v[80:83]
	v_mfma_f32_16x16x32_bf16 v[124:127], v[146:149], v[178:181], v[124:127]
	v_mfma_f32_16x16x32_bf16 v[120:123], v[154:157], v[178:181], v[120:123]
	v_mfma_f32_16x16x32_bf16 v[116:119], v[146:149], v[196:199], v[116:119]
	v_mfma_f32_16x16x32_bf16 v[112:115], v[154:157], v[196:199], v[112:115]
	v_mfma_f32_16x16x32_bf16 v[100:103], v[146:149], v[204:207], v[100:103]
	v_mfma_f32_16x16x32_bf16 v[96:99], v[154:157], v[204:207], v[96:99]
	v_mfma_f32_16x16x32_bf16 v[84:87], v[146:149], v[212:215], v[84:87]
	v_mfma_f32_16x16x32_bf16 v[80:83], v[154:157], v[212:215], v[80:83]
	s_setprio 0
	s_setprio 1
	v_mfma_f32_16x16x32_bf16 v[108:111], v[158:161], v[174:177], v[108:111]
	v_mfma_f32_16x16x32_bf16 v[104:107], v[166:169], v[174:177], v[104:107]
	v_mfma_f32_16x16x32_bf16 v[92:95], v[158:161], v[182:185], v[92:95]
	v_mfma_f32_16x16x32_bf16 v[88:91], v[166:169], v[182:185], v[88:91]
	v_mfma_f32_16x16x32_bf16 v[76:79], v[158:161], v[200:203], v[76:79]
	v_mfma_f32_16x16x32_bf16 v[72:75], v[166:169], v[200:203], v[72:75]
	v_mfma_f32_16x16x32_bf16 v[68:71], v[158:161], v[208:211], v[68:71]
	v_mfma_f32_16x16x32_bf16 v[64:67], v[166:169], v[208:211], v[64:67]
	v_mfma_f32_16x16x32_bf16 v[108:111], v[162:165], v[178:181], v[108:111]
	v_mfma_f32_16x16x32_bf16 v[104:107], v[170:173], v[178:181], v[104:107]
	v_mfma_f32_16x16x32_bf16 v[92:95], v[162:165], v[196:199], v[92:95]
	v_mfma_f32_16x16x32_bf16 v[88:91], v[170:173], v[196:199], v[88:91]
	v_mfma_f32_16x16x32_bf16 v[76:79], v[162:165], v[204:207], v[76:79]
	v_mfma_f32_16x16x32_bf16 v[72:75], v[170:173], v[204:207], v[72:75]
	v_mfma_f32_16x16x32_bf16 v[68:71], v[162:165], v[212:215], v[68:71]
	v_mfma_f32_16x16x32_bf16 v[64:67], v[170:173], v[212:215], v[64:67]
	s_setprio 0
	s_barrier
	s_add_i32 s34, s60, s38
	v_lshl_add_u64 v[186:187], v[186:187], 0, s[58:59]
	s_mov_b32 m0, s34
	ds_read_b128 v[174:177], v141 offset:49152
	ds_read_b128 v[178:181], v141 offset:50176
	ds_read_b128 v[182:185], v141 offset:51200
	ds_read_b128 v[196:199], v141 offset:52224
	ds_read_b128 v[200:203], v141 offset:53248
	ds_read_b128 v[204:207], v141 offset:54272
	ds_read_b128 v[208:211], v141 offset:55296
	ds_read_b128 v[212:215], v141 offset:56320
	global_load_lds_dwordx4 v[186:187], off
	s_add_i32 m0, s34, 0x2000
	s_add_u32 s30, s30, 0x80080
	v_lshl_add_u64 v[186:187], v[216:217], 0, s[58:59]
	s_addc_u32 s31, s31, 0
	s_add_i32 s34, s61, s38
	global_load_lds_dwordx4 v[186:187], off
	v_lshl_add_u64 v[186:187], s[30:31], 0, v[190:191]
	s_mov_b32 m0, s34
	s_nop 0
	global_load_lds_dwordx4 v[186:187], off
	v_lshl_add_u64 v[186:187], s[30:31], 0, v[132:133]
	s_add_i32 m0, s34, 0x2000
	s_nop 0
	global_load_lds_dwordx4 v[186:187], off
	v_lshl_add_u64 v[186:187], v[218:219], 0, s[58:59]
	s_mov_b32 m0, s43
	s_nop 0
	global_load_lds_dwordx4 v[186:187], off
	v_lshl_add_u64 v[186:187], v[220:221], 0, s[58:59]
	s_mov_b32 m0, s47
	s_nop 0
	global_load_lds_dwordx4 v[186:187], off
	s_waitcnt vmcnt(8)
	s_waitcnt lgkmcnt(0)
	s_barrier
	s_setprio 1
	v_mfma_f32_16x16x32_bf16 v[60:63], v[142:145], v[174:177], v[60:63]
	v_mfma_f32_16x16x32_bf16 v[56:59], v[150:153], v[174:177], v[56:59]
	v_mfma_f32_16x16x32_bf16 v[52:55], v[142:145], v[182:185], v[52:55]
	v_mfma_f32_16x16x32_bf16 v[48:51], v[150:153], v[182:185], v[48:51]
	v_mfma_f32_16x16x32_bf16 v[36:39], v[142:145], v[200:203], v[36:39]
	v_mfma_f32_16x16x32_bf16 v[32:35], v[150:153], v[200:203], v[32:35]
	v_mfma_f32_16x16x32_bf16 v[20:23], v[142:145], v[208:211], v[20:23]
	v_mfma_f32_16x16x32_bf16 v[16:19], v[150:153], v[208:211], v[16:19]
	v_mfma_f32_16x16x32_bf16 v[60:63], v[146:149], v[178:181], v[60:63]
	v_mfma_f32_16x16x32_bf16 v[56:59], v[154:157], v[178:181], v[56:59]
	v_mfma_f32_16x16x32_bf16 v[52:55], v[146:149], v[196:199], v[52:55]
	v_mfma_f32_16x16x32_bf16 v[48:51], v[154:157], v[196:199], v[48:51]
	v_mfma_f32_16x16x32_bf16 v[36:39], v[146:149], v[204:207], v[36:39]
	v_mfma_f32_16x16x32_bf16 v[32:35], v[154:157], v[204:207], v[32:35]
	v_mfma_f32_16x16x32_bf16 v[20:23], v[146:149], v[212:215], v[20:23]
	v_mfma_f32_16x16x32_bf16 v[16:19], v[154:157], v[212:215], v[16:19]
	s_setprio 0
	s_setprio 1
	v_mfma_f32_16x16x32_bf16 v[44:47], v[158:161], v[174:177], v[44:47]
	v_mfma_f32_16x16x32_bf16 v[40:43], v[166:169], v[174:177], v[40:43]
	v_mfma_f32_16x16x32_bf16 v[28:31], v[158:161], v[182:185], v[28:31]
	v_mfma_f32_16x16x32_bf16 v[24:27], v[166:169], v[182:185], v[24:27]
	v_mfma_f32_16x16x32_bf16 v[12:15], v[158:161], v[200:203], v[12:15]
	v_mfma_f32_16x16x32_bf16 v[8:11], v[166:169], v[200:203], v[8:11]
	v_mfma_f32_16x16x32_bf16 v[4:7], v[158:161], v[208:211], v[4:7]
	v_mfma_f32_16x16x32_bf16 v[0:3], v[166:169], v[208:211], v[0:3]
	v_mfma_f32_16x16x32_bf16 v[44:47], v[162:165], v[178:181], v[44:47]
	v_mfma_f32_16x16x32_bf16 v[40:43], v[170:173], v[178:181], v[40:43]
	v_mfma_f32_16x16x32_bf16 v[28:31], v[162:165], v[196:199], v[28:31]
	v_mfma_f32_16x16x32_bf16 v[24:27], v[170:173], v[196:199], v[24:27]
	v_mfma_f32_16x16x32_bf16 v[12:15], v[162:165], v[204:207], v[12:15]
	v_mfma_f32_16x16x32_bf16 v[8:11], v[170:173], v[204:207], v[8:11]
	v_mfma_f32_16x16x32_bf16 v[4:7], v[162:165], v[212:215], v[4:7]
	v_mfma_f32_16x16x32_bf16 v[0:3], v[170:173], v[212:215], v[0:3]
	s_setprio 0
	s_barrier
	s_add_i32 s57, s57, 2
	s_add_u32 s28, s28, 0x100
	s_addc_u32 s29, s29, 0
	s_add_u32 s55, s55, 0x100
	s_addc_u32 s56, s56, 0
	s_cmp_gt_u32 s57, 29
	s_cbranch_scc1 .Lpeel_done_6
	s_branch .LBB0_938
.Ltrip0_strict_6:
	s_add_u32 s30, s28, 0xfff80080
	s_addc_u32 s31, s29, -1
	s_add_i32 s60, 0, 0x10000
	s_cmp_eq_u32 s57, 28
	s_cselect_b32 s35, s11, s31
	s_cselect_b32 s34, s23, s30
	s_cselect_b32 s31, s21, s56
	s_cselect_b32 s30, s53, s55
	s_add_i32 s66, 0, 0x14000
	v_add_u32_e32 v154, s60, v139
	v_add_u32_e32 v170, s66, v139
	ds_read_b128 v[142:145], v154
	ds_read_b128 v[146:149], v154 offset:1024
	ds_read_b128 v[150:153], v154 offset:2048
	ds_read_b128 v[154:157], v154 offset:3072
	ds_read_b128 v[158:161], v170
	ds_read_b128 v[162:165], v170 offset:1024
	ds_read_b128 v[166:169], v170 offset:2048
	ds_read_b128 v[170:173], v170 offset:3072
	v_lshl_add_u64 v[186:187], s[28:29], 0, v[134:135]
	s_add_i32 m0, s13, 0xc000
	ds_read_b128 v[174:177], v141
	ds_read_b128 v[178:181], v141 offset:1024
	ds_read_b128 v[182:185], v141 offset:2048
	ds_read_b128 v[196:199], v141 offset:3072
	ds_read_b128 v[200:203], v141 offset:4096
	ds_read_b128 v[204:207], v141 offset:5120
	ds_read_b128 v[208:211], v141 offset:6144
	ds_read_b128 v[212:215], v141 offset:7168
	global_load_lds_dwordx4 v[186:187], off
	v_lshl_add_u64 v[186:187], s[28:29], 0, v[136:137]
	s_add_i32 m0, s13, 0xe000
	s_nop 0
	global_load_lds_dwordx4 v[186:187], off
	s_waitcnt vmcnt(8)
	s_waitcnt lgkmcnt(0)
	s_barrier
	s_setprio 1
	v_mfma_f32_16x16x32_bf16 v[124:127], v[142:145], v[174:177], 0
	v_mfma_f32_16x16x32_bf16 v[120:123], v[150:153], v[174:177], 0
	v_mfma_f32_16x16x32_bf16 v[116:119], v[142:145], v[182:185], 0
	v_mfma_f32_16x16x32_bf16 v[112:115], v[150:153], v[182:185], 0
	v_mfma_f32_16x16x32_bf16 v[100:103], v[142:145], v[200:203], 0
	v_mfma_f32_16x16x32_bf16 v[96:99], v[150:153], v[200:203], 0
	v_mfma_f32_16x16x32_bf16 v[84:87], v[142:145], v[208:211], 0
	v_mfma_f32_16x16x32_bf16 v[80:83], v[150:153], v[208:211], 0
	v_mfma_f32_16x16x32_bf16 v[124:127], v[146:149], v[178:181], v[124:127]
	v_mfma_f32_16x16x32_bf16 v[120:123], v[154:157], v[178:181], v[120:123]
	v_mfma_f32_16x16x32_bf16 v[116:119], v[146:149], v[196:199], v[116:119]
	v_mfma_f32_16x16x32_bf16 v[112:115], v[154:157], v[196:199], v[112:115]
	v_mfma_f32_16x16x32_bf16 v[100:103], v[146:149], v[204:207], v[100:103]
	v_mfma_f32_16x16x32_bf16 v[96:99], v[154:157], v[204:207], v[96:99]
	v_mfma_f32_16x16x32_bf16 v[84:87], v[146:149], v[212:215], v[84:87]
	v_mfma_f32_16x16x32_bf16 v[80:83], v[154:157], v[212:215], v[80:83]
	s_setprio 0
	s_setprio 1
	v_mfma_f32_16x16x32_bf16 v[108:111], v[158:161], v[174:177], 0
	v_mfma_f32_16x16x32_bf16 v[104:107], v[166:169], v[174:177], 0
	v_mfma_f32_16x16x32_bf16 v[92:95], v[158:161], v[182:185], 0
	v_mfma_f32_16x16x32_bf16 v[88:91], v[166:169], v[182:185], 0
	v_mfma_f32_16x16x32_bf16 v[76:79], v[158:161], v[200:203], 0
	v_mfma_f32_16x16x32_bf16 v[72:75], v[166:169], v[200:203], 0
	v_mfma_f32_16x16x32_bf16 v[68:71], v[158:161], v[208:211], 0
	v_mfma_f32_16x16x32_bf16 v[64:67], v[166:169], v[208:211], 0
	v_mfma_f32_16x16x32_bf16 v[108:111], v[162:165], v[178:181], v[108:111]
	v_mfma_f32_16x16x32_bf16 v[104:107], v[170:173], v[178:181], v[104:107]
	v_mfma_f32_16x16x32_bf16 v[92:95], v[162:165], v[196:199], v[92:95]
	v_mfma_f32_16x16x32_bf16 v[88:91], v[170:173], v[196:199], v[88:91]
	v_mfma_f32_16x16x32_bf16 v[76:79], v[162:165], v[204:207], v[76:79]
	v_mfma_f32_16x16x32_bf16 v[72:75], v[170:173], v[204:207], v[72:75]
	v_mfma_f32_16x16x32_bf16 v[68:71], v[162:165], v[212:215], v[68:71]
	v_mfma_f32_16x16x32_bf16 v[64:67], v[170:173], v[212:215], v[64:67]
	s_setprio 0
	s_barrier
	s_add_i32 s60, s60, s38
	v_lshl_add_u64 v[186:187], s[30:31], 0, v[190:191]
	s_mov_b32 m0, s60
	ds_read_b128 v[174:177], v141 offset:16384
	ds_read_b128 v[178:181], v141 offset:17408
	ds_read_b128 v[182:185], v141 offset:18432
	ds_read_b128 v[196:199], v141 offset:19456
	ds_read_b128 v[200:203], v141 offset:20480
	ds_read_b128 v[204:207], v141 offset:21504
	ds_read_b128 v[208:211], v141 offset:22528
	ds_read_b128 v[212:215], v141 offset:23552
	global_load_lds_dwordx4 v[186:187], off
	s_add_i32 m0, s60, 0x2000
	s_add_u32 s60, s30, 0x80000
	v_lshl_add_u64 v[216:217], s[30:31], 0, v[132:133]
	s_addc_u32 s61, s31, 0
	s_add_i32 s66, s66, s38
	global_load_lds_dwordx4 v[216:217], off
	v_lshl_add_u64 v[218:219], s[60:61], 0, v[190:191]
	s_mov_b32 m0, s66
	v_lshl_add_u64 v[220:221], s[34:35], 0, v[130:131]
	global_load_lds_dwordx4 v[218:219], off
	v_lshl_add_u64 v[218:219], s[60:61], 0, v[132:133]
	s_add_i32 m0, s66, 0x2000
	s_nop 0
	global_load_lds_dwordx4 v[218:219], off
	v_lshl_add_u64 v[218:219], s[34:35], 0, v[128:129]
	s_mov_b32 m0, s13
	s_nop 0
	global_load_lds_dwordx4 v[218:219], off
	s_mov_b32 m0, s39
	s_nop 0
	global_load_lds_dwordx4 v[220:221], off
	s_waitcnt vmcnt(8)
	s_waitcnt lgkmcnt(0)
	s_barrier
	s_setprio 1
	v_mfma_f32_16x16x32_bf16 v[60:63], v[142:145], v[174:177], 0
	v_mfma_f32_16x16x32_bf16 v[56:59], v[150:153], v[174:177], 0
	v_mfma_f32_16x16x32_bf16 v[52:55], v[142:145], v[182:185], 0
	v_mfma_f32_16x16x32_bf16 v[48:51], v[150:153], v[182:185], 0
	v_mfma_f32_16x16x32_bf16 v[36:39], v[142:145], v[200:203], 0
	v_mfma_f32_16x16x32_bf16 v[32:35], v[150:153], v[200:203], 0
	v_mfma_f32_16x16x32_bf16 v[20:23], v[142:145], v[208:211], 0
	v_mfma_f32_16x16x32_bf16 v[16:19], v[150:153], v[208:211], 0
	v_mfma_f32_16x16x32_bf16 v[60:63], v[146:149], v[178:181], v[60:63]
	v_mfma_f32_16x16x32_bf16 v[56:59], v[154:157], v[178:181], v[56:59]
	v_mfma_f32_16x16x32_bf16 v[52:55], v[146:149], v[196:199], v[52:55]
	v_mfma_f32_16x16x32_bf16 v[48:51], v[154:157], v[196:199], v[48:51]
	v_mfma_f32_16x16x32_bf16 v[36:39], v[146:149], v[204:207], v[36:39]
	v_mfma_f32_16x16x32_bf16 v[32:35], v[154:157], v[204:207], v[32:35]
	v_mfma_f32_16x16x32_bf16 v[20:23], v[146:149], v[212:215], v[20:23]
	v_mfma_f32_16x16x32_bf16 v[16:19], v[154:157], v[212:215], v[16:19]
	s_setprio 0
	s_setprio 1
	v_mfma_f32_16x16x32_bf16 v[44:47], v[158:161], v[174:177], 0
	v_mfma_f32_16x16x32_bf16 v[40:43], v[166:169], v[174:177], 0
	v_mfma_f32_16x16x32_bf16 v[28:31], v[158:161], v[182:185], 0
	v_mfma_f32_16x16x32_bf16 v[24:27], v[166:169], v[182:185], 0
	v_mfma_f32_16x16x32_bf16 v[12:15], v[158:161], v[200:203], 0
	v_mfma_f32_16x16x32_bf16 v[8:11], v[166:169], v[200:203], 0
	v_mfma_f32_16x16x32_bf16 v[4:7], v[158:161], v[208:211], 0
	v_mfma_f32_16x16x32_bf16 v[0:3], v[166:169], v[208:211], 0
	v_mfma_f32_16x16x32_bf16 v[44:47], v[162:165], v[178:181], v[44:47]
	v_mfma_f32_16x16x32_bf16 v[40:43], v[170:173], v[178:181], v[40:43]
	v_mfma_f32_16x16x32_bf16 v[28:31], v[162:165], v[196:199], v[28:31]
	v_mfma_f32_16x16x32_bf16 v[24:27], v[170:173], v[196:199], v[24:27]
	v_mfma_f32_16x16x32_bf16 v[12:15], v[162:165], v[204:207], v[12:15]
	v_mfma_f32_16x16x32_bf16 v[8:11], v[170:173], v[204:207], v[8:11]
	v_mfma_f32_16x16x32_bf16 v[4:7], v[162:165], v[212:215], v[4:7]
	v_mfma_f32_16x16x32_bf16 v[0:3], v[170:173], v[212:215], v[0:3]
	s_setprio 0
	s_barrier
	s_add_i32 s60, 0, 0x18000
	s_add_i32 s61, 0, 0x1c000
	v_add_u32_e32 v154, s60, v139
	v_add_u32_e32 v170, s61, v139
	ds_read_b128 v[142:145], v154
	ds_read_b128 v[146:149], v154 offset:1024
	ds_read_b128 v[150:153], v154 offset:2048
	ds_read_b128 v[154:157], v154 offset:3072
	ds_read_b128 v[158:161], v170
	ds_read_b128 v[162:165], v170 offset:1024
	ds_read_b128 v[166:169], v170 offset:2048
	ds_read_b128 v[170:173], v170 offset:3072
	s_add_u32 s34, s34, 0x80000
	s_addc_u32 s35, s35, 0
	s_mov_b32 m0, s41
	v_lshl_add_u64 v[222:223], s[34:35], 0, v[128:129]
	ds_read_b128 v[174:177], v141 offset:32768
	ds_read_b128 v[178:181], v141 offset:33792
	ds_read_b128 v[182:185], v141 offset:34816
	ds_read_b128 v[196:199], v141 offset:35840
	ds_read_b128 v[200:203], v141 offset:36864
	ds_read_b128 v[204:207], v141 offset:37888
	ds_read_b128 v[208:211], v141 offset:38912
	ds_read_b128 v[212:215], v141 offset:39936
	global_load_lds_dwordx4 v[222:223], off
	v_lshl_add_u64 v[222:223], s[34:35], 0, v[130:131]
	s_mov_b32 m0, s42
	s_nop 0
	global_load_lds_dwordx4 v[222:223], off
	s_waitcnt vmcnt(8)
	s_waitcnt lgkmcnt(0)
	s_barrier
	s_setprio 1
	v_mfma_f32_16x16x32_bf16 v[124:127], v[142:145], v[174:177], v[124:127]
	v_mfma_f32_16x16x32_bf16 v[120:123], v[150:153], v[174:177], v[120:123]
	v_mfma_f32_16x16x32_bf16 v[116:119], v[142:145], v[182:185], v[116:119]
	v_mfma_f32_16x16x32_bf16 v[112:115], v[150:153], v[182:185], v[112:115]
	v_mfma_f32_16x16x32_bf16 v[100:103], v[142:145], v[200:203], v[100:103]
	v_mfma_f32_16x16x32_bf16 v[96:99], v[150:153], v[200:203], v[96:99]
	v_mfma_f32_16x16x32_bf16 v[84:87], v[142:145], v[208:211], v[84:87]
	v_mfma_f32_16x16x32_bf16 v[80:83], v[150:153], v[208:211], v[80:83]
	v_mfma_f32_16x16x32_bf16 v[124:127], v[146:149], v[178:181], v[124:127]
	v_mfma_f32_16x16x32_bf16 v[120:123], v[154:157], v[178:181], v[120:123]
	v_mfma_f32_16x16x32_bf16 v[116:119], v[146:149], v[196:199], v[116:119]
	v_mfma_f32_16x16x32_bf16 v[112:115], v[154:157], v[196:199], v[112:115]
	v_mfma_f32_16x16x32_bf16 v[100:103], v[146:149], v[204:207], v[100:103]
	v_mfma_f32_16x16x32_bf16 v[96:99], v[154:157], v[204:207], v[96:99]
	v_mfma_f32_16x16x32_bf16 v[84:87], v[146:149], v[212:215], v[84:87]
	v_mfma_f32_16x16x32_bf16 v[80:83], v[154:157], v[212:215], v[80:83]
	s_setprio 0
	s_setprio 1
	v_mfma_f32_16x16x32_bf16 v[108:111], v[158:161], v[174:177], v[108:111]
	v_mfma_f32_16x16x32_bf16 v[104:107], v[166:169], v[174:177], v[104:107]
	v_mfma_f32_16x16x32_bf16 v[92:95], v[158:161], v[182:185], v[92:95]
	v_mfma_f32_16x16x32_bf16 v[88:91], v[166:169], v[182:185], v[88:91]
	v_mfma_f32_16x16x32_bf16 v[76:79], v[158:161], v[200:203], v[76:79]
	v_mfma_f32_16x16x32_bf16 v[72:75], v[166:169], v[200:203], v[72:75]
	v_mfma_f32_16x16x32_bf16 v[68:71], v[158:161], v[208:211], v[68:71]
	v_mfma_f32_16x16x32_bf16 v[64:67], v[166:169], v[208:211], v[64:67]
	v_mfma_f32_16x16x32_bf16 v[108:111], v[162:165], v[178:181], v[108:111]
	v_mfma_f32_16x16x32_bf16 v[104:107], v[170:173], v[178:181], v[104:107]
	v_mfma_f32_16x16x32_bf16 v[92:95], v[162:165], v[196:199], v[92:95]
	v_mfma_f32_16x16x32_bf16 v[88:91], v[170:173], v[196:199], v[88:91]
	v_mfma_f32_16x16x32_bf16 v[76:79], v[162:165], v[204:207], v[76:79]
	v_mfma_f32_16x16x32_bf16 v[72:75], v[170:173], v[204:207], v[72:75]
	v_mfma_f32_16x16x32_bf16 v[68:71], v[162:165], v[212:215], v[68:71]
	v_mfma_f32_16x16x32_bf16 v[64:67], v[170:173], v[212:215], v[64:67]
	s_setprio 0
	s_barrier
	s_add_i32 s34, s60, s38
	v_lshl_add_u64 v[186:187], v[186:187], 0, s[58:59]
	s_mov_b32 m0, s34
	ds_read_b128 v[174:177], v141 offset:49152
	ds_read_b128 v[178:181], v141 offset:50176
	ds_read_b128 v[182:185], v141 offset:51200
	ds_read_b128 v[196:199], v141 offset:52224
	ds_read_b128 v[200:203], v141 offset:53248
	ds_read_b128 v[204:207], v141 offset:54272
	ds_read_b128 v[208:211], v141 offset:55296
	ds_read_b128 v[212:215], v141 offset:56320
	global_load_lds_dwordx4 v[186:187], off
	s_add_i32 m0, s34, 0x2000
	s_add_u32 s30, s30, 0x80080
	v_lshl_add_u64 v[186:187], v[216:217], 0, s[58:59]
	s_addc_u32 s31, s31, 0
	s_add_i32 s34, s61, s38
	global_load_lds_dwordx4 v[186:187], off
	v_lshl_add_u64 v[186:187], s[30:31], 0, v[190:191]
	s_mov_b32 m0, s34
	s_nop 0
	global_load_lds_dwordx4 v[186:187], off
	v_lshl_add_u64 v[186:187], s[30:31], 0, v[132:133]
	s_add_i32 m0, s34, 0x2000
	s_nop 0
	global_load_lds_dwordx4 v[186:187], off
	v_lshl_add_u64 v[186:187], v[218:219], 0, s[58:59]
	s_mov_b32 m0, s43
	s_nop 0
	global_load_lds_dwordx4 v[186:187], off
	v_lshl_add_u64 v[186:187], v[220:221], 0, s[58:59]
	s_mov_b32 m0, s47
	s_nop 0
	global_load_lds_dwordx4 v[186:187], off
	s_waitcnt vmcnt(8)
	s_waitcnt lgkmcnt(0)
	s_barrier
	s_setprio 1
	v_mfma_f32_16x16x32_bf16 v[60:63], v[142:145], v[174:177], v[60:63]
	v_mfma_f32_16x16x32_bf16 v[56:59], v[150:153], v[174:177], v[56:59]
	v_mfma_f32_16x16x32_bf16 v[52:55], v[142:145], v[182:185], v[52:55]
	v_mfma_f32_16x16x32_bf16 v[48:51], v[150:153], v[182:185], v[48:51]
	v_mfma_f32_16x16x32_bf16 v[36:39], v[142:145], v[200:203], v[36:39]
	v_mfma_f32_16x16x32_bf16 v[32:35], v[150:153], v[200:203], v[32:35]
	v_mfma_f32_16x16x32_bf16 v[20:23], v[142:145], v[208:211], v[20:23]
	v_mfma_f32_16x16x32_bf16 v[16:19], v[150:153], v[208:211], v[16:19]
	v_mfma_f32_16x16x32_bf16 v[60:63], v[146:149], v[178:181], v[60:63]
	v_mfma_f32_16x16x32_bf16 v[56:59], v[154:157], v[178:181], v[56:59]
	v_mfma_f32_16x16x32_bf16 v[52:55], v[146:149], v[196:199], v[52:55]
	v_mfma_f32_16x16x32_bf16 v[48:51], v[154:157], v[196:199], v[48:51]
	v_mfma_f32_16x16x32_bf16 v[36:39], v[146:149], v[204:207], v[36:39]
	v_mfma_f32_16x16x32_bf16 v[32:35], v[154:157], v[204:207], v[32:35]
	v_mfma_f32_16x16x32_bf16 v[20:23], v[146:149], v[212:215], v[20:23]
	v_mfma_f32_16x16x32_bf16 v[16:19], v[154:157], v[212:215], v[16:19]
	s_setprio 0
	s_setprio 1
	v_mfma_f32_16x16x32_bf16 v[44:47], v[158:161], v[174:177], v[44:47]
	v_mfma_f32_16x16x32_bf16 v[40:43], v[166:169], v[174:177], v[40:43]
	v_mfma_f32_16x16x32_bf16 v[28:31], v[158:161], v[182:185], v[28:31]
	v_mfma_f32_16x16x32_bf16 v[24:27], v[166:169], v[182:185], v[24:27]
	v_mfma_f32_16x16x32_bf16 v[12:15], v[158:161], v[200:203], v[12:15]
	v_mfma_f32_16x16x32_bf16 v[8:11], v[166:169], v[200:203], v[8:11]
	v_mfma_f32_16x16x32_bf16 v[4:7], v[158:161], v[208:211], v[4:7]
	v_mfma_f32_16x16x32_bf16 v[0:3], v[166:169], v[208:211], v[0:3]
	v_mfma_f32_16x16x32_bf16 v[44:47], v[162:165], v[178:181], v[44:47]
	v_mfma_f32_16x16x32_bf16 v[40:43], v[170:173], v[178:181], v[40:43]
	v_mfma_f32_16x16x32_bf16 v[28:31], v[162:165], v[196:199], v[28:31]
	v_mfma_f32_16x16x32_bf16 v[24:27], v[170:173], v[196:199], v[24:27]
	v_mfma_f32_16x16x32_bf16 v[12:15], v[162:165], v[204:207], v[12:15]
	v_mfma_f32_16x16x32_bf16 v[8:11], v[170:173], v[204:207], v[8:11]
	v_mfma_f32_16x16x32_bf16 v[4:7], v[162:165], v[212:215], v[4:7]
	v_mfma_f32_16x16x32_bf16 v[0:3], v[170:173], v[212:215], v[0:3]
	s_setprio 0
	s_barrier
	s_add_i32 s57, s57, 2
	s_add_u32 s28, s28, 0x100
	s_addc_u32 s29, s29, 0
	s_add_u32 s55, s55, 0x100
	s_addc_u32 s56, s56, 0
	s_cmp_gt_u32 s57, 29
	s_cbranch_scc1 .Lpeel_done_6
.LBB0_938:
	s_add_u32 s30, s28, 0xfff80080
	s_addc_u32 s31, s29, -1
	s_add_i32 s60, 0, 0x10000
	s_cmp_eq_u32 s57, 28
	s_cselect_b32 s35, s11, s31
	s_cselect_b32 s34, s23, s30
	s_cselect_b32 s31, s21, s56
	s_cselect_b32 s30, s53, s55
	s_add_i32 s66, 0, 0x14000
	v_add_u32_e32 v154, s60, v139
	v_add_u32_e32 v170, s66, v139
	ds_read_b128 v[142:145], v154
	ds_read_b128 v[146:149], v154 offset:1024
	ds_read_b128 v[150:153], v154 offset:2048
	ds_read_b128 v[154:157], v154 offset:3072
	ds_read_b128 v[158:161], v170
	ds_read_b128 v[162:165], v170 offset:1024
	ds_read_b128 v[166:169], v170 offset:2048
	ds_read_b128 v[170:173], v170 offset:3072
	v_lshl_add_u64 v[186:187], s[28:29], 0, v[134:135]
	s_add_i32 m0, s13, 0xc000
	ds_read_b128 v[174:177], v141
	ds_read_b128 v[178:181], v141 offset:1024
	ds_read_b128 v[182:185], v141 offset:2048
	ds_read_b128 v[196:199], v141 offset:3072
	ds_read_b128 v[200:203], v141 offset:4096
	ds_read_b128 v[204:207], v141 offset:5120
	ds_read_b128 v[208:211], v141 offset:6144
	ds_read_b128 v[212:215], v141 offset:7168
	global_load_lds_dwordx4 v[186:187], off
	v_lshl_add_u64 v[186:187], s[28:29], 0, v[136:137]
	s_add_i32 m0, s13, 0xe000
	s_nop 0
	global_load_lds_dwordx4 v[186:187], off
	s_waitcnt vmcnt(8)
	s_waitcnt lgkmcnt(0)
	s_barrier
	s_setprio 1
	v_mfma_f32_16x16x32_bf16 v[124:127], v[142:145], v[174:177], v[124:127]
	v_mfma_f32_16x16x32_bf16 v[120:123], v[150:153], v[174:177], v[120:123]
	v_mfma_f32_16x16x32_bf16 v[116:119], v[142:145], v[182:185], v[116:119]
	v_mfma_f32_16x16x32_bf16 v[112:115], v[150:153], v[182:185], v[112:115]
	v_mfma_f32_16x16x32_bf16 v[100:103], v[142:145], v[200:203], v[100:103]
	v_mfma_f32_16x16x32_bf16 v[96:99], v[150:153], v[200:203], v[96:99]
	v_mfma_f32_16x16x32_bf16 v[84:87], v[142:145], v[208:211], v[84:87]
	v_mfma_f32_16x16x32_bf16 v[80:83], v[150:153], v[208:211], v[80:83]
	v_mfma_f32_16x16x32_bf16 v[124:127], v[146:149], v[178:181], v[124:127]
	v_mfma_f32_16x16x32_bf16 v[120:123], v[154:157], v[178:181], v[120:123]
	v_mfma_f32_16x16x32_bf16 v[116:119], v[146:149], v[196:199], v[116:119]
	v_mfma_f32_16x16x32_bf16 v[112:115], v[154:157], v[196:199], v[112:115]
	v_mfma_f32_16x16x32_bf16 v[100:103], v[146:149], v[204:207], v[100:103]
	v_mfma_f32_16x16x32_bf16 v[96:99], v[154:157], v[204:207], v[96:99]
	v_mfma_f32_16x16x32_bf16 v[84:87], v[146:149], v[212:215], v[84:87]
	v_mfma_f32_16x16x32_bf16 v[80:83], v[154:157], v[212:215], v[80:83]
	s_setprio 0
	s_setprio 1
	v_mfma_f32_16x16x32_bf16 v[108:111], v[158:161], v[174:177], v[108:111]
	v_mfma_f32_16x16x32_bf16 v[104:107], v[166:169], v[174:177], v[104:107]
	v_mfma_f32_16x16x32_bf16 v[92:95], v[158:161], v[182:185], v[92:95]
	v_mfma_f32_16x16x32_bf16 v[88:91], v[166:169], v[182:185], v[88:91]
	v_mfma_f32_16x16x32_bf16 v[76:79], v[158:161], v[200:203], v[76:79]
	v_mfma_f32_16x16x32_bf16 v[72:75], v[166:169], v[200:203], v[72:75]
	v_mfma_f32_16x16x32_bf16 v[68:71], v[158:161], v[208:211], v[68:71]
	v_mfma_f32_16x16x32_bf16 v[64:67], v[166:169], v[208:211], v[64:67]
	v_mfma_f32_16x16x32_bf16 v[108:111], v[162:165], v[178:181], v[108:111]
	v_mfma_f32_16x16x32_bf16 v[104:107], v[170:173], v[178:181], v[104:107]
	v_mfma_f32_16x16x32_bf16 v[92:95], v[162:165], v[196:199], v[92:95]
	v_mfma_f32_16x16x32_bf16 v[88:91], v[170:173], v[196:199], v[88:91]
	v_mfma_f32_16x16x32_bf16 v[76:79], v[162:165], v[204:207], v[76:79]
	v_mfma_f32_16x16x32_bf16 v[72:75], v[170:173], v[204:207], v[72:75]
	v_mfma_f32_16x16x32_bf16 v[68:71], v[162:165], v[212:215], v[68:71]
	v_mfma_f32_16x16x32_bf16 v[64:67], v[170:173], v[212:215], v[64:67]
	s_setprio 0
	s_barrier
	s_add_i32 s60, s60, s38
	v_lshl_add_u64 v[186:187], s[30:31], 0, v[190:191]
	s_mov_b32 m0, s60
	ds_read_b128 v[174:177], v141 offset:16384
	ds_read_b128 v[178:181], v141 offset:17408
	ds_read_b128 v[182:185], v141 offset:18432
	ds_read_b128 v[196:199], v141 offset:19456
	ds_read_b128 v[200:203], v141 offset:20480
	ds_read_b128 v[204:207], v141 offset:21504
	ds_read_b128 v[208:211], v141 offset:22528
	ds_read_b128 v[212:215], v141 offset:23552
	global_load_lds_dwordx4 v[186:187], off
	s_add_i32 m0, s60, 0x2000
	s_add_u32 s60, s30, 0x80000
	v_lshl_add_u64 v[216:217], s[30:31], 0, v[132:133]
	s_addc_u32 s61, s31, 0
	s_add_i32 s66, s66, s38
	global_load_lds_dwordx4 v[216:217], off
	v_lshl_add_u64 v[218:219], s[60:61], 0, v[190:191]
	s_mov_b32 m0, s66
	v_lshl_add_u64 v[220:221], s[34:35], 0, v[130:131]
	global_load_lds_dwordx4 v[218:219], off
	v_lshl_add_u64 v[218:219], s[60:61], 0, v[132:133]
	s_add_i32 m0, s66, 0x2000
	s_nop 0
	global_load_lds_dwordx4 v[218:219], off
	v_lshl_add_u64 v[218:219], s[34:35], 0, v[128:129]
	s_mov_b32 m0, s13
	s_nop 0
	global_load_lds_dwordx4 v[218:219], off
	s_mov_b32 m0, s39
	s_nop 0
	global_load_lds_dwordx4 v[220:221], off
	s_waitcnt vmcnt(8)
	s_waitcnt lgkmcnt(0)
	s_barrier
	s_setprio 1
	v_mfma_f32_16x16x32_bf16 v[60:63], v[142:145], v[174:177], v[60:63]
	v_mfma_f32_16x16x32_bf16 v[56:59], v[150:153], v[174:177], v[56:59]
	v_mfma_f32_16x16x32_bf16 v[52:55], v[142:145], v[182:185], v[52:55]
	v_mfma_f32_16x16x32_bf16 v[48:51], v[150:153], v[182:185], v[48:51]
	v_mfma_f32_16x16x32_bf16 v[36:39], v[142:145], v[200:203], v[36:39]
	v_mfma_f32_16x16x32_bf16 v[32:35], v[150:153], v[200:203], v[32:35]
	v_mfma_f32_16x16x32_bf16 v[20:23], v[142:145], v[208:211], v[20:23]
	v_mfma_f32_16x16x32_bf16 v[16:19], v[150:153], v[208:211], v[16:19]
	v_mfma_f32_16x16x32_bf16 v[60:63], v[146:149], v[178:181], v[60:63]
	v_mfma_f32_16x16x32_bf16 v[56:59], v[154:157], v[178:181], v[56:59]
	v_mfma_f32_16x16x32_bf16 v[52:55], v[146:149], v[196:199], v[52:55]
	v_mfma_f32_16x16x32_bf16 v[48:51], v[154:157], v[196:199], v[48:51]
	v_mfma_f32_16x16x32_bf16 v[36:39], v[146:149], v[204:207], v[36:39]
	v_mfma_f32_16x16x32_bf16 v[32:35], v[154:157], v[204:207], v[32:35]
	v_mfma_f32_16x16x32_bf16 v[20:23], v[146:149], v[212:215], v[20:23]
	v_mfma_f32_16x16x32_bf16 v[16:19], v[154:157], v[212:215], v[16:19]
	s_setprio 0
	s_setprio 1
	v_mfma_f32_16x16x32_bf16 v[44:47], v[158:161], v[174:177], v[44:47]
	v_mfma_f32_16x16x32_bf16 v[40:43], v[166:169], v[174:177], v[40:43]
	v_mfma_f32_16x16x32_bf16 v[28:31], v[158:161], v[182:185], v[28:31]
	v_mfma_f32_16x16x32_bf16 v[24:27], v[166:169], v[182:185], v[24:27]
	v_mfma_f32_16x16x32_bf16 v[12:15], v[158:161], v[200:203], v[12:15]
	v_mfma_f32_16x16x32_bf16 v[8:11], v[166:169], v[200:203], v[8:11]
	v_mfma_f32_16x16x32_bf16 v[4:7], v[158:161], v[208:211], v[4:7]
	v_mfma_f32_16x16x32_bf16 v[0:3], v[166:169], v[208:211], v[0:3]
	v_mfma_f32_16x16x32_bf16 v[44:47], v[162:165], v[178:181], v[44:47]
	v_mfma_f32_16x16x32_bf16 v[40:43], v[170:173], v[178:181], v[40:43]
	v_mfma_f32_16x16x32_bf16 v[28:31], v[162:165], v[196:199], v[28:31]
	v_mfma_f32_16x16x32_bf16 v[24:27], v[170:173], v[196:199], v[24:27]
	v_mfma_f32_16x16x32_bf16 v[12:15], v[162:165], v[204:207], v[12:15]
	v_mfma_f32_16x16x32_bf16 v[8:11], v[170:173], v[204:207], v[8:11]
	v_mfma_f32_16x16x32_bf16 v[4:7], v[162:165], v[212:215], v[4:7]
	v_mfma_f32_16x16x32_bf16 v[0:3], v[170:173], v[212:215], v[0:3]
	s_setprio 0
	s_barrier
	s_add_i32 s60, 0, 0x18000
	s_add_i32 s61, 0, 0x1c000
	v_add_u32_e32 v154, s60, v139
	v_add_u32_e32 v170, s61, v139
	ds_read_b128 v[142:145], v154
	ds_read_b128 v[146:149], v154 offset:1024
	ds_read_b128 v[150:153], v154 offset:2048
	ds_read_b128 v[154:157], v154 offset:3072
	ds_read_b128 v[158:161], v170
	ds_read_b128 v[162:165], v170 offset:1024
	ds_read_b128 v[166:169], v170 offset:2048
	ds_read_b128 v[170:173], v170 offset:3072
	s_add_u32 s34, s34, 0x80000
	s_addc_u32 s35, s35, 0
	s_mov_b32 m0, s41
	v_lshl_add_u64 v[222:223], s[34:35], 0, v[128:129]
	ds_read_b128 v[174:177], v141 offset:32768
	ds_read_b128 v[178:181], v141 offset:33792
	ds_read_b128 v[182:185], v141 offset:34816
	ds_read_b128 v[196:199], v141 offset:35840
	ds_read_b128 v[200:203], v141 offset:36864
	ds_read_b128 v[204:207], v141 offset:37888
	ds_read_b128 v[208:211], v141 offset:38912
	ds_read_b128 v[212:215], v141 offset:39936
	global_load_lds_dwordx4 v[222:223], off
	v_lshl_add_u64 v[222:223], s[34:35], 0, v[130:131]
	s_mov_b32 m0, s42
	s_nop 0
	global_load_lds_dwordx4 v[222:223], off
	s_waitcnt vmcnt(8)
	s_waitcnt lgkmcnt(0)
	s_barrier
	s_setprio 1
	v_mfma_f32_16x16x32_bf16 v[124:127], v[142:145], v[174:177], v[124:127]
	v_mfma_f32_16x16x32_bf16 v[120:123], v[150:153], v[174:177], v[120:123]
	v_mfma_f32_16x16x32_bf16 v[116:119], v[142:145], v[182:185], v[116:119]
	v_mfma_f32_16x16x32_bf16 v[112:115], v[150:153], v[182:185], v[112:115]
	v_mfma_f32_16x16x32_bf16 v[100:103], v[142:145], v[200:203], v[100:103]
	v_mfma_f32_16x16x32_bf16 v[96:99], v[150:153], v[200:203], v[96:99]
	v_mfma_f32_16x16x32_bf16 v[84:87], v[142:145], v[208:211], v[84:87]
	v_mfma_f32_16x16x32_bf16 v[80:83], v[150:153], v[208:211], v[80:83]
	v_mfma_f32_16x16x32_bf16 v[124:127], v[146:149], v[178:181], v[124:127]
	v_mfma_f32_16x16x32_bf16 v[120:123], v[154:157], v[178:181], v[120:123]
	v_mfma_f32_16x16x32_bf16 v[116:119], v[146:149], v[196:199], v[116:119]
	v_mfma_f32_16x16x32_bf16 v[112:115], v[154:157], v[196:199], v[112:115]
	v_mfma_f32_16x16x32_bf16 v[100:103], v[146:149], v[204:207], v[100:103]
	v_mfma_f32_16x16x32_bf16 v[96:99], v[154:157], v[204:207], v[96:99]
	v_mfma_f32_16x16x32_bf16 v[84:87], v[146:149], v[212:215], v[84:87]
	v_mfma_f32_16x16x32_bf16 v[80:83], v[154:157], v[212:215], v[80:83]
	s_setprio 0
	s_setprio 1
	v_mfma_f32_16x16x32_bf16 v[108:111], v[158:161], v[174:177], v[108:111]
	v_mfma_f32_16x16x32_bf16 v[104:107], v[166:169], v[174:177], v[104:107]
	v_mfma_f32_16x16x32_bf16 v[92:95], v[158:161], v[182:185], v[92:95]
	v_mfma_f32_16x16x32_bf16 v[88:91], v[166:169], v[182:185], v[88:91]
	v_mfma_f32_16x16x32_bf16 v[76:79], v[158:161], v[200:203], v[76:79]
	v_mfma_f32_16x16x32_bf16 v[72:75], v[166:169], v[200:203], v[72:75]
	v_mfma_f32_16x16x32_bf16 v[68:71], v[158:161], v[208:211], v[68:71]
	v_mfma_f32_16x16x32_bf16 v[64:67], v[166:169], v[208:211], v[64:67]
	v_mfma_f32_16x16x32_bf16 v[108:111], v[162:165], v[178:181], v[108:111]
	v_mfma_f32_16x16x32_bf16 v[104:107], v[170:173], v[178:181], v[104:107]
	v_mfma_f32_16x16x32_bf16 v[92:95], v[162:165], v[196:199], v[92:95]
	v_mfma_f32_16x16x32_bf16 v[88:91], v[170:173], v[196:199], v[88:91]
	v_mfma_f32_16x16x32_bf16 v[76:79], v[162:165], v[204:207], v[76:79]
	v_mfma_f32_16x16x32_bf16 v[72:75], v[170:173], v[204:207], v[72:75]
	v_mfma_f32_16x16x32_bf16 v[68:71], v[162:165], v[212:215], v[68:71]
	v_mfma_f32_16x16x32_bf16 v[64:67], v[170:173], v[212:215], v[64:67]
	s_setprio 0
	s_barrier
	s_add_i32 s34, s60, s38
	v_lshl_add_u64 v[186:187], v[186:187], 0, s[58:59]
	s_mov_b32 m0, s34
	ds_read_b128 v[174:177], v141 offset:49152
	ds_read_b128 v[178:181], v141 offset:50176
	ds_read_b128 v[182:185], v141 offset:51200
	ds_read_b128 v[196:199], v141 offset:52224
	ds_read_b128 v[200:203], v141 offset:53248
	ds_read_b128 v[204:207], v141 offset:54272
	ds_read_b128 v[208:211], v141 offset:55296
	ds_read_b128 v[212:215], v141 offset:56320
	global_load_lds_dwordx4 v[186:187], off
	s_add_i32 m0, s34, 0x2000
	s_add_u32 s30, s30, 0x80080
	v_lshl_add_u64 v[186:187], v[216:217], 0, s[58:59]
	s_addc_u32 s31, s31, 0
	s_add_i32 s34, s61, s38
	global_load_lds_dwordx4 v[186:187], off
	v_lshl_add_u64 v[186:187], s[30:31], 0, v[190:191]
	s_mov_b32 m0, s34
	s_nop 0
	global_load_lds_dwordx4 v[186:187], off
	v_lshl_add_u64 v[186:187], s[30:31], 0, v[132:133]
	s_add_i32 m0, s34, 0x2000
	s_nop 0
	global_load_lds_dwordx4 v[186:187], off
	v_lshl_add_u64 v[186:187], v[218:219], 0, s[58:59]
	s_mov_b32 m0, s43
	s_nop 0
	global_load_lds_dwordx4 v[186:187], off
	v_lshl_add_u64 v[186:187], v[220:221], 0, s[58:59]
	s_mov_b32 m0, s47
	s_nop 0
	global_load_lds_dwordx4 v[186:187], off
	s_waitcnt vmcnt(8)
	s_waitcnt lgkmcnt(0)
	s_barrier
	s_setprio 1
	v_mfma_f32_16x16x32_bf16 v[60:63], v[142:145], v[174:177], v[60:63]
	v_mfma_f32_16x16x32_bf16 v[56:59], v[150:153], v[174:177], v[56:59]
	v_mfma_f32_16x16x32_bf16 v[52:55], v[142:145], v[182:185], v[52:55]
	v_mfma_f32_16x16x32_bf16 v[48:51], v[150:153], v[182:185], v[48:51]
	v_mfma_f32_16x16x32_bf16 v[36:39], v[142:145], v[200:203], v[36:39]
	v_mfma_f32_16x16x32_bf16 v[32:35], v[150:153], v[200:203], v[32:35]
	v_mfma_f32_16x16x32_bf16 v[20:23], v[142:145], v[208:211], v[20:23]
	v_mfma_f32_16x16x32_bf16 v[16:19], v[150:153], v[208:211], v[16:19]
	v_mfma_f32_16x16x32_bf16 v[60:63], v[146:149], v[178:181], v[60:63]
	v_mfma_f32_16x16x32_bf16 v[56:59], v[154:157], v[178:181], v[56:59]
	v_mfma_f32_16x16x32_bf16 v[52:55], v[146:149], v[196:199], v[52:55]
	v_mfma_f32_16x16x32_bf16 v[48:51], v[154:157], v[196:199], v[48:51]
	v_mfma_f32_16x16x32_bf16 v[36:39], v[146:149], v[204:207], v[36:39]
	v_mfma_f32_16x16x32_bf16 v[32:35], v[154:157], v[204:207], v[32:35]
	v_mfma_f32_16x16x32_bf16 v[20:23], v[146:149], v[212:215], v[20:23]
	v_mfma_f32_16x16x32_bf16 v[16:19], v[154:157], v[212:215], v[16:19]
	s_setprio 0
	s_setprio 1
	v_mfma_f32_16x16x32_bf16 v[44:47], v[158:161], v[174:177], v[44:47]
	v_mfma_f32_16x16x32_bf16 v[40:43], v[166:169], v[174:177], v[40:43]
	v_mfma_f32_16x16x32_bf16 v[28:31], v[158:161], v[182:185], v[28:31]
	v_mfma_f32_16x16x32_bf16 v[24:27], v[166:169], v[182:185], v[24:27]
	v_mfma_f32_16x16x32_bf16 v[12:15], v[158:161], v[200:203], v[12:15]
	v_mfma_f32_16x16x32_bf16 v[8:11], v[166:169], v[200:203], v[8:11]
	v_mfma_f32_16x16x32_bf16 v[4:7], v[158:161], v[208:211], v[4:7]
	v_mfma_f32_16x16x32_bf16 v[0:3], v[166:169], v[208:211], v[0:3]
	v_mfma_f32_16x16x32_bf16 v[44:47], v[162:165], v[178:181], v[44:47]
	v_mfma_f32_16x16x32_bf16 v[40:43], v[170:173], v[178:181], v[40:43]
	v_mfma_f32_16x16x32_bf16 v[28:31], v[162:165], v[196:199], v[28:31]
	v_mfma_f32_16x16x32_bf16 v[24:27], v[170:173], v[196:199], v[24:27]
	v_mfma_f32_16x16x32_bf16 v[12:15], v[162:165], v[204:207], v[12:15]
	v_mfma_f32_16x16x32_bf16 v[8:11], v[170:173], v[204:207], v[8:11]
	v_mfma_f32_16x16x32_bf16 v[4:7], v[162:165], v[212:215], v[4:7]
	v_mfma_f32_16x16x32_bf16 v[0:3], v[170:173], v[212:215], v[0:3]
	s_setprio 0
	s_barrier
	s_add_i32 s57, s57, 2
	s_add_u32 s28, s28, 0x100
	s_addc_u32 s29, s29, 0
	s_add_u32 s55, s55, 0x100
	s_addc_u32 s56, s56, 0
	s_cmp_gt_u32 s57, 29
	s_cbranch_scc0 .LBB0_938

.LBB0_1104:
	s_ashr_i32 s61, s60, 31
	s_lshl_b64 s[52:53], s[60:61], 20
	v_readlane_b32 s0, v254, 17
	v_readlane_b32 s1, v254, 18
	s_add_u32 s88, s0, s52
	s_addc_u32 s89, s1, s53
	s_and_b64 s[52:53], s[8:9], exec
	s_cselect_b32 s13, s89, s11
	s_cselect_b32 s15, s88, s10
	s_ashr_i32 s57, s56, 31
	s_lshl_b64 s[52:53], s[56:57], 20
	v_readlane_b32 s0, v254, 36
	v_readlane_b32 s1, v254, 37
	s_add_u32 s90, s0, s52
	s_addc_u32 s91, s1, s53
	s_and_b64 s[52:53], s[8:9], exec
	s_cselect_b32 s57, s91, s17
	s_cselect_b32 s61, s90, s16
	s_add_u32 s66, s16, 0x100
	s_addc_u32 s67, s17, 0
	s_mov_b32 vcc_lo, -2
	v_readlane_b32 s0, v255, 49
	s_nop 3
	s_cmp_eq_u32 s0, 8
	v_writelane_b32 v255, 8, 49
	s_cbranch_scc0 .Ltrip0_strict_7
	s_add_u32 s16, s10, 0x100
	s_addc_u32 s17, s11, 0
	s_add_i32 vcc_hi, 0, 0x10000
	s_cmp_eq_u32 vcc_lo, 28
	s_cselect_b32 s69, s13, s17
	s_cselect_b32 s68, s15, s16
	s_cselect_b32 s53, s57, s67
	s_cselect_b32 s52, s61, s66
	s_add_i32 s0, 0, 0x14000
	v_add_u32_e32 v140, vcc_hi, v200
	v_add_u32_e32 v156, s0, v200
	ds_read_b128 v[128:131], v140
	ds_read_b128 v[132:135], v140 offset:1024
	ds_read_b128 v[136:139], v140 offset:2048
	ds_read_b128 v[140:143], v140 offset:3072
	ds_read_b128 v[144:147], v156
	ds_read_b128 v[148:151], v156 offset:1024
	ds_read_b128 v[152:155], v156 offset:2048
	ds_read_b128 v[156:159], v156 offset:3072
	v_lshl_add_u64 v[186:187], s[10:11], 0, v[182:183]
	s_add_i32 m0, s40, 0xc000
	ds_read_b128 v[160:163], v206
	ds_read_b128 v[164:167], v206 offset:1024
	ds_read_b128 v[168:171], v206 offset:2048
	ds_read_b128 v[172:175], v206 offset:3072
	ds_read_b128 v[196:199], v206 offset:4096
	ds_read_b128 v[208:211], v206 offset:5120
	ds_read_b128 v[212:215], v206 offset:6144
	ds_read_b128 v[216:219], v206 offset:7168
	global_load_lds_dwordx4 v[186:187], off
	v_lshl_add_u64 v[186:187], s[10:11], 0, v[184:185]
	s_add_i32 m0, s40, 0xe000
	s_nop 0
	global_load_lds_dwordx4 v[186:187], off
	s_waitcnt vmcnt(24)
	s_waitcnt lgkmcnt(0)
	s_barrier
	s_setprio 1
	v_mfma_f32_16x16x32_bf16 v[120:123], v[128:131], v[160:163], 0
	v_mfma_f32_16x16x32_bf16 v[48:51], v[136:139], v[160:163], 0
	v_mfma_f32_16x16x32_bf16 v[124:127], v[128:131], v[168:171], 0
	v_mfma_f32_16x16x32_bf16 v[60:63], v[136:139], v[168:171], 0
	v_mfma_f32_16x16x32_bf16 v[112:115], v[128:131], v[196:199], 0
	v_mfma_f32_16x16x32_bf16 v[52:55], v[136:139], v[196:199], 0
	v_mfma_f32_16x16x32_bf16 v[108:111], v[128:131], v[212:215], 0
	v_mfma_f32_16x16x32_bf16 v[36:39], v[136:139], v[212:215], 0
	v_mfma_f32_16x16x32_bf16 v[120:123], v[132:135], v[164:167], v[120:123]
	v_mfma_f32_16x16x32_bf16 v[48:51], v[140:143], v[164:167], v[48:51]
	v_mfma_f32_16x16x32_bf16 v[124:127], v[132:135], v[172:175], v[124:127]
	v_mfma_f32_16x16x32_bf16 v[60:63], v[140:143], v[172:175], v[60:63]
	v_mfma_f32_16x16x32_bf16 v[112:115], v[132:135], v[208:211], v[112:115]
	v_mfma_f32_16x16x32_bf16 v[52:55], v[140:143], v[208:211], v[52:55]
	v_mfma_f32_16x16x32_bf16 v[108:111], v[132:135], v[216:219], v[108:111]
	v_mfma_f32_16x16x32_bf16 v[36:39], v[140:143], v[216:219], v[36:39]
	s_setprio 0
	s_setprio 1
	v_mfma_f32_16x16x32_bf16 v[100:103], v[144:147], v[160:163], 0
	v_mfma_f32_16x16x32_bf16 v[40:43], v[152:155], v[160:163], 0
	v_mfma_f32_16x16x32_bf16 v[116:119], v[144:147], v[168:171], 0
	v_mfma_f32_16x16x32_bf16 v[56:59], v[152:155], v[168:171], 0
	v_mfma_f32_16x16x32_bf16 v[104:107], v[144:147], v[196:199], 0
	v_mfma_f32_16x16x32_bf16 v[44:47], v[152:155], v[196:199], 0
	v_mfma_f32_16x16x32_bf16 v[96:99], v[144:147], v[212:215], 0
	v_mfma_f32_16x16x32_bf16 v[32:35], v[152:155], v[212:215], 0
	v_mfma_f32_16x16x32_bf16 v[100:103], v[148:151], v[164:167], v[100:103]
	v_mfma_f32_16x16x32_bf16 v[40:43], v[156:159], v[164:167], v[40:43]
	v_mfma_f32_16x16x32_bf16 v[116:119], v[148:151], v[172:175], v[116:119]
	v_mfma_f32_16x16x32_bf16 v[56:59], v[156:159], v[172:175], v[56:59]
	v_mfma_f32_16x16x32_bf16 v[104:107], v[148:151], v[208:211], v[104:107]
	v_mfma_f32_16x16x32_bf16 v[44:47], v[156:159], v[208:211], v[44:47]
	v_mfma_f32_16x16x32_bf16 v[96:99], v[148:151], v[216:219], v[96:99]
	v_mfma_f32_16x16x32_bf16 v[32:35], v[156:159], v[216:219], v[32:35]
	s_setprio 0
	s_barrier
	s_add_i32 s1, vcc_hi, s33
	v_lshl_add_u64 v[186:187], s[52:53], 0, v[190:191]
	s_mov_b32 m0, s1
	ds_read_b128 v[160:163], v206 offset:16384
	ds_read_b128 v[164:167], v206 offset:17408
	ds_read_b128 v[168:171], v206 offset:18432
	ds_read_b128 v[172:175], v206 offset:19456
	ds_read_b128 v[196:199], v206 offset:20480
	ds_read_b128 v[208:211], v206 offset:21504
	ds_read_b128 v[212:215], v206 offset:22528
	ds_read_b128 v[216:219], v206 offset:23552
	global_load_lds_dwordx4 v[186:187], off
	s_add_i32 m0, s1, 0x2000
	s_add_u32 s10, s52, 0x80000
	v_lshl_add_u64 v[220:221], s[52:53], 0, v[180:181]
	s_addc_u32 s11, s53, 0
	s_add_i32 s0, s0, s33
	global_load_lds_dwordx4 v[220:221], off
	v_lshl_add_u64 v[222:223], s[10:11], 0, v[190:191]
	s_mov_b32 m0, s0
	v_lshl_add_u64 v[224:225], s[68:69], 0, v[178:179]
	global_load_lds_dwordx4 v[222:223], off
	v_lshl_add_u64 v[222:223], s[10:11], 0, v[180:181]
	s_add_i32 m0, s0, 0x2000
	s_nop 0
	global_load_lds_dwordx4 v[222:223], off
	v_lshl_add_u64 v[222:223], s[68:69], 0, v[176:177]
	s_mov_b32 m0, s40
	s_nop 0
	global_load_lds_dwordx4 v[222:223], off
	s_mov_b32 m0, s41
	s_nop 0
	global_load_lds_dwordx4 v[224:225], off
	s_waitcnt vmcnt(24)
	s_waitcnt lgkmcnt(0)
	s_barrier
	s_setprio 1
	v_mfma_f32_16x16x32_bf16 v[88:91], v[128:131], v[160:163], 0
	v_mfma_f32_16x16x32_bf16 v[20:23], v[136:139], v[160:163], 0
	v_mfma_f32_16x16x32_bf16 v[92:95], v[128:131], v[168:171], 0
	v_mfma_f32_16x16x32_bf16 v[28:31], v[136:139], v[168:171], 0
	v_mfma_f32_16x16x32_bf16 v[80:83], v[128:131], v[196:199], 0
	v_mfma_f32_16x16x32_bf16 v[16:19], v[136:139], v[196:199], 0
	v_mfma_f32_16x16x32_bf16 v[76:79], v[128:131], v[212:215], 0
	v_mfma_f32_16x16x32_bf16 v[12:15], v[136:139], v[212:215], 0
	v_mfma_f32_16x16x32_bf16 v[88:91], v[132:135], v[164:167], v[88:91]
	v_mfma_f32_16x16x32_bf16 v[20:23], v[140:143], v[164:167], v[20:23]
	v_mfma_f32_16x16x32_bf16 v[92:95], v[132:135], v[172:175], v[92:95]
	v_mfma_f32_16x16x32_bf16 v[28:31], v[140:143], v[172:175], v[28:31]
	v_mfma_f32_16x16x32_bf16 v[80:83], v[132:135], v[208:211], v[80:83]
	v_mfma_f32_16x16x32_bf16 v[16:19], v[140:143], v[208:211], v[16:19]
	v_mfma_f32_16x16x32_bf16 v[76:79], v[132:135], v[216:219], v[76:79]
	v_mfma_f32_16x16x32_bf16 v[12:15], v[140:143], v[216:219], v[12:15]
	s_setprio 0
	s_setprio 1
	v_mfma_f32_16x16x32_bf16 v[68:71], v[144:147], v[160:163], 0
	v_mfma_f32_16x16x32_bf16 v[4:7], v[152:155], v[160:163], 0
	v_mfma_f32_16x16x32_bf16 v[84:87], v[144:147], v[168:171], 0
	v_mfma_f32_16x16x32_bf16 v[24:27], v[152:155], v[168:171], 0
	v_mfma_f32_16x16x32_bf16 v[72:75], v[144:147], v[196:199], 0
	v_mfma_f32_16x16x32_bf16 v[8:11], v[152:155], v[196:199], 0
	v_mfma_f32_16x16x32_bf16 v[64:67], v[144:147], v[212:215], 0
	v_mfma_f32_16x16x32_bf16 v[0:3], v[152:155], v[212:215], 0
	v_mfma_f32_16x16x32_bf16 v[68:71], v[148:151], v[164:167], v[68:71]
	v_mfma_f32_16x16x32_bf16 v[4:7], v[156:159], v[164:167], v[4:7]
	v_mfma_f32_16x16x32_bf16 v[84:87], v[148:151], v[172:175], v[84:87]
	v_mfma_f32_16x16x32_bf16 v[24:27], v[156:159], v[172:175], v[24:27]
	v_mfma_f32_16x16x32_bf16 v[72:75], v[148:151], v[208:211], v[72:75]
	v_mfma_f32_16x16x32_bf16 v[8:11], v[156:159], v[208:211], v[8:11]
	v_mfma_f32_16x16x32_bf16 v[64:67], v[148:151], v[216:219], v[64:67]
	v_mfma_f32_16x16x32_bf16 v[0:3], v[156:159], v[216:219], v[0:3]
	s_setprio 0
	s_barrier
	s_add_i32 s0, 0, 0x18000
	s_add_i32 s1, 0, 0x1c000
	v_add_u32_e32 v140, s0, v200
	v_add_u32_e32 v156, s1, v200
	ds_read_b128 v[128:131], v140
	ds_read_b128 v[132:135], v140 offset:1024
	ds_read_b128 v[136:139], v140 offset:2048
	ds_read_b128 v[140:143], v140 offset:3072
	ds_read_b128 v[144:147], v156
	ds_read_b128 v[148:151], v156 offset:1024
	ds_read_b128 v[152:155], v156 offset:2048
	ds_read_b128 v[156:159], v156 offset:3072
	s_add_u32 s10, s68, 0x80000
	s_addc_u32 s11, s69, 0
	s_mov_b32 m0, s42
	v_lshl_add_u64 v[226:227], s[10:11], 0, v[176:177]
	ds_read_b128 v[160:163], v206 offset:32768
	ds_read_b128 v[164:167], v206 offset:33792
	ds_read_b128 v[168:171], v206 offset:34816
	ds_read_b128 v[172:175], v206 offset:35840
	ds_read_b128 v[196:199], v206 offset:36864
	ds_read_b128 v[208:211], v206 offset:37888
	ds_read_b128 v[212:215], v206 offset:38912
	ds_read_b128 v[216:219], v206 offset:39936
	global_load_lds_dwordx4 v[226:227], off
	v_lshl_add_u64 v[226:227], s[10:11], 0, v[178:179]
	s_mov_b32 m0, s43
	s_nop 0
	global_load_lds_dwordx4 v[226:227], off
	s_waitcnt vmcnt(8)
	s_waitcnt lgkmcnt(0)
	s_barrier
	s_setprio 1
	v_mfma_f32_16x16x32_bf16 v[120:123], v[128:131], v[160:163], v[120:123]
	v_mfma_f32_16x16x32_bf16 v[48:51], v[136:139], v[160:163], v[48:51]
	v_mfma_f32_16x16x32_bf16 v[124:127], v[128:131], v[168:171], v[124:127]
	v_mfma_f32_16x16x32_bf16 v[60:63], v[136:139], v[168:171], v[60:63]
	v_mfma_f32_16x16x32_bf16 v[112:115], v[128:131], v[196:199], v[112:115]
	v_mfma_f32_16x16x32_bf16 v[52:55], v[136:139], v[196:199], v[52:55]
	v_mfma_f32_16x16x32_bf16 v[108:111], v[128:131], v[212:215], v[108:111]
	v_mfma_f32_16x16x32_bf16 v[36:39], v[136:139], v[212:215], v[36:39]
	v_mfma_f32_16x16x32_bf16 v[120:123], v[132:135], v[164:167], v[120:123]
	v_mfma_f32_16x16x32_bf16 v[48:51], v[140:143], v[164:167], v[48:51]
	v_mfma_f32_16x16x32_bf16 v[124:127], v[132:135], v[172:175], v[124:127]
	v_mfma_f32_16x16x32_bf16 v[60:63], v[140:143], v[172:175], v[60:63]
	v_mfma_f32_16x16x32_bf16 v[112:115], v[132:135], v[208:211], v[112:115]
	v_mfma_f32_16x16x32_bf16 v[52:55], v[140:143], v[208:211], v[52:55]
	v_mfma_f32_16x16x32_bf16 v[108:111], v[132:135], v[216:219], v[108:111]
	v_mfma_f32_16x16x32_bf16 v[36:39], v[140:143], v[216:219], v[36:39]
	s_setprio 0
	s_setprio 1
	v_mfma_f32_16x16x32_bf16 v[100:103], v[144:147], v[160:163], v[100:103]
	v_mfma_f32_16x16x32_bf16 v[40:43], v[152:155], v[160:163], v[40:43]
	v_mfma_f32_16x16x32_bf16 v[116:119], v[144:147], v[168:171], v[116:119]
	v_mfma_f32_16x16x32_bf16 v[56:59], v[152:155], v[168:171], v[56:59]
	v_mfma_f32_16x16x32_bf16 v[104:107], v[144:147], v[196:199], v[104:107]
	v_mfma_f32_16x16x32_bf16 v[44:47], v[152:155], v[196:199], v[44:47]
	v_mfma_f32_16x16x32_bf16 v[96:99], v[144:147], v[212:215], v[96:99]
	v_mfma_f32_16x16x32_bf16 v[32:35], v[152:155], v[212:215], v[32:35]
	v_mfma_f32_16x16x32_bf16 v[100:103], v[148:151], v[164:167], v[100:103]
	v_mfma_f32_16x16x32_bf16 v[40:43], v[156:159], v[164:167], v[40:43]
	v_mfma_f32_16x16x32_bf16 v[116:119], v[148:151], v[172:175], v[116:119]
	v_mfma_f32_16x16x32_bf16 v[56:59], v[156:159], v[172:175], v[56:59]
	v_mfma_f32_16x16x32_bf16 v[104:107], v[148:151], v[208:211], v[104:107]
	v_mfma_f32_16x16x32_bf16 v[44:47], v[156:159], v[208:211], v[44:47]
	v_mfma_f32_16x16x32_bf16 v[96:99], v[148:151], v[216:219], v[96:99]
	v_mfma_f32_16x16x32_bf16 v[32:35], v[156:159], v[216:219], v[32:35]
	s_setprio 0
	s_barrier
	s_add_i32 s0, s0, s33
	v_lshl_add_u64 v[186:187], v[186:187], 0, s[58:59]
	s_mov_b32 m0, s0
	ds_read_b128 v[160:163], v206 offset:49152
	ds_read_b128 v[164:167], v206 offset:50176
	ds_read_b128 v[168:171], v206 offset:51200
	ds_read_b128 v[172:175], v206 offset:52224
	ds_read_b128 v[196:199], v206 offset:53248
	ds_read_b128 v[208:211], v206 offset:54272
	ds_read_b128 v[212:215], v206 offset:55296
	ds_read_b128 v[216:219], v206 offset:56320
	global_load_lds_dwordx4 v[186:187], off
	s_add_i32 m0, s0, 0x2000
	s_add_u32 s10, s52, 0x80080
	v_lshl_add_u64 v[186:187], v[220:221], 0, s[58:59]
	s_addc_u32 s11, s53, 0
	s_add_i32 s0, s1, s33
	global_load_lds_dwordx4 v[186:187], off
	v_lshl_add_u64 v[186:187], s[10:11], 0, v[190:191]
	s_mov_b32 m0, s0
	s_nop 0
	global_load_lds_dwordx4 v[186:187], off
	v_lshl_add_u64 v[186:187], s[10:11], 0, v[180:181]
	s_add_i32 m0, s0, 0x2000
	s_nop 0
	global_load_lds_dwordx4 v[186:187], off
	v_lshl_add_u64 v[186:187], v[222:223], 0, s[58:59]
	s_mov_b32 m0, s55
	s_nop 0
	global_load_lds_dwordx4 v[186:187], off
	v_lshl_add_u64 v[186:187], v[224:225], 0, s[58:59]
	s_mov_b32 m0, s77
	s_nop 0
	global_load_lds_dwordx4 v[186:187], off
	s_waitcnt vmcnt(8)
	s_waitcnt lgkmcnt(0)
	s_barrier
	s_setprio 1
	v_mfma_f32_16x16x32_bf16 v[88:91], v[128:131], v[160:163], v[88:91]
	v_mfma_f32_16x16x32_bf16 v[20:23], v[136:139], v[160:163], v[20:23]
	v_mfma_f32_16x16x32_bf16 v[92:95], v[128:131], v[168:171], v[92:95]
	v_mfma_f32_16x16x32_bf16 v[28:31], v[136:139], v[168:171], v[28:31]
	v_mfma_f32_16x16x32_bf16 v[80:83], v[128:131], v[196:199], v[80:83]
	v_mfma_f32_16x16x32_bf16 v[16:19], v[136:139], v[196:199], v[16:19]
	v_mfma_f32_16x16x32_bf16 v[76:79], v[128:131], v[212:215], v[76:79]
	v_mfma_f32_16x16x32_bf16 v[12:15], v[136:139], v[212:215], v[12:15]
	v_mfma_f32_16x16x32_bf16 v[88:91], v[132:135], v[164:167], v[88:91]
	v_mfma_f32_16x16x32_bf16 v[20:23], v[140:143], v[164:167], v[20:23]
	v_mfma_f32_16x16x32_bf16 v[92:95], v[132:135], v[172:175], v[92:95]
	v_mfma_f32_16x16x32_bf16 v[28:31], v[140:143], v[172:175], v[28:31]
	v_mfma_f32_16x16x32_bf16 v[80:83], v[132:135], v[208:211], v[80:83]
	v_mfma_f32_16x16x32_bf16 v[16:19], v[140:143], v[208:211], v[16:19]
	v_mfma_f32_16x16x32_bf16 v[76:79], v[132:135], v[216:219], v[76:79]
	v_mfma_f32_16x16x32_bf16 v[12:15], v[140:143], v[216:219], v[12:15]
	s_setprio 0
	s_setprio 1
	v_mfma_f32_16x16x32_bf16 v[68:71], v[144:147], v[160:163], v[68:71]
	v_mfma_f32_16x16x32_bf16 v[4:7], v[152:155], v[160:163], v[4:7]
	v_mfma_f32_16x16x32_bf16 v[84:87], v[144:147], v[168:171], v[84:87]
	v_mfma_f32_16x16x32_bf16 v[24:27], v[152:155], v[168:171], v[24:27]
	v_mfma_f32_16x16x32_bf16 v[72:75], v[144:147], v[196:199], v[72:75]
	v_mfma_f32_16x16x32_bf16 v[8:11], v[152:155], v[196:199], v[8:11]
	v_mfma_f32_16x16x32_bf16 v[64:67], v[144:147], v[212:215], v[64:67]
	v_mfma_f32_16x16x32_bf16 v[0:3], v[152:155], v[212:215], v[0:3]
	v_mfma_f32_16x16x32_bf16 v[68:71], v[148:151], v[164:167], v[68:71]
	v_mfma_f32_16x16x32_bf16 v[4:7], v[156:159], v[164:167], v[4:7]
	v_mfma_f32_16x16x32_bf16 v[84:87], v[148:151], v[172:175], v[84:87]
	v_mfma_f32_16x16x32_bf16 v[24:27], v[156:159], v[172:175], v[24:27]
	v_mfma_f32_16x16x32_bf16 v[72:75], v[148:151], v[208:211], v[72:75]
	v_mfma_f32_16x16x32_bf16 v[8:11], v[156:159], v[208:211], v[8:11]
	v_mfma_f32_16x16x32_bf16 v[64:67], v[148:151], v[216:219], v[64:67]
	v_mfma_f32_16x16x32_bf16 v[0:3], v[156:159], v[216:219], v[0:3]
	s_setprio 0
	s_barrier
	s_add_i32 vcc_lo, vcc_lo, 2
	s_add_u32 s66, s66, 0x100
	s_addc_u32 s67, s67, 0
	s_cmp_gt_u32 vcc_lo, 29
	s_mov_b64 s[10:11], s[16:17]
	s_cbranch_scc1 .Lpeel_done_7
	s_branch .LBB0_1105
.Ltrip0_strict_7:
	s_add_u32 s16, s10, 0x100
	s_addc_u32 s17, s11, 0
	s_add_i32 vcc_hi, 0, 0x10000
	s_cmp_eq_u32 vcc_lo, 28
	s_cselect_b32 s69, s13, s17
	s_cselect_b32 s68, s15, s16
	s_cselect_b32 s53, s57, s67
	s_cselect_b32 s52, s61, s66
	s_add_i32 s0, 0, 0x14000
	v_add_u32_e32 v140, vcc_hi, v200
	v_add_u32_e32 v156, s0, v200
	ds_read_b128 v[128:131], v140
	ds_read_b128 v[132:135], v140 offset:1024
	ds_read_b128 v[136:139], v140 offset:2048
	ds_read_b128 v[140:143], v140 offset:3072
	ds_read_b128 v[144:147], v156
	ds_read_b128 v[148:151], v156 offset:1024
	ds_read_b128 v[152:155], v156 offset:2048
	ds_read_b128 v[156:159], v156 offset:3072
	v_lshl_add_u64 v[186:187], s[10:11], 0, v[182:183]
	s_add_i32 m0, s40, 0xc000
	ds_read_b128 v[160:163], v206
	ds_read_b128 v[164:167], v206 offset:1024
	ds_read_b128 v[168:171], v206 offset:2048
	ds_read_b128 v[172:175], v206 offset:3072
	ds_read_b128 v[196:199], v206 offset:4096
	ds_read_b128 v[208:211], v206 offset:5120
	ds_read_b128 v[212:215], v206 offset:6144
	ds_read_b128 v[216:219], v206 offset:7168
	global_load_lds_dwordx4 v[186:187], off
	v_lshl_add_u64 v[186:187], s[10:11], 0, v[184:185]
	s_add_i32 m0, s40, 0xe000
	s_nop 0
	global_load_lds_dwordx4 v[186:187], off
	s_waitcnt vmcnt(8)
	s_waitcnt lgkmcnt(0)
	s_barrier
	s_setprio 1
	v_mfma_f32_16x16x32_bf16 v[120:123], v[128:131], v[160:163], 0
	v_mfma_f32_16x16x32_bf16 v[48:51], v[136:139], v[160:163], 0
	v_mfma_f32_16x16x32_bf16 v[124:127], v[128:131], v[168:171], 0
	v_mfma_f32_16x16x32_bf16 v[60:63], v[136:139], v[168:171], 0
	v_mfma_f32_16x16x32_bf16 v[112:115], v[128:131], v[196:199], 0
	v_mfma_f32_16x16x32_bf16 v[52:55], v[136:139], v[196:199], 0
	v_mfma_f32_16x16x32_bf16 v[108:111], v[128:131], v[212:215], 0
	v_mfma_f32_16x16x32_bf16 v[36:39], v[136:139], v[212:215], 0
	v_mfma_f32_16x16x32_bf16 v[120:123], v[132:135], v[164:167], v[120:123]
	v_mfma_f32_16x16x32_bf16 v[48:51], v[140:143], v[164:167], v[48:51]
	v_mfma_f32_16x16x32_bf16 v[124:127], v[132:135], v[172:175], v[124:127]
	v_mfma_f32_16x16x32_bf16 v[60:63], v[140:143], v[172:175], v[60:63]
	v_mfma_f32_16x16x32_bf16 v[112:115], v[132:135], v[208:211], v[112:115]
	v_mfma_f32_16x16x32_bf16 v[52:55], v[140:143], v[208:211], v[52:55]
	v_mfma_f32_16x16x32_bf16 v[108:111], v[132:135], v[216:219], v[108:111]
	v_mfma_f32_16x16x32_bf16 v[36:39], v[140:143], v[216:219], v[36:39]
	s_setprio 0
	s_setprio 1
	v_mfma_f32_16x16x32_bf16 v[100:103], v[144:147], v[160:163], 0
	v_mfma_f32_16x16x32_bf16 v[40:43], v[152:155], v[160:163], 0
	v_mfma_f32_16x16x32_bf16 v[116:119], v[144:147], v[168:171], 0
	v_mfma_f32_16x16x32_bf16 v[56:59], v[152:155], v[168:171], 0
	v_mfma_f32_16x16x32_bf16 v[104:107], v[144:147], v[196:199], 0
	v_mfma_f32_16x16x32_bf16 v[44:47], v[152:155], v[196:199], 0
	v_mfma_f32_16x16x32_bf16 v[96:99], v[144:147], v[212:215], 0
	v_mfma_f32_16x16x32_bf16 v[32:35], v[152:155], v[212:215], 0
	v_mfma_f32_16x16x32_bf16 v[100:103], v[148:151], v[164:167], v[100:103]
	v_mfma_f32_16x16x32_bf16 v[40:43], v[156:159], v[164:167], v[40:43]
	v_mfma_f32_16x16x32_bf16 v[116:119], v[148:151], v[172:175], v[116:119]
	v_mfma_f32_16x16x32_bf16 v[56:59], v[156:159], v[172:175], v[56:59]
	v_mfma_f32_16x16x32_bf16 v[104:107], v[148:151], v[208:211], v[104:107]
	v_mfma_f32_16x16x32_bf16 v[44:47], v[156:159], v[208:211], v[44:47]
	v_mfma_f32_16x16x32_bf16 v[96:99], v[148:151], v[216:219], v[96:99]
	v_mfma_f32_16x16x32_bf16 v[32:35], v[156:159], v[216:219], v[32:35]
	s_setprio 0
	s_barrier
	s_add_i32 s1, vcc_hi, s33
	v_lshl_add_u64 v[186:187], s[52:53], 0, v[190:191]
	s_mov_b32 m0, s1
	ds_read_b128 v[160:163], v206 offset:16384
	ds_read_b128 v[164:167], v206 offset:17408
	ds_read_b128 v[168:171], v206 offset:18432
	ds_read_b128 v[172:175], v206 offset:19456
	ds_read_b128 v[196:199], v206 offset:20480
	ds_read_b128 v[208:211], v206 offset:21504
	ds_read_b128 v[212:215], v206 offset:22528
	ds_read_b128 v[216:219], v206 offset:23552
	global_load_lds_dwordx4 v[186:187], off
	s_add_i32 m0, s1, 0x2000
	s_add_u32 s10, s52, 0x80000
	v_lshl_add_u64 v[220:221], s[52:53], 0, v[180:181]
	s_addc_u32 s11, s53, 0
	s_add_i32 s0, s0, s33
	global_load_lds_dwordx4 v[220:221], off
	v_lshl_add_u64 v[222:223], s[10:11], 0, v[190:191]
	s_mov_b32 m0, s0
	v_lshl_add_u64 v[224:225], s[68:69], 0, v[178:179]
	global_load_lds_dwordx4 v[222:223], off
	v_lshl_add_u64 v[222:223], s[10:11], 0, v[180:181]
	s_add_i32 m0, s0, 0x2000
	s_nop 0
	global_load_lds_dwordx4 v[222:223], off
	v_lshl_add_u64 v[222:223], s[68:69], 0, v[176:177]
	s_mov_b32 m0, s40
	s_nop 0
	global_load_lds_dwordx4 v[222:223], off
	s_mov_b32 m0, s41
	s_nop 0
	global_load_lds_dwordx4 v[224:225], off
	s_waitcnt vmcnt(8)
	s_waitcnt lgkmcnt(0)
	s_barrier
	s_setprio 1
	v_mfma_f32_16x16x32_bf16 v[88:91], v[128:131], v[160:163], 0
	v_mfma_f32_16x16x32_bf16 v[20:23], v[136:139], v[160:163], 0
	v_mfma_f32_16x16x32_bf16 v[92:95], v[128:131], v[168:171], 0
	v_mfma_f32_16x16x32_bf16 v[28:31], v[136:139], v[168:171], 0
	v_mfma_f32_16x16x32_bf16 v[80:83], v[128:131], v[196:199], 0
	v_mfma_f32_16x16x32_bf16 v[16:19], v[136:139], v[196:199], 0
	v_mfma_f32_16x16x32_bf16 v[76:79], v[128:131], v[212:215], 0
	v_mfma_f32_16x16x32_bf16 v[12:15], v[136:139], v[212:215], 0
	v_mfma_f32_16x16x32_bf16 v[88:91], v[132:135], v[164:167], v[88:91]
	v_mfma_f32_16x16x32_bf16 v[20:23], v[140:143], v[164:167], v[20:23]
	v_mfma_f32_16x16x32_bf16 v[92:95], v[132:135], v[172:175], v[92:95]
	v_mfma_f32_16x16x32_bf16 v[28:31], v[140:143], v[172:175], v[28:31]
	v_mfma_f32_16x16x32_bf16 v[80:83], v[132:135], v[208:211], v[80:83]
	v_mfma_f32_16x16x32_bf16 v[16:19], v[140:143], v[208:211], v[16:19]
	v_mfma_f32_16x16x32_bf16 v[76:79], v[132:135], v[216:219], v[76:79]
	v_mfma_f32_16x16x32_bf16 v[12:15], v[140:143], v[216:219], v[12:15]
	s_setprio 0
	s_setprio 1
	v_mfma_f32_16x16x32_bf16 v[68:71], v[144:147], v[160:163], 0
	v_mfma_f32_16x16x32_bf16 v[4:7], v[152:155], v[160:163], 0
	v_mfma_f32_16x16x32_bf16 v[84:87], v[144:147], v[168:171], 0
	v_mfma_f32_16x16x32_bf16 v[24:27], v[152:155], v[168:171], 0
	v_mfma_f32_16x16x32_bf16 v[72:75], v[144:147], v[196:199], 0
	v_mfma_f32_16x16x32_bf16 v[8:11], v[152:155], v[196:199], 0
	v_mfma_f32_16x16x32_bf16 v[64:67], v[144:147], v[212:215], 0
	v_mfma_f32_16x16x32_bf16 v[0:3], v[152:155], v[212:215], 0
	v_mfma_f32_16x16x32_bf16 v[68:71], v[148:151], v[164:167], v[68:71]
	v_mfma_f32_16x16x32_bf16 v[4:7], v[156:159], v[164:167], v[4:7]
	v_mfma_f32_16x16x32_bf16 v[84:87], v[148:151], v[172:175], v[84:87]
	v_mfma_f32_16x16x32_bf16 v[24:27], v[156:159], v[172:175], v[24:27]
	v_mfma_f32_16x16x32_bf16 v[72:75], v[148:151], v[208:211], v[72:75]
	v_mfma_f32_16x16x32_bf16 v[8:11], v[156:159], v[208:211], v[8:11]
	v_mfma_f32_16x16x32_bf16 v[64:67], v[148:151], v[216:219], v[64:67]
	v_mfma_f32_16x16x32_bf16 v[0:3], v[156:159], v[216:219], v[0:3]
	s_setprio 0
	s_barrier
	s_add_i32 s0, 0, 0x18000
	s_add_i32 s1, 0, 0x1c000
	v_add_u32_e32 v140, s0, v200
	v_add_u32_e32 v156, s1, v200
	ds_read_b128 v[128:131], v140
	ds_read_b128 v[132:135], v140 offset:1024
	ds_read_b128 v[136:139], v140 offset:2048
	ds_read_b128 v[140:143], v140 offset:3072
	ds_read_b128 v[144:147], v156
	ds_read_b128 v[148:151], v156 offset:1024
	ds_read_b128 v[152:155], v156 offset:2048
	ds_read_b128 v[156:159], v156 offset:3072
	s_add_u32 s10, s68, 0x80000
	s_addc_u32 s11, s69, 0
	s_mov_b32 m0, s42
	v_lshl_add_u64 v[226:227], s[10:11], 0, v[176:177]
	ds_read_b128 v[160:163], v206 offset:32768
	ds_read_b128 v[164:167], v206 offset:33792
	ds_read_b128 v[168:171], v206 offset:34816
	ds_read_b128 v[172:175], v206 offset:35840
	ds_read_b128 v[196:199], v206 offset:36864
	ds_read_b128 v[208:211], v206 offset:37888
	ds_read_b128 v[212:215], v206 offset:38912
	ds_read_b128 v[216:219], v206 offset:39936
	global_load_lds_dwordx4 v[226:227], off
	v_lshl_add_u64 v[226:227], s[10:11], 0, v[178:179]
	s_mov_b32 m0, s43
	s_nop 0
	global_load_lds_dwordx4 v[226:227], off
	s_waitcnt vmcnt(8)
	s_waitcnt lgkmcnt(0)
	s_barrier
	s_setprio 1
	v_mfma_f32_16x16x32_bf16 v[120:123], v[128:131], v[160:163], v[120:123]
	v_mfma_f32_16x16x32_bf16 v[48:51], v[136:139], v[160:163], v[48:51]
	v_mfma_f32_16x16x32_bf16 v[124:127], v[128:131], v[168:171], v[124:127]
	v_mfma_f32_16x16x32_bf16 v[60:63], v[136:139], v[168:171], v[60:63]
	v_mfma_f32_16x16x32_bf16 v[112:115], v[128:131], v[196:199], v[112:115]
	v_mfma_f32_16x16x32_bf16 v[52:55], v[136:139], v[196:199], v[52:55]
	v_mfma_f32_16x16x32_bf16 v[108:111], v[128:131], v[212:215], v[108:111]
	v_mfma_f32_16x16x32_bf16 v[36:39], v[136:139], v[212:215], v[36:39]
	v_mfma_f32_16x16x32_bf16 v[120:123], v[132:135], v[164:167], v[120:123]
	v_mfma_f32_16x16x32_bf16 v[48:51], v[140:143], v[164:167], v[48:51]
	v_mfma_f32_16x16x32_bf16 v[124:127], v[132:135], v[172:175], v[124:127]
	v_mfma_f32_16x16x32_bf16 v[60:63], v[140:143], v[172:175], v[60:63]
	v_mfma_f32_16x16x32_bf16 v[112:115], v[132:135], v[208:211], v[112:115]
	v_mfma_f32_16x16x32_bf16 v[52:55], v[140:143], v[208:211], v[52:55]
	v_mfma_f32_16x16x32_bf16 v[108:111], v[132:135], v[216:219], v[108:111]
	v_mfma_f32_16x16x32_bf16 v[36:39], v[140:143], v[216:219], v[36:39]
	s_setprio 0
	s_setprio 1
	v_mfma_f32_16x16x32_bf16 v[100:103], v[144:147], v[160:163], v[100:103]
	v_mfma_f32_16x16x32_bf16 v[40:43], v[152:155], v[160:163], v[40:43]
	v_mfma_f32_16x16x32_bf16 v[116:119], v[144:147], v[168:171], v[116:119]
	v_mfma_f32_16x16x32_bf16 v[56:59], v[152:155], v[168:171], v[56:59]
	v_mfma_f32_16x16x32_bf16 v[104:107], v[144:147], v[196:199], v[104:107]
	v_mfma_f32_16x16x32_bf16 v[44:47], v[152:155], v[196:199], v[44:47]
	v_mfma_f32_16x16x32_bf16 v[96:99], v[144:147], v[212:215], v[96:99]
	v_mfma_f32_16x16x32_bf16 v[32:35], v[152:155], v[212:215], v[32:35]
	v_mfma_f32_16x16x32_bf16 v[100:103], v[148:151], v[164:167], v[100:103]
	v_mfma_f32_16x16x32_bf16 v[40:43], v[156:159], v[164:167], v[40:43]
	v_mfma_f32_16x16x32_bf16 v[116:119], v[148:151], v[172:175], v[116:119]
	v_mfma_f32_16x16x32_bf16 v[56:59], v[156:159], v[172:175], v[56:59]
	v_mfma_f32_16x16x32_bf16 v[104:107], v[148:151], v[208:211], v[104:107]
	v_mfma_f32_16x16x32_bf16 v[44:47], v[156:159], v[208:211], v[44:47]
	v_mfma_f32_16x16x32_bf16 v[96:99], v[148:151], v[216:219], v[96:99]
	v_mfma_f32_16x16x32_bf16 v[32:35], v[156:159], v[216:219], v[32:35]
	s_setprio 0
	s_barrier
	s_add_i32 s0, s0, s33
	v_lshl_add_u64 v[186:187], v[186:187], 0, s[58:59]
	s_mov_b32 m0, s0
	ds_read_b128 v[160:163], v206 offset:49152
	ds_read_b128 v[164:167], v206 offset:50176
	ds_read_b128 v[168:171], v206 offset:51200
	ds_read_b128 v[172:175], v206 offset:52224
	ds_read_b128 v[196:199], v206 offset:53248
	ds_read_b128 v[208:211], v206 offset:54272
	ds_read_b128 v[212:215], v206 offset:55296
	ds_read_b128 v[216:219], v206 offset:56320
	global_load_lds_dwordx4 v[186:187], off
	s_add_i32 m0, s0, 0x2000
	s_add_u32 s10, s52, 0x80080
	v_lshl_add_u64 v[186:187], v[220:221], 0, s[58:59]
	s_addc_u32 s11, s53, 0
	s_add_i32 s0, s1, s33
	global_load_lds_dwordx4 v[186:187], off
	v_lshl_add_u64 v[186:187], s[10:11], 0, v[190:191]
	s_mov_b32 m0, s0
	s_nop 0
	global_load_lds_dwordx4 v[186:187], off
	v_lshl_add_u64 v[186:187], s[10:11], 0, v[180:181]
	s_add_i32 m0, s0, 0x2000
	s_nop 0
	global_load_lds_dwordx4 v[186:187], off
	v_lshl_add_u64 v[186:187], v[222:223], 0, s[58:59]
	s_mov_b32 m0, s55
	s_nop 0
	global_load_lds_dwordx4 v[186:187], off
	v_lshl_add_u64 v[186:187], v[224:225], 0, s[58:59]
	s_mov_b32 m0, s77
	s_nop 0
	global_load_lds_dwordx4 v[186:187], off
	s_waitcnt vmcnt(8)
	s_waitcnt lgkmcnt(0)
	s_barrier
	s_setprio 1
	v_mfma_f32_16x16x32_bf16 v[88:91], v[128:131], v[160:163], v[88:91]
	v_mfma_f32_16x16x32_bf16 v[20:23], v[136:139], v[160:163], v[20:23]
	v_mfma_f32_16x16x32_bf16 v[92:95], v[128:131], v[168:171], v[92:95]
	v_mfma_f32_16x16x32_bf16 v[28:31], v[136:139], v[168:171], v[28:31]
	v_mfma_f32_16x16x32_bf16 v[80:83], v[128:131], v[196:199], v[80:83]
	v_mfma_f32_16x16x32_bf16 v[16:19], v[136:139], v[196:199], v[16:19]
	v_mfma_f32_16x16x32_bf16 v[76:79], v[128:131], v[212:215], v[76:79]
	v_mfma_f32_16x16x32_bf16 v[12:15], v[136:139], v[212:215], v[12:15]
	v_mfma_f32_16x16x32_bf16 v[88:91], v[132:135], v[164:167], v[88:91]
	v_mfma_f32_16x16x32_bf16 v[20:23], v[140:143], v[164:167], v[20:23]
	v_mfma_f32_16x16x32_bf16 v[92:95], v[132:135], v[172:175], v[92:95]
	v_mfma_f32_16x16x32_bf16 v[28:31], v[140:143], v[172:175], v[28:31]
	v_mfma_f32_16x16x32_bf16 v[80:83], v[132:135], v[208:211], v[80:83]
	v_mfma_f32_16x16x32_bf16 v[16:19], v[140:143], v[208:211], v[16:19]
	v_mfma_f32_16x16x32_bf16 v[76:79], v[132:135], v[216:219], v[76:79]
	v_mfma_f32_16x16x32_bf16 v[12:15], v[140:143], v[216:219], v[12:15]
	s_setprio 0
	s_setprio 1
	v_mfma_f32_16x16x32_bf16 v[68:71], v[144:147], v[160:163], v[68:71]
	v_mfma_f32_16x16x32_bf16 v[4:7], v[152:155], v[160:163], v[4:7]
	v_mfma_f32_16x16x32_bf16 v[84:87], v[144:147], v[168:171], v[84:87]
	v_mfma_f32_16x16x32_bf16 v[24:27], v[152:155], v[168:171], v[24:27]
	v_mfma_f32_16x16x32_bf16 v[72:75], v[144:147], v[196:199], v[72:75]
	v_mfma_f32_16x16x32_bf16 v[8:11], v[152:155], v[196:199], v[8:11]
	v_mfma_f32_16x16x32_bf16 v[64:67], v[144:147], v[212:215], v[64:67]
	v_mfma_f32_16x16x32_bf16 v[0:3], v[152:155], v[212:215], v[0:3]
	v_mfma_f32_16x16x32_bf16 v[68:71], v[148:151], v[164:167], v[68:71]
	v_mfma_f32_16x16x32_bf16 v[4:7], v[156:159], v[164:167], v[4:7]
	v_mfma_f32_16x16x32_bf16 v[84:87], v[148:151], v[172:175], v[84:87]
	v_mfma_f32_16x16x32_bf16 v[24:27], v[156:159], v[172:175], v[24:27]
	v_mfma_f32_16x16x32_bf16 v[72:75], v[148:151], v[208:211], v[72:75]
	v_mfma_f32_16x16x32_bf16 v[8:11], v[156:159], v[208:211], v[8:11]
	v_mfma_f32_16x16x32_bf16 v[64:67], v[148:151], v[216:219], v[64:67]
	v_mfma_f32_16x16x32_bf16 v[0:3], v[156:159], v[216:219], v[0:3]
	s_setprio 0
	s_barrier
	s_add_i32 vcc_lo, vcc_lo, 2
	s_add_u32 s66, s66, 0x100
	s_addc_u32 s67, s67, 0
	s_cmp_gt_u32 vcc_lo, 29
	s_mov_b64 s[10:11], s[16:17]
	s_cbranch_scc1 .Lpeel_done_7
.LBB0_1105:
	s_add_u32 s16, s10, 0x100
	s_addc_u32 s17, s11, 0
	s_add_i32 vcc_hi, 0, 0x10000
	s_cmp_eq_u32 vcc_lo, 28
	s_cselect_b32 s69, s13, s17
	s_cselect_b32 s68, s15, s16
	s_cselect_b32 s53, s57, s67
	s_cselect_b32 s52, s61, s66
	s_add_i32 s0, 0, 0x14000
	v_add_u32_e32 v140, vcc_hi, v200
	v_add_u32_e32 v156, s0, v200
	ds_read_b128 v[128:131], v140
	ds_read_b128 v[132:135], v140 offset:1024
	ds_read_b128 v[136:139], v140 offset:2048
	ds_read_b128 v[140:143], v140 offset:3072
	ds_read_b128 v[144:147], v156
	ds_read_b128 v[148:151], v156 offset:1024
	ds_read_b128 v[152:155], v156 offset:2048
	ds_read_b128 v[156:159], v156 offset:3072
	v_lshl_add_u64 v[186:187], s[10:11], 0, v[182:183]
	s_add_i32 m0, s40, 0xc000
	ds_read_b128 v[160:163], v206
	ds_read_b128 v[164:167], v206 offset:1024
	ds_read_b128 v[168:171], v206 offset:2048
	ds_read_b128 v[172:175], v206 offset:3072
	ds_read_b128 v[196:199], v206 offset:4096
	ds_read_b128 v[208:211], v206 offset:5120
	ds_read_b128 v[212:215], v206 offset:6144
	ds_read_b128 v[216:219], v206 offset:7168
	global_load_lds_dwordx4 v[186:187], off
	v_lshl_add_u64 v[186:187], s[10:11], 0, v[184:185]
	s_add_i32 m0, s40, 0xe000
	s_nop 0
	global_load_lds_dwordx4 v[186:187], off
	s_waitcnt vmcnt(8)
	s_waitcnt lgkmcnt(0)
	s_barrier
	s_setprio 1
	v_mfma_f32_16x16x32_bf16 v[120:123], v[128:131], v[160:163], v[120:123]
	v_mfma_f32_16x16x32_bf16 v[48:51], v[136:139], v[160:163], v[48:51]
	v_mfma_f32_16x16x32_bf16 v[124:127], v[128:131], v[168:171], v[124:127]
	v_mfma_f32_16x16x32_bf16 v[60:63], v[136:139], v[168:171], v[60:63]
	v_mfma_f32_16x16x32_bf16 v[112:115], v[128:131], v[196:199], v[112:115]
	v_mfma_f32_16x16x32_bf16 v[52:55], v[136:139], v[196:199], v[52:55]
	v_mfma_f32_16x16x32_bf16 v[108:111], v[128:131], v[212:215], v[108:111]
	v_mfma_f32_16x16x32_bf16 v[36:39], v[136:139], v[212:215], v[36:39]
	v_mfma_f32_16x16x32_bf16 v[120:123], v[132:135], v[164:167], v[120:123]
	v_mfma_f32_16x16x32_bf16 v[48:51], v[140:143], v[164:167], v[48:51]
	v_mfma_f32_16x16x32_bf16 v[124:127], v[132:135], v[172:175], v[124:127]
	v_mfma_f32_16x16x32_bf16 v[60:63], v[140:143], v[172:175], v[60:63]
	v_mfma_f32_16x16x32_bf16 v[112:115], v[132:135], v[208:211], v[112:115]
	v_mfma_f32_16x16x32_bf16 v[52:55], v[140:143], v[208:211], v[52:55]
	v_mfma_f32_16x16x32_bf16 v[108:111], v[132:135], v[216:219], v[108:111]
	v_mfma_f32_16x16x32_bf16 v[36:39], v[140:143], v[216:219], v[36:39]
	s_setprio 0
	s_setprio 1
	v_mfma_f32_16x16x32_bf16 v[100:103], v[144:147], v[160:163], v[100:103]
	v_mfma_f32_16x16x32_bf16 v[40:43], v[152:155], v[160:163], v[40:43]
	v_mfma_f32_16x16x32_bf16 v[116:119], v[144:147], v[168:171], v[116:119]
	v_mfma_f32_16x16x32_bf16 v[56:59], v[152:155], v[168:171], v[56:59]
	v_mfma_f32_16x16x32_bf16 v[104:107], v[144:147], v[196:199], v[104:107]
	v_mfma_f32_16x16x32_bf16 v[44:47], v[152:155], v[196:199], v[44:47]
	v_mfma_f32_16x16x32_bf16 v[96:99], v[144:147], v[212:215], v[96:99]
	v_mfma_f32_16x16x32_bf16 v[32:35], v[152:155], v[212:215], v[32:35]
	v_mfma_f32_16x16x32_bf16 v[100:103], v[148:151], v[164:167], v[100:103]
	v_mfma_f32_16x16x32_bf16 v[40:43], v[156:159], v[164:167], v[40:43]
	v_mfma_f32_16x16x32_bf16 v[116:119], v[148:151], v[172:175], v[116:119]
	v_mfma_f32_16x16x32_bf16 v[56:59], v[156:159], v[172:175], v[56:59]
	v_mfma_f32_16x16x32_bf16 v[104:107], v[148:151], v[208:211], v[104:107]
	v_mfma_f32_16x16x32_bf16 v[44:47], v[156:159], v[208:211], v[44:47]
	v_mfma_f32_16x16x32_bf16 v[96:99], v[148:151], v[216:219], v[96:99]
	v_mfma_f32_16x16x32_bf16 v[32:35], v[156:159], v[216:219], v[32:35]
	s_setprio 0
	s_barrier
	s_add_i32 s1, vcc_hi, s33
	v_lshl_add_u64 v[186:187], s[52:53], 0, v[190:191]
	s_mov_b32 m0, s1
	ds_read_b128 v[160:163], v206 offset:16384
	ds_read_b128 v[164:167], v206 offset:17408
	ds_read_b128 v[168:171], v206 offset:18432
	ds_read_b128 v[172:175], v206 offset:19456
	ds_read_b128 v[196:199], v206 offset:20480
	ds_read_b128 v[208:211], v206 offset:21504
	ds_read_b128 v[212:215], v206 offset:22528
	ds_read_b128 v[216:219], v206 offset:23552
	global_load_lds_dwordx4 v[186:187], off
	s_add_i32 m0, s1, 0x2000
	s_add_u32 s10, s52, 0x80000
	v_lshl_add_u64 v[220:221], s[52:53], 0, v[180:181]
	s_addc_u32 s11, s53, 0
	s_add_i32 s0, s0, s33
	global_load_lds_dwordx4 v[220:221], off
	v_lshl_add_u64 v[222:223], s[10:11], 0, v[190:191]
	s_mov_b32 m0, s0
	v_lshl_add_u64 v[224:225], s[68:69], 0, v[178:179]
	global_load_lds_dwordx4 v[222:223], off
	v_lshl_add_u64 v[222:223], s[10:11], 0, v[180:181]
	s_add_i32 m0, s0, 0x2000
	s_nop 0
	global_load_lds_dwordx4 v[222:223], off
	v_lshl_add_u64 v[222:223], s[68:69], 0, v[176:177]
	s_mov_b32 m0, s40
	s_nop 0
	global_load_lds_dwordx4 v[222:223], off
	s_mov_b32 m0, s41
	s_nop 0
	global_load_lds_dwordx4 v[224:225], off
	s_waitcnt vmcnt(8)
	s_waitcnt lgkmcnt(0)
	s_barrier
	s_setprio 1
	v_mfma_f32_16x16x32_bf16 v[88:91], v[128:131], v[160:163], v[88:91]
	v_mfma_f32_16x16x32_bf16 v[20:23], v[136:139], v[160:163], v[20:23]
	v_mfma_f32_16x16x32_bf16 v[92:95], v[128:131], v[168:171], v[92:95]
	v_mfma_f32_16x16x32_bf16 v[28:31], v[136:139], v[168:171], v[28:31]
	v_mfma_f32_16x16x32_bf16 v[80:83], v[128:131], v[196:199], v[80:83]
	v_mfma_f32_16x16x32_bf16 v[16:19], v[136:139], v[196:199], v[16:19]
	v_mfma_f32_16x16x32_bf16 v[76:79], v[128:131], v[212:215], v[76:79]
	v_mfma_f32_16x16x32_bf16 v[12:15], v[136:139], v[212:215], v[12:15]
	v_mfma_f32_16x16x32_bf16 v[88:91], v[132:135], v[164:167], v[88:91]
	v_mfma_f32_16x16x32_bf16 v[20:23], v[140:143], v[164:167], v[20:23]
	v_mfma_f32_16x16x32_bf16 v[92:95], v[132:135], v[172:175], v[92:95]
	v_mfma_f32_16x16x32_bf16 v[28:31], v[140:143], v[172:175], v[28:31]
	v_mfma_f32_16x16x32_bf16 v[80:83], v[132:135], v[208:211], v[80:83]
	v_mfma_f32_16x16x32_bf16 v[16:19], v[140:143], v[208:211], v[16:19]
	v_mfma_f32_16x16x32_bf16 v[76:79], v[132:135], v[216:219], v[76:79]
	v_mfma_f32_16x16x32_bf16 v[12:15], v[140:143], v[216:219], v[12:15]
	s_setprio 0
	s_setprio 1
	v_mfma_f32_16x16x32_bf16 v[68:71], v[144:147], v[160:163], v[68:71]
	v_mfma_f32_16x16x32_bf16 v[4:7], v[152:155], v[160:163], v[4:7]
	v_mfma_f32_16x16x32_bf16 v[84:87], v[144:147], v[168:171], v[84:87]
	v_mfma_f32_16x16x32_bf16 v[24:27], v[152:155], v[168:171], v[24:27]
	v_mfma_f32_16x16x32_bf16 v[72:75], v[144:147], v[196:199], v[72:75]
	v_mfma_f32_16x16x32_bf16 v[8:11], v[152:155], v[196:199], v[8:11]
	v_mfma_f32_16x16x32_bf16 v[64:67], v[144:147], v[212:215], v[64:67]
	v_mfma_f32_16x16x32_bf16 v[0:3], v[152:155], v[212:215], v[0:3]
	v_mfma_f32_16x16x32_bf16 v[68:71], v[148:151], v[164:167], v[68:71]
	v_mfma_f32_16x16x32_bf16 v[4:7], v[156:159], v[164:167], v[4:7]
	v_mfma_f32_16x16x32_bf16 v[84:87], v[148:151], v[172:175], v[84:87]
	v_mfma_f32_16x16x32_bf16 v[24:27], v[156:159], v[172:175], v[24:27]
	v_mfma_f32_16x16x32_bf16 v[72:75], v[148:151], v[208:211], v[72:75]
	v_mfma_f32_16x16x32_bf16 v[8:11], v[156:159], v[208:211], v[8:11]
	v_mfma_f32_16x16x32_bf16 v[64:67], v[148:151], v[216:219], v[64:67]
	v_mfma_f32_16x16x32_bf16 v[0:3], v[156:159], v[216:219], v[0:3]
	s_setprio 0
	s_barrier
	s_add_i32 s0, 0, 0x18000
	s_add_i32 s1, 0, 0x1c000
	v_add_u32_e32 v140, s0, v200
	v_add_u32_e32 v156, s1, v200
	ds_read_b128 v[128:131], v140
	ds_read_b128 v[132:135], v140 offset:1024
	ds_read_b128 v[136:139], v140 offset:2048
	ds_read_b128 v[140:143], v140 offset:3072
	ds_read_b128 v[144:147], v156
	ds_read_b128 v[148:151], v156 offset:1024
	ds_read_b128 v[152:155], v156 offset:2048
	ds_read_b128 v[156:159], v156 offset:3072
	s_add_u32 s10, s68, 0x80000
	s_addc_u32 s11, s69, 0
	s_mov_b32 m0, s42
	v_lshl_add_u64 v[226:227], s[10:11], 0, v[176:177]
	ds_read_b128 v[160:163], v206 offset:32768
	ds_read_b128 v[164:167], v206 offset:33792
	ds_read_b128 v[168:171], v206 offset:34816
	ds_read_b128 v[172:175], v206 offset:35840
	ds_read_b128 v[196:199], v206 offset:36864
	ds_read_b128 v[208:211], v206 offset:37888
	ds_read_b128 v[212:215], v206 offset:38912
	ds_read_b128 v[216:219], v206 offset:39936
	global_load_lds_dwordx4 v[226:227], off
	v_lshl_add_u64 v[226:227], s[10:11], 0, v[178:179]
	s_mov_b32 m0, s43
	s_nop 0
	global_load_lds_dwordx4 v[226:227], off
	s_waitcnt vmcnt(8)
	s_waitcnt lgkmcnt(0)
	s_barrier
	s_setprio 1
	v_mfma_f32_16x16x32_bf16 v[120:123], v[128:131], v[160:163], v[120:123]
	v_mfma_f32_16x16x32_bf16 v[48:51], v[136:139], v[160:163], v[48:51]
	v_mfma_f32_16x16x32_bf16 v[124:127], v[128:131], v[168:171], v[124:127]
	v_mfma_f32_16x16x32_bf16 v[60:63], v[136:139], v[168:171], v[60:63]
	v_mfma_f32_16x16x32_bf16 v[112:115], v[128:131], v[196:199], v[112:115]
	v_mfma_f32_16x16x32_bf16 v[52:55], v[136:139], v[196:199], v[52:55]
	v_mfma_f32_16x16x32_bf16 v[108:111], v[128:131], v[212:215], v[108:111]
	v_mfma_f32_16x16x32_bf16 v[36:39], v[136:139], v[212:215], v[36:39]
	v_mfma_f32_16x16x32_bf16 v[120:123], v[132:135], v[164:167], v[120:123]
	v_mfma_f32_16x16x32_bf16 v[48:51], v[140:143], v[164:167], v[48:51]
	v_mfma_f32_16x16x32_bf16 v[124:127], v[132:135], v[172:175], v[124:127]
	v_mfma_f32_16x16x32_bf16 v[60:63], v[140:143], v[172:175], v[60:63]
	v_mfma_f32_16x16x32_bf16 v[112:115], v[132:135], v[208:211], v[112:115]
	v_mfma_f32_16x16x32_bf16 v[52:55], v[140:143], v[208:211], v[52:55]
	v_mfma_f32_16x16x32_bf16 v[108:111], v[132:135], v[216:219], v[108:111]
	v_mfma_f32_16x16x32_bf16 v[36:39], v[140:143], v[216:219], v[36:39]
	s_setprio 0
	s_setprio 1
	v_mfma_f32_16x16x32_bf16 v[100:103], v[144:147], v[160:163], v[100:103]
	v_mfma_f32_16x16x32_bf16 v[40:43], v[152:155], v[160:163], v[40:43]
	v_mfma_f32_16x16x32_bf16 v[116:119], v[144:147], v[168:171], v[116:119]
	v_mfma_f32_16x16x32_bf16 v[56:59], v[152:155], v[168:171], v[56:59]
	v_mfma_f32_16x16x32_bf16 v[104:107], v[144:147], v[196:199], v[104:107]
	v_mfma_f32_16x16x32_bf16 v[44:47], v[152:155], v[196:199], v[44:47]
	v_mfma_f32_16x16x32_bf16 v[96:99], v[144:147], v[212:215], v[96:99]
	v_mfma_f32_16x16x32_bf16 v[32:35], v[152:155], v[212:215], v[32:35]
	v_mfma_f32_16x16x32_bf16 v[100:103], v[148:151], v[164:167], v[100:103]
	v_mfma_f32_16x16x32_bf16 v[40:43], v[156:159], v[164:167], v[40:43]
	v_mfma_f32_16x16x32_bf16 v[116:119], v[148:151], v[172:175], v[116:119]
	v_mfma_f32_16x16x32_bf16 v[56:59], v[156:159], v[172:175], v[56:59]
	v_mfma_f32_16x16x32_bf16 v[104:107], v[148:151], v[208:211], v[104:107]
	v_mfma_f32_16x16x32_bf16 v[44:47], v[156:159], v[208:211], v[44:47]
	v_mfma_f32_16x16x32_bf16 v[96:99], v[148:151], v[216:219], v[96:99]
	v_mfma_f32_16x16x32_bf16 v[32:35], v[156:159], v[216:219], v[32:35]
	s_setprio 0
	s_barrier
	s_add_i32 s0, s0, s33
	v_lshl_add_u64 v[186:187], v[186:187], 0, s[58:59]
	s_mov_b32 m0, s0
	ds_read_b128 v[160:163], v206 offset:49152
	ds_read_b128 v[164:167], v206 offset:50176
	ds_read_b128 v[168:171], v206 offset:51200
	ds_read_b128 v[172:175], v206 offset:52224
	ds_read_b128 v[196:199], v206 offset:53248
	ds_read_b128 v[208:211], v206 offset:54272
	ds_read_b128 v[212:215], v206 offset:55296
	ds_read_b128 v[216:219], v206 offset:56320
	global_load_lds_dwordx4 v[186:187], off
	s_add_i32 m0, s0, 0x2000
	s_add_u32 s10, s52, 0x80080
	v_lshl_add_u64 v[186:187], v[220:221], 0, s[58:59]
	s_addc_u32 s11, s53, 0
	s_add_i32 s0, s1, s33
	global_load_lds_dwordx4 v[186:187], off
	v_lshl_add_u64 v[186:187], s[10:11], 0, v[190:191]
	s_mov_b32 m0, s0
	s_nop 0
	global_load_lds_dwordx4 v[186:187], off
	v_lshl_add_u64 v[186:187], s[10:11], 0, v[180:181]
	s_add_i32 m0, s0, 0x2000
	s_nop 0
	global_load_lds_dwordx4 v[186:187], off
	v_lshl_add_u64 v[186:187], v[222:223], 0, s[58:59]
	s_mov_b32 m0, s55
	s_nop 0
	global_load_lds_dwordx4 v[186:187], off
	v_lshl_add_u64 v[186:187], v[224:225], 0, s[58:59]
	s_mov_b32 m0, s77
	s_nop 0
	global_load_lds_dwordx4 v[186:187], off
	s_waitcnt vmcnt(8)
	s_waitcnt lgkmcnt(0)
	s_barrier
	s_setprio 1
	v_mfma_f32_16x16x32_bf16 v[88:91], v[128:131], v[160:163], v[88:91]
	v_mfma_f32_16x16x32_bf16 v[20:23], v[136:139], v[160:163], v[20:23]
	v_mfma_f32_16x16x32_bf16 v[92:95], v[128:131], v[168:171], v[92:95]
	v_mfma_f32_16x16x32_bf16 v[28:31], v[136:139], v[168:171], v[28:31]
	v_mfma_f32_16x16x32_bf16 v[80:83], v[128:131], v[196:199], v[80:83]
	v_mfma_f32_16x16x32_bf16 v[16:19], v[136:139], v[196:199], v[16:19]
	v_mfma_f32_16x16x32_bf16 v[76:79], v[128:131], v[212:215], v[76:79]
	v_mfma_f32_16x16x32_bf16 v[12:15], v[136:139], v[212:215], v[12:15]
	v_mfma_f32_16x16x32_bf16 v[88:91], v[132:135], v[164:167], v[88:91]
	v_mfma_f32_16x16x32_bf16 v[20:23], v[140:143], v[164:167], v[20:23]
	v_mfma_f32_16x16x32_bf16 v[92:95], v[132:135], v[172:175], v[92:95]
	v_mfma_f32_16x16x32_bf16 v[28:31], v[140:143], v[172:175], v[28:31]
	v_mfma_f32_16x16x32_bf16 v[80:83], v[132:135], v[208:211], v[80:83]
	v_mfma_f32_16x16x32_bf16 v[16:19], v[140:143], v[208:211], v[16:19]
	v_mfma_f32_16x16x32_bf16 v[76:79], v[132:135], v[216:219], v[76:79]
	v_mfma_f32_16x16x32_bf16 v[12:15], v[140:143], v[216:219], v[12:15]
	s_setprio 0
	s_setprio 1
	v_mfma_f32_16x16x32_bf16 v[68:71], v[144:147], v[160:163], v[68:71]
	v_mfma_f32_16x16x32_bf16 v[4:7], v[152:155], v[160:163], v[4:7]
	v_mfma_f32_16x16x32_bf16 v[84:87], v[144:147], v[168:171], v[84:87]
	v_mfma_f32_16x16x32_bf16 v[24:27], v[152:155], v[168:171], v[24:27]
	v_mfma_f32_16x16x32_bf16 v[72:75], v[144:147], v[196:199], v[72:75]
	v_mfma_f32_16x16x32_bf16 v[8:11], v[152:155], v[196:199], v[8:11]
	v_mfma_f32_16x16x32_bf16 v[64:67], v[144:147], v[212:215], v[64:67]
	v_mfma_f32_16x16x32_bf16 v[0:3], v[152:155], v[212:215], v[0:3]
	v_mfma_f32_16x16x32_bf16 v[68:71], v[148:151], v[164:167], v[68:71]
	v_mfma_f32_16x16x32_bf16 v[4:7], v[156:159], v[164:167], v[4:7]
	v_mfma_f32_16x16x32_bf16 v[84:87], v[148:151], v[172:175], v[84:87]
	v_mfma_f32_16x16x32_bf16 v[24:27], v[156:159], v[172:175], v[24:27]
	v_mfma_f32_16x16x32_bf16 v[72:75], v[148:151], v[208:211], v[72:75]
	v_mfma_f32_16x16x32_bf16 v[8:11], v[156:159], v[208:211], v[8:11]
	v_mfma_f32_16x16x32_bf16 v[64:67], v[148:151], v[216:219], v[64:67]
	v_mfma_f32_16x16x32_bf16 v[0:3], v[156:159], v[216:219], v[0:3]
	s_setprio 0
	s_barrier
	s_add_i32 vcc_lo, vcc_lo, 2
	s_add_u32 s66, s66, 0x100
	s_addc_u32 s67, s67, 0
	s_cmp_gt_u32 vcc_lo, 29
	s_mov_b64 s[10:11], s[16:17]
	s_cbranch_scc0 .LBB0_1105

.LBB0_1349:
	s_add_u32 s47, s20, 0x100
	s_addc_u32 s52, s21, 0
	s_mov_b32 s53, -2
	v_readlane_b32 s0, v255, 49
	s_nop 3
	s_cmp_eq_u32 s0, 9
	v_writelane_b32 v255, 9, 49
	s_cbranch_scc0 .Ltrip0_strict_8
	s_add_u32 s20, s16, 0x100
	s_addc_u32 s21, s17, 0
	s_add_i32 s0, 0, 0x10000
	s_cmpk_eq_i32 s53, 0x54
	s_cselect_b32 s25, s13, s21
	s_cselect_b32 s24, s12, s20
	s_cselect_b32 s23, s15, s52
	s_cselect_b32 s22, s14, s47
	s_add_i32 s1, 0, 0x14000
	v_add_u32_e32 v154, s0, v139
	v_add_u32_e32 v170, s1, v139
	ds_read_b128 v[142:145], v154
	ds_read_b128 v[146:149], v154 offset:1024
	ds_read_b128 v[150:153], v154 offset:2048
	ds_read_b128 v[154:157], v154 offset:3072
	ds_read_b128 v[158:161], v170
	ds_read_b128 v[162:165], v170 offset:1024
	ds_read_b128 v[166:169], v170 offset:2048
	ds_read_b128 v[170:173], v170 offset:3072
	v_lshl_add_u64 v[186:187], s[16:17], 0, v[134:135]
	s_add_i32 m0, s29, 0xc000
	ds_read_b128 v[174:177], v141
	ds_read_b128 v[178:181], v141 offset:1024
	ds_read_b128 v[182:185], v141 offset:2048
	ds_read_b128 v[196:199], v141 offset:3072
	ds_read_b128 v[200:203], v141 offset:4096
	ds_read_b128 v[204:207], v141 offset:5120
	ds_read_b128 v[208:211], v141 offset:6144
	ds_read_b128 v[212:215], v141 offset:7168
	global_load_lds_dwordx4 v[186:187], off
	v_lshl_add_u64 v[186:187], s[16:17], 0, v[136:137]
	s_add_i32 m0, s29, 0xe000
	s_nop 0
	global_load_lds_dwordx4 v[186:187], off
	s_waitcnt vmcnt(24)
	s_waitcnt lgkmcnt(0)
	s_barrier
	s_setprio 1
	v_mfma_f32_16x16x32_bf16 v[124:127], v[142:145], v[174:177], 0
	v_mfma_f32_16x16x32_bf16 v[120:123], v[150:153], v[174:177], 0
	v_mfma_f32_16x16x32_bf16 v[116:119], v[142:145], v[182:185], 0
	v_mfma_f32_16x16x32_bf16 v[112:115], v[150:153], v[182:185], 0
	v_mfma_f32_16x16x32_bf16 v[100:103], v[142:145], v[200:203], 0
	v_mfma_f32_16x16x32_bf16 v[96:99], v[150:153], v[200:203], 0
	v_mfma_f32_16x16x32_bf16 v[84:87], v[142:145], v[208:211], 0
	v_mfma_f32_16x16x32_bf16 v[80:83], v[150:153], v[208:211], 0
	v_mfma_f32_16x16x32_bf16 v[124:127], v[146:149], v[178:181], v[124:127]
	v_mfma_f32_16x16x32_bf16 v[120:123], v[154:157], v[178:181], v[120:123]
	v_mfma_f32_16x16x32_bf16 v[116:119], v[146:149], v[196:199], v[116:119]
	v_mfma_f32_16x16x32_bf16 v[112:115], v[154:157], v[196:199], v[112:115]
	v_mfma_f32_16x16x32_bf16 v[100:103], v[146:149], v[204:207], v[100:103]
	v_mfma_f32_16x16x32_bf16 v[96:99], v[154:157], v[204:207], v[96:99]
	v_mfma_f32_16x16x32_bf16 v[84:87], v[146:149], v[212:215], v[84:87]
	v_mfma_f32_16x16x32_bf16 v[80:83], v[154:157], v[212:215], v[80:83]
	s_setprio 0
	s_setprio 1
	v_mfma_f32_16x16x32_bf16 v[108:111], v[158:161], v[174:177], 0
	v_mfma_f32_16x16x32_bf16 v[104:107], v[166:169], v[174:177], 0
	v_mfma_f32_16x16x32_bf16 v[92:95], v[158:161], v[182:185], 0
	v_mfma_f32_16x16x32_bf16 v[88:91], v[166:169], v[182:185], 0
	v_mfma_f32_16x16x32_bf16 v[76:79], v[158:161], v[200:203], 0
	v_mfma_f32_16x16x32_bf16 v[72:75], v[166:169], v[200:203], 0
	v_mfma_f32_16x16x32_bf16 v[68:71], v[158:161], v[208:211], 0
	v_mfma_f32_16x16x32_bf16 v[64:67], v[166:169], v[208:211], 0
	v_mfma_f32_16x16x32_bf16 v[108:111], v[162:165], v[178:181], v[108:111]
	v_mfma_f32_16x16x32_bf16 v[104:107], v[170:173], v[178:181], v[104:107]
	v_mfma_f32_16x16x32_bf16 v[92:95], v[162:165], v[196:199], v[92:95]
	v_mfma_f32_16x16x32_bf16 v[88:91], v[170:173], v[196:199], v[88:91]
	v_mfma_f32_16x16x32_bf16 v[76:79], v[162:165], v[204:207], v[76:79]
	v_mfma_f32_16x16x32_bf16 v[72:75], v[170:173], v[204:207], v[72:75]
	v_mfma_f32_16x16x32_bf16 v[68:71], v[162:165], v[212:215], v[68:71]
	v_mfma_f32_16x16x32_bf16 v[64:67], v[170:173], v[212:215], v[64:67]
	s_setprio 0
	s_barrier
	s_add_i32 s0, s0, s28
	v_lshl_add_u64 v[186:187], s[22:23], 0, v[190:191]
	s_mov_b32 m0, s0
	ds_read_b128 v[174:177], v141 offset:16384
	ds_read_b128 v[178:181], v141 offset:17408
	ds_read_b128 v[182:185], v141 offset:18432
	ds_read_b128 v[196:199], v141 offset:19456
	ds_read_b128 v[200:203], v141 offset:20480
	ds_read_b128 v[204:207], v141 offset:21504
	ds_read_b128 v[208:211], v141 offset:22528
	ds_read_b128 v[212:215], v141 offset:23552
	global_load_lds_dwordx4 v[186:187], off
	s_add_i32 m0, s0, 0x2000
	s_add_u32 s16, s22, 0x160000
	v_lshl_add_u64 v[216:217], s[22:23], 0, v[132:133]
	s_addc_u32 s17, s23, 0
	s_add_i32 s0, s1, s28
	global_load_lds_dwordx4 v[216:217], off
	v_lshl_add_u64 v[218:219], s[16:17], 0, v[190:191]
	s_mov_b32 m0, s0
	v_lshl_add_u64 v[220:221], s[24:25], 0, v[130:131]
	global_load_lds_dwordx4 v[218:219], off
	v_lshl_add_u64 v[218:219], s[16:17], 0, v[132:133]
	s_add_i32 m0, s0, 0x2000
	s_nop 0
	global_load_lds_dwordx4 v[218:219], off
	v_lshl_add_u64 v[218:219], s[24:25], 0, v[128:129]
	s_mov_b32 m0, s29
	s_nop 0
	global_load_lds_dwordx4 v[218:219], off
	s_mov_b32 m0, s30
	s_nop 0
	global_load_lds_dwordx4 v[220:221], off
	s_waitcnt vmcnt(24)
	s_waitcnt lgkmcnt(0)
	s_barrier
	s_setprio 1
	v_mfma_f32_16x16x32_bf16 v[60:63], v[142:145], v[174:177], 0
	v_mfma_f32_16x16x32_bf16 v[56:59], v[150:153], v[174:177], 0
	v_mfma_f32_16x16x32_bf16 v[52:55], v[142:145], v[182:185], 0
	v_mfma_f32_16x16x32_bf16 v[48:51], v[150:153], v[182:185], 0
	v_mfma_f32_16x16x32_bf16 v[36:39], v[142:145], v[200:203], 0
	v_mfma_f32_16x16x32_bf16 v[32:35], v[150:153], v[200:203], 0
	v_mfma_f32_16x16x32_bf16 v[20:23], v[142:145], v[208:211], 0
	v_mfma_f32_16x16x32_bf16 v[16:19], v[150:153], v[208:211], 0
	v_mfma_f32_16x16x32_bf16 v[60:63], v[146:149], v[178:181], v[60:63]
	v_mfma_f32_16x16x32_bf16 v[56:59], v[154:157], v[178:181], v[56:59]
	v_mfma_f32_16x16x32_bf16 v[52:55], v[146:149], v[196:199], v[52:55]
	v_mfma_f32_16x16x32_bf16 v[48:51], v[154:157], v[196:199], v[48:51]
	v_mfma_f32_16x16x32_bf16 v[36:39], v[146:149], v[204:207], v[36:39]
	v_mfma_f32_16x16x32_bf16 v[32:35], v[154:157], v[204:207], v[32:35]
	v_mfma_f32_16x16x32_bf16 v[20:23], v[146:149], v[212:215], v[20:23]
	v_mfma_f32_16x16x32_bf16 v[16:19], v[154:157], v[212:215], v[16:19]
	s_setprio 0
	s_setprio 1
	v_mfma_f32_16x16x32_bf16 v[44:47], v[158:161], v[174:177], 0
	v_mfma_f32_16x16x32_bf16 v[40:43], v[166:169], v[174:177], 0
	v_mfma_f32_16x16x32_bf16 v[28:31], v[158:161], v[182:185], 0
	v_mfma_f32_16x16x32_bf16 v[24:27], v[166:169], v[182:185], 0
	v_mfma_f32_16x16x32_bf16 v[12:15], v[158:161], v[200:203], 0
	v_mfma_f32_16x16x32_bf16 v[8:11], v[166:169], v[200:203], 0
	v_mfma_f32_16x16x32_bf16 v[4:7], v[158:161], v[208:211], 0
	v_mfma_f32_16x16x32_bf16 v[0:3], v[166:169], v[208:211], 0
	v_mfma_f32_16x16x32_bf16 v[44:47], v[162:165], v[178:181], v[44:47]
	v_mfma_f32_16x16x32_bf16 v[40:43], v[170:173], v[178:181], v[40:43]
	v_mfma_f32_16x16x32_bf16 v[28:31], v[162:165], v[196:199], v[28:31]
	v_mfma_f32_16x16x32_bf16 v[24:27], v[170:173], v[196:199], v[24:27]
	v_mfma_f32_16x16x32_bf16 v[12:15], v[162:165], v[204:207], v[12:15]
	v_mfma_f32_16x16x32_bf16 v[8:11], v[170:173], v[204:207], v[8:11]
	v_mfma_f32_16x16x32_bf16 v[4:7], v[162:165], v[212:215], v[4:7]
	v_mfma_f32_16x16x32_bf16 v[0:3], v[170:173], v[212:215], v[0:3]
	s_setprio 0
	s_barrier
	s_add_i32 s0, 0, 0x18000
	s_add_i32 s1, 0, 0x1c000
	v_add_u32_e32 v154, s0, v139
	v_add_u32_e32 v170, s1, v139
	ds_read_b128 v[142:145], v154
	ds_read_b128 v[146:149], v154 offset:1024
	ds_read_b128 v[150:153], v154 offset:2048
	ds_read_b128 v[154:157], v154 offset:3072
	ds_read_b128 v[158:161], v170
	ds_read_b128 v[162:165], v170 offset:1024
	ds_read_b128 v[166:169], v170 offset:2048
	ds_read_b128 v[170:173], v170 offset:3072
	s_add_u32 s16, s24, 0x160000
	s_addc_u32 s17, s25, 0
	s_mov_b32 m0, s31
	v_lshl_add_u64 v[222:223], s[16:17], 0, v[128:129]
	ds_read_b128 v[174:177], v141 offset:32768
	ds_read_b128 v[178:181], v141 offset:33792
	ds_read_b128 v[182:185], v141 offset:34816
	ds_read_b128 v[196:199], v141 offset:35840
	ds_read_b128 v[200:203], v141 offset:36864
	ds_read_b128 v[204:207], v141 offset:37888
	ds_read_b128 v[208:211], v141 offset:38912
	ds_read_b128 v[212:215], v141 offset:39936
	global_load_lds_dwordx4 v[222:223], off
	v_lshl_add_u64 v[222:223], s[16:17], 0, v[130:131]
	s_mov_b32 m0, s33
	s_nop 0
	global_load_lds_dwordx4 v[222:223], off
	s_waitcnt vmcnt(8)
	s_waitcnt lgkmcnt(0)
	s_barrier
	s_setprio 1
	v_mfma_f32_16x16x32_bf16 v[124:127], v[142:145], v[174:177], v[124:127]
	v_mfma_f32_16x16x32_bf16 v[120:123], v[150:153], v[174:177], v[120:123]
	v_mfma_f32_16x16x32_bf16 v[116:119], v[142:145], v[182:185], v[116:119]
	v_mfma_f32_16x16x32_bf16 v[112:115], v[150:153], v[182:185], v[112:115]
	v_mfma_f32_16x16x32_bf16 v[100:103], v[142:145], v[200:203], v[100:103]
	v_mfma_f32_16x16x32_bf16 v[96:99], v[150:153], v[200:203], v[96:99]
	v_mfma_f32_16x16x32_bf16 v[84:87], v[142:145], v[208:211], v[84:87]
	v_mfma_f32_16x16x32_bf16 v[80:83], v[150:153], v[208:211], v[80:83]
	v_mfma_f32_16x16x32_bf16 v[124:127], v[146:149], v[178:181], v[124:127]
	v_mfma_f32_16x16x32_bf16 v[120:123], v[154:157], v[178:181], v[120:123]
	v_mfma_f32_16x16x32_bf16 v[116:119], v[146:149], v[196:199], v[116:119]
	v_mfma_f32_16x16x32_bf16 v[112:115], v[154:157], v[196:199], v[112:115]
	v_mfma_f32_16x16x32_bf16 v[100:103], v[146:149], v[204:207], v[100:103]
	v_mfma_f32_16x16x32_bf16 v[96:99], v[154:157], v[204:207], v[96:99]
	v_mfma_f32_16x16x32_bf16 v[84:87], v[146:149], v[212:215], v[84:87]
	v_mfma_f32_16x16x32_bf16 v[80:83], v[154:157], v[212:215], v[80:83]
	s_setprio 0
	s_setprio 1
	v_mfma_f32_16x16x32_bf16 v[108:111], v[158:161], v[174:177], v[108:111]
	v_mfma_f32_16x16x32_bf16 v[104:107], v[166:169], v[174:177], v[104:107]
	v_mfma_f32_16x16x32_bf16 v[92:95], v[158:161], v[182:185], v[92:95]
	v_mfma_f32_16x16x32_bf16 v[88:91], v[166:169], v[182:185], v[88:91]
	v_mfma_f32_16x16x32_bf16 v[76:79], v[158:161], v[200:203], v[76:79]
	v_mfma_f32_16x16x32_bf16 v[72:75], v[166:169], v[200:203], v[72:75]
	v_mfma_f32_16x16x32_bf16 v[68:71], v[158:161], v[208:211], v[68:71]
	v_mfma_f32_16x16x32_bf16 v[64:67], v[166:169], v[208:211], v[64:67]
	v_mfma_f32_16x16x32_bf16 v[108:111], v[162:165], v[178:181], v[108:111]
	v_mfma_f32_16x16x32_bf16 v[104:107], v[170:173], v[178:181], v[104:107]
	v_mfma_f32_16x16x32_bf16 v[92:95], v[162:165], v[196:199], v[92:95]
	v_mfma_f32_16x16x32_bf16 v[88:91], v[170:173], v[196:199], v[88:91]
	v_mfma_f32_16x16x32_bf16 v[76:79], v[162:165], v[204:207], v[76:79]
	v_mfma_f32_16x16x32_bf16 v[72:75], v[170:173], v[204:207], v[72:75]
	v_mfma_f32_16x16x32_bf16 v[68:71], v[162:165], v[212:215], v[68:71]
	v_mfma_f32_16x16x32_bf16 v[64:67], v[170:173], v[212:215], v[64:67]
	s_setprio 0
	s_barrier
	s_add_i32 s0, s0, s28
	v_lshl_add_u64 v[186:187], v[186:187], 0, s[58:59]
	s_mov_b32 m0, s0
	ds_read_b128 v[174:177], v141 offset:49152
	ds_read_b128 v[178:181], v141 offset:50176
	ds_read_b128 v[182:185], v141 offset:51200
	ds_read_b128 v[196:199], v141 offset:52224
	ds_read_b128 v[200:203], v141 offset:53248
	ds_read_b128 v[204:207], v141 offset:54272
	ds_read_b128 v[208:211], v141 offset:55296
	ds_read_b128 v[212:215], v141 offset:56320
	global_load_lds_dwordx4 v[186:187], off
	s_add_i32 m0, s0, 0x2000
	s_add_u32 s16, s22, 0x160080
	v_lshl_add_u64 v[186:187], v[216:217], 0, s[58:59]
	s_addc_u32 s17, s23, 0
	s_add_i32 s0, s1, s28
	global_load_lds_dwordx4 v[186:187], off
	v_lshl_add_u64 v[186:187], s[16:17], 0, v[190:191]
	s_mov_b32 m0, s0
	s_nop 0
	global_load_lds_dwordx4 v[186:187], off
	v_lshl_add_u64 v[186:187], s[16:17], 0, v[132:133]
	s_add_i32 m0, s0, 0x2000
	s_nop 0
	global_load_lds_dwordx4 v[186:187], off
	v_lshl_add_u64 v[186:187], v[218:219], 0, s[58:59]
	s_mov_b32 m0, s37
	s_nop 0
	global_load_lds_dwordx4 v[186:187], off
	v_lshl_add_u64 v[186:187], v[220:221], 0, s[58:59]
	s_mov_b32 m0, s38
	s_nop 0
	global_load_lds_dwordx4 v[186:187], off
	s_waitcnt vmcnt(8)
	s_waitcnt lgkmcnt(0)
	s_barrier
	s_setprio 1
	v_mfma_f32_16x16x32_bf16 v[60:63], v[142:145], v[174:177], v[60:63]
	v_mfma_f32_16x16x32_bf16 v[56:59], v[150:153], v[174:177], v[56:59]
	v_mfma_f32_16x16x32_bf16 v[52:55], v[142:145], v[182:185], v[52:55]
	v_mfma_f32_16x16x32_bf16 v[48:51], v[150:153], v[182:185], v[48:51]
	v_mfma_f32_16x16x32_bf16 v[36:39], v[142:145], v[200:203], v[36:39]
	v_mfma_f32_16x16x32_bf16 v[32:35], v[150:153], v[200:203], v[32:35]
	v_mfma_f32_16x16x32_bf16 v[20:23], v[142:145], v[208:211], v[20:23]
	v_mfma_f32_16x16x32_bf16 v[16:19], v[150:153], v[208:211], v[16:19]
	v_mfma_f32_16x16x32_bf16 v[60:63], v[146:149], v[178:181], v[60:63]
	v_mfma_f32_16x16x32_bf16 v[56:59], v[154:157], v[178:181], v[56:59]
	v_mfma_f32_16x16x32_bf16 v[52:55], v[146:149], v[196:199], v[52:55]
	v_mfma_f32_16x16x32_bf16 v[48:51], v[154:157], v[196:199], v[48:51]
	v_mfma_f32_16x16x32_bf16 v[36:39], v[146:149], v[204:207], v[36:39]
	v_mfma_f32_16x16x32_bf16 v[32:35], v[154:157], v[204:207], v[32:35]
	v_mfma_f32_16x16x32_bf16 v[20:23], v[146:149], v[212:215], v[20:23]
	v_mfma_f32_16x16x32_bf16 v[16:19], v[154:157], v[212:215], v[16:19]
	s_setprio 0
	s_setprio 1
	v_mfma_f32_16x16x32_bf16 v[44:47], v[158:161], v[174:177], v[44:47]
	v_mfma_f32_16x16x32_bf16 v[40:43], v[166:169], v[174:177], v[40:43]
	v_mfma_f32_16x16x32_bf16 v[28:31], v[158:161], v[182:185], v[28:31]
	v_mfma_f32_16x16x32_bf16 v[24:27], v[166:169], v[182:185], v[24:27]
	v_mfma_f32_16x16x32_bf16 v[12:15], v[158:161], v[200:203], v[12:15]
	v_mfma_f32_16x16x32_bf16 v[8:11], v[166:169], v[200:203], v[8:11]
	v_mfma_f32_16x16x32_bf16 v[4:7], v[158:161], v[208:211], v[4:7]
	v_mfma_f32_16x16x32_bf16 v[0:3], v[166:169], v[208:211], v[0:3]
	v_mfma_f32_16x16x32_bf16 v[44:47], v[162:165], v[178:181], v[44:47]
	v_mfma_f32_16x16x32_bf16 v[40:43], v[170:173], v[178:181], v[40:43]
	v_mfma_f32_16x16x32_bf16 v[28:31], v[162:165], v[196:199], v[28:31]
	v_mfma_f32_16x16x32_bf16 v[24:27], v[170:173], v[196:199], v[24:27]
	v_mfma_f32_16x16x32_bf16 v[12:15], v[162:165], v[204:207], v[12:15]
	v_mfma_f32_16x16x32_bf16 v[8:11], v[170:173], v[204:207], v[8:11]
	v_mfma_f32_16x16x32_bf16 v[4:7], v[162:165], v[212:215], v[4:7]
	v_mfma_f32_16x16x32_bf16 v[0:3], v[170:173], v[212:215], v[0:3]
	s_setprio 0
	s_barrier
	s_add_i32 s53, s53, 2
	s_add_u32 s47, s47, 0x100
	s_addc_u32 s52, s52, 0
	s_cmpk_gt_u32 s53, 0x55
	s_mov_b64 s[16:17], s[20:21]
	s_cbranch_scc1 .Lpeel_done_8
	s_branch .LBB0_1350
.Ltrip0_strict_8:
	s_add_u32 s20, s16, 0x100
	s_addc_u32 s21, s17, 0
	s_add_i32 s0, 0, 0x10000
	s_cmpk_eq_i32 s53, 0x54
	s_cselect_b32 s25, s13, s21
	s_cselect_b32 s24, s12, s20
	s_cselect_b32 s23, s15, s52
	s_cselect_b32 s22, s14, s47
	s_add_i32 s1, 0, 0x14000
	v_add_u32_e32 v154, s0, v139
	v_add_u32_e32 v170, s1, v139
	ds_read_b128 v[142:145], v154
	ds_read_b128 v[146:149], v154 offset:1024
	ds_read_b128 v[150:153], v154 offset:2048
	ds_read_b128 v[154:157], v154 offset:3072
	ds_read_b128 v[158:161], v170
	ds_read_b128 v[162:165], v170 offset:1024
	ds_read_b128 v[166:169], v170 offset:2048
	ds_read_b128 v[170:173], v170 offset:3072
	v_lshl_add_u64 v[186:187], s[16:17], 0, v[134:135]
	s_add_i32 m0, s29, 0xc000
	ds_read_b128 v[174:177], v141
	ds_read_b128 v[178:181], v141 offset:1024
	ds_read_b128 v[182:185], v141 offset:2048
	ds_read_b128 v[196:199], v141 offset:3072
	ds_read_b128 v[200:203], v141 offset:4096
	ds_read_b128 v[204:207], v141 offset:5120
	ds_read_b128 v[208:211], v141 offset:6144
	ds_read_b128 v[212:215], v141 offset:7168
	global_load_lds_dwordx4 v[186:187], off
	v_lshl_add_u64 v[186:187], s[16:17], 0, v[136:137]
	s_add_i32 m0, s29, 0xe000
	s_nop 0
	global_load_lds_dwordx4 v[186:187], off
	s_waitcnt vmcnt(8)
	s_waitcnt lgkmcnt(0)
	s_barrier
	s_setprio 1
	v_mfma_f32_16x16x32_bf16 v[124:127], v[142:145], v[174:177], 0
	v_mfma_f32_16x16x32_bf16 v[120:123], v[150:153], v[174:177], 0
	v_mfma_f32_16x16x32_bf16 v[116:119], v[142:145], v[182:185], 0
	v_mfma_f32_16x16x32_bf16 v[112:115], v[150:153], v[182:185], 0
	v_mfma_f32_16x16x32_bf16 v[100:103], v[142:145], v[200:203], 0
	v_mfma_f32_16x16x32_bf16 v[96:99], v[150:153], v[200:203], 0
	v_mfma_f32_16x16x32_bf16 v[84:87], v[142:145], v[208:211], 0
	v_mfma_f32_16x16x32_bf16 v[80:83], v[150:153], v[208:211], 0
	v_mfma_f32_16x16x32_bf16 v[124:127], v[146:149], v[178:181], v[124:127]
	v_mfma_f32_16x16x32_bf16 v[120:123], v[154:157], v[178:181], v[120:123]
	v_mfma_f32_16x16x32_bf16 v[116:119], v[146:149], v[196:199], v[116:119]
	v_mfma_f32_16x16x32_bf16 v[112:115], v[154:157], v[196:199], v[112:115]
	v_mfma_f32_16x16x32_bf16 v[100:103], v[146:149], v[204:207], v[100:103]
	v_mfma_f32_16x16x32_bf16 v[96:99], v[154:157], v[204:207], v[96:99]
	v_mfma_f32_16x16x32_bf16 v[84:87], v[146:149], v[212:215], v[84:87]
	v_mfma_f32_16x16x32_bf16 v[80:83], v[154:157], v[212:215], v[80:83]
	s_setprio 0
	s_setprio 1
	v_mfma_f32_16x16x32_bf16 v[108:111], v[158:161], v[174:177], 0
	v_mfma_f32_16x16x32_bf16 v[104:107], v[166:169], v[174:177], 0
	v_mfma_f32_16x16x32_bf16 v[92:95], v[158:161], v[182:185], 0
	v_mfma_f32_16x16x32_bf16 v[88:91], v[166:169], v[182:185], 0
	v_mfma_f32_16x16x32_bf16 v[76:79], v[158:161], v[200:203], 0
	v_mfma_f32_16x16x32_bf16 v[72:75], v[166:169], v[200:203], 0
	v_mfma_f32_16x16x32_bf16 v[68:71], v[158:161], v[208:211], 0
	v_mfma_f32_16x16x32_bf16 v[64:67], v[166:169], v[208:211], 0
	v_mfma_f32_16x16x32_bf16 v[108:111], v[162:165], v[178:181], v[108:111]
	v_mfma_f32_16x16x32_bf16 v[104:107], v[170:173], v[178:181], v[104:107]
	v_mfma_f32_16x16x32_bf16 v[92:95], v[162:165], v[196:199], v[92:95]
	v_mfma_f32_16x16x32_bf16 v[88:91], v[170:173], v[196:199], v[88:91]
	v_mfma_f32_16x16x32_bf16 v[76:79], v[162:165], v[204:207], v[76:79]
	v_mfma_f32_16x16x32_bf16 v[72:75], v[170:173], v[204:207], v[72:75]
	v_mfma_f32_16x16x32_bf16 v[68:71], v[162:165], v[212:215], v[68:71]
	v_mfma_f32_16x16x32_bf16 v[64:67], v[170:173], v[212:215], v[64:67]
	s_setprio 0
	s_barrier
	s_add_i32 s0, s0, s28
	v_lshl_add_u64 v[186:187], s[22:23], 0, v[190:191]
	s_mov_b32 m0, s0
	ds_read_b128 v[174:177], v141 offset:16384
	ds_read_b128 v[178:181], v141 offset:17408
	ds_read_b128 v[182:185], v141 offset:18432
	ds_read_b128 v[196:199], v141 offset:19456
	ds_read_b128 v[200:203], v141 offset:20480
	ds_read_b128 v[204:207], v141 offset:21504
	ds_read_b128 v[208:211], v141 offset:22528
	ds_read_b128 v[212:215], v141 offset:23552
	global_load_lds_dwordx4 v[186:187], off
	s_add_i32 m0, s0, 0x2000
	s_add_u32 s16, s22, 0x160000
	v_lshl_add_u64 v[216:217], s[22:23], 0, v[132:133]
	s_addc_u32 s17, s23, 0
	s_add_i32 s0, s1, s28
	global_load_lds_dwordx4 v[216:217], off
	v_lshl_add_u64 v[218:219], s[16:17], 0, v[190:191]
	s_mov_b32 m0, s0
	v_lshl_add_u64 v[220:221], s[24:25], 0, v[130:131]
	global_load_lds_dwordx4 v[218:219], off
	v_lshl_add_u64 v[218:219], s[16:17], 0, v[132:133]
	s_add_i32 m0, s0, 0x2000
	s_nop 0
	global_load_lds_dwordx4 v[218:219], off
	v_lshl_add_u64 v[218:219], s[24:25], 0, v[128:129]
	s_mov_b32 m0, s29
	s_nop 0
	global_load_lds_dwordx4 v[218:219], off
	s_mov_b32 m0, s30
	s_nop 0
	global_load_lds_dwordx4 v[220:221], off
	s_waitcnt vmcnt(8)
	s_waitcnt lgkmcnt(0)
	s_barrier
	s_setprio 1
	v_mfma_f32_16x16x32_bf16 v[60:63], v[142:145], v[174:177], 0
	v_mfma_f32_16x16x32_bf16 v[56:59], v[150:153], v[174:177], 0
	v_mfma_f32_16x16x32_bf16 v[52:55], v[142:145], v[182:185], 0
	v_mfma_f32_16x16x32_bf16 v[48:51], v[150:153], v[182:185], 0
	v_mfma_f32_16x16x32_bf16 v[36:39], v[142:145], v[200:203], 0
	v_mfma_f32_16x16x32_bf16 v[32:35], v[150:153], v[200:203], 0
	v_mfma_f32_16x16x32_bf16 v[20:23], v[142:145], v[208:211], 0
	v_mfma_f32_16x16x32_bf16 v[16:19], v[150:153], v[208:211], 0
	v_mfma_f32_16x16x32_bf16 v[60:63], v[146:149], v[178:181], v[60:63]
	v_mfma_f32_16x16x32_bf16 v[56:59], v[154:157], v[178:181], v[56:59]
	v_mfma_f32_16x16x32_bf16 v[52:55], v[146:149], v[196:199], v[52:55]
	v_mfma_f32_16x16x32_bf16 v[48:51], v[154:157], v[196:199], v[48:51]
	v_mfma_f32_16x16x32_bf16 v[36:39], v[146:149], v[204:207], v[36:39]
	v_mfma_f32_16x16x32_bf16 v[32:35], v[154:157], v[204:207], v[32:35]
	v_mfma_f32_16x16x32_bf16 v[20:23], v[146:149], v[212:215], v[20:23]
	v_mfma_f32_16x16x32_bf16 v[16:19], v[154:157], v[212:215], v[16:19]
	s_setprio 0
	s_setprio 1
	v_mfma_f32_16x16x32_bf16 v[44:47], v[158:161], v[174:177], 0
	v_mfma_f32_16x16x32_bf16 v[40:43], v[166:169], v[174:177], 0
	v_mfma_f32_16x16x32_bf16 v[28:31], v[158:161], v[182:185], 0
	v_mfma_f32_16x16x32_bf16 v[24:27], v[166:169], v[182:185], 0
	v_mfma_f32_16x16x32_bf16 v[12:15], v[158:161], v[200:203], 0
	v_mfma_f32_16x16x32_bf16 v[8:11], v[166:169], v[200:203], 0
	v_mfma_f32_16x16x32_bf16 v[4:7], v[158:161], v[208:211], 0
	v_mfma_f32_16x16x32_bf16 v[0:3], v[166:169], v[208:211], 0
	v_mfma_f32_16x16x32_bf16 v[44:47], v[162:165], v[178:181], v[44:47]
	v_mfma_f32_16x16x32_bf16 v[40:43], v[170:173], v[178:181], v[40:43]
	v_mfma_f32_16x16x32_bf16 v[28:31], v[162:165], v[196:199], v[28:31]
	v_mfma_f32_16x16x32_bf16 v[24:27], v[170:173], v[196:199], v[24:27]
	v_mfma_f32_16x16x32_bf16 v[12:15], v[162:165], v[204:207], v[12:15]
	v_mfma_f32_16x16x32_bf16 v[8:11], v[170:173], v[204:207], v[8:11]
	v_mfma_f32_16x16x32_bf16 v[4:7], v[162:165], v[212:215], v[4:7]
	v_mfma_f32_16x16x32_bf16 v[0:3], v[170:173], v[212:215], v[0:3]
	s_setprio 0
	s_barrier
	s_add_i32 s0, 0, 0x18000
	s_add_i32 s1, 0, 0x1c000
	v_add_u32_e32 v154, s0, v139
	v_add_u32_e32 v170, s1, v139
	ds_read_b128 v[142:145], v154
	ds_read_b128 v[146:149], v154 offset:1024
	ds_read_b128 v[150:153], v154 offset:2048
	ds_read_b128 v[154:157], v154 offset:3072
	ds_read_b128 v[158:161], v170
	ds_read_b128 v[162:165], v170 offset:1024
	ds_read_b128 v[166:169], v170 offset:2048
	ds_read_b128 v[170:173], v170 offset:3072
	s_add_u32 s16, s24, 0x160000
	s_addc_u32 s17, s25, 0
	s_mov_b32 m0, s31
	v_lshl_add_u64 v[222:223], s[16:17], 0, v[128:129]
	ds_read_b128 v[174:177], v141 offset:32768
	ds_read_b128 v[178:181], v141 offset:33792
	ds_read_b128 v[182:185], v141 offset:34816
	ds_read_b128 v[196:199], v141 offset:35840
	ds_read_b128 v[200:203], v141 offset:36864
	ds_read_b128 v[204:207], v141 offset:37888
	ds_read_b128 v[208:211], v141 offset:38912
	ds_read_b128 v[212:215], v141 offset:39936
	global_load_lds_dwordx4 v[222:223], off
	v_lshl_add_u64 v[222:223], s[16:17], 0, v[130:131]
	s_mov_b32 m0, s33
	s_nop 0
	global_load_lds_dwordx4 v[222:223], off
	s_waitcnt vmcnt(8)
	s_waitcnt lgkmcnt(0)
	s_barrier
	s_setprio 1
	v_mfma_f32_16x16x32_bf16 v[124:127], v[142:145], v[174:177], v[124:127]
	v_mfma_f32_16x16x32_bf16 v[120:123], v[150:153], v[174:177], v[120:123]
	v_mfma_f32_16x16x32_bf16 v[116:119], v[142:145], v[182:185], v[116:119]
	v_mfma_f32_16x16x32_bf16 v[112:115], v[150:153], v[182:185], v[112:115]
	v_mfma_f32_16x16x32_bf16 v[100:103], v[142:145], v[200:203], v[100:103]
	v_mfma_f32_16x16x32_bf16 v[96:99], v[150:153], v[200:203], v[96:99]
	v_mfma_f32_16x16x32_bf16 v[84:87], v[142:145], v[208:211], v[84:87]
	v_mfma_f32_16x16x32_bf16 v[80:83], v[150:153], v[208:211], v[80:83]
	v_mfma_f32_16x16x32_bf16 v[124:127], v[146:149], v[178:181], v[124:127]
	v_mfma_f32_16x16x32_bf16 v[120:123], v[154:157], v[178:181], v[120:123]
	v_mfma_f32_16x16x32_bf16 v[116:119], v[146:149], v[196:199], v[116:119]
	v_mfma_f32_16x16x32_bf16 v[112:115], v[154:157], v[196:199], v[112:115]
	v_mfma_f32_16x16x32_bf16 v[100:103], v[146:149], v[204:207], v[100:103]
	v_mfma_f32_16x16x32_bf16 v[96:99], v[154:157], v[204:207], v[96:99]
	v_mfma_f32_16x16x32_bf16 v[84:87], v[146:149], v[212:215], v[84:87]
	v_mfma_f32_16x16x32_bf16 v[80:83], v[154:157], v[212:215], v[80:83]
	s_setprio 0
	s_setprio 1
	v_mfma_f32_16x16x32_bf16 v[108:111], v[158:161], v[174:177], v[108:111]
	v_mfma_f32_16x16x32_bf16 v[104:107], v[166:169], v[174:177], v[104:107]
	v_mfma_f32_16x16x32_bf16 v[92:95], v[158:161], v[182:185], v[92:95]
	v_mfma_f32_16x16x32_bf16 v[88:91], v[166:169], v[182:185], v[88:91]
	v_mfma_f32_16x16x32_bf16 v[76:79], v[158:161], v[200:203], v[76:79]
	v_mfma_f32_16x16x32_bf16 v[72:75], v[166:169], v[200:203], v[72:75]
	v_mfma_f32_16x16x32_bf16 v[68:71], v[158:161], v[208:211], v[68:71]
	v_mfma_f32_16x16x32_bf16 v[64:67], v[166:169], v[208:211], v[64:67]
	v_mfma_f32_16x16x32_bf16 v[108:111], v[162:165], v[178:181], v[108:111]
	v_mfma_f32_16x16x32_bf16 v[104:107], v[170:173], v[178:181], v[104:107]
	v_mfma_f32_16x16x32_bf16 v[92:95], v[162:165], v[196:199], v[92:95]
	v_mfma_f32_16x16x32_bf16 v[88:91], v[170:173], v[196:199], v[88:91]
	v_mfma_f32_16x16x32_bf16 v[76:79], v[162:165], v[204:207], v[76:79]
	v_mfma_f32_16x16x32_bf16 v[72:75], v[170:173], v[204:207], v[72:75]
	v_mfma_f32_16x16x32_bf16 v[68:71], v[162:165], v[212:215], v[68:71]
	v_mfma_f32_16x16x32_bf16 v[64:67], v[170:173], v[212:215], v[64:67]
	s_setprio 0
	s_barrier
	s_add_i32 s0, s0, s28
	v_lshl_add_u64 v[186:187], v[186:187], 0, s[58:59]
	s_mov_b32 m0, s0
	ds_read_b128 v[174:177], v141 offset:49152
	ds_read_b128 v[178:181], v141 offset:50176
	ds_read_b128 v[182:185], v141 offset:51200
	ds_read_b128 v[196:199], v141 offset:52224
	ds_read_b128 v[200:203], v141 offset:53248
	ds_read_b128 v[204:207], v141 offset:54272
	ds_read_b128 v[208:211], v141 offset:55296
	ds_read_b128 v[212:215], v141 offset:56320
	global_load_lds_dwordx4 v[186:187], off
	s_add_i32 m0, s0, 0x2000
	s_add_u32 s16, s22, 0x160080
	v_lshl_add_u64 v[186:187], v[216:217], 0, s[58:59]
	s_addc_u32 s17, s23, 0
	s_add_i32 s0, s1, s28
	global_load_lds_dwordx4 v[186:187], off
	v_lshl_add_u64 v[186:187], s[16:17], 0, v[190:191]
	s_mov_b32 m0, s0
	s_nop 0
	global_load_lds_dwordx4 v[186:187], off
	v_lshl_add_u64 v[186:187], s[16:17], 0, v[132:133]
	s_add_i32 m0, s0, 0x2000
	s_nop 0
	global_load_lds_dwordx4 v[186:187], off
	v_lshl_add_u64 v[186:187], v[218:219], 0, s[58:59]
	s_mov_b32 m0, s37
	s_nop 0
	global_load_lds_dwordx4 v[186:187], off
	v_lshl_add_u64 v[186:187], v[220:221], 0, s[58:59]
	s_mov_b32 m0, s38
	s_nop 0
	global_load_lds_dwordx4 v[186:187], off
	s_waitcnt vmcnt(8)
	s_waitcnt lgkmcnt(0)
	s_barrier
	s_setprio 1
	v_mfma_f32_16x16x32_bf16 v[60:63], v[142:145], v[174:177], v[60:63]
	v_mfma_f32_16x16x32_bf16 v[56:59], v[150:153], v[174:177], v[56:59]
	v_mfma_f32_16x16x32_bf16 v[52:55], v[142:145], v[182:185], v[52:55]
	v_mfma_f32_16x16x32_bf16 v[48:51], v[150:153], v[182:185], v[48:51]
	v_mfma_f32_16x16x32_bf16 v[36:39], v[142:145], v[200:203], v[36:39]
	v_mfma_f32_16x16x32_bf16 v[32:35], v[150:153], v[200:203], v[32:35]
	v_mfma_f32_16x16x32_bf16 v[20:23], v[142:145], v[208:211], v[20:23]
	v_mfma_f32_16x16x32_bf16 v[16:19], v[150:153], v[208:211], v[16:19]
	v_mfma_f32_16x16x32_bf16 v[60:63], v[146:149], v[178:181], v[60:63]
	v_mfma_f32_16x16x32_bf16 v[56:59], v[154:157], v[178:181], v[56:59]
	v_mfma_f32_16x16x32_bf16 v[52:55], v[146:149], v[196:199], v[52:55]
	v_mfma_f32_16x16x32_bf16 v[48:51], v[154:157], v[196:199], v[48:51]
	v_mfma_f32_16x16x32_bf16 v[36:39], v[146:149], v[204:207], v[36:39]
	v_mfma_f32_16x16x32_bf16 v[32:35], v[154:157], v[204:207], v[32:35]
	v_mfma_f32_16x16x32_bf16 v[20:23], v[146:149], v[212:215], v[20:23]
	v_mfma_f32_16x16x32_bf16 v[16:19], v[154:157], v[212:215], v[16:19]
	s_setprio 0
	s_setprio 1
	v_mfma_f32_16x16x32_bf16 v[44:47], v[158:161], v[174:177], v[44:47]
	v_mfma_f32_16x16x32_bf16 v[40:43], v[166:169], v[174:177], v[40:43]
	v_mfma_f32_16x16x32_bf16 v[28:31], v[158:161], v[182:185], v[28:31]
	v_mfma_f32_16x16x32_bf16 v[24:27], v[166:169], v[182:185], v[24:27]
	v_mfma_f32_16x16x32_bf16 v[12:15], v[158:161], v[200:203], v[12:15]
	v_mfma_f32_16x16x32_bf16 v[8:11], v[166:169], v[200:203], v[8:11]
	v_mfma_f32_16x16x32_bf16 v[4:7], v[158:161], v[208:211], v[4:7]
	v_mfma_f32_16x16x32_bf16 v[0:3], v[166:169], v[208:211], v[0:3]
	v_mfma_f32_16x16x32_bf16 v[44:47], v[162:165], v[178:181], v[44:47]
	v_mfma_f32_16x16x32_bf16 v[40:43], v[170:173], v[178:181], v[40:43]
	v_mfma_f32_16x16x32_bf16 v[28:31], v[162:165], v[196:199], v[28:31]
	v_mfma_f32_16x16x32_bf16 v[24:27], v[170:173], v[196:199], v[24:27]
	v_mfma_f32_16x16x32_bf16 v[12:15], v[162:165], v[204:207], v[12:15]
	v_mfma_f32_16x16x32_bf16 v[8:11], v[170:173], v[204:207], v[8:11]
	v_mfma_f32_16x16x32_bf16 v[4:7], v[162:165], v[212:215], v[4:7]
	v_mfma_f32_16x16x32_bf16 v[0:3], v[170:173], v[212:215], v[0:3]
	s_setprio 0
	s_barrier
	s_add_i32 s53, s53, 2
	s_add_u32 s47, s47, 0x100
	s_addc_u32 s52, s52, 0
	s_cmpk_gt_u32 s53, 0x55
	s_mov_b64 s[16:17], s[20:21]
	s_cbranch_scc1 .Lpeel_done_8
.LBB0_1350:
	s_add_u32 s20, s16, 0x100
	s_addc_u32 s21, s17, 0
	s_add_i32 s0, 0, 0x10000
	s_cmpk_eq_i32 s53, 0x54
	s_cselect_b32 s25, s13, s21
	s_cselect_b32 s24, s12, s20
	s_cselect_b32 s23, s15, s52
	s_cselect_b32 s22, s14, s47
	s_add_i32 s1, 0, 0x14000
	v_add_u32_e32 v154, s0, v139
	v_add_u32_e32 v170, s1, v139
	ds_read_b128 v[142:145], v154
	ds_read_b128 v[146:149], v154 offset:1024
	ds_read_b128 v[150:153], v154 offset:2048
	ds_read_b128 v[154:157], v154 offset:3072
	ds_read_b128 v[158:161], v170
	ds_read_b128 v[162:165], v170 offset:1024
	ds_read_b128 v[166:169], v170 offset:2048
	ds_read_b128 v[170:173], v170 offset:3072
	v_lshl_add_u64 v[186:187], s[16:17], 0, v[134:135]
	s_add_i32 m0, s29, 0xc000
	ds_read_b128 v[174:177], v141
	ds_read_b128 v[178:181], v141 offset:1024
	ds_read_b128 v[182:185], v141 offset:2048
	ds_read_b128 v[196:199], v141 offset:3072
	ds_read_b128 v[200:203], v141 offset:4096
	ds_read_b128 v[204:207], v141 offset:5120
	ds_read_b128 v[208:211], v141 offset:6144
	ds_read_b128 v[212:215], v141 offset:7168
	global_load_lds_dwordx4 v[186:187], off
	v_lshl_add_u64 v[186:187], s[16:17], 0, v[136:137]
	s_add_i32 m0, s29, 0xe000
	s_nop 0
	global_load_lds_dwordx4 v[186:187], off
	s_waitcnt vmcnt(8)
	s_waitcnt lgkmcnt(0)
	s_barrier
	s_setprio 1
	v_mfma_f32_16x16x32_bf16 v[124:127], v[142:145], v[174:177], v[124:127]
	v_mfma_f32_16x16x32_bf16 v[120:123], v[150:153], v[174:177], v[120:123]
	v_mfma_f32_16x16x32_bf16 v[116:119], v[142:145], v[182:185], v[116:119]
	v_mfma_f32_16x16x32_bf16 v[112:115], v[150:153], v[182:185], v[112:115]
	v_mfma_f32_16x16x32_bf16 v[100:103], v[142:145], v[200:203], v[100:103]
	v_mfma_f32_16x16x32_bf16 v[96:99], v[150:153], v[200:203], v[96:99]
	v_mfma_f32_16x16x32_bf16 v[84:87], v[142:145], v[208:211], v[84:87]
	v_mfma_f32_16x16x32_bf16 v[80:83], v[150:153], v[208:211], v[80:83]
	v_mfma_f32_16x16x32_bf16 v[124:127], v[146:149], v[178:181], v[124:127]
	v_mfma_f32_16x16x32_bf16 v[120:123], v[154:157], v[178:181], v[120:123]
	v_mfma_f32_16x16x32_bf16 v[116:119], v[146:149], v[196:199], v[116:119]
	v_mfma_f32_16x16x32_bf16 v[112:115], v[154:157], v[196:199], v[112:115]
	v_mfma_f32_16x16x32_bf16 v[100:103], v[146:149], v[204:207], v[100:103]
	v_mfma_f32_16x16x32_bf16 v[96:99], v[154:157], v[204:207], v[96:99]
	v_mfma_f32_16x16x32_bf16 v[84:87], v[146:149], v[212:215], v[84:87]
	v_mfma_f32_16x16x32_bf16 v[80:83], v[154:157], v[212:215], v[80:83]
	s_setprio 0
	s_setprio 1
	v_mfma_f32_16x16x32_bf16 v[108:111], v[158:161], v[174:177], v[108:111]
	v_mfma_f32_16x16x32_bf16 v[104:107], v[166:169], v[174:177], v[104:107]
	v_mfma_f32_16x16x32_bf16 v[92:95], v[158:161], v[182:185], v[92:95]
	v_mfma_f32_16x16x32_bf16 v[88:91], v[166:169], v[182:185], v[88:91]
	v_mfma_f32_16x16x32_bf16 v[76:79], v[158:161], v[200:203], v[76:79]
	v_mfma_f32_16x16x32_bf16 v[72:75], v[166:169], v[200:203], v[72:75]
	v_mfma_f32_16x16x32_bf16 v[68:71], v[158:161], v[208:211], v[68:71]
	v_mfma_f32_16x16x32_bf16 v[64:67], v[166:169], v[208:211], v[64:67]
	v_mfma_f32_16x16x32_bf16 v[108:111], v[162:165], v[178:181], v[108:111]
	v_mfma_f32_16x16x32_bf16 v[104:107], v[170:173], v[178:181], v[104:107]
	v_mfma_f32_16x16x32_bf16 v[92:95], v[162:165], v[196:199], v[92:95]
	v_mfma_f32_16x16x32_bf16 v[88:91], v[170:173], v[196:199], v[88:91]
	v_mfma_f32_16x16x32_bf16 v[76:79], v[162:165], v[204:207], v[76:79]
	v_mfma_f32_16x16x32_bf16 v[72:75], v[170:173], v[204:207], v[72:75]
	v_mfma_f32_16x16x32_bf16 v[68:71], v[162:165], v[212:215], v[68:71]
	v_mfma_f32_16x16x32_bf16 v[64:67], v[170:173], v[212:215], v[64:67]
	s_setprio 0
	s_barrier
	s_add_i32 s0, s0, s28
	v_lshl_add_u64 v[186:187], s[22:23], 0, v[190:191]
	s_mov_b32 m0, s0
	ds_read_b128 v[174:177], v141 offset:16384
	ds_read_b128 v[178:181], v141 offset:17408
	ds_read_b128 v[182:185], v141 offset:18432
	ds_read_b128 v[196:199], v141 offset:19456
	ds_read_b128 v[200:203], v141 offset:20480
	ds_read_b128 v[204:207], v141 offset:21504
	ds_read_b128 v[208:211], v141 offset:22528
	ds_read_b128 v[212:215], v141 offset:23552
	global_load_lds_dwordx4 v[186:187], off
	s_add_i32 m0, s0, 0x2000
	s_add_u32 s16, s22, 0x160000
	v_lshl_add_u64 v[216:217], s[22:23], 0, v[132:133]
	s_addc_u32 s17, s23, 0
	s_add_i32 s0, s1, s28
	global_load_lds_dwordx4 v[216:217], off
	v_lshl_add_u64 v[218:219], s[16:17], 0, v[190:191]
	s_mov_b32 m0, s0
	v_lshl_add_u64 v[220:221], s[24:25], 0, v[130:131]
	global_load_lds_dwordx4 v[218:219], off
	v_lshl_add_u64 v[218:219], s[16:17], 0, v[132:133]
	s_add_i32 m0, s0, 0x2000
	s_nop 0
	global_load_lds_dwordx4 v[218:219], off
	v_lshl_add_u64 v[218:219], s[24:25], 0, v[128:129]
	s_mov_b32 m0, s29
	s_nop 0
	global_load_lds_dwordx4 v[218:219], off
	s_mov_b32 m0, s30
	s_nop 0
	global_load_lds_dwordx4 v[220:221], off
	s_waitcnt vmcnt(8)
	s_waitcnt lgkmcnt(0)
	s_barrier
	s_setprio 1
	v_mfma_f32_16x16x32_bf16 v[60:63], v[142:145], v[174:177], v[60:63]
	v_mfma_f32_16x16x32_bf16 v[56:59], v[150:153], v[174:177], v[56:59]
	v_mfma_f32_16x16x32_bf16 v[52:55], v[142:145], v[182:185], v[52:55]
	v_mfma_f32_16x16x32_bf16 v[48:51], v[150:153], v[182:185], v[48:51]
	v_mfma_f32_16x16x32_bf16 v[36:39], v[142:145], v[200:203], v[36:39]
	v_mfma_f32_16x16x32_bf16 v[32:35], v[150:153], v[200:203], v[32:35]
	v_mfma_f32_16x16x32_bf16 v[20:23], v[142:145], v[208:211], v[20:23]
	v_mfma_f32_16x16x32_bf16 v[16:19], v[150:153], v[208:211], v[16:19]
	v_mfma_f32_16x16x32_bf16 v[60:63], v[146:149], v[178:181], v[60:63]
	v_mfma_f32_16x16x32_bf16 v[56:59], v[154:157], v[178:181], v[56:59]
	v_mfma_f32_16x16x32_bf16 v[52:55], v[146:149], v[196:199], v[52:55]
	v_mfma_f32_16x16x32_bf16 v[48:51], v[154:157], v[196:199], v[48:51]
	v_mfma_f32_16x16x32_bf16 v[36:39], v[146:149], v[204:207], v[36:39]
	v_mfma_f32_16x16x32_bf16 v[32:35], v[154:157], v[204:207], v[32:35]
	v_mfma_f32_16x16x32_bf16 v[20:23], v[146:149], v[212:215], v[20:23]
	v_mfma_f32_16x16x32_bf16 v[16:19], v[154:157], v[212:215], v[16:19]
	s_setprio 0
	s_setprio 1
	v_mfma_f32_16x16x32_bf16 v[44:47], v[158:161], v[174:177], v[44:47]
	v_mfma_f32_16x16x32_bf16 v[40:43], v[166:169], v[174:177], v[40:43]
	v_mfma_f32_16x16x32_bf16 v[28:31], v[158:161], v[182:185], v[28:31]
	v_mfma_f32_16x16x32_bf16 v[24:27], v[166:169], v[182:185], v[24:27]
	v_mfma_f32_16x16x32_bf16 v[12:15], v[158:161], v[200:203], v[12:15]
	v_mfma_f32_16x16x32_bf16 v[8:11], v[166:169], v[200:203], v[8:11]
	v_mfma_f32_16x16x32_bf16 v[4:7], v[158:161], v[208:211], v[4:7]
	v_mfma_f32_16x16x32_bf16 v[0:3], v[166:169], v[208:211], v[0:3]
	v_mfma_f32_16x16x32_bf16 v[44:47], v[162:165], v[178:181], v[44:47]
	v_mfma_f32_16x16x32_bf16 v[40:43], v[170:173], v[178:181], v[40:43]
	v_mfma_f32_16x16x32_bf16 v[28:31], v[162:165], v[196:199], v[28:31]
	v_mfma_f32_16x16x32_bf16 v[24:27], v[170:173], v[196:199], v[24:27]
	v_mfma_f32_16x16x32_bf16 v[12:15], v[162:165], v[204:207], v[12:15]
	v_mfma_f32_16x16x32_bf16 v[8:11], v[170:173], v[204:207], v[8:11]
	v_mfma_f32_16x16x32_bf16 v[4:7], v[162:165], v[212:215], v[4:7]
	v_mfma_f32_16x16x32_bf16 v[0:3], v[170:173], v[212:215], v[0:3]
	s_setprio 0
	s_barrier
	s_add_i32 s0, 0, 0x18000
	s_add_i32 s1, 0, 0x1c000
	v_add_u32_e32 v154, s0, v139
	v_add_u32_e32 v170, s1, v139
	ds_read_b128 v[142:145], v154
	ds_read_b128 v[146:149], v154 offset:1024
	ds_read_b128 v[150:153], v154 offset:2048
	ds_read_b128 v[154:157], v154 offset:3072
	ds_read_b128 v[158:161], v170
	ds_read_b128 v[162:165], v170 offset:1024
	ds_read_b128 v[166:169], v170 offset:2048
	ds_read_b128 v[170:173], v170 offset:3072
	s_add_u32 s16, s24, 0x160000
	s_addc_u32 s17, s25, 0
	s_mov_b32 m0, s31
	v_lshl_add_u64 v[222:223], s[16:17], 0, v[128:129]
	ds_read_b128 v[174:177], v141 offset:32768
	ds_read_b128 v[178:181], v141 offset:33792
	ds_read_b128 v[182:185], v141 offset:34816
	ds_read_b128 v[196:199], v141 offset:35840
	ds_read_b128 v[200:203], v141 offset:36864
	ds_read_b128 v[204:207], v141 offset:37888
	ds_read_b128 v[208:211], v141 offset:38912
	ds_read_b128 v[212:215], v141 offset:39936
	global_load_lds_dwordx4 v[222:223], off
	v_lshl_add_u64 v[222:223], s[16:17], 0, v[130:131]
	s_mov_b32 m0, s33
	s_nop 0
	global_load_lds_dwordx4 v[222:223], off
	s_waitcnt vmcnt(8)
	s_waitcnt lgkmcnt(0)
	s_barrier
	s_setprio 1
	v_mfma_f32_16x16x32_bf16 v[124:127], v[142:145], v[174:177], v[124:127]
	v_mfma_f32_16x16x32_bf16 v[120:123], v[150:153], v[174:177], v[120:123]
	v_mfma_f32_16x16x32_bf16 v[116:119], v[142:145], v[182:185], v[116:119]
	v_mfma_f32_16x16x32_bf16 v[112:115], v[150:153], v[182:185], v[112:115]
	v_mfma_f32_16x16x32_bf16 v[100:103], v[142:145], v[200:203], v[100:103]
	v_mfma_f32_16x16x32_bf16 v[96:99], v[150:153], v[200:203], v[96:99]
	v_mfma_f32_16x16x32_bf16 v[84:87], v[142:145], v[208:211], v[84:87]
	v_mfma_f32_16x16x32_bf16 v[80:83], v[150:153], v[208:211], v[80:83]
	v_mfma_f32_16x16x32_bf16 v[124:127], v[146:149], v[178:181], v[124:127]
	v_mfma_f32_16x16x32_bf16 v[120:123], v[154:157], v[178:181], v[120:123]
	v_mfma_f32_16x16x32_bf16 v[116:119], v[146:149], v[196:199], v[116:119]
	v_mfma_f32_16x16x32_bf16 v[112:115], v[154:157], v[196:199], v[112:115]
	v_mfma_f32_16x16x32_bf16 v[100:103], v[146:149], v[204:207], v[100:103]
	v_mfma_f32_16x16x32_bf16 v[96:99], v[154:157], v[204:207], v[96:99]
	v_mfma_f32_16x16x32_bf16 v[84:87], v[146:149], v[212:215], v[84:87]
	v_mfma_f32_16x16x32_bf16 v[80:83], v[154:157], v[212:215], v[80:83]
	s_setprio 0
	s_setprio 1
	v_mfma_f32_16x16x32_bf16 v[108:111], v[158:161], v[174:177], v[108:111]
	v_mfma_f32_16x16x32_bf16 v[104:107], v[166:169], v[174:177], v[104:107]
	v_mfma_f32_16x16x32_bf16 v[92:95], v[158:161], v[182:185], v[92:95]
	v_mfma_f32_16x16x32_bf16 v[88:91], v[166:169], v[182:185], v[88:91]
	v_mfma_f32_16x16x32_bf16 v[76:79], v[158:161], v[200:203], v[76:79]
	v_mfma_f32_16x16x32_bf16 v[72:75], v[166:169], v[200:203], v[72:75]
	v_mfma_f32_16x16x32_bf16 v[68:71], v[158:161], v[208:211], v[68:71]
	v_mfma_f32_16x16x32_bf16 v[64:67], v[166:169], v[208:211], v[64:67]
	v_mfma_f32_16x16x32_bf16 v[108:111], v[162:165], v[178:181], v[108:111]
	v_mfma_f32_16x16x32_bf16 v[104:107], v[170:173], v[178:181], v[104:107]
	v_mfma_f32_16x16x32_bf16 v[92:95], v[162:165], v[196:199], v[92:95]
	v_mfma_f32_16x16x32_bf16 v[88:91], v[170:173], v[196:199], v[88:91]
	v_mfma_f32_16x16x32_bf16 v[76:79], v[162:165], v[204:207], v[76:79]
	v_mfma_f32_16x16x32_bf16 v[72:75], v[170:173], v[204:207], v[72:75]
	v_mfma_f32_16x16x32_bf16 v[68:71], v[162:165], v[212:215], v[68:71]
	v_mfma_f32_16x16x32_bf16 v[64:67], v[170:173], v[212:215], v[64:67]
	s_setprio 0
	s_barrier
	s_add_i32 s0, s0, s28
	v_lshl_add_u64 v[186:187], v[186:187], 0, s[58:59]
	s_mov_b32 m0, s0
	ds_read_b128 v[174:177], v141 offset:49152
	ds_read_b128 v[178:181], v141 offset:50176
	ds_read_b128 v[182:185], v141 offset:51200
	ds_read_b128 v[196:199], v141 offset:52224
	ds_read_b128 v[200:203], v141 offset:53248
	ds_read_b128 v[204:207], v141 offset:54272
	ds_read_b128 v[208:211], v141 offset:55296
	ds_read_b128 v[212:215], v141 offset:56320
	global_load_lds_dwordx4 v[186:187], off
	s_add_i32 m0, s0, 0x2000
	s_add_u32 s16, s22, 0x160080
	v_lshl_add_u64 v[186:187], v[216:217], 0, s[58:59]
	s_addc_u32 s17, s23, 0
	s_add_i32 s0, s1, s28
	global_load_lds_dwordx4 v[186:187], off
	v_lshl_add_u64 v[186:187], s[16:17], 0, v[190:191]
	s_mov_b32 m0, s0
	s_nop 0
	global_load_lds_dwordx4 v[186:187], off
	v_lshl_add_u64 v[186:187], s[16:17], 0, v[132:133]
	s_add_i32 m0, s0, 0x2000
	s_nop 0
	global_load_lds_dwordx4 v[186:187], off
	v_lshl_add_u64 v[186:187], v[218:219], 0, s[58:59]
	s_mov_b32 m0, s37
	s_nop 0
	global_load_lds_dwordx4 v[186:187], off
	v_lshl_add_u64 v[186:187], v[220:221], 0, s[58:59]
	s_mov_b32 m0, s38
	s_nop 0
	global_load_lds_dwordx4 v[186:187], off
	s_waitcnt vmcnt(8)
	s_waitcnt lgkmcnt(0)
	s_barrier
	s_setprio 1
	v_mfma_f32_16x16x32_bf16 v[60:63], v[142:145], v[174:177], v[60:63]
	v_mfma_f32_16x16x32_bf16 v[56:59], v[150:153], v[174:177], v[56:59]
	v_mfma_f32_16x16x32_bf16 v[52:55], v[142:145], v[182:185], v[52:55]
	v_mfma_f32_16x16x32_bf16 v[48:51], v[150:153], v[182:185], v[48:51]
	v_mfma_f32_16x16x32_bf16 v[36:39], v[142:145], v[200:203], v[36:39]
	v_mfma_f32_16x16x32_bf16 v[32:35], v[150:153], v[200:203], v[32:35]
	v_mfma_f32_16x16x32_bf16 v[20:23], v[142:145], v[208:211], v[20:23]
	v_mfma_f32_16x16x32_bf16 v[16:19], v[150:153], v[208:211], v[16:19]
	v_mfma_f32_16x16x32_bf16 v[60:63], v[146:149], v[178:181], v[60:63]
	v_mfma_f32_16x16x32_bf16 v[56:59], v[154:157], v[178:181], v[56:59]
	v_mfma_f32_16x16x32_bf16 v[52:55], v[146:149], v[196:199], v[52:55]
	v_mfma_f32_16x16x32_bf16 v[48:51], v[154:157], v[196:199], v[48:51]
	v_mfma_f32_16x16x32_bf16 v[36:39], v[146:149], v[204:207], v[36:39]
	v_mfma_f32_16x16x32_bf16 v[32:35], v[154:157], v[204:207], v[32:35]
	v_mfma_f32_16x16x32_bf16 v[20:23], v[146:149], v[212:215], v[20:23]
	v_mfma_f32_16x16x32_bf16 v[16:19], v[154:157], v[212:215], v[16:19]
	s_setprio 0
	s_setprio 1
	v_mfma_f32_16x16x32_bf16 v[44:47], v[158:161], v[174:177], v[44:47]
	v_mfma_f32_16x16x32_bf16 v[40:43], v[166:169], v[174:177], v[40:43]
	v_mfma_f32_16x16x32_bf16 v[28:31], v[158:161], v[182:185], v[28:31]
	v_mfma_f32_16x16x32_bf16 v[24:27], v[166:169], v[182:185], v[24:27]
	v_mfma_f32_16x16x32_bf16 v[12:15], v[158:161], v[200:203], v[12:15]
	v_mfma_f32_16x16x32_bf16 v[8:11], v[166:169], v[200:203], v[8:11]
	v_mfma_f32_16x16x32_bf16 v[4:7], v[158:161], v[208:211], v[4:7]
	v_mfma_f32_16x16x32_bf16 v[0:3], v[166:169], v[208:211], v[0:3]
	v_mfma_f32_16x16x32_bf16 v[44:47], v[162:165], v[178:181], v[44:47]
	v_mfma_f32_16x16x32_bf16 v[40:43], v[170:173], v[178:181], v[40:43]
	v_mfma_f32_16x16x32_bf16 v[28:31], v[162:165], v[196:199], v[28:31]
	v_mfma_f32_16x16x32_bf16 v[24:27], v[170:173], v[196:199], v[24:27]
	v_mfma_f32_16x16x32_bf16 v[12:15], v[162:165], v[204:207], v[12:15]
	v_mfma_f32_16x16x32_bf16 v[8:11], v[170:173], v[204:207], v[8:11]
	v_mfma_f32_16x16x32_bf16 v[4:7], v[162:165], v[212:215], v[4:7]
	v_mfma_f32_16x16x32_bf16 v[0:3], v[170:173], v[212:215], v[0:3]
	s_setprio 0
	s_barrier
	s_add_i32 s53, s53, 2
	s_add_u32 s47, s47, 0x100
	s_addc_u32 s52, s52, 0
	s_cmpk_gt_u32 s53, 0x55
	s_mov_b64 s[16:17], s[20:21]
	s_cbranch_scc0 .LBB0_1350
